# deferred softmax rescale: running max moves only when the tile max exceeds it by more than 8 (log2), exact softmax; on top of v33
# speedup vs baseline: 1.0107x; 1.0107x over previous
; DI int crow(int i, int h) { return (i & 3) + 8 * (i >> 2) + 4 * h; }
;     ...
;   float mx = NINF;
; #pragma unroll
;   for (int k2 = 0; k2 < 2; ++k2)
; #pragma unroll
;     for (int i = 0; i < 16; ++i) {
;       if (!(HM & (1 << k2))) continue;
;       float v = s[k2][i];
;       if (MASKED) {
;         const int tk = key0 + 32 * k2 + crow(i, h);
;         const bool valid = (MODE == 0) ? ((tk <= tq) && (tq - tk <= maxdist)) : (tk <= tq);
;         v = valid ? v : NINF; s[k2][i] = v;
;       }
;       mx = fmaxf(mx, v);
;     }
;   mx = fmaxf(mx, __shfl_xor(mx, 32));
;   if (MODE != 1) mx *= L2E;
;   if (MODE == 2) mx = lanesel ? mx : NINF;
;   const float mn = fmaxf(m, mx); const float alpha = __builtin_amdgcn_exp2f(m - mn);
;   const float neg = (MODE == 2 && !lanesel) ? NINF : -mn;
; template <int MODE>
; DI void flash_loop(char* smem, const bf16_t* Kbase, size_t ldk, const bf16_t* Vtbase, size_t ldv, ull tiles, ull wtiles,
;                    const bf16x8 (&qf)[4], f32x16 (&o)[2], float& m, float& l, int tq, int tqmin, int tqmax, int maxdist, const float* cn_lds, ull lmask) {
;     ...
;     if (!((wtiles >> kt) & 1ull)) return;
;     const bf16_t* Ks = (const bf16_t*)(smem + stage * (2 * 64 * LSTR * 2)); const bf16_t* Vs = Ks + 64 * LSTR;
;     const bool sel = ((lmask >> kt) & 1ull) != 0;
;     const bool interior = (64 * kt + 63 <= tqmin) && (MODE != 0 || (tqmax - 64 * kt <= maxdist));
;     int hm = 3;
;     if (MODE == 0) {
;       hm = 0;
;       if (64 * kt <= tqmax && 64 * kt + 31 >= tqmin - maxdist) hm |= 1;
;       if (64 * kt + 32 <= tqmax && 64 * kt + 63 >= tqmin - maxdist) hm |= 2;
;     }
;     if (MODE == 0 && hm == 1) attn_tile<MODE, true, 1>(Ks, Vs, qf, o, m, l, 64 * kt, tq, maxdist, cn_lds, sel);
;     else if (MODE == 0 && hm == 2) attn_tile<MODE, true, 2>(Ks, Vs, qf, o, m, l, 64 * kt, tq, maxdist, cn_lds, sel);
.LBB0_466:
	s_lshr_b64 s[6:7], s[4:5], s33
	s_and_b32 s58, s6, 1
	s_cmp_eq_u64 s[58:59], 0
	s_cbranch_scc1 .LBB0_490
	s_lshl_b32 s58, s33, 6
	s_or_b32 s33, s58, 63
	s_cmp_le_u32 s58, s30
	s_cselect_b64 s[6:7], -1, 0
	s_or_b32 s36, s58, 31
	s_cmp_ge_i32 s36, s29
	s_cselect_b64 s[36:37], -1, 0
	s_and_b64 s[6:7], s[6:7], s[36:37]
	v_cndmask_b32_e64 v0, 0, 1, s[6:7]
	s_or_b32 s6, s58, 32
	s_cmp_gt_u32 s6, s30
	s_cselect_b64 s[6:7], -1, 0
	s_cmp_lt_i32 s33, s29
	s_cselect_b64 s[36:37], -1, 0
	v_readfirstlane_b32 s38, v0
	s_or_b32 s39, s38, 2
	s_or_b64 s[6:7], s[6:7], s[36:37]
	s_and_b64 s[6:7], s[6:7], exec
	s_cselect_b32 s67, s38, s39
	s_mov_b64 s[62:63], -1
	s_mov_b64 s[54:55], 0
	s_cmp_lt_i32 s67, 2
	s_mov_b64 s[6:7], 0
	s_cbranch_scc1 .LBB0_483
	s_cmp_eq_u32 s67, 2
	s_mov_b64 s[6:7], -1
	s_cbranch_scc0 .LBB0_472
	ds_read_b128 v[34:37], v199 offset:4608
	ds_read_b128 v[50:53], v199 offset:4640
	v_or_b32_e32 v0, s58, v197
	s_waitcnt lgkmcnt(1)
	v_mfma_f32_32x32x16_bf16 v[34:49], v[34:37], v[98:101], 0
	s_waitcnt lgkmcnt(0)
	v_mfma_f32_32x32x16_bf16 v[34:49], v[50:53], v[102:105], v[34:49]
	ds_read_b128 v[50:53], v199 offset:4672
	s_waitcnt lgkmcnt(0)
	v_mfma_f32_32x32x16_bf16 v[34:49], v[50:53], v[106:109], v[34:49]
	ds_read_b128 v[50:53], v199 offset:4704
	s_waitcnt lgkmcnt(0)
	v_mfma_f32_32x32x16_bf16 v[34:49], v[50:53], v[110:113], v[34:49]
	v_or_b32_e32 v50, 32, v0
	v_cmp_gt_u32_e32 vcc, v50, v154
	v_cmp_lt_i32_e64 s[6:7], v50, v155
	s_or_b64 vcc, vcc, s[6:7]
	s_nop 7
	v_cndmask_b32_e32 v66, v34, v204, vcc
	v_bitop3_b32 v34, s58, v205, v197 bitop3:0x36
	v_cmp_ge_u32_e32 vcc, v50, v154
	v_cmp_gt_i32_e64 s[6:7], v34, v156
	s_or_b64 vcc, vcc, s[6:7]
	v_cndmask_b32_e32 v67, v35, v204, vcc
	v_or_b32_e32 v35, 34, v0
	v_cmp_gt_u32_e32 vcc, v35, v154
	v_cmp_lt_i32_e64 s[6:7], v35, v155
	s_or_b64 vcc, vcc, s[6:7]
	v_or_b32_e32 v35, 35, v0
	v_cndmask_b32_e32 v68, v36, v204, vcc
	v_cmp_gt_u32_e32 vcc, v35, v154
	v_cmp_lt_i32_e64 s[6:7], v35, v155
	s_or_b64 vcc, vcc, s[6:7]
	v_or_b32_e32 v35, 40, v0
	v_cndmask_b32_e32 v69, v37, v204, vcc
	v_cmp_gt_u32_e32 vcc, v35, v154
	v_cmp_lt_i32_e64 s[6:7], v35, v155
	s_or_b64 vcc, vcc, s[6:7]
	v_or_b32_e32 v35, 41, v0
	v_cndmask_b32_e32 v70, v38, v204, vcc
	v_cmp_gt_u32_e32 vcc, v35, v154
	v_cmp_lt_i32_e64 s[6:7], v35, v155
	s_or_b64 vcc, vcc, s[6:7]
	v_or_b32_e32 v35, 42, v0
	v_cndmask_b32_e32 v71, v39, v204, vcc
	v_cmp_gt_u32_e32 vcc, v35, v154
	v_cmp_lt_i32_e64 s[6:7], v35, v155
	s_or_b64 vcc, vcc, s[6:7]
	v_or_b32_e32 v35, 43, v0
	v_cndmask_b32_e32 v77, v40, v204, vcc
	v_cmp_gt_u32_e32 vcc, v35, v154
	v_cmp_lt_i32_e64 s[6:7], v35, v155
	s_or_b64 vcc, vcc, s[6:7]
	v_or_b32_e32 v35, 48, v0
	v_cndmask_b32_e32 v78, v41, v204, vcc
	v_cmp_gt_u32_e32 vcc, v35, v154
	v_cmp_lt_i32_e64 s[6:7], v35, v155
	s_or_b64 vcc, vcc, s[6:7]
	v_or_b32_e32 v35, 49, v0
	v_cndmask_b32_e32 v79, v42, v204, vcc
	v_cmp_gt_u32_e32 vcc, v35, v154
	v_cmp_lt_i32_e64 s[6:7], v35, v155
	s_or_b64 vcc, vcc, s[6:7]
	v_or_b32_e32 v35, 50, v0
	v_cndmask_b32_e32 v80, v43, v204, vcc
	v_cmp_gt_u32_e32 vcc, v35, v154
	v_cmp_lt_i32_e64 s[6:7], v35, v155
	s_or_b64 vcc, vcc, s[6:7]
	v_or_b32_e32 v35, 51, v0
	v_cndmask_b32_e32 v81, v44, v204, vcc
	v_cmp_gt_u32_e32 vcc, v35, v154
	v_cmp_lt_i32_e64 s[6:7], v35, v155
	s_or_b64 vcc, vcc, s[6:7]
	v_or_b32_e32 v35, 56, v0
	v_cndmask_b32_e32 v76, v45, v204, vcc
	v_cmp_gt_u32_e32 vcc, v35, v154
	v_cmp_lt_i32_e64 s[6:7], v35, v155
	s_or_b64 vcc, vcc, s[6:7]
	v_or_b32_e32 v35, 57, v0
	v_max3_f32 v34, v66, s35, v67
	v_cndmask_b32_e32 v73, v46, v204, vcc
	v_cmp_gt_u32_e32 vcc, v35, v154
	v_cmp_lt_i32_e64 s[6:7], v35, v155
	v_max3_f32 v34, v34, v68, v69
	s_or_b64 vcc, vcc, s[6:7]
	v_or_b32_e32 v35, 58, v0
	v_max3_f32 v34, v34, v70, v71
	v_cndmask_b32_e32 v74, v47, v204, vcc
	v_cmp_gt_u32_e32 vcc, v35, v154
	v_cmp_lt_i32_e64 s[6:7], v35, v155
	v_max3_f32 v34, v34, v77, v78
	s_or_b64 vcc, vcc, s[6:7]
	v_or_b32_e32 v0, 59, v0
	v_max3_f32 v34, v34, v79, v80
	v_cndmask_b32_e32 v75, v48, v204, vcc
	v_cmp_gt_u32_e32 vcc, v0, v154
	v_cmp_lt_i32_e64 s[6:7], v0, v155
	v_max3_f32 v34, v34, v81, v76
	s_or_b64 vcc, vcc, s[6:7]
	v_max3_f32 v34, v34, v73, v74
	v_cndmask_b32_e32 v72, v49, v204, vcc
	v_and_b32_e32 v35, 64, v202
	v_max3_f32 v0, v34, v75, v72
	v_xor_b32_e32 v34, 32, v202
	v_add_u32_e32 v35, 64, v35
	v_cmp_lt_i32_e32 vcc, v34, v35
	s_nop 1
	v_cndmask_b32_e32 v34, v202, v34, vcc
	v_lshlrev_b32_e32 v34, 2, v34
	ds_bpermute_b32 v34, v34, v0
	s_waitcnt lgkmcnt(0)
	v_max_f32_e32 v34, v34, v34
	v_max_f32_e32 v0, v0, v34
	v_mul_f32_e32 v0, 0x3fb8aa3b, v0
	v_max_f32_e32 v34, v157, v157
	v_sub_f32_e32 v232, v0, v34
	v_cmp_lt_f32_e32 vcc, 0x41000000, v232
	s_nop 1
	v_cndmask_b32_e32 v158, v34, v0, vcc
	v_sub_f32_e32 v0, v157, v158
	v_exp_f32_e32 v0, v0
	v_cmp_neq_f32_e32 vcc, v158, v157
	s_cbranch_vccz .LBB0_471
	v_pk_mul_f32 v[32:33], v[32:33], v[0:1] op_sel_hi:[1,0]
	v_pk_mul_f32 v[30:31], v[30:31], v[0:1] op_sel_hi:[1,0]
	v_pk_mul_f32 v[28:29], v[28:29], v[0:1] op_sel_hi:[1,0]
	v_pk_mul_f32 v[26:27], v[26:27], v[0:1] op_sel_hi:[1,0]
	v_pk_mul_f32 v[24:25], v[24:25], v[0:1] op_sel_hi:[1,0]
	v_pk_mul_f32 v[22:23], v[22:23], v[0:1] op_sel_hi:[1,0]
	v_pk_mul_f32 v[20:21], v[20:21], v[0:1] op_sel_hi:[1,0]
	v_pk_mul_f32 v[18:19], v[18:19], v[0:1] op_sel_hi:[1,0]
	v_pk_mul_f32 v[16:17], v[16:17], v[0:1] op_sel_hi:[1,0]
	v_pk_mul_f32 v[14:15], v[14:15], v[0:1] op_sel_hi:[1,0]
	v_pk_mul_f32 v[12:13], v[12:13], v[0:1] op_sel_hi:[1,0]
	v_pk_mul_f32 v[10:11], v[10:11], v[0:1] op_sel_hi:[1,0]
	v_pk_mul_f32 v[8:9], v[8:9], v[0:1] op_sel_hi:[1,0]
	v_pk_mul_f32 v[6:7], v[6:7], v[0:1] op_sel_hi:[1,0]
	v_pk_mul_f32 v[4:5], v[4:5], v[0:1] op_sel_hi:[1,0]
	v_pk_mul_f32 v[2:3], v[2:3], v[0:1] op_sel_hi:[1,0]

; DI f32x16 mfma32(bf16x8 a, bf16x8 b, f32x16 c) { return __builtin_amdgcn_mfma_f32_32x32x16_bf16(a, b, c, 0, 0, 0); }
; DI int crow(int i, int h) { return (i & 3) + 8 * (i >> 2) + 4 * h; }
;     ...
;   f32x16 s[2];
; #pragma unroll
;   for (int k2 = 0; k2 < 2; ++k2) {
;     if (!(HM & (1 << k2))) continue;
; #pragma unroll
;     for (int i = 0; i < 16; ++i) s[k2][i] = 0.f;
; #pragma unroll
;     for (int ks = 0; ks < 4; ++ks) {
;       const bf16x8 a = *(const bf16x8*)(Ks + (32 * k2 + r) * LSTR + 16 * ks + 8 * h);
;       s[k2] = mfma32(a, qf[ks], s[k2]);
;     }
;   }
;   if (MODE == 1) {
; #pragma unroll
;     for (int k2 = 0; k2 < 2; ++k2)
; #pragma unroll
;       for (int g = 0; g < 4; ++g) {
;         if (!(HM & (1 << k2))) continue;
;         const f32x4 cv = *(const f32x4*)(cn_lds + key0 + 32 * k2 + 8 * g + 4 * h);
; #pragma unroll
;         for (int e = 0; e < 4; ++e) s[k2][4 * g + e] = fmaf(s[k2][4 * g + e], L2E, cv[e]);
;       }
;   }
;   float mx = NINF;
; #pragma unroll
;   for (int k2 = 0; k2 < 2; ++k2)
; #pragma unroll
;     for (int i = 0; i < 16; ++i) {
;       if (!(HM & (1 << k2))) continue;
;       float v = s[k2][i];
;       if (MASKED) {
;         const int tk = key0 + 32 * k2 + crow(i, h);
;         const bool valid = (MODE == 0) ? ((tk <= tq) && (tq - tk <= maxdist)) : (tk <= tq);
;         v = valid ? v : NINF; s[k2][i] = v;
; template <int MODE>
; DI void flash_loop(char* smem, const bf16_t* Kbase, size_t ldk, const bf16_t* Vtbase, size_t ldv, ull tiles, ull wtiles,
;                    const bf16x8 (&qf)[4], f32x16 (&o)[2], float& m, float& l, int tq, int tqmin, int tqmax, int maxdist, const float* cn_lds, ull lmask) {
;     ...
;     const bool interior = (64 * kt + 63 <= tqmin) && (MODE != 0 || (tqmax - 64 * kt <= maxdist));
.LBB0_474:
	ds_read_b128 v[82:85], v196
	ds_read_b128 v[78:81], v196 offset:32
	ds_read_b128 v[74:77], v196 offset:64
	ds_read_b128 v[66:69], v196 offset:96
	ds_read_b128 v[70:73], v196 offset:4608
	s_cmp_le_u32 s33, s28
	s_cselect_b64 s[6:7], -1, 0
	s_cmp_ge_i32 s58, s31
	s_cselect_b64 s[36:37], -1, 0
	s_and_b64 s[6:7], s[6:7], s[36:37]
	s_andn2_b64 vcc, exec, s[6:7]
	s_mov_b64 s[6:7], -1
	s_cbranch_vccz .LBB0_478
	s_waitcnt lgkmcnt(4)
	v_mfma_f32_32x32x16_bf16 v[50:65], v[82:85], v[98:101], 0
	ds_read_b128 v[86:89], v196 offset:4640
	ds_read_b128 v[90:93], v196 offset:4672
	v_or_b32_e32 v0, s58, v197
	v_cmp_gt_u32_e32 vcc, v0, v154
	v_cmp_lt_i32_e64 s[6:7], v0, v155
	s_or_b64 vcc, vcc, s[6:7]
	s_waitcnt lgkmcnt(5)
	v_mfma_f32_32x32x16_bf16 v[50:65], v[78:81], v[102:105], v[50:65]
	s_waitcnt lgkmcnt(2)
	v_mfma_f32_32x32x16_bf16 v[34:49], v[70:73], v[98:101], 0
	v_mfma_f32_32x32x16_bf16 v[50:65], v[74:77], v[106:109], v[50:65]
	s_waitcnt lgkmcnt(1)
	v_mfma_f32_32x32x16_bf16 v[34:49], v[86:89], v[102:105], v[34:49]
	ds_read_b128 v[86:89], v196 offset:4704
	v_mfma_f32_32x32x16_bf16 v[50:65], v[66:69], v[110:113], v[50:65]
	s_waitcnt lgkmcnt(1)
	v_mfma_f32_32x32x16_bf16 v[34:49], v[90:93], v[106:109], v[34:49]
	s_waitcnt lgkmcnt(0)
	v_mfma_f32_32x32x16_bf16 v[34:49], v[86:89], v[110:113], v[34:49]
	s_nop 7
	v_cndmask_b32_e32 v86, v50, v204, vcc
	v_bitop3_b32 v50, s58, v197, s58 bitop3:3
	v_cmp_ge_u32_e32 vcc, v0, v154
	v_cmp_lt_i32_e64 s[6:7], v156, v50
	s_or_b64 vcc, vcc, s[6:7]
	v_cndmask_b32_e32 v87, v51, v204, vcc
	v_or_b32_e32 v51, 2, v0
	v_cmp_gt_u32_e32 vcc, v51, v154
	v_cmp_lt_i32_e64 s[6:7], v51, v155
	s_or_b64 vcc, vcc, s[6:7]
	v_or_b32_e32 v51, 3, v0
	v_cndmask_b32_e32 v88, v52, v204, vcc
	v_cmp_gt_u32_e32 vcc, v51, v154
	v_cmp_lt_i32_e64 s[6:7], v51, v155
	s_or_b64 vcc, vcc, s[6:7]
	v_or_b32_e32 v51, 8, v0
	v_cndmask_b32_e32 v89, v53, v204, vcc
	v_cmp_gt_u32_e32 vcc, v51, v154
	v_cmp_lt_i32_e64 s[6:7], v51, v155
	s_or_b64 vcc, vcc, s[6:7]
	v_or_b32_e32 v51, 9, v0
	v_cndmask_b32_e32 v90, v54, v204, vcc
	v_cmp_gt_u32_e32 vcc, v51, v154
	v_cmp_lt_i32_e64 s[6:7], v51, v155
	s_or_b64 vcc, vcc, s[6:7]
	v_or_b32_e32 v51, 10, v0
	v_cndmask_b32_e32 v192, v55, v204, vcc
	v_cmp_gt_u32_e32 vcc, v51, v154
	v_cmp_lt_i32_e64 s[6:7], v51, v155
	s_or_b64 vcc, vcc, s[6:7]
	v_or_b32_e32 v51, 11, v0
	v_cndmask_b32_e32 v191, v56, v204, vcc
	v_cmp_gt_u32_e32 vcc, v51, v154
	v_cmp_lt_i32_e64 s[6:7], v51, v155
	s_or_b64 vcc, vcc, s[6:7]
	v_or_b32_e32 v51, 16, v0
	v_cndmask_b32_e32 v193, v57, v204, vcc
	v_cmp_gt_u32_e32 vcc, v51, v154
	v_cmp_lt_i32_e64 s[6:7], v51, v155
	s_or_b64 vcc, vcc, s[6:7]
	v_or_b32_e32 v51, 17, v0
	v_cndmask_b32_e32 v188, v58, v204, vcc
	v_cmp_gt_u32_e32 vcc, v51, v154
	v_cmp_lt_i32_e64 s[6:7], v51, v155
	s_or_b64 vcc, vcc, s[6:7]
	v_or_b32_e32 v51, 18, v0
	v_cndmask_b32_e32 v190, v59, v204, vcc
	v_cmp_gt_u32_e32 vcc, v51, v154
	v_cmp_lt_i32_e64 s[6:7], v51, v155
	s_or_b64 vcc, vcc, s[6:7]
	v_or_b32_e32 v51, 19, v0
	v_cndmask_b32_e32 v189, v60, v204, vcc
	v_cmp_gt_u32_e32 vcc, v51, v154
	v_cmp_lt_i32_e64 s[6:7], v51, v155
	s_or_b64 vcc, vcc, s[6:7]
	v_or_b32_e32 v51, 24, v0
	v_cndmask_b32_e32 v187, v61, v204, vcc
	v_cmp_gt_u32_e32 vcc, v51, v154
	v_cmp_lt_i32_e64 s[6:7], v51, v155
	s_or_b64 vcc, vcc, s[6:7]
	v_or_b32_e32 v51, 25, v0
	v_cndmask_b32_e32 v186, v62, v204, vcc
	v_cmp_gt_u32_e32 vcc, v51, v154
	v_cmp_lt_i32_e64 s[6:7], v51, v155
	s_or_b64 vcc, vcc, s[6:7]
	v_or_b32_e32 v51, 26, v0
	v_cndmask_b32_e32 v185, v63, v204, vcc
	v_cmp_gt_u32_e32 vcc, v51, v154
	v_cmp_lt_i32_e64 s[6:7], v51, v155
	s_or_b64 vcc, vcc, s[6:7]
	v_or_b32_e32 v51, 27, v0
	v_cndmask_b32_e32 v184, v64, v204, vcc
	v_cmp_gt_u32_e32 vcc, v51, v154
	v_cmp_lt_i32_e64 s[6:7], v51, v155
	s_or_b64 vcc, vcc, s[6:7]
	v_or_b32_e32 v51, 32, v0
	v_cndmask_b32_e32 v182, v65, v204, vcc
	v_cmp_gt_u32_e32 vcc, v51, v154
	v_cmp_lt_i32_e64 s[6:7], v51, v155
	s_or_b64 vcc, vcc, s[6:7]
	v_cndmask_b32_e32 v164, v34, v204, vcc
	v_or_b32_e32 v34, 33, v0
	v_cmp_gt_u32_e32 vcc, v34, v154
	v_cmp_lt_i32_e64 s[6:7], v34, v155
	s_or_b64 vcc, vcc, s[6:7]
	v_cndmask_b32_e32 v162, v35, v204, vcc
	v_or_b32_e32 v35, 34, v0
	v_cmp_gt_u32_e32 vcc, v35, v154
; DI int crow(int i, int h) { return (i & 3) + 8 * (i >> 2) + 4 * h; }
;     ...
;   float mx = NINF;
; #pragma unroll
;   for (int k2 = 0; k2 < 2; ++k2)
; #pragma unroll
;     for (int i = 0; i < 16; ++i) {
;       if (!(HM & (1 << k2))) continue;
;       float v = s[k2][i];
;       if (MASKED) {
;         const int tk = key0 + 32 * k2 + crow(i, h);
;         const bool valid = (MODE == 0) ? ((tk <= tq) && (tq - tk <= maxdist)) : (tk <= tq);
;         v = valid ? v : NINF; s[k2][i] = v;
;       }
;       mx = fmaxf(mx, v);
;     }
;   mx = fmaxf(mx, __shfl_xor(mx, 32));
;   if (MODE != 1) mx *= L2E;
;   if (MODE == 2) mx = lanesel ? mx : NINF;
;   const float mn = fmaxf(m, mx); const float alpha = __builtin_amdgcn_exp2f(m - mn);
;   const float neg = (MODE == 2 && !lanesel) ? NINF : -mn;
;   float ps = 0.f;
; #pragma unroll
;   for (int k2 = 0; k2 < 2; ++k2)
; #pragma unroll
;     for (int i = 0; i < 16; ++i) {
;       if (!(HM & (1 << k2))) continue;
;       const float pv = (MODE == 1) ? __builtin_amdgcn_exp2f(s[k2][i] + neg) : __builtin_amdgcn_exp2f(fmaf(s[k2][i], L2E, neg));
;       s[k2][i] = pv; ps += pv;
;     }
;   l = l * alpha + ps;
;   if (__builtin_amdgcn_ballot_w64(mn != m) != 0ull) {
; #pragma unroll
;     for (int dt = 0; dt < 2; ++dt)
; #pragma unroll
;       for (int i = 0; i < 16; ++i) o[dt][i] *= alpha;
;   }
	v_cmp_lt_i32_e64 s[6:7], v35, v155
	s_or_b64 vcc, vcc, s[6:7]
	v_or_b32_e32 v35, 35, v0
	v_cndmask_b32_e32 v160, v36, v204, vcc
	v_cmp_gt_u32_e32 vcc, v35, v154
	v_cmp_lt_i32_e64 s[6:7], v35, v155
	s_or_b64 vcc, vcc, s[6:7]
	v_or_b32_e32 v35, 40, v0
	v_cndmask_b32_e32 v97, v37, v204, vcc
	v_cmp_gt_u32_e32 vcc, v35, v154
	v_cmp_lt_i32_e64 s[6:7], v35, v155
	s_or_b64 vcc, vcc, s[6:7]
	v_or_b32_e32 v35, 41, v0
	v_cndmask_b32_e32 v92, v38, v204, vcc
	v_cmp_gt_u32_e32 vcc, v35, v154
	v_cmp_lt_i32_e64 s[6:7], v35, v155
	s_or_b64 vcc, vcc, s[6:7]
	v_or_b32_e32 v35, 42, v0
	v_cndmask_b32_e32 v91, v39, v204, vcc
	v_cmp_gt_u32_e32 vcc, v35, v154
	v_cmp_lt_i32_e64 s[6:7], v35, v155
	s_or_b64 vcc, vcc, s[6:7]
	v_or_b32_e32 v35, 43, v0
	v_cndmask_b32_e32 v93, v40, v204, vcc
	v_cmp_gt_u32_e32 vcc, v35, v154
	v_cmp_lt_i32_e64 s[6:7], v35, v155
	s_or_b64 vcc, vcc, s[6:7]
	v_or_b32_e32 v35, 48, v0
	v_cndmask_b32_e32 v94, v41, v204, vcc
	v_cmp_gt_u32_e32 vcc, v35, v154
	v_cmp_lt_i32_e64 s[6:7], v35, v155
	s_or_b64 vcc, vcc, s[6:7]
	v_or_b32_e32 v35, 49, v0
	v_max3_f32 v50, v86, s35, v87
	v_cndmask_b32_e32 v95, v42, v204, vcc
	v_cmp_gt_u32_e32 vcc, v35, v154
	v_cmp_lt_i32_e64 s[6:7], v35, v155
	v_max3_f32 v50, v50, v88, v89
	s_or_b64 vcc, vcc, s[6:7]
	v_or_b32_e32 v35, 50, v0
	v_max3_f32 v50, v50, v90, v192
	v_cndmask_b32_e32 v96, v43, v204, vcc
	v_cmp_gt_u32_e32 vcc, v35, v154
	v_cmp_lt_i32_e64 s[6:7], v35, v155
	v_max3_f32 v50, v50, v191, v193
	s_or_b64 vcc, vcc, s[6:7]
	v_or_b32_e32 v35, 51, v0
	v_max3_f32 v50, v50, v188, v190
	v_cndmask_b32_e32 v161, v44, v204, vcc
	v_cmp_gt_u32_e32 vcc, v35, v154
	v_cmp_lt_i32_e64 s[6:7], v35, v155
	v_max3_f32 v50, v50, v189, v187
	s_or_b64 vcc, vcc, s[6:7]
	v_or_b32_e32 v35, 56, v0
	v_max3_f32 v50, v50, v186, v185
	v_cndmask_b32_e32 v163, v45, v204, vcc
	v_cmp_gt_u32_e32 vcc, v35, v154
	v_cmp_lt_i32_e64 s[6:7], v35, v155
	v_max3_f32 v50, v50, v184, v182
	s_or_b64 vcc, vcc, s[6:7]
	v_or_b32_e32 v35, 57, v0
	v_max3_f32 v34, v50, v164, v162
	v_cndmask_b32_e32 v165, v46, v204, vcc
	v_cmp_gt_u32_e32 vcc, v35, v154
	v_cmp_lt_i32_e64 s[6:7], v35, v155
	v_max3_f32 v34, v34, v160, v97
	s_or_b64 vcc, vcc, s[6:7]
	v_or_b32_e32 v35, 58, v0
	v_max3_f32 v34, v34, v92, v91
	v_cndmask_b32_e32 v180, v47, v204, vcc
	v_cmp_gt_u32_e32 vcc, v35, v154
	v_cmp_lt_i32_e64 s[6:7], v35, v155
	v_max3_f32 v34, v34, v93, v94
	s_or_b64 vcc, vcc, s[6:7]
	v_or_b32_e32 v0, 59, v0
	v_max3_f32 v34, v34, v95, v96
	v_cndmask_b32_e32 v181, v48, v204, vcc
	v_cmp_gt_u32_e32 vcc, v0, v154
	v_cmp_lt_i32_e64 s[6:7], v0, v155
	v_max3_f32 v34, v34, v161, v163
	s_or_b64 vcc, vcc, s[6:7]
	v_max3_f32 v34, v34, v165, v180
	v_cndmask_b32_e32 v183, v49, v204, vcc
	v_and_b32_e32 v35, 64, v202
	v_max3_f32 v0, v34, v181, v183
	v_xor_b32_e32 v34, 32, v202
	v_add_u32_e32 v35, 64, v35
	v_cmp_lt_i32_e32 vcc, v34, v35
	s_nop 1
	v_cndmask_b32_e32 v34, v202, v34, vcc
	v_lshlrev_b32_e32 v34, 2, v34
	ds_bpermute_b32 v34, v34, v0
	s_waitcnt lgkmcnt(0)
	v_max_f32_e32 v34, v34, v34
	v_max_f32_e32 v0, v0, v34
	v_mul_f32_e32 v0, 0x3fb8aa3b, v0
	v_max_f32_e32 v34, v157, v157
	v_sub_f32_e32 v232, v0, v34
	v_cmp_lt_f32_e32 vcc, 0x41000000, v232
	s_nop 1
	v_cndmask_b32_e32 v158, v34, v0, vcc
	v_sub_f32_e32 v0, v157, v158
	v_exp_f32_e32 v0, v0
	v_cmp_neq_f32_e32 vcc, v158, v157
	s_cbranch_vccz .LBB0_477
	v_pk_mul_f32 v[32:33], v[32:33], v[0:1] op_sel_hi:[1,0]
	v_pk_mul_f32 v[30:31], v[30:31], v[0:1] op_sel_hi:[1,0]
	v_pk_mul_f32 v[28:29], v[28:29], v[0:1] op_sel_hi:[1,0]
	v_pk_mul_f32 v[26:27], v[26:27], v[0:1] op_sel_hi:[1,0]
	v_pk_mul_f32 v[24:25], v[24:25], v[0:1] op_sel_hi:[1,0]
	v_pk_mul_f32 v[22:23], v[22:23], v[0:1] op_sel_hi:[1,0]
	v_pk_mul_f32 v[20:21], v[20:21], v[0:1] op_sel_hi:[1,0]
	v_pk_mul_f32 v[18:19], v[18:19], v[0:1] op_sel_hi:[1,0]
	v_pk_mul_f32 v[16:17], v[16:17], v[0:1] op_sel_hi:[1,0]
	v_pk_mul_f32 v[14:15], v[14:15], v[0:1] op_sel_hi:[1,0]
	v_pk_mul_f32 v[12:13], v[12:13], v[0:1] op_sel_hi:[1,0]
	v_pk_mul_f32 v[10:11], v[10:11], v[0:1] op_sel_hi:[1,0]
	v_pk_mul_f32 v[8:9], v[8:9], v[0:1] op_sel_hi:[1,0]
	v_pk_mul_f32 v[6:7], v[6:7], v[0:1] op_sel_hi:[1,0]
	v_pk_mul_f32 v[4:5], v[4:5], v[0:1] op_sel_hi:[1,0]
	v_pk_mul_f32 v[2:3], v[2:3], v[0:1] op_sel_hi:[1,0]

; DI f32x16 mfma32(bf16x8 a, bf16x8 b, f32x16 c) { return __builtin_amdgcn_mfma_f32_32x32x16_bf16(a, b, c, 0, 0, 0); }
; DI int crow(int i, int h) { return (i & 3) + 8 * (i >> 2) + 4 * h; }
;     ...
;   f32x16 s[2];
; #pragma unroll
;   for (int k2 = 0; k2 < 2; ++k2) {
;     if (!(HM & (1 << k2))) continue;
; #pragma unroll
;     for (int i = 0; i < 16; ++i) s[k2][i] = 0.f;
; #pragma unroll
;     for (int ks = 0; ks < 4; ++ks) {
;       const bf16x8 a = *(const bf16x8*)(Ks + (32 * k2 + r) * LSTR + 16 * ks + 8 * h);
;       s[k2] = mfma32(a, qf[ks], s[k2]);
;     }
;   }
;   if (MODE == 1) {
; #pragma unroll
;     for (int k2 = 0; k2 < 2; ++k2)
; #pragma unroll
;       for (int g = 0; g < 4; ++g) {
;         if (!(HM & (1 << k2))) continue;
;         const f32x4 cv = *(const f32x4*)(cn_lds + key0 + 32 * k2 + 8 * g + 4 * h);
; #pragma unroll
;         for (int e = 0; e < 4; ++e) s[k2][4 * g + e] = fmaf(s[k2][4 * g + e], L2E, cv[e]);
;       }
;   }
;   float mx = NINF;
; #pragma unroll
;   for (int k2 = 0; k2 < 2; ++k2)
; #pragma unroll
;     for (int i = 0; i < 16; ++i) {
;       if (!(HM & (1 << k2))) continue;
;       float v = s[k2][i];
;       if (MASKED) {
;         const int tk = key0 + 32 * k2 + crow(i, h);
;         const bool valid = (MODE == 0) ? ((tk <= tq) && (tq - tk <= maxdist)) : (tk <= tq);
;         v = valid ? v : NINF; s[k2][i] = v;
;       }
;       mx = fmaxf(mx, v);
;     }
;   mx = fmaxf(mx, __shfl_xor(mx, 32));
;   if (MODE != 1) mx *= L2E;
;   if (MODE == 2) mx = lanesel ? mx : NINF;
;   const float mn = fmaxf(m, mx); const float alpha = __builtin_amdgcn_exp2f(m - mn);
;   const float neg = (MODE == 2 && !lanesel) ? NINF : -mn;
;   float ps = 0.f;
; #pragma unroll
;   for (int k2 = 0; k2 < 2; ++k2)
; #pragma unroll
;     for (int i = 0; i < 16; ++i) {
;       if (!(HM & (1 << k2))) continue;
;       const float pv = (MODE == 1) ? __builtin_amdgcn_exp2f(s[k2][i] + neg) : __builtin_amdgcn_exp2f(fmaf(s[k2][i], L2E, neg));
;       s[k2][i] = pv; ps += pv;
;     }
;   l = l * alpha + ps;
;   if (__builtin_amdgcn_ballot_w64(mn != m) != 0ull) {
; #pragma unroll
;     for (int dt = 0; dt < 2; ++dt)
; #pragma unroll
;       for (int i = 0; i < 16; ++i) o[dt][i] *= alpha;
;   }
.LBB0_478:
	s_and_b64 vcc, exec, s[6:7]
	s_cbranch_vccz .LBB0_482
	s_waitcnt lgkmcnt(4)
	v_mfma_f32_32x32x16_bf16 v[82:97], v[82:85], v[98:101], 0
	s_nop 4
	ds_read_b128 v[34:37], v196 offset:4640
	ds_read_b128 v[38:41], v196 offset:4672
	s_waitcnt lgkmcnt(5)
	v_mfma_f32_32x32x16_bf16 v[82:97], v[78:81], v[102:105], v[82:97]
	s_waitcnt lgkmcnt(4)
	v_mfma_f32_32x32x16_bf16 v[82:97], v[74:77], v[106:109], v[82:97]
	s_waitcnt lgkmcnt(3)
	v_mfma_f32_32x32x16_bf16 v[82:97], v[66:69], v[110:113], v[82:97]
	s_waitcnt lgkmcnt(2)
	v_mfma_f32_32x32x16_bf16 v[66:81], v[70:73], v[98:101], 0
	s_nop 9
	v_max3_f32 v0, v82, s35, v83
	v_max3_f32 v0, v0, v84, v85
	v_max3_f32 v0, v0, v86, v87
	v_max3_f32 v0, v0, v88, v89
	v_max3_f32 v0, v0, v90, v91
	v_max3_f32 v0, v0, v92, v93
	v_max3_f32 v0, v0, v94, v95
	s_waitcnt lgkmcnt(1)
	v_mfma_f32_32x32x16_bf16 v[66:81], v[34:37], v[102:105], v[66:81]
	ds_read_b128 v[34:37], v196 offset:4704
	v_max3_f32 v0, v0, v96, v97
	s_waitcnt lgkmcnt(1)
	v_mfma_f32_32x32x16_bf16 v[66:81], v[38:41], v[106:109], v[66:81]
	s_waitcnt lgkmcnt(0)
	v_mfma_f32_32x32x16_bf16 v[66:81], v[34:37], v[110:113], v[66:81]
	v_and_b32_e32 v35, 64, v202
	v_xor_b32_e32 v34, 32, v202
	v_add_u32_e32 v35, 64, v35
	v_cmp_lt_i32_e32 vcc, v34, v35
	s_nop 1
	v_cndmask_b32_e32 v34, v202, v34, vcc
	s_nop 4
	v_max3_f32 v0, v0, v66, v67
	v_max3_f32 v0, v0, v68, v69
	v_max3_f32 v0, v0, v70, v71
	v_max3_f32 v0, v0, v72, v73
	v_max3_f32 v0, v0, v74, v75
	v_max3_f32 v0, v0, v76, v77
	v_max3_f32 v0, v0, v78, v79
	v_max3_f32 v0, v0, v80, v81
	v_lshlrev_b32_e32 v34, 2, v34
	ds_bpermute_b32 v34, v34, v0
	s_waitcnt lgkmcnt(0)
	v_max_f32_e32 v34, v34, v34
	v_max_f32_e32 v0, v0, v34
	v_mul_f32_e32 v0, 0x3fb8aa3b, v0
	v_max_f32_e32 v34, v157, v157
	v_sub_f32_e32 v232, v0, v34
	v_cmp_lt_f32_e32 vcc, 0x41000000, v232
	s_nop 1
	v_cndmask_b32_e32 v158, v34, v0, vcc
	v_sub_f32_e32 v0, v157, v158
	v_exp_f32_e32 v0, v0
	v_cmp_neq_f32_e32 vcc, v158, v157
	s_cbranch_vccz .LBB0_481
	v_pk_mul_f32 v[32:33], v[32:33], v[0:1] op_sel_hi:[1,0]
	v_pk_mul_f32 v[30:31], v[30:31], v[0:1] op_sel_hi:[1,0]
	v_pk_mul_f32 v[28:29], v[28:29], v[0:1] op_sel_hi:[1,0]
	v_pk_mul_f32 v[26:27], v[26:27], v[0:1] op_sel_hi:[1,0]
	v_pk_mul_f32 v[24:25], v[24:25], v[0:1] op_sel_hi:[1,0]
	v_pk_mul_f32 v[22:23], v[22:23], v[0:1] op_sel_hi:[1,0]
	v_pk_mul_f32 v[20:21], v[20:21], v[0:1] op_sel_hi:[1,0]
	v_pk_mul_f32 v[18:19], v[18:19], v[0:1] op_sel_hi:[1,0]
	v_pk_mul_f32 v[16:17], v[16:17], v[0:1] op_sel_hi:[1,0]
	v_pk_mul_f32 v[14:15], v[14:15], v[0:1] op_sel_hi:[1,0]
	v_pk_mul_f32 v[12:13], v[12:13], v[0:1] op_sel_hi:[1,0]
	v_pk_mul_f32 v[10:11], v[10:11], v[0:1] op_sel_hi:[1,0]
	v_pk_mul_f32 v[8:9], v[8:9], v[0:1] op_sel_hi:[1,0]
	v_pk_mul_f32 v[6:7], v[6:7], v[0:1] op_sel_hi:[1,0]
	v_pk_mul_f32 v[4:5], v[4:5], v[0:1] op_sel_hi:[1,0]
	v_pk_mul_f32 v[2:3], v[2:3], v[0:1] op_sel_hi:[1,0]

;     ...
;   f32x16 s[2];
; #pragma unroll
;   for (int k2 = 0; k2 < 2; ++k2) {
;     if (!(HM & (1 << k2))) continue;
; #pragma unroll
;     for (int i = 0; i < 16; ++i) s[k2][i] = 0.f;
; #pragma unroll
;     for (int ks = 0; ks < 4; ++ks) {
;       const bf16x8 a = *(const bf16x8*)(Ks + (32 * k2 + r) * LSTR + 16 * ks + 8 * h);
;       s[k2] = mfma32(a, qf[ks], s[k2]);
;     }
;   }
;   if (MODE == 1) {
; #pragma unroll
;     for (int k2 = 0; k2 < 2; ++k2)
; #pragma unroll
;       for (int g = 0; g < 4; ++g) {
;         if (!(HM & (1 << k2))) continue;
;         const f32x4 cv = *(const f32x4*)(cn_lds + key0 + 32 * k2 + 8 * g + 4 * h);
; #pragma unroll
;         for (int e = 0; e < 4; ++e) s[k2][4 * g + e] = fmaf(s[k2][4 * g + e], L2E, cv[e]);
;       }
;   }
;   float mx = NINF;
; #pragma unroll
;   for (int k2 = 0; k2 < 2; ++k2)
; #pragma unroll
;     for (int i = 0; i < 16; ++i) {
;       if (!(HM & (1 << k2))) continue;
;       float v = s[k2][i];
;       if (MASKED) {
;         const int tk = key0 + 32 * k2 + crow(i, h);
;         const bool valid = (MODE == 0) ? ((tk <= tq) && (tq - tk <= maxdist)) : (tk <= tq);
;         v = valid ? v : NINF; s[k2][i] = v;
;       }
;       mx = fmaxf(mx, v);
;     }
;   mx = fmaxf(mx, __shfl_xor(mx, 32));
;   if (MODE != 1) mx *= L2E;
;   if (MODE == 2) mx = lanesel ? mx : NINF;
;   const float mn = fmaxf(m, mx); const float alpha = __builtin_amdgcn_exp2f(m - mn);
;   const float neg = (MODE == 2 && !lanesel) ? NINF : -mn;
;   float ps = 0.f;
; #pragma unroll
;   for (int k2 = 0; k2 < 2; ++k2)
; #pragma unroll
;     for (int i = 0; i < 16; ++i) {
;       if (!(HM & (1 << k2))) continue;
;       const float pv = (MODE == 1) ? __builtin_amdgcn_exp2f(s[k2][i] + neg) : __builtin_amdgcn_exp2f(fmaf(s[k2][i], L2E, neg));
;       s[k2][i] = pv; ps += pv;
;     }
; template <int MODE>
; DI void flash_loop(char* smem, const bf16_t* Kbase, size_t ldk, const bf16_t* Vtbase, size_t ldv, ull tiles, ull wtiles,
;                    const bf16x8 (&qf)[4], f32x16 (&o)[2], float& m, float& l, int tq, int tqmin, int tqmax, int maxdist, const float* cn_lds, ull lmask) {
;     ...
;       if (64 * kt <= tqmax && 64 * kt + 31 >= tqmin - maxdist) hm |= 1;
;       if (64 * kt + 32 <= tqmax && 64 * kt + 63 >= tqmin - maxdist) hm |= 2;
;     }
;     if (MODE == 0 && hm == 1) attn_tile<MODE, true, 1>(Ks, Vs, qf, o, m, l, 64 * kt, tq, maxdist, cn_lds, sel);
.LBB0_486:
	s_nop 6
	ds_read_b128 v[34:37], v196
	s_nop 1
	ds_read_b128 v[50:53], v196 offset:32
	v_or_b32_e32 v0, s58, v197
	v_cmp_gt_u32_e32 vcc, v0, v154
	v_cmp_lt_i32_e64 s[6:7], v0, v155
	s_waitcnt lgkmcnt(1)
	v_mfma_f32_32x32x16_bf16 v[34:49], v[34:37], v[98:101], 0
	s_or_b64 vcc, vcc, s[6:7]
	s_waitcnt lgkmcnt(0)
	v_mfma_f32_32x32x16_bf16 v[34:49], v[50:53], v[102:105], v[34:49]
	ds_read_b128 v[50:53], v196 offset:64
	s_waitcnt lgkmcnt(0)
	v_mfma_f32_32x32x16_bf16 v[34:49], v[50:53], v[106:109], v[34:49]
	ds_read_b128 v[50:53], v196 offset:96
	s_waitcnt lgkmcnt(0)
	v_mfma_f32_32x32x16_bf16 v[34:49], v[50:53], v[110:113], v[34:49]
	v_bitop3_b32 v50, s58, v197, s58 bitop3:3
	v_cmp_lt_i32_e64 s[6:7], v156, v50
	v_or_b32_e32 v51, 2, v0
	s_nop 8
	v_cndmask_b32_e32 v34, v34, v204, vcc
	v_cmp_ge_u32_e32 vcc, v0, v154
	s_or_b64 vcc, vcc, s[6:7]
	v_cmp_lt_i32_e64 s[6:7], v51, v155
	v_cndmask_b32_e32 v35, v35, v204, vcc
	v_cmp_gt_u32_e32 vcc, v51, v154
	s_or_b64 vcc, vcc, s[6:7]
	v_or_b32_e32 v51, 3, v0
	v_cndmask_b32_e32 v36, v36, v204, vcc
	v_cmp_gt_u32_e32 vcc, v51, v154
	v_cmp_lt_i32_e64 s[6:7], v51, v155
	s_or_b64 vcc, vcc, s[6:7]
	v_or_b32_e32 v51, 8, v0
	v_cndmask_b32_e32 v37, v37, v204, vcc
	v_cmp_gt_u32_e32 vcc, v51, v154
	v_cmp_lt_i32_e64 s[6:7], v51, v155
	s_or_b64 vcc, vcc, s[6:7]
	v_or_b32_e32 v51, 9, v0
	v_cndmask_b32_e32 v38, v38, v204, vcc
	v_cmp_gt_u32_e32 vcc, v51, v154
	v_cmp_lt_i32_e64 s[6:7], v51, v155
	v_max3_f32 v50, v34, s35, v35
	s_or_b64 vcc, vcc, s[6:7]
	v_max3_f32 v50, v50, v36, v37
	v_cndmask_b32_e32 v39, v39, v204, vcc
	v_max3_f32 v52, v50, v38, v39
	v_or_b32_e32 v50, 10, v0
	v_cmp_gt_u32_e32 vcc, v50, v154
	v_cmp_lt_i32_e64 s[6:7], v50, v155
	s_or_b64 vcc, vcc, s[6:7]
	v_cndmask_b32_e32 v50, v40, v204, vcc
	v_or_b32_e32 v40, 11, v0
	v_cmp_gt_u32_e32 vcc, v40, v154
	v_cmp_lt_i32_e64 s[6:7], v40, v155
	s_or_b64 vcc, vcc, s[6:7]
	v_cndmask_b32_e32 v51, v41, v204, vcc
	v_or_b32_e32 v41, 16, v0
	v_cmp_gt_u32_e32 vcc, v41, v154
	v_cmp_lt_i32_e64 s[6:7], v41, v155
	s_or_b64 vcc, vcc, s[6:7]
	v_or_b32_e32 v41, 17, v0
	v_max3_f32 v40, v52, v50, v51
	v_cndmask_b32_e32 v52, v42, v204, vcc
	v_cmp_gt_u32_e32 vcc, v41, v154
	v_cmp_lt_i32_e64 s[6:7], v41, v155
	s_or_b64 vcc, vcc, s[6:7]
	v_or_b32_e32 v41, 18, v0
	v_cndmask_b32_e32 v53, v43, v204, vcc
	v_cmp_gt_u32_e32 vcc, v41, v154
	v_cmp_lt_i32_e64 s[6:7], v41, v155
	s_or_b64 vcc, vcc, s[6:7]
	v_or_b32_e32 v41, 19, v0
	v_cndmask_b32_e32 v54, v44, v204, vcc
	v_cmp_gt_u32_e32 vcc, v41, v154
	v_cmp_lt_i32_e64 s[6:7], v41, v155
	s_or_b64 vcc, vcc, s[6:7]
	v_or_b32_e32 v41, 24, v0
	v_cndmask_b32_e32 v44, v45, v204, vcc
	v_cmp_gt_u32_e32 vcc, v41, v154
	v_cmp_lt_i32_e64 s[6:7], v41, v155
	s_or_b64 vcc, vcc, s[6:7]
	v_or_b32_e32 v42, 25, v0
	v_cndmask_b32_e32 v41, v46, v204, vcc
	v_cmp_gt_u32_e32 vcc, v42, v154
	v_cmp_lt_i32_e64 s[6:7], v42, v155
	v_max3_f32 v40, v40, v52, v53
	s_or_b64 vcc, vcc, s[6:7]
	v_max3_f32 v40, v40, v54, v44
	v_cndmask_b32_e32 v42, v47, v204, vcc
	v_max3_f32 v45, v40, v41, v42
	v_or_b32_e32 v40, 26, v0
	v_cmp_gt_u32_e32 vcc, v40, v154
	v_cmp_lt_i32_e64 s[6:7], v40, v155
	s_or_b64 vcc, vcc, s[6:7]
	v_or_b32_e32 v0, 27, v0
	v_cndmask_b32_e32 v43, v48, v204, vcc
	v_cmp_gt_u32_e32 vcc, v0, v154
	v_cmp_lt_i32_e64 s[6:7], v0, v155
	s_or_b64 vcc, vcc, s[6:7]
	v_cndmask_b32_e32 v40, v49, v204, vcc
	v_and_b32_e32 v46, 64, v202
	v_max3_f32 v0, v45, v43, v40
	v_xor_b32_e32 v45, 32, v202
	v_add_u32_e32 v46, 64, v46
	v_cmp_lt_i32_e32 vcc, v45, v46
	s_nop 1
	v_cndmask_b32_e32 v45, v202, v45, vcc
	v_lshlrev_b32_e32 v45, 2, v45
	ds_bpermute_b32 v45, v45, v0
	s_waitcnt lgkmcnt(0)
	v_max_f32_e32 v45, v45, v45
	v_max_f32_e32 v0, v0, v45
	v_mul_f32_e32 v0, 0x3fb8aa3b, v0
	v_max_f32_e32 v45, v157, v157
	v_sub_f32_e32 v232, v0, v45
	v_cmp_lt_f32_e32 vcc, 0x41000000, v232
	s_nop 1
	v_cndmask_b32_e32 v158, v45, v0, vcc
	v_sub_f32_e32 v0, v157, v158
	v_exp_f32_e32 v0, v0
	v_cmp_neq_f32_e32 vcc, v158, v157
	s_cbranch_vccz .LBB0_488
	v_pk_mul_f32 v[32:33], v[32:33], v[0:1] op_sel_hi:[1,0]
	v_pk_mul_f32 v[30:31], v[30:31], v[0:1] op_sel_hi:[1,0]
	v_pk_mul_f32 v[28:29], v[28:29], v[0:1] op_sel_hi:[1,0]
	v_pk_mul_f32 v[26:27], v[26:27], v[0:1] op_sel_hi:[1,0]
	v_pk_mul_f32 v[24:25], v[24:25], v[0:1] op_sel_hi:[1,0]
	v_pk_mul_f32 v[22:23], v[22:23], v[0:1] op_sel_hi:[1,0]
	v_pk_mul_f32 v[20:21], v[20:21], v[0:1] op_sel_hi:[1,0]
	v_pk_mul_f32 v[18:19], v[18:19], v[0:1] op_sel_hi:[1,0]
	v_pk_mul_f32 v[16:17], v[16:17], v[0:1] op_sel_hi:[1,0]
	v_pk_mul_f32 v[14:15], v[14:15], v[0:1] op_sel_hi:[1,0]
	v_pk_mul_f32 v[12:13], v[12:13], v[0:1] op_sel_hi:[1,0]
	v_pk_mul_f32 v[10:11], v[10:11], v[0:1] op_sel_hi:[1,0]
	v_pk_mul_f32 v[8:9], v[8:9], v[0:1] op_sel_hi:[1,0]
	v_pk_mul_f32 v[6:7], v[6:7], v[0:1] op_sel_hi:[1,0]
	v_pk_mul_f32 v[4:5], v[4:5], v[0:1] op_sel_hi:[1,0]
	v_pk_mul_f32 v[2:3], v[2:3], v[0:1] op_sel_hi:[1,0]

;     ...
;   f32x16 s[2];
; #pragma unroll
;   for (int k2 = 0; k2 < 2; ++k2) {
;     if (!(HM & (1 << k2))) continue;
; #pragma unroll
;     for (int i = 0; i < 16; ++i) s[k2][i] = 0.f;
; #pragma unroll
;     for (int ks = 0; ks < 4; ++ks) {
;       const bf16x8 a = *(const bf16x8*)(Ks + (32 * k2 + r) * LSTR + 16 * ks + 8 * h);
;       s[k2] = mfma32(a, qf[ks], s[k2]);
;     }
;   }
;   if (MODE == 1) {
; #pragma unroll
;     for (int k2 = 0; k2 < 2; ++k2)
; #pragma unroll
;       for (int g = 0; g < 4; ++g) {
;         if (!(HM & (1 << k2))) continue;
;         const f32x4 cv = *(const f32x4*)(cn_lds + key0 + 32 * k2 + 8 * g + 4 * h);
; #pragma unroll
;         for (int e = 0; e < 4; ++e) s[k2][4 * g + e] = fmaf(s[k2][4 * g + e], L2E, cv[e]);
;       }
;   }
;   float mx = NINF;
; #pragma unroll
;   for (int k2 = 0; k2 < 2; ++k2)
; #pragma unroll
;     for (int i = 0; i < 16; ++i) {
;       if (!(HM & (1 << k2))) continue;
;       float v = s[k2][i];
;       if (MASKED) {
;         const int tk = key0 + 32 * k2 + crow(i, h);
;         const bool valid = (MODE == 0) ? ((tk <= tq) && (tq - tk <= maxdist)) : (tk <= tq);
;         v = valid ? v : NINF; s[k2][i] = v;
;       }
;       mx = fmaxf(mx, v);
;     }
;   mx = fmaxf(mx, __shfl_xor(mx, 32));
;   if (MODE != 1) mx *= L2E;
;   if (MODE == 2) mx = lanesel ? mx : NINF;
;   const float mn = fmaxf(m, mx); const float alpha = __builtin_amdgcn_exp2f(m - mn);
;   const float neg = (MODE == 2 && !lanesel) ? NINF : -mn;
;   float ps = 0.f;
; #pragma unroll
;   for (int k2 = 0; k2 < 2; ++k2)
; #pragma unroll
; template <int MODE>
; DI void flash_loop(char* smem, const bf16_t* Kbase, size_t ldk, const bf16_t* Vtbase, size_t ldv, ull tiles, ull wtiles,
;                    const bf16x8 (&qf)[4], f32x16 (&o)[2], float& m, float& l, int tq, int tqmin, int tqmax, int maxdist, const float* cn_lds, ull lmask) {
;     ...
;     if (!((wtiles >> kt) & 1ull)) return;
;     const bf16_t* Ks = (const bf16_t*)(smem + stage * (2 * 64 * LSTR * 2)); const bf16_t* Vs = Ks + 64 * LSTR;
;     const bool sel = ((lmask >> kt) & 1ull) != 0;
;     const bool interior = (64 * kt + 63 <= tqmin) && (MODE != 0 || (tqmax - 64 * kt <= maxdist));
;     int hm = 3;
;     if (MODE == 0) {
;       hm = 0;
;       if (64 * kt <= tqmax && 64 * kt + 31 >= tqmin - maxdist) hm |= 1;
;       if (64 * kt + 32 <= tqmax && 64 * kt + 63 >= tqmin - maxdist) hm |= 2;
;     }
.LBB0_494:
	s_lshr_b64 s[6:7], s[4:5], s65
	s_and_b32 s58, s6, 1
	s_cmp_eq_u64 s[58:59], 0
	s_cbranch_scc1 .LBB0_518
	s_lshl_b32 s58, s65, 6
	s_or_b32 s33, s58, 63
	s_cmp_le_u32 s58, s30
	s_cselect_b64 s[6:7], -1, 0
	s_or_b32 s36, s58, 31
	s_cmp_ge_i32 s36, s29
	s_cselect_b64 s[36:37], -1, 0
	s_and_b64 s[6:7], s[6:7], s[36:37]
	v_cndmask_b32_e64 v0, 0, 1, s[6:7]
	s_or_b32 s6, s58, 32
	s_cmp_gt_u32 s6, s30
	s_cselect_b64 s[6:7], -1, 0
	s_cmp_lt_i32 s33, s29
	s_cselect_b64 s[36:37], -1, 0
	v_readfirstlane_b32 s38, v0
	s_or_b32 s39, s38, 2
	s_or_b64 s[6:7], s[6:7], s[36:37]
	s_and_b64 s[6:7], s[6:7], exec
	s_cselect_b32 s65, s38, s39
	s_mov_b64 s[62:63], -1
	s_mov_b64 s[54:55], 0
	s_cmp_lt_i32 s65, 2
	s_mov_b64 s[6:7], 0
	s_cbranch_scc1 .LBB0_511
	s_cmp_eq_u32 s65, 2
	s_mov_b64 s[6:7], -1
	s_cbranch_scc0 .LBB0_500
	ds_read_b128 v[34:37], v199 offset:23040
	ds_read_b128 v[50:53], v199 offset:23072
	v_or_b32_e32 v0, s58, v197
	s_waitcnt lgkmcnt(1)
	v_mfma_f32_32x32x16_bf16 v[34:49], v[34:37], v[98:101], 0
	s_waitcnt lgkmcnt(0)
	v_mfma_f32_32x32x16_bf16 v[34:49], v[50:53], v[102:105], v[34:49]
	ds_read_b128 v[50:53], v199 offset:23104
	s_waitcnt lgkmcnt(0)
	v_mfma_f32_32x32x16_bf16 v[34:49], v[50:53], v[106:109], v[34:49]
	ds_read_b128 v[50:53], v199 offset:23136
	s_waitcnt lgkmcnt(0)
	v_mfma_f32_32x32x16_bf16 v[34:49], v[50:53], v[110:113], v[34:49]
	v_or_b32_e32 v50, 32, v0
	v_cmp_gt_u32_e32 vcc, v50, v154
	v_cmp_lt_i32_e64 s[6:7], v50, v155
	s_or_b64 vcc, vcc, s[6:7]
	s_nop 7
	v_cndmask_b32_e32 v66, v34, v204, vcc
	v_bitop3_b32 v34, s58, v205, v197 bitop3:0x36
	v_cmp_ge_u32_e32 vcc, v50, v154
	v_cmp_gt_i32_e64 s[6:7], v34, v156
	s_or_b64 vcc, vcc, s[6:7]
	v_cndmask_b32_e32 v67, v35, v204, vcc
	v_or_b32_e32 v35, 34, v0
	v_cmp_gt_u32_e32 vcc, v35, v154
	v_cmp_lt_i32_e64 s[6:7], v35, v155
	s_or_b64 vcc, vcc, s[6:7]
	v_or_b32_e32 v35, 35, v0
	v_cndmask_b32_e32 v68, v36, v204, vcc
	v_cmp_gt_u32_e32 vcc, v35, v154
	v_cmp_lt_i32_e64 s[6:7], v35, v155
	s_or_b64 vcc, vcc, s[6:7]
	v_or_b32_e32 v35, 40, v0
	v_cndmask_b32_e32 v69, v37, v204, vcc
	v_cmp_gt_u32_e32 vcc, v35, v154
	v_cmp_lt_i32_e64 s[6:7], v35, v155
	s_or_b64 vcc, vcc, s[6:7]
	v_or_b32_e32 v35, 41, v0
	v_cndmask_b32_e32 v70, v38, v204, vcc
	v_cmp_gt_u32_e32 vcc, v35, v154
	v_cmp_lt_i32_e64 s[6:7], v35, v155
	s_or_b64 vcc, vcc, s[6:7]
	v_or_b32_e32 v35, 42, v0
	v_cndmask_b32_e32 v71, v39, v204, vcc
	v_cmp_gt_u32_e32 vcc, v35, v154
	v_cmp_lt_i32_e64 s[6:7], v35, v155
	s_or_b64 vcc, vcc, s[6:7]
	v_or_b32_e32 v35, 43, v0
	v_cndmask_b32_e32 v76, v40, v204, vcc
	v_cmp_gt_u32_e32 vcc, v35, v154
	v_cmp_lt_i32_e64 s[6:7], v35, v155
	s_or_b64 vcc, vcc, s[6:7]
	v_or_b32_e32 v35, 48, v0
	v_cndmask_b32_e32 v77, v41, v204, vcc
	v_cmp_gt_u32_e32 vcc, v35, v154
	v_cmp_lt_i32_e64 s[6:7], v35, v155
	s_or_b64 vcc, vcc, s[6:7]
	v_or_b32_e32 v35, 49, v0
	v_cndmask_b32_e32 v78, v42, v204, vcc
	v_cmp_gt_u32_e32 vcc, v35, v154
	v_cmp_lt_i32_e64 s[6:7], v35, v155
	s_or_b64 vcc, vcc, s[6:7]
	v_or_b32_e32 v35, 50, v0
	v_cndmask_b32_e32 v79, v43, v204, vcc
	v_cmp_gt_u32_e32 vcc, v35, v154
	v_cmp_lt_i32_e64 s[6:7], v35, v155
	s_or_b64 vcc, vcc, s[6:7]
	v_or_b32_e32 v35, 51, v0
	v_cndmask_b32_e32 v80, v44, v204, vcc
	v_cmp_gt_u32_e32 vcc, v35, v154
	v_cmp_lt_i32_e64 s[6:7], v35, v155
	s_or_b64 vcc, vcc, s[6:7]
	v_or_b32_e32 v35, 56, v0
	v_cndmask_b32_e32 v81, v45, v204, vcc
	v_cmp_gt_u32_e32 vcc, v35, v154
	v_cmp_lt_i32_e64 s[6:7], v35, v155
	s_or_b64 vcc, vcc, s[6:7]
	v_or_b32_e32 v35, 57, v0
	v_max3_f32 v34, v66, s35, v67
	v_cndmask_b32_e32 v73, v46, v204, vcc
	v_cmp_gt_u32_e32 vcc, v35, v154
	v_cmp_lt_i32_e64 s[6:7], v35, v155
	v_max3_f32 v34, v34, v68, v69
	s_or_b64 vcc, vcc, s[6:7]
	v_or_b32_e32 v35, 58, v0
	v_max3_f32 v34, v34, v70, v71
	v_cndmask_b32_e32 v74, v47, v204, vcc
	v_cmp_gt_u32_e32 vcc, v35, v154
	v_cmp_lt_i32_e64 s[6:7], v35, v155
	v_max3_f32 v34, v34, v76, v77
	s_or_b64 vcc, vcc, s[6:7]
	v_or_b32_e32 v0, 59, v0
	v_max3_f32 v34, v34, v78, v79
	v_cndmask_b32_e32 v75, v48, v204, vcc
	v_cmp_gt_u32_e32 vcc, v0, v154
	v_cmp_lt_i32_e64 s[6:7], v0, v155
	v_max3_f32 v34, v34, v80, v81
	s_or_b64 vcc, vcc, s[6:7]
	v_max3_f32 v34, v34, v73, v74
	v_cndmask_b32_e32 v72, v49, v204, vcc
	v_and_b32_e32 v35, 64, v202
	v_max3_f32 v0, v34, v75, v72
	v_xor_b32_e32 v34, 32, v202
	v_add_u32_e32 v35, 64, v35
	v_cmp_lt_i32_e32 vcc, v34, v35
	s_nop 1
	v_cndmask_b32_e32 v34, v202, v34, vcc
	v_lshlrev_b32_e32 v34, 2, v34
	ds_bpermute_b32 v34, v34, v0
	s_waitcnt lgkmcnt(0)
	v_max_f32_e32 v34, v34, v34
	v_max_f32_e32 v0, v0, v34
	v_mul_f32_e32 v0, 0x3fb8aa3b, v0
	v_max_f32_e32 v34, v158, v158
	v_sub_f32_e32 v232, v0, v34
	v_cmp_lt_f32_e32 vcc, 0x41000000, v232
	s_nop 1
	v_cndmask_b32_e32 v157, v34, v0, vcc
	v_sub_f32_e32 v0, v158, v157
	v_exp_f32_e32 v0, v0
	v_cmp_neq_f32_e32 vcc, v157, v158
	s_cbranch_vccz .LBB0_499
	v_pk_mul_f32 v[32:33], v[32:33], v[0:1] op_sel_hi:[1,0]
	v_pk_mul_f32 v[30:31], v[30:31], v[0:1] op_sel_hi:[1,0]
	v_pk_mul_f32 v[28:29], v[28:29], v[0:1] op_sel_hi:[1,0]
	v_pk_mul_f32 v[26:27], v[26:27], v[0:1] op_sel_hi:[1,0]
	v_pk_mul_f32 v[24:25], v[24:25], v[0:1] op_sel_hi:[1,0]
	v_pk_mul_f32 v[22:23], v[22:23], v[0:1] op_sel_hi:[1,0]
	v_pk_mul_f32 v[20:21], v[20:21], v[0:1] op_sel_hi:[1,0]
	v_pk_mul_f32 v[18:19], v[18:19], v[0:1] op_sel_hi:[1,0]
	v_pk_mul_f32 v[16:17], v[16:17], v[0:1] op_sel_hi:[1,0]
	v_pk_mul_f32 v[14:15], v[14:15], v[0:1] op_sel_hi:[1,0]
	v_pk_mul_f32 v[12:13], v[12:13], v[0:1] op_sel_hi:[1,0]
	v_pk_mul_f32 v[10:11], v[10:11], v[0:1] op_sel_hi:[1,0]
	v_pk_mul_f32 v[8:9], v[8:9], v[0:1] op_sel_hi:[1,0]
	v_pk_mul_f32 v[6:7], v[6:7], v[0:1] op_sel_hi:[1,0]
	v_pk_mul_f32 v[4:5], v[4:5], v[0:1] op_sel_hi:[1,0]
	v_pk_mul_f32 v[2:3], v[2:3], v[0:1] op_sel_hi:[1,0]

; DI f32x16 mfma32(bf16x8 a, bf16x8 b, f32x16 c) { return __builtin_amdgcn_mfma_f32_32x32x16_bf16(a, b, c, 0, 0, 0); }
; DI int crow(int i, int h) { return (i & 3) + 8 * (i >> 2) + 4 * h; }
;     ...
;   f32x16 s[2];
; #pragma unroll
;   for (int k2 = 0; k2 < 2; ++k2) {
;     if (!(HM & (1 << k2))) continue;
; #pragma unroll
;     for (int i = 0; i < 16; ++i) s[k2][i] = 0.f;
; #pragma unroll
;     for (int ks = 0; ks < 4; ++ks) {
;       const bf16x8 a = *(const bf16x8*)(Ks + (32 * k2 + r) * LSTR + 16 * ks + 8 * h);
;       s[k2] = mfma32(a, qf[ks], s[k2]);
;     }
;   }
;   if (MODE == 1) {
; #pragma unroll
;     for (int k2 = 0; k2 < 2; ++k2)
; #pragma unroll
;       for (int g = 0; g < 4; ++g) {
;         if (!(HM & (1 << k2))) continue;
;         const f32x4 cv = *(const f32x4*)(cn_lds + key0 + 32 * k2 + 8 * g + 4 * h);
; #pragma unroll
;         for (int e = 0; e < 4; ++e) s[k2][4 * g + e] = fmaf(s[k2][4 * g + e], L2E, cv[e]);
;       }
;   }
;   float mx = NINF;
; #pragma unroll
;   for (int k2 = 0; k2 < 2; ++k2)
; #pragma unroll
;     for (int i = 0; i < 16; ++i) {
;       if (!(HM & (1 << k2))) continue;
;       float v = s[k2][i];
;       if (MASKED) {
;         const int tk = key0 + 32 * k2 + crow(i, h);
;         const bool valid = (MODE == 0) ? ((tk <= tq) && (tq - tk <= maxdist)) : (tk <= tq);
;         v = valid ? v : NINF; s[k2][i] = v;
; template <int MODE>
; DI void flash_loop(char* smem, const bf16_t* Kbase, size_t ldk, const bf16_t* Vtbase, size_t ldv, ull tiles, ull wtiles,
;                    const bf16x8 (&qf)[4], f32x16 (&o)[2], float& m, float& l, int tq, int tqmin, int tqmax, int maxdist, const float* cn_lds, ull lmask) {
;     ...
;     const bool interior = (64 * kt + 63 <= tqmin) && (MODE != 0 || (tqmax - 64 * kt <= maxdist));
.LBB0_502:
	ds_read_b128 v[82:85], v196 offset:18432
	ds_read_b128 v[78:81], v196 offset:18464
	ds_read_b128 v[74:77], v196 offset:18496
	ds_read_b128 v[66:69], v196 offset:18528
	ds_read_b128 v[70:73], v196 offset:23040
	s_cmp_le_u32 s33, s28
	s_cselect_b64 s[6:7], -1, 0
	s_cmp_ge_i32 s58, s31
	s_cselect_b64 s[36:37], -1, 0
	s_and_b64 s[6:7], s[6:7], s[36:37]
	s_andn2_b64 vcc, exec, s[6:7]
	s_mov_b64 s[6:7], -1
	s_cbranch_vccz .LBB0_506
	s_waitcnt lgkmcnt(4)
	v_mfma_f32_32x32x16_bf16 v[50:65], v[82:85], v[98:101], 0
	ds_read_b128 v[86:89], v196 offset:23072
	ds_read_b128 v[90:93], v196 offset:23104
	v_or_b32_e32 v0, s58, v197
	v_cmp_gt_u32_e32 vcc, v0, v154
	v_cmp_lt_i32_e64 s[6:7], v0, v155
	s_or_b64 vcc, vcc, s[6:7]
	s_waitcnt lgkmcnt(5)
	v_mfma_f32_32x32x16_bf16 v[50:65], v[78:81], v[102:105], v[50:65]
	s_waitcnt lgkmcnt(2)
	v_mfma_f32_32x32x16_bf16 v[34:49], v[70:73], v[98:101], 0
	v_mfma_f32_32x32x16_bf16 v[50:65], v[74:77], v[106:109], v[50:65]
	s_waitcnt lgkmcnt(1)
	v_mfma_f32_32x32x16_bf16 v[34:49], v[86:89], v[102:105], v[34:49]
	ds_read_b128 v[86:89], v196 offset:23136
	v_mfma_f32_32x32x16_bf16 v[50:65], v[66:69], v[110:113], v[50:65]
	s_waitcnt lgkmcnt(1)
	v_mfma_f32_32x32x16_bf16 v[34:49], v[90:93], v[106:109], v[34:49]
	s_waitcnt lgkmcnt(0)
	v_mfma_f32_32x32x16_bf16 v[34:49], v[86:89], v[110:113], v[34:49]
	s_nop 7
	v_cndmask_b32_e32 v86, v50, v204, vcc
	v_bitop3_b32 v50, s58, v197, s58 bitop3:3
	v_cmp_ge_u32_e32 vcc, v0, v154
	v_cmp_lt_i32_e64 s[6:7], v156, v50
	s_or_b64 vcc, vcc, s[6:7]
	v_cndmask_b32_e32 v87, v51, v204, vcc
	v_or_b32_e32 v51, 2, v0
	v_cmp_gt_u32_e32 vcc, v51, v154
	v_cmp_lt_i32_e64 s[6:7], v51, v155
	s_or_b64 vcc, vcc, s[6:7]
	v_or_b32_e32 v51, 3, v0
	v_cndmask_b32_e32 v88, v52, v204, vcc
	v_cmp_gt_u32_e32 vcc, v51, v154
	v_cmp_lt_i32_e64 s[6:7], v51, v155
	s_or_b64 vcc, vcc, s[6:7]
	v_or_b32_e32 v51, 8, v0
	v_cndmask_b32_e32 v89, v53, v204, vcc
	v_cmp_gt_u32_e32 vcc, v51, v154
	v_cmp_lt_i32_e64 s[6:7], v51, v155
	s_or_b64 vcc, vcc, s[6:7]
	v_or_b32_e32 v51, 9, v0
	v_cndmask_b32_e32 v90, v54, v204, vcc
	v_cmp_gt_u32_e32 vcc, v51, v154
	v_cmp_lt_i32_e64 s[6:7], v51, v155
	s_or_b64 vcc, vcc, s[6:7]
	v_or_b32_e32 v51, 10, v0
	v_cndmask_b32_e32 v192, v55, v204, vcc
	v_cmp_gt_u32_e32 vcc, v51, v154
	v_cmp_lt_i32_e64 s[6:7], v51, v155
	s_or_b64 vcc, vcc, s[6:7]
	v_or_b32_e32 v51, 11, v0
	v_cndmask_b32_e32 v191, v56, v204, vcc
	v_cmp_gt_u32_e32 vcc, v51, v154
	v_cmp_lt_i32_e64 s[6:7], v51, v155
	s_or_b64 vcc, vcc, s[6:7]
	v_or_b32_e32 v51, 16, v0
	v_cndmask_b32_e32 v193, v57, v204, vcc
	v_cmp_gt_u32_e32 vcc, v51, v154
	v_cmp_lt_i32_e64 s[6:7], v51, v155
	s_or_b64 vcc, vcc, s[6:7]
	v_or_b32_e32 v51, 17, v0
	v_cndmask_b32_e32 v188, v58, v204, vcc
	v_cmp_gt_u32_e32 vcc, v51, v154
	v_cmp_lt_i32_e64 s[6:7], v51, v155
	s_or_b64 vcc, vcc, s[6:7]
	v_or_b32_e32 v51, 18, v0
	v_cndmask_b32_e32 v190, v59, v204, vcc
	v_cmp_gt_u32_e32 vcc, v51, v154
	v_cmp_lt_i32_e64 s[6:7], v51, v155
	s_or_b64 vcc, vcc, s[6:7]
	v_or_b32_e32 v51, 19, v0
	v_cndmask_b32_e32 v189, v60, v204, vcc
	v_cmp_gt_u32_e32 vcc, v51, v154
	v_cmp_lt_i32_e64 s[6:7], v51, v155
	s_or_b64 vcc, vcc, s[6:7]
	v_or_b32_e32 v51, 24, v0
	v_cndmask_b32_e32 v187, v61, v204, vcc
	v_cmp_gt_u32_e32 vcc, v51, v154
	v_cmp_lt_i32_e64 s[6:7], v51, v155
	s_or_b64 vcc, vcc, s[6:7]
	v_or_b32_e32 v51, 25, v0
	v_cndmask_b32_e32 v186, v62, v204, vcc
	v_cmp_gt_u32_e32 vcc, v51, v154
	v_cmp_lt_i32_e64 s[6:7], v51, v155
	s_or_b64 vcc, vcc, s[6:7]
	v_or_b32_e32 v51, 26, v0
	v_cndmask_b32_e32 v185, v63, v204, vcc
	v_cmp_gt_u32_e32 vcc, v51, v154
	v_cmp_lt_i32_e64 s[6:7], v51, v155
	s_or_b64 vcc, vcc, s[6:7]
	v_or_b32_e32 v51, 27, v0
	v_cndmask_b32_e32 v184, v64, v204, vcc
	v_cmp_gt_u32_e32 vcc, v51, v154
	v_cmp_lt_i32_e64 s[6:7], v51, v155
	s_or_b64 vcc, vcc, s[6:7]
	v_or_b32_e32 v51, 32, v0
	v_cndmask_b32_e32 v182, v65, v204, vcc
	v_cmp_gt_u32_e32 vcc, v51, v154
	v_cmp_lt_i32_e64 s[6:7], v51, v155
	s_or_b64 vcc, vcc, s[6:7]
	v_cndmask_b32_e32 v164, v34, v204, vcc
	v_or_b32_e32 v34, 33, v0
	v_cmp_gt_u32_e32 vcc, v34, v154
	v_cmp_lt_i32_e64 s[6:7], v34, v155
	s_or_b64 vcc, vcc, s[6:7]
	v_cndmask_b32_e32 v162, v35, v204, vcc
	v_or_b32_e32 v35, 34, v0
	v_cmp_gt_u32_e32 vcc, v35, v154
; DI int crow(int i, int h) { return (i & 3) + 8 * (i >> 2) + 4 * h; }
;     ...
;   float mx = NINF;
; #pragma unroll
;   for (int k2 = 0; k2 < 2; ++k2)
; #pragma unroll
;     for (int i = 0; i < 16; ++i) {
;       if (!(HM & (1 << k2))) continue;
;       float v = s[k2][i];
;       if (MASKED) {
;         const int tk = key0 + 32 * k2 + crow(i, h);
;         const bool valid = (MODE == 0) ? ((tk <= tq) && (tq - tk <= maxdist)) : (tk <= tq);
;         v = valid ? v : NINF; s[k2][i] = v;
;       }
;       mx = fmaxf(mx, v);
;     }
;   mx = fmaxf(mx, __shfl_xor(mx, 32));
;   if (MODE != 1) mx *= L2E;
;   if (MODE == 2) mx = lanesel ? mx : NINF;
;   const float mn = fmaxf(m, mx); const float alpha = __builtin_amdgcn_exp2f(m - mn);
;   const float neg = (MODE == 2 && !lanesel) ? NINF : -mn;
;   float ps = 0.f;
; #pragma unroll
;   for (int k2 = 0; k2 < 2; ++k2)
; #pragma unroll
;     for (int i = 0; i < 16; ++i) {
;       if (!(HM & (1 << k2))) continue;
;       const float pv = (MODE == 1) ? __builtin_amdgcn_exp2f(s[k2][i] + neg) : __builtin_amdgcn_exp2f(fmaf(s[k2][i], L2E, neg));
;       s[k2][i] = pv; ps += pv;
;     }
;   l = l * alpha + ps;
;   if (__builtin_amdgcn_ballot_w64(mn != m) != 0ull) {
; #pragma unroll
;     for (int dt = 0; dt < 2; ++dt)
; #pragma unroll
;       for (int i = 0; i < 16; ++i) o[dt][i] *= alpha;
;   }
	v_cmp_lt_i32_e64 s[6:7], v35, v155
	s_or_b64 vcc, vcc, s[6:7]
	v_or_b32_e32 v35, 35, v0
	v_cndmask_b32_e32 v159, v36, v204, vcc
	v_cmp_gt_u32_e32 vcc, v35, v154
	v_cmp_lt_i32_e64 s[6:7], v35, v155
	s_or_b64 vcc, vcc, s[6:7]
	v_or_b32_e32 v35, 40, v0
	v_cndmask_b32_e32 v97, v37, v204, vcc
	v_cmp_gt_u32_e32 vcc, v35, v154
	v_cmp_lt_i32_e64 s[6:7], v35, v155
	s_or_b64 vcc, vcc, s[6:7]
	v_or_b32_e32 v35, 41, v0
	v_cndmask_b32_e32 v92, v38, v204, vcc
	v_cmp_gt_u32_e32 vcc, v35, v154
	v_cmp_lt_i32_e64 s[6:7], v35, v155
	s_or_b64 vcc, vcc, s[6:7]
	v_or_b32_e32 v35, 42, v0
	v_cndmask_b32_e32 v91, v39, v204, vcc
	v_cmp_gt_u32_e32 vcc, v35, v154
	v_cmp_lt_i32_e64 s[6:7], v35, v155
	s_or_b64 vcc, vcc, s[6:7]
	v_or_b32_e32 v35, 43, v0
	v_cndmask_b32_e32 v93, v40, v204, vcc
	v_cmp_gt_u32_e32 vcc, v35, v154
	v_cmp_lt_i32_e64 s[6:7], v35, v155
	s_or_b64 vcc, vcc, s[6:7]
	v_or_b32_e32 v35, 48, v0
	v_cndmask_b32_e32 v94, v41, v204, vcc
	v_cmp_gt_u32_e32 vcc, v35, v154
	v_cmp_lt_i32_e64 s[6:7], v35, v155
	s_or_b64 vcc, vcc, s[6:7]
	v_or_b32_e32 v35, 49, v0
	v_max3_f32 v50, v86, s35, v87
	v_cndmask_b32_e32 v95, v42, v204, vcc
	v_cmp_gt_u32_e32 vcc, v35, v154
	v_cmp_lt_i32_e64 s[6:7], v35, v155
	v_max3_f32 v50, v50, v88, v89
	s_or_b64 vcc, vcc, s[6:7]
	v_or_b32_e32 v35, 50, v0
	v_max3_f32 v50, v50, v90, v192
	v_cndmask_b32_e32 v96, v43, v204, vcc
	v_cmp_gt_u32_e32 vcc, v35, v154
	v_cmp_lt_i32_e64 s[6:7], v35, v155
	v_max3_f32 v50, v50, v191, v193
	s_or_b64 vcc, vcc, s[6:7]
	v_or_b32_e32 v35, 51, v0
	v_max3_f32 v50, v50, v188, v190
	v_cndmask_b32_e32 v161, v44, v204, vcc
	v_cmp_gt_u32_e32 vcc, v35, v154
	v_cmp_lt_i32_e64 s[6:7], v35, v155
	v_max3_f32 v50, v50, v189, v187
	s_or_b64 vcc, vcc, s[6:7]
	v_or_b32_e32 v35, 56, v0
	v_max3_f32 v50, v50, v186, v185
	v_cndmask_b32_e32 v163, v45, v204, vcc
	v_cmp_gt_u32_e32 vcc, v35, v154
	v_cmp_lt_i32_e64 s[6:7], v35, v155
	v_max3_f32 v50, v50, v184, v182
	s_or_b64 vcc, vcc, s[6:7]
	v_or_b32_e32 v35, 57, v0
	v_max3_f32 v34, v50, v164, v162
	v_cndmask_b32_e32 v165, v46, v204, vcc
	v_cmp_gt_u32_e32 vcc, v35, v154
	v_cmp_lt_i32_e64 s[6:7], v35, v155
	v_max3_f32 v34, v34, v159, v97
	s_or_b64 vcc, vcc, s[6:7]
	v_or_b32_e32 v35, 58, v0
	v_max3_f32 v34, v34, v92, v91
	v_cndmask_b32_e32 v180, v47, v204, vcc
	v_cmp_gt_u32_e32 vcc, v35, v154
	v_cmp_lt_i32_e64 s[6:7], v35, v155
	v_max3_f32 v34, v34, v93, v94
	s_or_b64 vcc, vcc, s[6:7]
	v_or_b32_e32 v0, 59, v0
	v_max3_f32 v34, v34, v95, v96
	v_cndmask_b32_e32 v181, v48, v204, vcc
	v_cmp_gt_u32_e32 vcc, v0, v154
	v_cmp_lt_i32_e64 s[6:7], v0, v155
	v_max3_f32 v34, v34, v161, v163
	s_or_b64 vcc, vcc, s[6:7]
	v_max3_f32 v34, v34, v165, v180
	v_cndmask_b32_e32 v183, v49, v204, vcc
	v_and_b32_e32 v35, 64, v202
	v_max3_f32 v0, v34, v181, v183
	v_xor_b32_e32 v34, 32, v202
	v_add_u32_e32 v35, 64, v35
	v_cmp_lt_i32_e32 vcc, v34, v35
	s_nop 1
	v_cndmask_b32_e32 v34, v202, v34, vcc
	v_lshlrev_b32_e32 v34, 2, v34
	ds_bpermute_b32 v34, v34, v0
	s_waitcnt lgkmcnt(0)
	v_max_f32_e32 v34, v34, v34
	v_max_f32_e32 v0, v0, v34
	v_mul_f32_e32 v0, 0x3fb8aa3b, v0
	v_max_f32_e32 v34, v158, v158
	v_sub_f32_e32 v232, v0, v34
	v_cmp_lt_f32_e32 vcc, 0x41000000, v232
	s_nop 1
	v_cndmask_b32_e32 v157, v34, v0, vcc
	v_sub_f32_e32 v0, v158, v157
	v_exp_f32_e32 v0, v0
	v_cmp_neq_f32_e32 vcc, v157, v158
	s_cbranch_vccz .LBB0_505
	v_pk_mul_f32 v[32:33], v[32:33], v[0:1] op_sel_hi:[1,0]
	v_pk_mul_f32 v[30:31], v[30:31], v[0:1] op_sel_hi:[1,0]
	v_pk_mul_f32 v[28:29], v[28:29], v[0:1] op_sel_hi:[1,0]
	v_pk_mul_f32 v[26:27], v[26:27], v[0:1] op_sel_hi:[1,0]
	v_pk_mul_f32 v[24:25], v[24:25], v[0:1] op_sel_hi:[1,0]
	v_pk_mul_f32 v[22:23], v[22:23], v[0:1] op_sel_hi:[1,0]
	v_pk_mul_f32 v[20:21], v[20:21], v[0:1] op_sel_hi:[1,0]
	v_pk_mul_f32 v[18:19], v[18:19], v[0:1] op_sel_hi:[1,0]
	v_pk_mul_f32 v[16:17], v[16:17], v[0:1] op_sel_hi:[1,0]
	v_pk_mul_f32 v[14:15], v[14:15], v[0:1] op_sel_hi:[1,0]
	v_pk_mul_f32 v[12:13], v[12:13], v[0:1] op_sel_hi:[1,0]
	v_pk_mul_f32 v[10:11], v[10:11], v[0:1] op_sel_hi:[1,0]
	v_pk_mul_f32 v[8:9], v[8:9], v[0:1] op_sel_hi:[1,0]
	v_pk_mul_f32 v[6:7], v[6:7], v[0:1] op_sel_hi:[1,0]
	v_pk_mul_f32 v[4:5], v[4:5], v[0:1] op_sel_hi:[1,0]
	v_pk_mul_f32 v[2:3], v[2:3], v[0:1] op_sel_hi:[1,0]

; DI f32x16 mfma32(bf16x8 a, bf16x8 b, f32x16 c) { return __builtin_amdgcn_mfma_f32_32x32x16_bf16(a, b, c, 0, 0, 0); }
; DI int crow(int i, int h) { return (i & 3) + 8 * (i >> 2) + 4 * h; }
;     ...
;   f32x16 s[2];
; #pragma unroll
;   for (int k2 = 0; k2 < 2; ++k2) {
;     if (!(HM & (1 << k2))) continue;
; #pragma unroll
;     for (int i = 0; i < 16; ++i) s[k2][i] = 0.f;
; #pragma unroll
;     for (int ks = 0; ks < 4; ++ks) {
;       const bf16x8 a = *(const bf16x8*)(Ks + (32 * k2 + r) * LSTR + 16 * ks + 8 * h);
;       s[k2] = mfma32(a, qf[ks], s[k2]);
;     }
;   }
;   if (MODE == 1) {
; #pragma unroll
;     for (int k2 = 0; k2 < 2; ++k2)
; #pragma unroll
;       for (int g = 0; g < 4; ++g) {
;         if (!(HM & (1 << k2))) continue;
;         const f32x4 cv = *(const f32x4*)(cn_lds + key0 + 32 * k2 + 8 * g + 4 * h);
; #pragma unroll
;         for (int e = 0; e < 4; ++e) s[k2][4 * g + e] = fmaf(s[k2][4 * g + e], L2E, cv[e]);
;       }
;   }
;   float mx = NINF;
; #pragma unroll
;   for (int k2 = 0; k2 < 2; ++k2)
; #pragma unroll
;     for (int i = 0; i < 16; ++i) {
;       if (!(HM & (1 << k2))) continue;
;       float v = s[k2][i];
;       if (MASKED) {
;         const int tk = key0 + 32 * k2 + crow(i, h);
;         const bool valid = (MODE == 0) ? ((tk <= tq) && (tq - tk <= maxdist)) : (tk <= tq);
;         v = valid ? v : NINF; s[k2][i] = v;
;       }
;       mx = fmaxf(mx, v);
;     }
;   mx = fmaxf(mx, __shfl_xor(mx, 32));
;   if (MODE != 1) mx *= L2E;
;   if (MODE == 2) mx = lanesel ? mx : NINF;
;   const float mn = fmaxf(m, mx); const float alpha = __builtin_amdgcn_exp2f(m - mn);
;   const float neg = (MODE == 2 && !lanesel) ? NINF : -mn;
;   float ps = 0.f;
; #pragma unroll
;   for (int k2 = 0; k2 < 2; ++k2)
; #pragma unroll
;     for (int i = 0; i < 16; ++i) {
;       if (!(HM & (1 << k2))) continue;
;       const float pv = (MODE == 1) ? __builtin_amdgcn_exp2f(s[k2][i] + neg) : __builtin_amdgcn_exp2f(fmaf(s[k2][i], L2E, neg));
;       s[k2][i] = pv; ps += pv;
;     }
;   l = l * alpha + ps;
;   if (__builtin_amdgcn_ballot_w64(mn != m) != 0ull) {
; #pragma unroll
;     for (int dt = 0; dt < 2; ++dt)
; #pragma unroll
;       for (int i = 0; i < 16; ++i) o[dt][i] *= alpha;
;   }
.LBB0_506:
	s_and_b64 vcc, exec, s[6:7]
	s_cbranch_vccz .LBB0_510
	s_waitcnt lgkmcnt(4)
	v_mfma_f32_32x32x16_bf16 v[82:97], v[82:85], v[98:101], 0
	s_nop 4
	ds_read_b128 v[34:37], v196 offset:23072
	ds_read_b128 v[38:41], v196 offset:23104
	s_waitcnt lgkmcnt(5)
	v_mfma_f32_32x32x16_bf16 v[82:97], v[78:81], v[102:105], v[82:97]
	s_waitcnt lgkmcnt(4)
	v_mfma_f32_32x32x16_bf16 v[82:97], v[74:77], v[106:109], v[82:97]
	s_waitcnt lgkmcnt(3)
	v_mfma_f32_32x32x16_bf16 v[82:97], v[66:69], v[110:113], v[82:97]
	s_waitcnt lgkmcnt(2)
	v_mfma_f32_32x32x16_bf16 v[66:81], v[70:73], v[98:101], 0
	s_nop 9
	v_max3_f32 v0, v82, s35, v83
	v_max3_f32 v0, v0, v84, v85
	v_max3_f32 v0, v0, v86, v87
	v_max3_f32 v0, v0, v88, v89
	v_max3_f32 v0, v0, v90, v91
	v_max3_f32 v0, v0, v92, v93
	v_max3_f32 v0, v0, v94, v95
	s_waitcnt lgkmcnt(1)
	v_mfma_f32_32x32x16_bf16 v[66:81], v[34:37], v[102:105], v[66:81]
	ds_read_b128 v[34:37], v196 offset:23136
	v_max3_f32 v0, v0, v96, v97
	s_waitcnt lgkmcnt(1)
	v_mfma_f32_32x32x16_bf16 v[66:81], v[38:41], v[106:109], v[66:81]
	s_waitcnt lgkmcnt(0)
	v_mfma_f32_32x32x16_bf16 v[66:81], v[34:37], v[110:113], v[66:81]
	v_and_b32_e32 v35, 64, v202
	v_xor_b32_e32 v34, 32, v202
	v_add_u32_e32 v35, 64, v35
	v_cmp_lt_i32_e32 vcc, v34, v35
	s_nop 1
	v_cndmask_b32_e32 v34, v202, v34, vcc
	s_nop 4
	v_max3_f32 v0, v0, v66, v67
	v_max3_f32 v0, v0, v68, v69
	v_max3_f32 v0, v0, v70, v71
	v_max3_f32 v0, v0, v72, v73
	v_max3_f32 v0, v0, v74, v75
	v_max3_f32 v0, v0, v76, v77
	v_max3_f32 v0, v0, v78, v79
	v_max3_f32 v0, v0, v80, v81
	v_lshlrev_b32_e32 v34, 2, v34
	ds_bpermute_b32 v34, v34, v0
	s_waitcnt lgkmcnt(0)
	v_max_f32_e32 v34, v34, v34
	v_max_f32_e32 v0, v0, v34
	v_mul_f32_e32 v0, 0x3fb8aa3b, v0
	v_max_f32_e32 v34, v158, v158
	v_sub_f32_e32 v232, v0, v34
	v_cmp_lt_f32_e32 vcc, 0x41000000, v232
	s_nop 1
	v_cndmask_b32_e32 v157, v34, v0, vcc
	v_sub_f32_e32 v0, v158, v157
	v_exp_f32_e32 v0, v0
	v_cmp_neq_f32_e32 vcc, v157, v158
	s_cbranch_vccz .LBB0_509
	v_pk_mul_f32 v[32:33], v[32:33], v[0:1] op_sel_hi:[1,0]
	v_pk_mul_f32 v[30:31], v[30:31], v[0:1] op_sel_hi:[1,0]
	v_pk_mul_f32 v[28:29], v[28:29], v[0:1] op_sel_hi:[1,0]
	v_pk_mul_f32 v[26:27], v[26:27], v[0:1] op_sel_hi:[1,0]
	v_pk_mul_f32 v[24:25], v[24:25], v[0:1] op_sel_hi:[1,0]
	v_pk_mul_f32 v[22:23], v[22:23], v[0:1] op_sel_hi:[1,0]
	v_pk_mul_f32 v[20:21], v[20:21], v[0:1] op_sel_hi:[1,0]
	v_pk_mul_f32 v[18:19], v[18:19], v[0:1] op_sel_hi:[1,0]
	v_pk_mul_f32 v[16:17], v[16:17], v[0:1] op_sel_hi:[1,0]
	v_pk_mul_f32 v[14:15], v[14:15], v[0:1] op_sel_hi:[1,0]
	v_pk_mul_f32 v[12:13], v[12:13], v[0:1] op_sel_hi:[1,0]
	v_pk_mul_f32 v[10:11], v[10:11], v[0:1] op_sel_hi:[1,0]
	v_pk_mul_f32 v[8:9], v[8:9], v[0:1] op_sel_hi:[1,0]
	v_pk_mul_f32 v[6:7], v[6:7], v[0:1] op_sel_hi:[1,0]
	v_pk_mul_f32 v[4:5], v[4:5], v[0:1] op_sel_hi:[1,0]
	v_pk_mul_f32 v[2:3], v[2:3], v[0:1] op_sel_hi:[1,0]

;     ...
;   f32x16 s[2];
; #pragma unroll
;   for (int k2 = 0; k2 < 2; ++k2) {
;     if (!(HM & (1 << k2))) continue;
; #pragma unroll
;     for (int i = 0; i < 16; ++i) s[k2][i] = 0.f;
; #pragma unroll
;     for (int ks = 0; ks < 4; ++ks) {
;       const bf16x8 a = *(const bf16x8*)(Ks + (32 * k2 + r) * LSTR + 16 * ks + 8 * h);
;       s[k2] = mfma32(a, qf[ks], s[k2]);
;     }
;   }
;   if (MODE == 1) {
; #pragma unroll
;     for (int k2 = 0; k2 < 2; ++k2)
; #pragma unroll
;       for (int g = 0; g < 4; ++g) {
;         if (!(HM & (1 << k2))) continue;
;         const f32x4 cv = *(const f32x4*)(cn_lds + key0 + 32 * k2 + 8 * g + 4 * h);
; #pragma unroll
;         for (int e = 0; e < 4; ++e) s[k2][4 * g + e] = fmaf(s[k2][4 * g + e], L2E, cv[e]);
;       }
;   }
;   float mx = NINF;
; #pragma unroll
;   for (int k2 = 0; k2 < 2; ++k2)
; #pragma unroll
;     for (int i = 0; i < 16; ++i) {
;       if (!(HM & (1 << k2))) continue;
;       float v = s[k2][i];
;       if (MASKED) {
;         const int tk = key0 + 32 * k2 + crow(i, h);
;         const bool valid = (MODE == 0) ? ((tk <= tq) && (tq - tk <= maxdist)) : (tk <= tq);
;         v = valid ? v : NINF; s[k2][i] = v;
;       }
;       mx = fmaxf(mx, v);
;     }
;   mx = fmaxf(mx, __shfl_xor(mx, 32));
;   if (MODE != 1) mx *= L2E;
;   if (MODE == 2) mx = lanesel ? mx : NINF;
;   const float mn = fmaxf(m, mx); const float alpha = __builtin_amdgcn_exp2f(m - mn);
;   const float neg = (MODE == 2 && !lanesel) ? NINF : -mn;
;   float ps = 0.f;
; #pragma unroll
;   for (int k2 = 0; k2 < 2; ++k2)
; #pragma unroll
;     for (int i = 0; i < 16; ++i) {
;       if (!(HM & (1 << k2))) continue;
;       const float pv = (MODE == 1) ? __builtin_amdgcn_exp2f(s[k2][i] + neg) : __builtin_amdgcn_exp2f(fmaf(s[k2][i], L2E, neg));
;       s[k2][i] = pv; ps += pv;
;     }
; template <int MODE>
; DI void flash_loop(char* smem, const bf16_t* Kbase, size_t ldk, const bf16_t* Vtbase, size_t ldv, ull tiles, ull wtiles,
;                    const bf16x8 (&qf)[4], f32x16 (&o)[2], float& m, float& l, int tq, int tqmin, int tqmax, int maxdist, const float* cn_lds, ull lmask) {
;     ...
;       if (64 * kt <= tqmax && 64 * kt + 31 >= tqmin - maxdist) hm |= 1;
;       if (64 * kt + 32 <= tqmax && 64 * kt + 63 >= tqmin - maxdist) hm |= 2;
;     }
;     if (MODE == 0 && hm == 1) attn_tile<MODE, true, 1>(Ks, Vs, qf, o, m, l, 64 * kt, tq, maxdist, cn_lds, sel);
.LBB0_514:
	s_nop 6
	ds_read_b128 v[34:37], v196 offset:18432
	s_nop 1
	ds_read_b128 v[50:53], v196 offset:18464
	v_or_b32_e32 v0, s58, v197
	v_cmp_gt_u32_e32 vcc, v0, v154
	v_cmp_lt_i32_e64 s[6:7], v0, v155
	s_waitcnt lgkmcnt(1)
	v_mfma_f32_32x32x16_bf16 v[34:49], v[34:37], v[98:101], 0
	s_or_b64 vcc, vcc, s[6:7]
	s_waitcnt lgkmcnt(0)
	v_mfma_f32_32x32x16_bf16 v[34:49], v[50:53], v[102:105], v[34:49]
	ds_read_b128 v[50:53], v196 offset:18496
	s_waitcnt lgkmcnt(0)
	v_mfma_f32_32x32x16_bf16 v[34:49], v[50:53], v[106:109], v[34:49]
	ds_read_b128 v[50:53], v196 offset:18528
	s_waitcnt lgkmcnt(0)
	v_mfma_f32_32x32x16_bf16 v[34:49], v[50:53], v[110:113], v[34:49]
	v_bitop3_b32 v50, s58, v197, s58 bitop3:3
	v_cmp_lt_i32_e64 s[6:7], v156, v50
	v_or_b32_e32 v51, 2, v0
	s_nop 8
	v_cndmask_b32_e32 v34, v34, v204, vcc
	v_cmp_ge_u32_e32 vcc, v0, v154
	s_or_b64 vcc, vcc, s[6:7]
	v_cmp_lt_i32_e64 s[6:7], v51, v155
	v_cndmask_b32_e32 v35, v35, v204, vcc
	v_cmp_gt_u32_e32 vcc, v51, v154
	s_or_b64 vcc, vcc, s[6:7]
	v_or_b32_e32 v51, 3, v0
	v_cndmask_b32_e32 v36, v36, v204, vcc
	v_cmp_gt_u32_e32 vcc, v51, v154
	v_cmp_lt_i32_e64 s[6:7], v51, v155
	s_or_b64 vcc, vcc, s[6:7]
	v_or_b32_e32 v51, 8, v0
	v_cndmask_b32_e32 v37, v37, v204, vcc
	v_cmp_gt_u32_e32 vcc, v51, v154
	v_cmp_lt_i32_e64 s[6:7], v51, v155
	s_or_b64 vcc, vcc, s[6:7]
	v_or_b32_e32 v51, 9, v0
	v_cndmask_b32_e32 v38, v38, v204, vcc
	v_cmp_gt_u32_e32 vcc, v51, v154
	v_cmp_lt_i32_e64 s[6:7], v51, v155
	v_max3_f32 v50, v34, s35, v35
	s_or_b64 vcc, vcc, s[6:7]
	v_max3_f32 v50, v50, v36, v37
	v_cndmask_b32_e32 v39, v39, v204, vcc
	v_max3_f32 v52, v50, v38, v39
	v_or_b32_e32 v50, 10, v0
	v_cmp_gt_u32_e32 vcc, v50, v154
	v_cmp_lt_i32_e64 s[6:7], v50, v155
	s_or_b64 vcc, vcc, s[6:7]
	v_cndmask_b32_e32 v50, v40, v204, vcc
	v_or_b32_e32 v40, 11, v0
	v_cmp_gt_u32_e32 vcc, v40, v154
	v_cmp_lt_i32_e64 s[6:7], v40, v155
	s_or_b64 vcc, vcc, s[6:7]
	v_cndmask_b32_e32 v51, v41, v204, vcc
	v_or_b32_e32 v41, 16, v0
	v_cmp_gt_u32_e32 vcc, v41, v154
	v_cmp_lt_i32_e64 s[6:7], v41, v155
	s_or_b64 vcc, vcc, s[6:7]
	v_or_b32_e32 v41, 17, v0
	v_max3_f32 v40, v52, v50, v51
	v_cndmask_b32_e32 v52, v42, v204, vcc
	v_cmp_gt_u32_e32 vcc, v41, v154
	v_cmp_lt_i32_e64 s[6:7], v41, v155
	s_or_b64 vcc, vcc, s[6:7]
	v_or_b32_e32 v41, 18, v0
	v_cndmask_b32_e32 v53, v43, v204, vcc
	v_cmp_gt_u32_e32 vcc, v41, v154
	v_cmp_lt_i32_e64 s[6:7], v41, v155
	s_or_b64 vcc, vcc, s[6:7]
	v_or_b32_e32 v41, 19, v0
	v_cndmask_b32_e32 v44, v44, v204, vcc
	v_cmp_gt_u32_e32 vcc, v41, v154
	v_cmp_lt_i32_e64 s[6:7], v41, v155
	s_or_b64 vcc, vcc, s[6:7]
	v_or_b32_e32 v41, 24, v0
	v_cndmask_b32_e32 v45, v45, v204, vcc
	v_cmp_gt_u32_e32 vcc, v41, v154
	v_cmp_lt_i32_e64 s[6:7], v41, v155
	s_or_b64 vcc, vcc, s[6:7]
	v_or_b32_e32 v42, 25, v0
	v_cndmask_b32_e32 v41, v46, v204, vcc
	v_cmp_gt_u32_e32 vcc, v42, v154
	v_cmp_lt_i32_e64 s[6:7], v42, v155
	v_max3_f32 v40, v40, v52, v53
	s_or_b64 vcc, vcc, s[6:7]
	v_max3_f32 v40, v40, v44, v45
	v_cndmask_b32_e32 v42, v47, v204, vcc
	v_max3_f32 v46, v40, v41, v42
	v_or_b32_e32 v40, 26, v0
	v_cmp_gt_u32_e32 vcc, v40, v154
	v_cmp_lt_i32_e64 s[6:7], v40, v155
	s_or_b64 vcc, vcc, s[6:7]
	v_or_b32_e32 v0, 27, v0
	v_cndmask_b32_e32 v43, v48, v204, vcc
	v_cmp_gt_u32_e32 vcc, v0, v154
	v_cmp_lt_i32_e64 s[6:7], v0, v155
	s_or_b64 vcc, vcc, s[6:7]
	v_cndmask_b32_e32 v40, v49, v204, vcc
	v_and_b32_e32 v47, 64, v202
	v_max3_f32 v0, v46, v43, v40
	v_xor_b32_e32 v46, 32, v202
	v_add_u32_e32 v47, 64, v47
	v_cmp_lt_i32_e32 vcc, v46, v47
	s_nop 1
	v_cndmask_b32_e32 v46, v202, v46, vcc
	v_lshlrev_b32_e32 v46, 2, v46
	ds_bpermute_b32 v46, v46, v0
	s_waitcnt lgkmcnt(0)
	v_max_f32_e32 v46, v46, v46
	v_max_f32_e32 v0, v0, v46
	v_mul_f32_e32 v0, 0x3fb8aa3b, v0
	v_max_f32_e32 v46, v158, v158
	v_sub_f32_e32 v232, v0, v46
	v_cmp_lt_f32_e32 vcc, 0x41000000, v232
	s_nop 1
	v_cndmask_b32_e32 v157, v46, v0, vcc
	v_sub_f32_e32 v0, v158, v157
	v_exp_f32_e32 v0, v0
	v_cmp_neq_f32_e32 vcc, v157, v158
	s_cbranch_vccz .LBB0_516
	v_pk_mul_f32 v[32:33], v[32:33], v[0:1] op_sel_hi:[1,0]
	v_pk_mul_f32 v[30:31], v[30:31], v[0:1] op_sel_hi:[1,0]
	v_pk_mul_f32 v[28:29], v[28:29], v[0:1] op_sel_hi:[1,0]
	v_pk_mul_f32 v[26:27], v[26:27], v[0:1] op_sel_hi:[1,0]
	v_pk_mul_f32 v[24:25], v[24:25], v[0:1] op_sel_hi:[1,0]
	v_pk_mul_f32 v[22:23], v[22:23], v[0:1] op_sel_hi:[1,0]
	v_pk_mul_f32 v[20:21], v[20:21], v[0:1] op_sel_hi:[1,0]
	v_pk_mul_f32 v[18:19], v[18:19], v[0:1] op_sel_hi:[1,0]
	v_pk_mul_f32 v[16:17], v[16:17], v[0:1] op_sel_hi:[1,0]
	v_pk_mul_f32 v[14:15], v[14:15], v[0:1] op_sel_hi:[1,0]
	v_pk_mul_f32 v[12:13], v[12:13], v[0:1] op_sel_hi:[1,0]
	v_pk_mul_f32 v[10:11], v[10:11], v[0:1] op_sel_hi:[1,0]
	v_pk_mul_f32 v[8:9], v[8:9], v[0:1] op_sel_hi:[1,0]
	v_pk_mul_f32 v[6:7], v[6:7], v[0:1] op_sel_hi:[1,0]
	v_pk_mul_f32 v[4:5], v[4:5], v[0:1] op_sel_hi:[1,0]
	v_pk_mul_f32 v[2:3], v[2:3], v[0:1] op_sel_hi:[1,0]

;     ...
;   f32x16 s[2];
; #pragma unroll
;   for (int k2 = 0; k2 < 2; ++k2) {
;     if (!(HM & (1 << k2))) continue;
; #pragma unroll
;     for (int i = 0; i < 16; ++i) s[k2][i] = 0.f;
; #pragma unroll
;     for (int ks = 0; ks < 4; ++ks) {
;       const bf16x8 a = *(const bf16x8*)(Ks + (32 * k2 + r) * LSTR + 16 * ks + 8 * h);
;       s[k2] = mfma32(a, qf[ks], s[k2]);
;     }
;   }
;   if (MODE == 1) {
; #pragma unroll
;     for (int k2 = 0; k2 < 2; ++k2)
; #pragma unroll
;       for (int g = 0; g < 4; ++g) {
;         if (!(HM & (1 << k2))) continue;
;         const f32x4 cv = *(const f32x4*)(cn_lds + key0 + 32 * k2 + 8 * g + 4 * h);
; #pragma unroll
;         for (int e = 0; e < 4; ++e) s[k2][4 * g + e] = fmaf(s[k2][4 * g + e], L2E, cv[e]);
;       }
;   }
;   float mx = NINF;
; #pragma unroll
;   for (int k2 = 0; k2 < 2; ++k2)
; #pragma unroll
;     for (int i = 0; i < 16; ++i) {
;       if (!(HM & (1 << k2))) continue;
;       float v = s[k2][i];
;       if (MASKED) {
;         const int tk = key0 + 32 * k2 + crow(i, h);
;         const bool valid = (MODE == 0) ? ((tk <= tq) && (tq - tk <= maxdist)) : (tk <= tq);
;         v = valid ? v : NINF; s[k2][i] = v;
;       }
;       mx = fmaxf(mx, v);
;     }
;   mx = fmaxf(mx, __shfl_xor(mx, 32));
;   if (MODE != 1) mx *= L2E;
;   if (MODE == 2) mx = lanesel ? mx : NINF;
;   const float mn = fmaxf(m, mx); const float alpha = __builtin_amdgcn_exp2f(m - mn);
;   const float neg = (MODE == 2 && !lanesel) ? NINF : -mn;
;   float ps = 0.f;
; #pragma unroll
;   for (int k2 = 0; k2 < 2; ++k2)
; #pragma unroll
; template <int MODE>
; DI void flash_loop(char* smem, const bf16_t* Kbase, size_t ldk, const bf16_t* Vtbase, size_t ldv, ull tiles, ull wtiles,
;                    const bf16x8 (&qf)[4], f32x16 (&o)[2], float& m, float& l, int tq, int tqmin, int tqmax, int maxdist, const float* cn_lds, ull lmask) {
;     ...
;     if (!((wtiles >> kt) & 1ull)) return;
;     const bf16_t* Ks = (const bf16_t*)(smem + stage * (2 * 64 * LSTR * 2)); const bf16_t* Vs = Ks + 64 * LSTR;
;     const bool sel = ((lmask >> kt) & 1ull) != 0;
;     const bool interior = (64 * kt + 63 <= tqmin) && (MODE != 0 || (tqmax - 64 * kt <= maxdist));
;     int hm = 3;
;     if (MODE == 0) {
;       hm = 0;
;       if (64 * kt <= tqmax && 64 * kt + 31 >= tqmin - maxdist) hm |= 1;
;       if (64 * kt + 32 <= tqmax && 64 * kt + 63 >= tqmin - maxdist) hm |= 2;
;     }
.LBB0_622:
	s_lshr_b64 s[6:7], s[4:5], s65
	s_and_b32 s58, s6, 1
	s_cmp_eq_u64 s[58:59], 0
	s_cbranch_scc1 .LBB0_646
	s_lshl_b32 s58, s65, 6
	s_or_b32 s33, s58, 63
	s_cmp_le_u32 s58, s30
	s_cselect_b64 s[6:7], -1, 0
	s_or_b32 s36, s58, 31
	s_cmp_ge_i32 s36, s29
	s_cselect_b64 s[36:37], -1, 0
	s_and_b64 s[6:7], s[6:7], s[36:37]
	v_cndmask_b32_e64 v0, 0, 1, s[6:7]
	s_or_b32 s6, s58, 32
	s_cmp_gt_u32 s6, s30
	s_cselect_b64 s[6:7], -1, 0
	s_cmp_lt_i32 s33, s29
	s_cselect_b64 s[36:37], -1, 0
	v_or_b32_e32 v34, 2, v0
	s_or_b64 vcc, s[6:7], s[36:37]
	v_cndmask_b32_e32 v66, v34, v0, vcc
	v_cmp_gt_i32_e32 vcc, 2, v66
	s_mov_b64 s[62:63], -1
	s_mov_b64 s[54:55], 0
	s_and_b64 vcc, exec, vcc
	s_mov_b64 s[6:7], 0
	s_cbranch_vccnz .LBB0_639
	v_cmp_eq_u32_e32 vcc, 2, v66
	s_and_b64 vcc, exec, vcc
	s_mov_b64 s[6:7], -1
	s_cbranch_vccz .LBB0_628
	ds_read_b128 v[34:37], v199 offset:23040
	ds_read_b128 v[50:53], v199 offset:23072
	v_or_b32_e32 v0, s58, v197
	s_waitcnt lgkmcnt(1)
	v_mfma_f32_32x32x16_bf16 v[34:49], v[34:37], v[98:101], 0
	s_waitcnt lgkmcnt(0)
	v_mfma_f32_32x32x16_bf16 v[34:49], v[50:53], v[102:105], v[34:49]
	ds_read_b128 v[50:53], v199 offset:23104
	s_waitcnt lgkmcnt(0)
	v_mfma_f32_32x32x16_bf16 v[34:49], v[50:53], v[106:109], v[34:49]
	ds_read_b128 v[50:53], v199 offset:23136
	s_waitcnt lgkmcnt(0)
	v_mfma_f32_32x32x16_bf16 v[34:49], v[50:53], v[110:113], v[34:49]
	v_or_b32_e32 v50, 32, v0
	v_cmp_gt_u32_e32 vcc, v50, v154
	v_cmp_lt_i32_e64 s[6:7], v50, v155
	s_or_b64 vcc, vcc, s[6:7]
	s_nop 7
	v_cndmask_b32_e32 v67, v34, v204, vcc
	v_bitop3_b32 v34, s58, v205, v197 bitop3:0x36
	v_cmp_ge_u32_e32 vcc, v50, v154
	v_cmp_gt_i32_e64 s[6:7], v34, v156
	s_or_b64 vcc, vcc, s[6:7]
	v_cndmask_b32_e32 v68, v35, v204, vcc
	v_or_b32_e32 v35, 34, v0
	v_cmp_gt_u32_e32 vcc, v35, v154
	v_cmp_lt_i32_e64 s[6:7], v35, v155
	s_or_b64 vcc, vcc, s[6:7]
	v_or_b32_e32 v35, 35, v0
	v_cndmask_b32_e32 v69, v36, v204, vcc
	v_cmp_gt_u32_e32 vcc, v35, v154
	v_cmp_lt_i32_e64 s[6:7], v35, v155
	s_or_b64 vcc, vcc, s[6:7]
	v_or_b32_e32 v35, 40, v0
	v_cndmask_b32_e32 v70, v37, v204, vcc
	v_cmp_gt_u32_e32 vcc, v35, v154
	v_cmp_lt_i32_e64 s[6:7], v35, v155
	s_or_b64 vcc, vcc, s[6:7]
	v_or_b32_e32 v35, 41, v0
	v_cndmask_b32_e32 v71, v38, v204, vcc
	v_cmp_gt_u32_e32 vcc, v35, v154
	v_cmp_lt_i32_e64 s[6:7], v35, v155
	s_or_b64 vcc, vcc, s[6:7]
	v_or_b32_e32 v35, 42, v0
	v_cndmask_b32_e32 v72, v39, v204, vcc
	v_cmp_gt_u32_e32 vcc, v35, v154
	v_cmp_lt_i32_e64 s[6:7], v35, v155
	s_or_b64 vcc, vcc, s[6:7]
	v_or_b32_e32 v35, 43, v0
	v_cndmask_b32_e32 v77, v40, v204, vcc
	v_cmp_gt_u32_e32 vcc, v35, v154
	v_cmp_lt_i32_e64 s[6:7], v35, v155
	s_or_b64 vcc, vcc, s[6:7]
	v_or_b32_e32 v35, 48, v0
	v_cndmask_b32_e32 v78, v41, v204, vcc
	v_cmp_gt_u32_e32 vcc, v35, v154
	v_cmp_lt_i32_e64 s[6:7], v35, v155
	s_or_b64 vcc, vcc, s[6:7]
	v_or_b32_e32 v35, 49, v0
	v_cndmask_b32_e32 v79, v42, v204, vcc
	v_cmp_gt_u32_e32 vcc, v35, v154
	v_cmp_lt_i32_e64 s[6:7], v35, v155
	s_or_b64 vcc, vcc, s[6:7]
	v_or_b32_e32 v35, 50, v0
	v_cndmask_b32_e32 v80, v43, v204, vcc
	v_cmp_gt_u32_e32 vcc, v35, v154
	v_cmp_lt_i32_e64 s[6:7], v35, v155
	s_or_b64 vcc, vcc, s[6:7]
	v_or_b32_e32 v35, 51, v0
	v_cndmask_b32_e32 v81, v44, v204, vcc
	v_cmp_gt_u32_e32 vcc, v35, v154
	v_cmp_lt_i32_e64 s[6:7], v35, v155
	s_or_b64 vcc, vcc, s[6:7]
	v_or_b32_e32 v35, 56, v0
	v_cndmask_b32_e32 v82, v45, v204, vcc
	v_cmp_gt_u32_e32 vcc, v35, v154
	v_cmp_lt_i32_e64 s[6:7], v35, v155
	s_or_b64 vcc, vcc, s[6:7]
	v_or_b32_e32 v35, 57, v0
	v_max3_f32 v34, v67, s35, v68
	v_cndmask_b32_e32 v74, v46, v204, vcc
	v_cmp_gt_u32_e32 vcc, v35, v154
	v_cmp_lt_i32_e64 s[6:7], v35, v155
	v_max3_f32 v34, v34, v69, v70
	s_or_b64 vcc, vcc, s[6:7]
	v_or_b32_e32 v35, 58, v0
	v_max3_f32 v34, v34, v71, v72
	v_cndmask_b32_e32 v75, v47, v204, vcc
	v_cmp_gt_u32_e32 vcc, v35, v154
	v_cmp_lt_i32_e64 s[6:7], v35, v155
	v_max3_f32 v34, v34, v77, v78
	s_or_b64 vcc, vcc, s[6:7]
	v_or_b32_e32 v0, 59, v0
	v_max3_f32 v34, v34, v79, v80
	v_cndmask_b32_e32 v76, v48, v204, vcc
	v_cmp_gt_u32_e32 vcc, v0, v154
	v_cmp_lt_i32_e64 s[6:7], v0, v155
	v_max3_f32 v34, v34, v81, v82
	s_or_b64 vcc, vcc, s[6:7]
	v_max3_f32 v34, v34, v74, v75
	v_cndmask_b32_e32 v73, v49, v204, vcc
	v_and_b32_e32 v35, 64, v202
	v_max3_f32 v0, v34, v76, v73
	v_xor_b32_e32 v34, 32, v202
	v_add_u32_e32 v35, 64, v35
	v_cmp_lt_i32_e32 vcc, v34, v35
	s_nop 1
	v_cndmask_b32_e32 v34, v202, v34, vcc
	v_lshlrev_b32_e32 v34, 2, v34
	ds_bpermute_b32 v34, v34, v0
	s_waitcnt lgkmcnt(0)
	v_max_f32_e32 v34, v34, v34
	v_max_f32_e32 v0, v0, v34
	v_mul_f32_e32 v0, 0x3fb8aa3b, v0
	v_max_f32_e32 v34, v158, v158
	v_sub_f32_e32 v232, v0, v34
	v_cmp_lt_f32_e32 vcc, 0x41000000, v232
	s_nop 1
	v_cndmask_b32_e32 v157, v34, v0, vcc
	v_sub_f32_e32 v0, v158, v157
	v_exp_f32_e32 v0, v0
	v_cmp_neq_f32_e32 vcc, v157, v158
	s_cbranch_vccz .LBB0_627
	v_pk_mul_f32 v[32:33], v[32:33], v[0:1] op_sel_hi:[1,0]
	v_pk_mul_f32 v[30:31], v[30:31], v[0:1] op_sel_hi:[1,0]
	v_pk_mul_f32 v[28:29], v[28:29], v[0:1] op_sel_hi:[1,0]
	v_pk_mul_f32 v[26:27], v[26:27], v[0:1] op_sel_hi:[1,0]
	v_pk_mul_f32 v[24:25], v[24:25], v[0:1] op_sel_hi:[1,0]
	v_pk_mul_f32 v[22:23], v[22:23], v[0:1] op_sel_hi:[1,0]
	v_pk_mul_f32 v[20:21], v[20:21], v[0:1] op_sel_hi:[1,0]
	v_pk_mul_f32 v[18:19], v[18:19], v[0:1] op_sel_hi:[1,0]
	v_pk_mul_f32 v[16:17], v[16:17], v[0:1] op_sel_hi:[1,0]
	v_pk_mul_f32 v[14:15], v[14:15], v[0:1] op_sel_hi:[1,0]
	v_pk_mul_f32 v[12:13], v[12:13], v[0:1] op_sel_hi:[1,0]
	v_pk_mul_f32 v[10:11], v[10:11], v[0:1] op_sel_hi:[1,0]
	v_pk_mul_f32 v[8:9], v[8:9], v[0:1] op_sel_hi:[1,0]
	v_pk_mul_f32 v[6:7], v[6:7], v[0:1] op_sel_hi:[1,0]
	v_pk_mul_f32 v[4:5], v[4:5], v[0:1] op_sel_hi:[1,0]
	v_pk_mul_f32 v[2:3], v[2:3], v[0:1] op_sel_hi:[1,0]

;     ...
;   f32x16 s[2];
; #pragma unroll
;   for (int k2 = 0; k2 < 2; ++k2) {
;     if (!(HM & (1 << k2))) continue;
; #pragma unroll
;     for (int i = 0; i < 16; ++i) s[k2][i] = 0.f;
; #pragma unroll
;     for (int ks = 0; ks < 4; ++ks) {
;       const bf16x8 a = *(const bf16x8*)(Ks + (32 * k2 + r) * LSTR + 16 * ks + 8 * h);
;       s[k2] = mfma32(a, qf[ks], s[k2]);
;     }
;   }
;   if (MODE == 1) {
; #pragma unroll
;     for (int k2 = 0; k2 < 2; ++k2)
; #pragma unroll
;       for (int g = 0; g < 4; ++g) {
;         if (!(HM & (1 << k2))) continue;
;         const f32x4 cv = *(const f32x4*)(cn_lds + key0 + 32 * k2 + 8 * g + 4 * h);
; #pragma unroll
;         for (int e = 0; e < 4; ++e) s[k2][4 * g + e] = fmaf(s[k2][4 * g + e], L2E, cv[e]);
;       }
;   }
;   float mx = NINF;
; #pragma unroll
;   for (int k2 = 0; k2 < 2; ++k2)
; #pragma unroll
;     for (int i = 0; i < 16; ++i) {
;       if (!(HM & (1 << k2))) continue;
;       float v = s[k2][i];
;       if (MASKED) {
;         const int tk = key0 + 32 * k2 + crow(i, h);
;         const bool valid = (MODE == 0) ? ((tk <= tq) && (tq - tk <= maxdist)) : (tk <= tq);
;         v = valid ? v : NINF; s[k2][i] = v;
;       }
;       mx = fmaxf(mx, v);
;     }
;   mx = fmaxf(mx, __shfl_xor(mx, 32));
;   if (MODE != 1) mx *= L2E;
;   if (MODE == 2) mx = lanesel ? mx : NINF;
;   const float mn = fmaxf(m, mx); const float alpha = __builtin_amdgcn_exp2f(m - mn);
;   const float neg = (MODE == 2 && !lanesel) ? NINF : -mn;
;   float ps = 0.f;
; #pragma unroll
;   for (int k2 = 0; k2 < 2; ++k2)
; #pragma unroll
; template <int MODE>
; DI void flash_loop(char* smem, const bf16_t* Kbase, size_t ldk, const bf16_t* Vtbase, size_t ldv, ull tiles, ull wtiles,
;                    const bf16x8 (&qf)[4], f32x16 (&o)[2], float& m, float& l, int tq, int tqmin, int tqmax, int maxdist, const float* cn_lds, ull lmask) {
;     ...
;     if (!((wtiles >> kt) & 1ull)) return;
;     const bf16_t* Ks = (const bf16_t*)(smem + stage * (2 * 64 * LSTR * 2)); const bf16_t* Vs = Ks + 64 * LSTR;
;     const bool sel = ((lmask >> kt) & 1ull) != 0;
;     const bool interior = (64 * kt + 63 <= tqmin) && (MODE != 0 || (tqmax - 64 * kt <= maxdist));
;     int hm = 3;
;     if (MODE == 0) {
;       hm = 0;
;       if (64 * kt <= tqmax && 64 * kt + 31 >= tqmin - maxdist) hm |= 1;
;       if (64 * kt + 32 <= tqmax && 64 * kt + 63 >= tqmin - maxdist) hm |= 2;
;     }
.LBB0_662:
	s_lshr_b64 s[6:7], s[4:5], s33
	s_and_b32 s58, s6, 1
	s_cmp_eq_u64 s[58:59], 0
	s_cbranch_scc1 .LBB0_686
	s_lshl_b32 s58, s33, 6
	s_or_b32 s33, s58, 63
	s_cmp_le_u32 s58, s31
	s_cselect_b64 s[6:7], -1, 0
	s_or_b32 s36, s58, 31
	s_cmp_ge_i32 s36, s30
	s_cselect_b64 s[36:37], -1, 0
	s_and_b64 s[6:7], s[6:7], s[36:37]
	v_cndmask_b32_e64 v0, 0, 1, s[6:7]
	s_or_b32 s6, s58, 32
	s_cmp_gt_u32 s6, s31
	s_cselect_b64 s[6:7], -1, 0
	s_cmp_lt_i32 s33, s30
	s_cselect_b64 s[36:37], -1, 0
	v_readfirstlane_b32 s38, v0
	s_or_b32 s39, s38, 2
	s_or_b64 s[6:7], s[6:7], s[36:37]
	s_and_b64 s[6:7], s[6:7], exec
	s_cselect_b32 s68, s38, s39
	s_mov_b64 s[62:63], -1
	s_mov_b64 s[54:55], 0
	s_cmp_lt_i32 s68, 2
	s_mov_b64 s[6:7], 0
	s_cbranch_scc1 .LBB0_679
	s_cmp_eq_u32 s68, 2
	s_mov_b64 s[6:7], -1
	s_cbranch_scc0 .LBB0_668
	ds_read_b128 v[34:37], v199 offset:4608
	ds_read_b128 v[50:53], v199 offset:4640
	v_or_b32_e32 v0, s58, v197
	s_waitcnt lgkmcnt(1)
	v_mfma_f32_32x32x16_bf16 v[34:49], v[34:37], v[98:101], 0
	s_waitcnt lgkmcnt(0)
	v_mfma_f32_32x32x16_bf16 v[34:49], v[50:53], v[102:105], v[34:49]
	ds_read_b128 v[50:53], v199 offset:4672
	s_waitcnt lgkmcnt(0)
	v_mfma_f32_32x32x16_bf16 v[34:49], v[50:53], v[106:109], v[34:49]
	ds_read_b128 v[50:53], v199 offset:4704
	s_waitcnt lgkmcnt(0)
	v_mfma_f32_32x32x16_bf16 v[34:49], v[50:53], v[110:113], v[34:49]
	v_or_b32_e32 v50, 32, v0
	v_cmp_gt_u32_e32 vcc, v50, v154
	v_cmp_lt_i32_e64 s[6:7], v50, v155
	s_or_b64 vcc, vcc, s[6:7]
	s_nop 7
	v_cndmask_b32_e32 v66, v34, v204, vcc
	v_bitop3_b32 v34, s58, v205, v197 bitop3:0x36
	v_cmp_ge_u32_e32 vcc, v50, v154
	v_cmp_gt_i32_e64 s[6:7], v34, v156
	s_or_b64 vcc, vcc, s[6:7]
	v_cndmask_b32_e32 v67, v35, v204, vcc
	v_or_b32_e32 v35, 34, v0
	v_cmp_gt_u32_e32 vcc, v35, v154
	v_cmp_lt_i32_e64 s[6:7], v35, v155
	s_or_b64 vcc, vcc, s[6:7]
	v_or_b32_e32 v35, 35, v0
	v_cndmask_b32_e32 v68, v36, v204, vcc
	v_cmp_gt_u32_e32 vcc, v35, v154
	v_cmp_lt_i32_e64 s[6:7], v35, v155
	s_or_b64 vcc, vcc, s[6:7]
	v_or_b32_e32 v35, 40, v0
	v_cndmask_b32_e32 v69, v37, v204, vcc
	v_cmp_gt_u32_e32 vcc, v35, v154
	v_cmp_lt_i32_e64 s[6:7], v35, v155
	s_or_b64 vcc, vcc, s[6:7]
	v_or_b32_e32 v35, 41, v0
	v_cndmask_b32_e32 v70, v38, v204, vcc
	v_cmp_gt_u32_e32 vcc, v35, v154
	v_cmp_lt_i32_e64 s[6:7], v35, v155
	s_or_b64 vcc, vcc, s[6:7]
	v_or_b32_e32 v35, 42, v0
	v_cndmask_b32_e32 v71, v39, v204, vcc
	v_cmp_gt_u32_e32 vcc, v35, v154
	v_cmp_lt_i32_e64 s[6:7], v35, v155
	s_or_b64 vcc, vcc, s[6:7]
	v_or_b32_e32 v35, 43, v0
	v_cndmask_b32_e32 v77, v40, v204, vcc
	v_cmp_gt_u32_e32 vcc, v35, v154
	v_cmp_lt_i32_e64 s[6:7], v35, v155
	s_or_b64 vcc, vcc, s[6:7]
	v_or_b32_e32 v35, 48, v0
	v_cndmask_b32_e32 v78, v41, v204, vcc
	v_cmp_gt_u32_e32 vcc, v35, v154
	v_cmp_lt_i32_e64 s[6:7], v35, v155
	s_or_b64 vcc, vcc, s[6:7]
	v_or_b32_e32 v35, 49, v0
	v_cndmask_b32_e32 v79, v42, v204, vcc
	v_cmp_gt_u32_e32 vcc, v35, v154
	v_cmp_lt_i32_e64 s[6:7], v35, v155
	s_or_b64 vcc, vcc, s[6:7]
	v_or_b32_e32 v35, 50, v0
	v_cndmask_b32_e32 v80, v43, v204, vcc
	v_cmp_gt_u32_e32 vcc, v35, v154
	v_cmp_lt_i32_e64 s[6:7], v35, v155
	s_or_b64 vcc, vcc, s[6:7]
	v_or_b32_e32 v35, 51, v0
	v_cndmask_b32_e32 v81, v44, v204, vcc
	v_cmp_gt_u32_e32 vcc, v35, v154
	v_cmp_lt_i32_e64 s[6:7], v35, v155
	s_or_b64 vcc, vcc, s[6:7]
	v_or_b32_e32 v35, 56, v0
	v_cndmask_b32_e32 v76, v45, v204, vcc
	v_cmp_gt_u32_e32 vcc, v35, v154
	v_cmp_lt_i32_e64 s[6:7], v35, v155
	s_or_b64 vcc, vcc, s[6:7]
	v_or_b32_e32 v35, 57, v0
	v_max3_f32 v34, v66, s35, v67
	v_cndmask_b32_e32 v73, v46, v204, vcc
	v_cmp_gt_u32_e32 vcc, v35, v154
	v_cmp_lt_i32_e64 s[6:7], v35, v155
	v_max3_f32 v34, v34, v68, v69
	s_or_b64 vcc, vcc, s[6:7]
	v_or_b32_e32 v35, 58, v0
	v_max3_f32 v34, v34, v70, v71
	v_cndmask_b32_e32 v74, v47, v204, vcc
	v_cmp_gt_u32_e32 vcc, v35, v154
	v_cmp_lt_i32_e64 s[6:7], v35, v155
	v_max3_f32 v34, v34, v77, v78
	s_or_b64 vcc, vcc, s[6:7]
	v_or_b32_e32 v0, 59, v0
	v_max3_f32 v34, v34, v79, v80
	v_cndmask_b32_e32 v75, v48, v204, vcc
	v_cmp_gt_u32_e32 vcc, v0, v154
	v_cmp_lt_i32_e64 s[6:7], v0, v155
	v_max3_f32 v34, v34, v81, v76
	s_or_b64 vcc, vcc, s[6:7]
	v_max3_f32 v34, v34, v73, v74
	v_cndmask_b32_e32 v72, v49, v204, vcc
	v_and_b32_e32 v35, 64, v202
	v_max3_f32 v0, v34, v75, v72
	v_xor_b32_e32 v34, 32, v202
	v_add_u32_e32 v35, 64, v35
	v_cmp_lt_i32_e32 vcc, v34, v35
	s_nop 1
	v_cndmask_b32_e32 v34, v202, v34, vcc
	v_lshlrev_b32_e32 v34, 2, v34
	ds_bpermute_b32 v34, v34, v0
	s_waitcnt lgkmcnt(0)
	v_max_f32_e32 v34, v34, v34
	v_max_f32_e32 v0, v0, v34
	v_mul_f32_e32 v0, 0x3fb8aa3b, v0
	v_max_f32_e32 v34, v157, v157
	v_sub_f32_e32 v232, v0, v34
	v_cmp_lt_f32_e32 vcc, 0x41000000, v232
	s_nop 1
	v_cndmask_b32_e32 v158, v34, v0, vcc
	v_sub_f32_e32 v0, v157, v158
	v_exp_f32_e32 v0, v0
	v_cmp_neq_f32_e32 vcc, v158, v157
	s_cbranch_vccz .LBB0_667
	v_pk_mul_f32 v[32:33], v[32:33], v[0:1] op_sel_hi:[1,0]
	v_pk_mul_f32 v[30:31], v[30:31], v[0:1] op_sel_hi:[1,0]
	v_pk_mul_f32 v[28:29], v[28:29], v[0:1] op_sel_hi:[1,0]
	v_pk_mul_f32 v[26:27], v[26:27], v[0:1] op_sel_hi:[1,0]
	v_pk_mul_f32 v[24:25], v[24:25], v[0:1] op_sel_hi:[1,0]
	v_pk_mul_f32 v[22:23], v[22:23], v[0:1] op_sel_hi:[1,0]
	v_pk_mul_f32 v[20:21], v[20:21], v[0:1] op_sel_hi:[1,0]
	v_pk_mul_f32 v[18:19], v[18:19], v[0:1] op_sel_hi:[1,0]
	v_pk_mul_f32 v[16:17], v[16:17], v[0:1] op_sel_hi:[1,0]
	v_pk_mul_f32 v[14:15], v[14:15], v[0:1] op_sel_hi:[1,0]
	v_pk_mul_f32 v[12:13], v[12:13], v[0:1] op_sel_hi:[1,0]
	v_pk_mul_f32 v[10:11], v[10:11], v[0:1] op_sel_hi:[1,0]
	v_pk_mul_f32 v[8:9], v[8:9], v[0:1] op_sel_hi:[1,0]
	v_pk_mul_f32 v[6:7], v[6:7], v[0:1] op_sel_hi:[1,0]
	v_pk_mul_f32 v[4:5], v[4:5], v[0:1] op_sel_hi:[1,0]
	v_pk_mul_f32 v[2:3], v[2:3], v[0:1] op_sel_hi:[1,0]

; DI f32x16 mfma32(bf16x8 a, bf16x8 b, f32x16 c) { return __builtin_amdgcn_mfma_f32_32x32x16_bf16(a, b, c, 0, 0, 0); }
; DI int crow(int i, int h) { return (i & 3) + 8 * (i >> 2) + 4 * h; }
;     ...
;   f32x16 s[2];
; #pragma unroll
;   for (int k2 = 0; k2 < 2; ++k2) {
;     if (!(HM & (1 << k2))) continue;
; #pragma unroll
;     for (int i = 0; i < 16; ++i) s[k2][i] = 0.f;
; #pragma unroll
;     for (int ks = 0; ks < 4; ++ks) {
;       const bf16x8 a = *(const bf16x8*)(Ks + (32 * k2 + r) * LSTR + 16 * ks + 8 * h);
;       s[k2] = mfma32(a, qf[ks], s[k2]);
;     }
;   }
;   if (MODE == 1) {
; #pragma unroll
;     for (int k2 = 0; k2 < 2; ++k2)
; #pragma unroll
;       for (int g = 0; g < 4; ++g) {
;         if (!(HM & (1 << k2))) continue;
;         const f32x4 cv = *(const f32x4*)(cn_lds + key0 + 32 * k2 + 8 * g + 4 * h);
; #pragma unroll
;         for (int e = 0; e < 4; ++e) s[k2][4 * g + e] = fmaf(s[k2][4 * g + e], L2E, cv[e]);
;       }
;   }
;   float mx = NINF;
; #pragma unroll
;   for (int k2 = 0; k2 < 2; ++k2)
; #pragma unroll
;     for (int i = 0; i < 16; ++i) {
;       if (!(HM & (1 << k2))) continue;
;       float v = s[k2][i];
;       if (MASKED) {
;         const int tk = key0 + 32 * k2 + crow(i, h);
;         const bool valid = (MODE == 0) ? ((tk <= tq) && (tq - tk <= maxdist)) : (tk <= tq);
;         v = valid ? v : NINF; s[k2][i] = v;
; template <int MODE>
; DI void flash_loop(char* smem, const bf16_t* Kbase, size_t ldk, const bf16_t* Vtbase, size_t ldv, ull tiles, ull wtiles,
;                    const bf16x8 (&qf)[4], f32x16 (&o)[2], float& m, float& l, int tq, int tqmin, int tqmax, int maxdist, const float* cn_lds, ull lmask) {
;     ...
;     const bool interior = (64 * kt + 63 <= tqmin) && (MODE != 0 || (tqmax - 64 * kt <= maxdist));
.LBB0_670:
	ds_read_b128 v[82:85], v196
	ds_read_b128 v[78:81], v196 offset:32
	ds_read_b128 v[74:77], v196 offset:64
	ds_read_b128 v[66:69], v196 offset:96
	ds_read_b128 v[70:73], v196 offset:4608
	s_cmp_le_u32 s33, s29
	s_cselect_b64 s[6:7], -1, 0
	s_cmp_ge_i32 s58, s64
	s_cselect_b64 s[36:37], -1, 0
	s_and_b64 s[6:7], s[6:7], s[36:37]
	s_andn2_b64 vcc, exec, s[6:7]
	s_mov_b64 s[6:7], -1
	s_cbranch_vccz .LBB0_674
	s_waitcnt lgkmcnt(4)
	v_mfma_f32_32x32x16_bf16 v[50:65], v[82:85], v[98:101], 0
	ds_read_b128 v[86:89], v196 offset:4640
	ds_read_b128 v[90:93], v196 offset:4672
	v_or_b32_e32 v0, s58, v197
	v_cmp_gt_u32_e32 vcc, v0, v154
	v_cmp_lt_i32_e64 s[6:7], v0, v155
	s_or_b64 vcc, vcc, s[6:7]
	s_waitcnt lgkmcnt(5)
	v_mfma_f32_32x32x16_bf16 v[50:65], v[78:81], v[102:105], v[50:65]
	s_waitcnt lgkmcnt(2)
	v_mfma_f32_32x32x16_bf16 v[34:49], v[70:73], v[98:101], 0
	v_mfma_f32_32x32x16_bf16 v[50:65], v[74:77], v[106:109], v[50:65]
	s_waitcnt lgkmcnt(1)
	v_mfma_f32_32x32x16_bf16 v[34:49], v[86:89], v[102:105], v[34:49]
	ds_read_b128 v[86:89], v196 offset:4704
	v_mfma_f32_32x32x16_bf16 v[50:65], v[66:69], v[110:113], v[50:65]
	s_waitcnt lgkmcnt(1)
	v_mfma_f32_32x32x16_bf16 v[34:49], v[90:93], v[106:109], v[34:49]
	s_waitcnt lgkmcnt(0)
	v_mfma_f32_32x32x16_bf16 v[34:49], v[86:89], v[110:113], v[34:49]
	s_nop 7
	v_cndmask_b32_e32 v86, v50, v204, vcc
	v_bitop3_b32 v50, s58, v197, s58 bitop3:3
	v_cmp_ge_u32_e32 vcc, v0, v154
	v_cmp_lt_i32_e64 s[6:7], v156, v50
	s_or_b64 vcc, vcc, s[6:7]
	v_cndmask_b32_e32 v87, v51, v204, vcc
	v_or_b32_e32 v51, 2, v0
	v_cmp_gt_u32_e32 vcc, v51, v154
	v_cmp_lt_i32_e64 s[6:7], v51, v155
	s_or_b64 vcc, vcc, s[6:7]
	v_or_b32_e32 v51, 3, v0
	v_cndmask_b32_e32 v88, v52, v204, vcc
	v_cmp_gt_u32_e32 vcc, v51, v154
	v_cmp_lt_i32_e64 s[6:7], v51, v155
	s_or_b64 vcc, vcc, s[6:7]
	v_or_b32_e32 v51, 8, v0
	v_cndmask_b32_e32 v89, v53, v204, vcc
	v_cmp_gt_u32_e32 vcc, v51, v154
	v_cmp_lt_i32_e64 s[6:7], v51, v155
	s_or_b64 vcc, vcc, s[6:7]
	v_or_b32_e32 v51, 9, v0
	v_cndmask_b32_e32 v90, v54, v204, vcc
	v_cmp_gt_u32_e32 vcc, v51, v154
	v_cmp_lt_i32_e64 s[6:7], v51, v155
	s_or_b64 vcc, vcc, s[6:7]
	v_or_b32_e32 v51, 10, v0
	v_cndmask_b32_e32 v192, v55, v204, vcc
	v_cmp_gt_u32_e32 vcc, v51, v154
	v_cmp_lt_i32_e64 s[6:7], v51, v155
	s_or_b64 vcc, vcc, s[6:7]
	v_or_b32_e32 v51, 11, v0
	v_cndmask_b32_e32 v191, v56, v204, vcc
	v_cmp_gt_u32_e32 vcc, v51, v154
	v_cmp_lt_i32_e64 s[6:7], v51, v155
	s_or_b64 vcc, vcc, s[6:7]
	v_or_b32_e32 v51, 16, v0
	v_cndmask_b32_e32 v193, v57, v204, vcc
	v_cmp_gt_u32_e32 vcc, v51, v154
	v_cmp_lt_i32_e64 s[6:7], v51, v155
	s_or_b64 vcc, vcc, s[6:7]
	v_or_b32_e32 v51, 17, v0
	v_cndmask_b32_e32 v188, v58, v204, vcc
	v_cmp_gt_u32_e32 vcc, v51, v154
	v_cmp_lt_i32_e64 s[6:7], v51, v155
	s_or_b64 vcc, vcc, s[6:7]
	v_or_b32_e32 v51, 18, v0
	v_cndmask_b32_e32 v190, v59, v204, vcc
	v_cmp_gt_u32_e32 vcc, v51, v154
	v_cmp_lt_i32_e64 s[6:7], v51, v155
	s_or_b64 vcc, vcc, s[6:7]
	v_or_b32_e32 v51, 19, v0
	v_cndmask_b32_e32 v189, v60, v204, vcc
	v_cmp_gt_u32_e32 vcc, v51, v154
	v_cmp_lt_i32_e64 s[6:7], v51, v155
	s_or_b64 vcc, vcc, s[6:7]
	v_or_b32_e32 v51, 24, v0
	v_cndmask_b32_e32 v187, v61, v204, vcc
	v_cmp_gt_u32_e32 vcc, v51, v154
	v_cmp_lt_i32_e64 s[6:7], v51, v155
	s_or_b64 vcc, vcc, s[6:7]
	v_or_b32_e32 v51, 25, v0
	v_cndmask_b32_e32 v186, v62, v204, vcc
	v_cmp_gt_u32_e32 vcc, v51, v154
	v_cmp_lt_i32_e64 s[6:7], v51, v155
	s_or_b64 vcc, vcc, s[6:7]
	v_or_b32_e32 v51, 26, v0
	v_cndmask_b32_e32 v185, v63, v204, vcc
	v_cmp_gt_u32_e32 vcc, v51, v154
	v_cmp_lt_i32_e64 s[6:7], v51, v155
	s_or_b64 vcc, vcc, s[6:7]
	v_or_b32_e32 v51, 27, v0
	v_cndmask_b32_e32 v184, v64, v204, vcc
	v_cmp_gt_u32_e32 vcc, v51, v154
	v_cmp_lt_i32_e64 s[6:7], v51, v155
	s_or_b64 vcc, vcc, s[6:7]
	v_or_b32_e32 v51, 32, v0
	v_cndmask_b32_e32 v182, v65, v204, vcc
	v_cmp_gt_u32_e32 vcc, v51, v154
	v_cmp_lt_i32_e64 s[6:7], v51, v155
	s_or_b64 vcc, vcc, s[6:7]
	v_cndmask_b32_e32 v164, v34, v204, vcc
	v_or_b32_e32 v34, 33, v0
	v_cmp_gt_u32_e32 vcc, v34, v154
	v_cmp_lt_i32_e64 s[6:7], v34, v155
	s_or_b64 vcc, vcc, s[6:7]
	v_cndmask_b32_e32 v162, v35, v204, vcc
	v_or_b32_e32 v35, 34, v0
	v_cmp_gt_u32_e32 vcc, v35, v154
; DI int crow(int i, int h) { return (i & 3) + 8 * (i >> 2) + 4 * h; }
;     ...
;   float mx = NINF;
; #pragma unroll
;   for (int k2 = 0; k2 < 2; ++k2)
; #pragma unroll
;     for (int i = 0; i < 16; ++i) {
;       if (!(HM & (1 << k2))) continue;
;       float v = s[k2][i];
;       if (MASKED) {
;         const int tk = key0 + 32 * k2 + crow(i, h);
;         const bool valid = (MODE == 0) ? ((tk <= tq) && (tq - tk <= maxdist)) : (tk <= tq);
;         v = valid ? v : NINF; s[k2][i] = v;
;       }
;       mx = fmaxf(mx, v);
;     }
;   mx = fmaxf(mx, __shfl_xor(mx, 32));
;   if (MODE != 1) mx *= L2E;
;   if (MODE == 2) mx = lanesel ? mx : NINF;
;   const float mn = fmaxf(m, mx); const float alpha = __builtin_amdgcn_exp2f(m - mn);
;   const float neg = (MODE == 2 && !lanesel) ? NINF : -mn;
;   float ps = 0.f;
; #pragma unroll
;   for (int k2 = 0; k2 < 2; ++k2)
; #pragma unroll
;     for (int i = 0; i < 16; ++i) {
;       if (!(HM & (1 << k2))) continue;
;       const float pv = (MODE == 1) ? __builtin_amdgcn_exp2f(s[k2][i] + neg) : __builtin_amdgcn_exp2f(fmaf(s[k2][i], L2E, neg));
;       s[k2][i] = pv; ps += pv;
;     }
;   l = l * alpha + ps;
;   if (__builtin_amdgcn_ballot_w64(mn != m) != 0ull) {
; #pragma unroll
;     for (int dt = 0; dt < 2; ++dt)
; #pragma unroll
;       for (int i = 0; i < 16; ++i) o[dt][i] *= alpha;
;   }
	v_cmp_lt_i32_e64 s[6:7], v35, v155
	s_or_b64 vcc, vcc, s[6:7]
	v_or_b32_e32 v35, 35, v0
	v_cndmask_b32_e32 v160, v36, v204, vcc
	v_cmp_gt_u32_e32 vcc, v35, v154
	v_cmp_lt_i32_e64 s[6:7], v35, v155
	s_or_b64 vcc, vcc, s[6:7]
	v_or_b32_e32 v35, 40, v0
	v_cndmask_b32_e32 v97, v37, v204, vcc
	v_cmp_gt_u32_e32 vcc, v35, v154
	v_cmp_lt_i32_e64 s[6:7], v35, v155
	s_or_b64 vcc, vcc, s[6:7]
	v_or_b32_e32 v35, 41, v0
	v_cndmask_b32_e32 v92, v38, v204, vcc
	v_cmp_gt_u32_e32 vcc, v35, v154
	v_cmp_lt_i32_e64 s[6:7], v35, v155
	s_or_b64 vcc, vcc, s[6:7]
	v_or_b32_e32 v35, 42, v0
	v_cndmask_b32_e32 v91, v39, v204, vcc
	v_cmp_gt_u32_e32 vcc, v35, v154
	v_cmp_lt_i32_e64 s[6:7], v35, v155
	s_or_b64 vcc, vcc, s[6:7]
	v_or_b32_e32 v35, 43, v0
	v_cndmask_b32_e32 v93, v40, v204, vcc
	v_cmp_gt_u32_e32 vcc, v35, v154
	v_cmp_lt_i32_e64 s[6:7], v35, v155
	s_or_b64 vcc, vcc, s[6:7]
	v_or_b32_e32 v35, 48, v0
	v_cndmask_b32_e32 v94, v41, v204, vcc
	v_cmp_gt_u32_e32 vcc, v35, v154
	v_cmp_lt_i32_e64 s[6:7], v35, v155
	s_or_b64 vcc, vcc, s[6:7]
	v_or_b32_e32 v35, 49, v0
	v_max3_f32 v50, v86, s35, v87
	v_cndmask_b32_e32 v95, v42, v204, vcc
	v_cmp_gt_u32_e32 vcc, v35, v154
	v_cmp_lt_i32_e64 s[6:7], v35, v155
	v_max3_f32 v50, v50, v88, v89
	s_or_b64 vcc, vcc, s[6:7]
	v_or_b32_e32 v35, 50, v0
	v_max3_f32 v50, v50, v90, v192
	v_cndmask_b32_e32 v96, v43, v204, vcc
	v_cmp_gt_u32_e32 vcc, v35, v154
	v_cmp_lt_i32_e64 s[6:7], v35, v155
	v_max3_f32 v50, v50, v191, v193
	s_or_b64 vcc, vcc, s[6:7]
	v_or_b32_e32 v35, 51, v0
	v_max3_f32 v50, v50, v188, v190
	v_cndmask_b32_e32 v161, v44, v204, vcc
	v_cmp_gt_u32_e32 vcc, v35, v154
	v_cmp_lt_i32_e64 s[6:7], v35, v155
	v_max3_f32 v50, v50, v189, v187
	s_or_b64 vcc, vcc, s[6:7]
	v_or_b32_e32 v35, 56, v0
	v_max3_f32 v50, v50, v186, v185
	v_cndmask_b32_e32 v163, v45, v204, vcc
	v_cmp_gt_u32_e32 vcc, v35, v154
	v_cmp_lt_i32_e64 s[6:7], v35, v155
	v_max3_f32 v50, v50, v184, v182
	s_or_b64 vcc, vcc, s[6:7]
	v_or_b32_e32 v35, 57, v0
	v_max3_f32 v34, v50, v164, v162
	v_cndmask_b32_e32 v165, v46, v204, vcc
	v_cmp_gt_u32_e32 vcc, v35, v154
	v_cmp_lt_i32_e64 s[6:7], v35, v155
	v_max3_f32 v34, v34, v160, v97
	s_or_b64 vcc, vcc, s[6:7]
	v_or_b32_e32 v35, 58, v0
	v_max3_f32 v34, v34, v92, v91
	v_cndmask_b32_e32 v180, v47, v204, vcc
	v_cmp_gt_u32_e32 vcc, v35, v154
	v_cmp_lt_i32_e64 s[6:7], v35, v155
	v_max3_f32 v34, v34, v93, v94
	s_or_b64 vcc, vcc, s[6:7]
	v_or_b32_e32 v0, 59, v0
	v_max3_f32 v34, v34, v95, v96
	v_cndmask_b32_e32 v181, v48, v204, vcc
	v_cmp_gt_u32_e32 vcc, v0, v154
	v_cmp_lt_i32_e64 s[6:7], v0, v155
	v_max3_f32 v34, v34, v161, v163
	s_or_b64 vcc, vcc, s[6:7]
	v_max3_f32 v34, v34, v165, v180
	v_cndmask_b32_e32 v183, v49, v204, vcc
	v_and_b32_e32 v35, 64, v202
	v_max3_f32 v0, v34, v181, v183
	v_xor_b32_e32 v34, 32, v202
	v_add_u32_e32 v35, 64, v35
	v_cmp_lt_i32_e32 vcc, v34, v35
	s_nop 1
	v_cndmask_b32_e32 v34, v202, v34, vcc
	v_lshlrev_b32_e32 v34, 2, v34
	ds_bpermute_b32 v34, v34, v0
	s_waitcnt lgkmcnt(0)
	v_max_f32_e32 v34, v34, v34
	v_max_f32_e32 v0, v0, v34
	v_mul_f32_e32 v0, 0x3fb8aa3b, v0
	v_max_f32_e32 v34, v157, v157
	v_sub_f32_e32 v232, v0, v34
	v_cmp_lt_f32_e32 vcc, 0x41000000, v232
	s_nop 1
	v_cndmask_b32_e32 v158, v34, v0, vcc
	v_sub_f32_e32 v0, v157, v158
	v_exp_f32_e32 v0, v0
	v_cmp_neq_f32_e32 vcc, v158, v157
	s_cbranch_vccz .LBB0_673
	v_pk_mul_f32 v[32:33], v[32:33], v[0:1] op_sel_hi:[1,0]
	v_pk_mul_f32 v[30:31], v[30:31], v[0:1] op_sel_hi:[1,0]
	v_pk_mul_f32 v[28:29], v[28:29], v[0:1] op_sel_hi:[1,0]
	v_pk_mul_f32 v[26:27], v[26:27], v[0:1] op_sel_hi:[1,0]
	v_pk_mul_f32 v[24:25], v[24:25], v[0:1] op_sel_hi:[1,0]
	v_pk_mul_f32 v[22:23], v[22:23], v[0:1] op_sel_hi:[1,0]
	v_pk_mul_f32 v[20:21], v[20:21], v[0:1] op_sel_hi:[1,0]
	v_pk_mul_f32 v[18:19], v[18:19], v[0:1] op_sel_hi:[1,0]
	v_pk_mul_f32 v[16:17], v[16:17], v[0:1] op_sel_hi:[1,0]
	v_pk_mul_f32 v[14:15], v[14:15], v[0:1] op_sel_hi:[1,0]
	v_pk_mul_f32 v[12:13], v[12:13], v[0:1] op_sel_hi:[1,0]
	v_pk_mul_f32 v[10:11], v[10:11], v[0:1] op_sel_hi:[1,0]
	v_pk_mul_f32 v[8:9], v[8:9], v[0:1] op_sel_hi:[1,0]
	v_pk_mul_f32 v[6:7], v[6:7], v[0:1] op_sel_hi:[1,0]
	v_pk_mul_f32 v[4:5], v[4:5], v[0:1] op_sel_hi:[1,0]
	v_pk_mul_f32 v[2:3], v[2:3], v[0:1] op_sel_hi:[1,0]

;     ...
;   f32x16 s[2];
; #pragma unroll
;   for (int k2 = 0; k2 < 2; ++k2) {
;     if (!(HM & (1 << k2))) continue;
; #pragma unroll
;     for (int i = 0; i < 16; ++i) s[k2][i] = 0.f;
; #pragma unroll
;     for (int ks = 0; ks < 4; ++ks) {
;       const bf16x8 a = *(const bf16x8*)(Ks + (32 * k2 + r) * LSTR + 16 * ks + 8 * h);
;       s[k2] = mfma32(a, qf[ks], s[k2]);
;     }
;   }
;   if (MODE == 1) {
; #pragma unroll
;     for (int k2 = 0; k2 < 2; ++k2)
; #pragma unroll
;       for (int g = 0; g < 4; ++g) {
;         if (!(HM & (1 << k2))) continue;
;         const f32x4 cv = *(const f32x4*)(cn_lds + key0 + 32 * k2 + 8 * g + 4 * h);
; #pragma unroll
;         for (int e = 0; e < 4; ++e) s[k2][4 * g + e] = fmaf(s[k2][4 * g + e], L2E, cv[e]);
;       }
;   }
;   float mx = NINF;
; #pragma unroll
;   for (int k2 = 0; k2 < 2; ++k2)
; #pragma unroll
;     for (int i = 0; i < 16; ++i) {
;       if (!(HM & (1 << k2))) continue;
;       float v = s[k2][i];
;       if (MASKED) {
;         const int tk = key0 + 32 * k2 + crow(i, h);
;         const bool valid = (MODE == 0) ? ((tk <= tq) && (tq - tk <= maxdist)) : (tk <= tq);
;         v = valid ? v : NINF; s[k2][i] = v;
;       }
;       mx = fmaxf(mx, v);
;     }
;   mx = fmaxf(mx, __shfl_xor(mx, 32));
;   if (MODE != 1) mx *= L2E;
;   if (MODE == 2) mx = lanesel ? mx : NINF;
;   const float mn = fmaxf(m, mx); const float alpha = __builtin_amdgcn_exp2f(m - mn);
;   const float neg = (MODE == 2 && !lanesel) ? NINF : -mn;
;   float ps = 0.f;
; #pragma unroll
;   for (int k2 = 0; k2 < 2; ++k2)
; #pragma unroll
; template <int MODE>
; DI void flash_loop(char* smem, const bf16_t* Kbase, size_t ldk, const bf16_t* Vtbase, size_t ldv, ull tiles, ull wtiles,
;                    const bf16x8 (&qf)[4], f32x16 (&o)[2], float& m, float& l, int tq, int tqmin, int tqmax, int maxdist, const float* cn_lds, ull lmask) {
;     ...
;     if (!((wtiles >> kt) & 1ull)) return;
;     const bf16_t* Ks = (const bf16_t*)(smem + stage * (2 * 64 * LSTR * 2)); const bf16_t* Vs = Ks + 64 * LSTR;
;     const bool sel = ((lmask >> kt) & 1ull) != 0;
;     const bool interior = (64 * kt + 63 <= tqmin) && (MODE != 0 || (tqmax - 64 * kt <= maxdist));
;     int hm = 3;
;     if (MODE == 0) {
;       hm = 0;
;       if (64 * kt <= tqmax && 64 * kt + 31 >= tqmin - maxdist) hm |= 1;
;       if (64 * kt + 32 <= tqmax && 64 * kt + 63 >= tqmin - maxdist) hm |= 2;
;     }
.LBB0_690:
	s_lshr_b64 s[6:7], s[4:5], s67
	s_and_b32 s58, s6, 1
	s_cmp_eq_u64 s[58:59], 0
	s_cbranch_scc1 .LBB0_714
	s_lshl_b32 s58, s67, 6
	s_or_b32 s33, s58, 63
	s_cmp_le_u32 s58, s31
	s_cselect_b64 s[6:7], -1, 0
	s_or_b32 s36, s58, 31
	s_cmp_ge_i32 s36, s30
	s_cselect_b64 s[36:37], -1, 0
	s_and_b64 s[6:7], s[6:7], s[36:37]
	v_cndmask_b32_e64 v0, 0, 1, s[6:7]
	s_or_b32 s6, s58, 32
	s_cmp_gt_u32 s6, s31
	s_cselect_b64 s[6:7], -1, 0
	s_cmp_lt_i32 s33, s30
	s_cselect_b64 s[36:37], -1, 0
	v_or_b32_e32 v34, 2, v0
	s_or_b64 vcc, s[6:7], s[36:37]
	v_cndmask_b32_e32 v66, v34, v0, vcc
	v_cmp_gt_i32_e32 vcc, 2, v66
	s_mov_b64 s[62:63], -1
	s_mov_b64 s[54:55], 0
	s_and_b64 vcc, exec, vcc
	s_mov_b64 s[6:7], 0
	s_cbranch_vccnz .LBB0_707
	v_cmp_eq_u32_e32 vcc, 2, v66
	s_and_b64 vcc, exec, vcc
	s_mov_b64 s[6:7], -1
	s_cbranch_vccz .LBB0_696
	ds_read_b128 v[34:37], v199 offset:23040
	ds_read_b128 v[50:53], v199 offset:23072
	v_or_b32_e32 v0, s58, v197
	s_waitcnt lgkmcnt(1)
	v_mfma_f32_32x32x16_bf16 v[34:49], v[34:37], v[98:101], 0
	s_waitcnt lgkmcnt(0)
	v_mfma_f32_32x32x16_bf16 v[34:49], v[50:53], v[102:105], v[34:49]
	ds_read_b128 v[50:53], v199 offset:23104
	s_waitcnt lgkmcnt(0)
	v_mfma_f32_32x32x16_bf16 v[34:49], v[50:53], v[106:109], v[34:49]
	ds_read_b128 v[50:53], v199 offset:23136
	s_waitcnt lgkmcnt(0)
	v_mfma_f32_32x32x16_bf16 v[34:49], v[50:53], v[110:113], v[34:49]
	v_or_b32_e32 v50, 32, v0
	v_cmp_gt_u32_e32 vcc, v50, v154
	v_cmp_lt_i32_e64 s[6:7], v50, v155
	s_or_b64 vcc, vcc, s[6:7]
	s_nop 7
	v_cndmask_b32_e32 v67, v34, v204, vcc
	v_bitop3_b32 v34, s58, v205, v197 bitop3:0x36
	v_cmp_ge_u32_e32 vcc, v50, v154
	v_cmp_gt_i32_e64 s[6:7], v34, v156
	s_or_b64 vcc, vcc, s[6:7]
	v_cndmask_b32_e32 v68, v35, v204, vcc
	v_or_b32_e32 v35, 34, v0
	v_cmp_gt_u32_e32 vcc, v35, v154
	v_cmp_lt_i32_e64 s[6:7], v35, v155
	s_or_b64 vcc, vcc, s[6:7]
	v_or_b32_e32 v35, 35, v0
	v_cndmask_b32_e32 v69, v36, v204, vcc
	v_cmp_gt_u32_e32 vcc, v35, v154
	v_cmp_lt_i32_e64 s[6:7], v35, v155
	s_or_b64 vcc, vcc, s[6:7]
	v_or_b32_e32 v35, 40, v0
	v_cndmask_b32_e32 v70, v37, v204, vcc
	v_cmp_gt_u32_e32 vcc, v35, v154
	v_cmp_lt_i32_e64 s[6:7], v35, v155
	s_or_b64 vcc, vcc, s[6:7]
	v_or_b32_e32 v35, 41, v0
	v_cndmask_b32_e32 v71, v38, v204, vcc
	v_cmp_gt_u32_e32 vcc, v35, v154
	v_cmp_lt_i32_e64 s[6:7], v35, v155
	s_or_b64 vcc, vcc, s[6:7]
	v_or_b32_e32 v35, 42, v0
	v_cndmask_b32_e32 v72, v39, v204, vcc
	v_cmp_gt_u32_e32 vcc, v35, v154
	v_cmp_lt_i32_e64 s[6:7], v35, v155
	s_or_b64 vcc, vcc, s[6:7]
	v_or_b32_e32 v35, 43, v0
	v_cndmask_b32_e32 v77, v40, v204, vcc
	v_cmp_gt_u32_e32 vcc, v35, v154
	v_cmp_lt_i32_e64 s[6:7], v35, v155
	s_or_b64 vcc, vcc, s[6:7]
	v_or_b32_e32 v35, 48, v0
	v_cndmask_b32_e32 v78, v41, v204, vcc
	v_cmp_gt_u32_e32 vcc, v35, v154
	v_cmp_lt_i32_e64 s[6:7], v35, v155
	s_or_b64 vcc, vcc, s[6:7]
	v_or_b32_e32 v35, 49, v0
	v_cndmask_b32_e32 v79, v42, v204, vcc
	v_cmp_gt_u32_e32 vcc, v35, v154
	v_cmp_lt_i32_e64 s[6:7], v35, v155
	s_or_b64 vcc, vcc, s[6:7]
	v_or_b32_e32 v35, 50, v0
	v_cndmask_b32_e32 v80, v43, v204, vcc
	v_cmp_gt_u32_e32 vcc, v35, v154
	v_cmp_lt_i32_e64 s[6:7], v35, v155
	s_or_b64 vcc, vcc, s[6:7]
	v_or_b32_e32 v35, 51, v0
	v_cndmask_b32_e32 v81, v44, v204, vcc
	v_cmp_gt_u32_e32 vcc, v35, v154
	v_cmp_lt_i32_e64 s[6:7], v35, v155
	s_or_b64 vcc, vcc, s[6:7]
	v_or_b32_e32 v35, 56, v0
	v_cndmask_b32_e32 v82, v45, v204, vcc
	v_cmp_gt_u32_e32 vcc, v35, v154
	v_cmp_lt_i32_e64 s[6:7], v35, v155
	s_or_b64 vcc, vcc, s[6:7]
	v_or_b32_e32 v35, 57, v0
	v_max3_f32 v34, v67, s35, v68
	v_cndmask_b32_e32 v74, v46, v204, vcc
	v_cmp_gt_u32_e32 vcc, v35, v154
	v_cmp_lt_i32_e64 s[6:7], v35, v155
	v_max3_f32 v34, v34, v69, v70
	s_or_b64 vcc, vcc, s[6:7]
	v_or_b32_e32 v35, 58, v0
	v_max3_f32 v34, v34, v71, v72
	v_cndmask_b32_e32 v75, v47, v204, vcc
	v_cmp_gt_u32_e32 vcc, v35, v154
	v_cmp_lt_i32_e64 s[6:7], v35, v155
	v_max3_f32 v34, v34, v77, v78
	s_or_b64 vcc, vcc, s[6:7]
	v_or_b32_e32 v0, 59, v0
	v_max3_f32 v34, v34, v79, v80
	v_cndmask_b32_e32 v76, v48, v204, vcc
	v_cmp_gt_u32_e32 vcc, v0, v154
	v_cmp_lt_i32_e64 s[6:7], v0, v155
	v_max3_f32 v34, v34, v81, v82
	s_or_b64 vcc, vcc, s[6:7]
	v_max3_f32 v34, v34, v74, v75
	v_cndmask_b32_e32 v73, v49, v204, vcc
	v_and_b32_e32 v35, 64, v202
	v_max3_f32 v0, v34, v76, v73
	v_xor_b32_e32 v34, 32, v202
	v_add_u32_e32 v35, 64, v35
	v_cmp_lt_i32_e32 vcc, v34, v35
	s_nop 1
	v_cndmask_b32_e32 v34, v202, v34, vcc
	v_lshlrev_b32_e32 v34, 2, v34
	ds_bpermute_b32 v34, v34, v0
	s_waitcnt lgkmcnt(0)
	v_max_f32_e32 v34, v34, v34
	v_max_f32_e32 v0, v0, v34
	v_mul_f32_e32 v0, 0x3fb8aa3b, v0
	v_max_f32_e32 v34, v158, v158
	v_sub_f32_e32 v232, v0, v34
	v_cmp_lt_f32_e32 vcc, 0x41000000, v232
	s_nop 1
	v_cndmask_b32_e32 v157, v34, v0, vcc
	v_sub_f32_e32 v0, v158, v157
	v_exp_f32_e32 v0, v0
	v_cmp_neq_f32_e32 vcc, v157, v158
	s_cbranch_vccz .LBB0_695
	v_pk_mul_f32 v[32:33], v[32:33], v[0:1] op_sel_hi:[1,0]
	v_pk_mul_f32 v[30:31], v[30:31], v[0:1] op_sel_hi:[1,0]
	v_pk_mul_f32 v[28:29], v[28:29], v[0:1] op_sel_hi:[1,0]
	v_pk_mul_f32 v[26:27], v[26:27], v[0:1] op_sel_hi:[1,0]
	v_pk_mul_f32 v[24:25], v[24:25], v[0:1] op_sel_hi:[1,0]
	v_pk_mul_f32 v[22:23], v[22:23], v[0:1] op_sel_hi:[1,0]
	v_pk_mul_f32 v[20:21], v[20:21], v[0:1] op_sel_hi:[1,0]
	v_pk_mul_f32 v[18:19], v[18:19], v[0:1] op_sel_hi:[1,0]
	v_pk_mul_f32 v[16:17], v[16:17], v[0:1] op_sel_hi:[1,0]
	v_pk_mul_f32 v[14:15], v[14:15], v[0:1] op_sel_hi:[1,0]
	v_pk_mul_f32 v[12:13], v[12:13], v[0:1] op_sel_hi:[1,0]
	v_pk_mul_f32 v[10:11], v[10:11], v[0:1] op_sel_hi:[1,0]
	v_pk_mul_f32 v[8:9], v[8:9], v[0:1] op_sel_hi:[1,0]
	v_pk_mul_f32 v[6:7], v[6:7], v[0:1] op_sel_hi:[1,0]
	v_pk_mul_f32 v[4:5], v[4:5], v[0:1] op_sel_hi:[1,0]
	v_pk_mul_f32 v[2:3], v[2:3], v[0:1] op_sel_hi:[1,0]

; DI f32x16 mfma32(bf16x8 a, bf16x8 b, f32x16 c) { return __builtin_amdgcn_mfma_f32_32x32x16_bf16(a, b, c, 0, 0, 0); }
; DI int crow(int i, int h) { return (i & 3) + 8 * (i >> 2) + 4 * h; }
;     ...
;   f32x16 s[2];
; #pragma unroll
;   for (int k2 = 0; k2 < 2; ++k2) {
;     if (!(HM & (1 << k2))) continue;
; #pragma unroll
;     for (int i = 0; i < 16; ++i) s[k2][i] = 0.f;
; #pragma unroll
;     for (int ks = 0; ks < 4; ++ks) {
;       const bf16x8 a = *(const bf16x8*)(Ks + (32 * k2 + r) * LSTR + 16 * ks + 8 * h);
;       s[k2] = mfma32(a, qf[ks], s[k2]);
;     }
;   }
;   if (MODE == 1) {
; #pragma unroll
;     for (int k2 = 0; k2 < 2; ++k2)
; #pragma unroll
;       for (int g = 0; g < 4; ++g) {
;         if (!(HM & (1 << k2))) continue;
;         const f32x4 cv = *(const f32x4*)(cn_lds + key0 + 32 * k2 + 8 * g + 4 * h);
; #pragma unroll
;         for (int e = 0; e < 4; ++e) s[k2][4 * g + e] = fmaf(s[k2][4 * g + e], L2E, cv[e]);
;       }
;   }
;   float mx = NINF;
; #pragma unroll
;   for (int k2 = 0; k2 < 2; ++k2)
; #pragma unroll
;     for (int i = 0; i < 16; ++i) {
;       if (!(HM & (1 << k2))) continue;
;       float v = s[k2][i];
;       if (MASKED) {
;         const int tk = key0 + 32 * k2 + crow(i, h);
;         const bool valid = (MODE == 0) ? ((tk <= tq) && (tq - tk <= maxdist)) : (tk <= tq);
;         v = valid ? v : NINF; s[k2][i] = v;
; template <int MODE>
; DI void flash_loop(char* smem, const bf16_t* Kbase, size_t ldk, const bf16_t* Vtbase, size_t ldv, ull tiles, ull wtiles,
;                    const bf16x8 (&qf)[4], f32x16 (&o)[2], float& m, float& l, int tq, int tqmin, int tqmax, int maxdist, const float* cn_lds, ull lmask) {
;     ...
;     const bool interior = (64 * kt + 63 <= tqmin) && (MODE != 0 || (tqmax - 64 * kt <= maxdist));
.LBB0_698:
	ds_read_b128 v[82:85], v196 offset:18432
	ds_read_b128 v[78:81], v196 offset:18464
	ds_read_b128 v[74:77], v196 offset:18496
	ds_read_b128 v[66:69], v196 offset:18528
	ds_read_b128 v[70:73], v196 offset:23040
	s_cmp_le_u32 s33, s29
	s_cselect_b64 s[6:7], -1, 0
	s_cmp_ge_i32 s58, s64
	s_cselect_b64 s[36:37], -1, 0
	s_and_b64 s[6:7], s[6:7], s[36:37]
	s_andn2_b64 vcc, exec, s[6:7]
	s_mov_b64 s[6:7], -1
	s_cbranch_vccz .LBB0_702
	s_waitcnt lgkmcnt(4)
	v_mfma_f32_32x32x16_bf16 v[50:65], v[82:85], v[98:101], 0
	ds_read_b128 v[86:89], v196 offset:23072
	ds_read_b128 v[90:93], v196 offset:23104
	v_or_b32_e32 v0, s58, v197
	v_cmp_gt_u32_e32 vcc, v0, v154
	v_cmp_lt_i32_e64 s[6:7], v0, v155
	s_or_b64 vcc, vcc, s[6:7]
	s_waitcnt lgkmcnt(5)
	v_mfma_f32_32x32x16_bf16 v[50:65], v[78:81], v[102:105], v[50:65]
	s_waitcnt lgkmcnt(2)
	v_mfma_f32_32x32x16_bf16 v[34:49], v[70:73], v[98:101], 0
	v_mfma_f32_32x32x16_bf16 v[50:65], v[74:77], v[106:109], v[50:65]
	s_waitcnt lgkmcnt(1)
	v_mfma_f32_32x32x16_bf16 v[34:49], v[86:89], v[102:105], v[34:49]
	ds_read_b128 v[86:89], v196 offset:23136
	v_mfma_f32_32x32x16_bf16 v[50:65], v[66:69], v[110:113], v[50:65]
	s_waitcnt lgkmcnt(1)
	v_mfma_f32_32x32x16_bf16 v[34:49], v[90:93], v[106:109], v[34:49]
	s_waitcnt lgkmcnt(0)
	v_mfma_f32_32x32x16_bf16 v[34:49], v[86:89], v[110:113], v[34:49]
	s_nop 7
	v_cndmask_b32_e32 v86, v50, v204, vcc
	v_bitop3_b32 v50, s58, v197, s58 bitop3:3
	v_cmp_ge_u32_e32 vcc, v0, v154
	v_cmp_lt_i32_e64 s[6:7], v156, v50
	s_or_b64 vcc, vcc, s[6:7]
	v_cndmask_b32_e32 v87, v51, v204, vcc
	v_or_b32_e32 v51, 2, v0
	v_cmp_gt_u32_e32 vcc, v51, v154
	v_cmp_lt_i32_e64 s[6:7], v51, v155
	s_or_b64 vcc, vcc, s[6:7]
	v_or_b32_e32 v51, 3, v0
	v_cndmask_b32_e32 v88, v52, v204, vcc
	v_cmp_gt_u32_e32 vcc, v51, v154
	v_cmp_lt_i32_e64 s[6:7], v51, v155
	s_or_b64 vcc, vcc, s[6:7]
	v_or_b32_e32 v51, 8, v0
	v_cndmask_b32_e32 v89, v53, v204, vcc
	v_cmp_gt_u32_e32 vcc, v51, v154
	v_cmp_lt_i32_e64 s[6:7], v51, v155
	s_or_b64 vcc, vcc, s[6:7]
	v_or_b32_e32 v51, 9, v0
	v_cndmask_b32_e32 v90, v54, v204, vcc
	v_cmp_gt_u32_e32 vcc, v51, v154
	v_cmp_lt_i32_e64 s[6:7], v51, v155
	s_or_b64 vcc, vcc, s[6:7]
	v_or_b32_e32 v51, 10, v0
	v_cndmask_b32_e32 v192, v55, v204, vcc
	v_cmp_gt_u32_e32 vcc, v51, v154
	v_cmp_lt_i32_e64 s[6:7], v51, v155
	s_or_b64 vcc, vcc, s[6:7]
	v_or_b32_e32 v51, 11, v0
	v_cndmask_b32_e32 v191, v56, v204, vcc
	v_cmp_gt_u32_e32 vcc, v51, v154
	v_cmp_lt_i32_e64 s[6:7], v51, v155
	s_or_b64 vcc, vcc, s[6:7]
	v_or_b32_e32 v51, 16, v0
	v_cndmask_b32_e32 v193, v57, v204, vcc
	v_cmp_gt_u32_e32 vcc, v51, v154
	v_cmp_lt_i32_e64 s[6:7], v51, v155
	s_or_b64 vcc, vcc, s[6:7]
	v_or_b32_e32 v51, 17, v0
	v_cndmask_b32_e32 v188, v58, v204, vcc
	v_cmp_gt_u32_e32 vcc, v51, v154
	v_cmp_lt_i32_e64 s[6:7], v51, v155
	s_or_b64 vcc, vcc, s[6:7]
	v_or_b32_e32 v51, 18, v0
	v_cndmask_b32_e32 v190, v59, v204, vcc
	v_cmp_gt_u32_e32 vcc, v51, v154
	v_cmp_lt_i32_e64 s[6:7], v51, v155
	s_or_b64 vcc, vcc, s[6:7]
	v_or_b32_e32 v51, 19, v0
	v_cndmask_b32_e32 v189, v60, v204, vcc
	v_cmp_gt_u32_e32 vcc, v51, v154
	v_cmp_lt_i32_e64 s[6:7], v51, v155
	s_or_b64 vcc, vcc, s[6:7]
	v_or_b32_e32 v51, 24, v0
	v_cndmask_b32_e32 v187, v61, v204, vcc
	v_cmp_gt_u32_e32 vcc, v51, v154
	v_cmp_lt_i32_e64 s[6:7], v51, v155
	s_or_b64 vcc, vcc, s[6:7]
	v_or_b32_e32 v51, 25, v0
	v_cndmask_b32_e32 v186, v62, v204, vcc
	v_cmp_gt_u32_e32 vcc, v51, v154
	v_cmp_lt_i32_e64 s[6:7], v51, v155
	s_or_b64 vcc, vcc, s[6:7]
	v_or_b32_e32 v51, 26, v0
	v_cndmask_b32_e32 v185, v63, v204, vcc
	v_cmp_gt_u32_e32 vcc, v51, v154
	v_cmp_lt_i32_e64 s[6:7], v51, v155
	s_or_b64 vcc, vcc, s[6:7]
	v_or_b32_e32 v51, 27, v0
	v_cndmask_b32_e32 v184, v64, v204, vcc
	v_cmp_gt_u32_e32 vcc, v51, v154
	v_cmp_lt_i32_e64 s[6:7], v51, v155
	s_or_b64 vcc, vcc, s[6:7]
	v_or_b32_e32 v51, 32, v0
	v_cndmask_b32_e32 v182, v65, v204, vcc
	v_cmp_gt_u32_e32 vcc, v51, v154
	v_cmp_lt_i32_e64 s[6:7], v51, v155
	s_or_b64 vcc, vcc, s[6:7]
	v_cndmask_b32_e32 v164, v34, v204, vcc
	v_or_b32_e32 v34, 33, v0
	v_cmp_gt_u32_e32 vcc, v34, v154
	v_cmp_lt_i32_e64 s[6:7], v34, v155
	s_or_b64 vcc, vcc, s[6:7]
	v_cndmask_b32_e32 v162, v35, v204, vcc
	v_or_b32_e32 v35, 34, v0
	v_cmp_gt_u32_e32 vcc, v35, v154
; DI int crow(int i, int h) { return (i & 3) + 8 * (i >> 2) + 4 * h; }
;     ...
;   float mx = NINF;
; #pragma unroll
;   for (int k2 = 0; k2 < 2; ++k2)
; #pragma unroll
;     for (int i = 0; i < 16; ++i) {
;       if (!(HM & (1 << k2))) continue;
;       float v = s[k2][i];
;       if (MASKED) {
;         const int tk = key0 + 32 * k2 + crow(i, h);
;         const bool valid = (MODE == 0) ? ((tk <= tq) && (tq - tk <= maxdist)) : (tk <= tq);
;         v = valid ? v : NINF; s[k2][i] = v;
;       }
;       mx = fmaxf(mx, v);
;     }
;   mx = fmaxf(mx, __shfl_xor(mx, 32));
;   if (MODE != 1) mx *= L2E;
;   if (MODE == 2) mx = lanesel ? mx : NINF;
;   const float mn = fmaxf(m, mx); const float alpha = __builtin_amdgcn_exp2f(m - mn);
;   const float neg = (MODE == 2 && !lanesel) ? NINF : -mn;
;   float ps = 0.f;
; #pragma unroll
;   for (int k2 = 0; k2 < 2; ++k2)
; #pragma unroll
;     for (int i = 0; i < 16; ++i) {
;       if (!(HM & (1 << k2))) continue;
;       const float pv = (MODE == 1) ? __builtin_amdgcn_exp2f(s[k2][i] + neg) : __builtin_amdgcn_exp2f(fmaf(s[k2][i], L2E, neg));
;       s[k2][i] = pv; ps += pv;
;     }
;   l = l * alpha + ps;
;   if (__builtin_amdgcn_ballot_w64(mn != m) != 0ull) {
; #pragma unroll
;     for (int dt = 0; dt < 2; ++dt)
; #pragma unroll
;       for (int i = 0; i < 16; ++i) o[dt][i] *= alpha;
;   }
	v_cmp_lt_i32_e64 s[6:7], v35, v155
	s_or_b64 vcc, vcc, s[6:7]
	v_or_b32_e32 v35, 35, v0
	v_cndmask_b32_e32 v159, v36, v204, vcc
	v_cmp_gt_u32_e32 vcc, v35, v154
	v_cmp_lt_i32_e64 s[6:7], v35, v155
	s_or_b64 vcc, vcc, s[6:7]
	v_or_b32_e32 v35, 40, v0
	v_cndmask_b32_e32 v97, v37, v204, vcc
	v_cmp_gt_u32_e32 vcc, v35, v154
	v_cmp_lt_i32_e64 s[6:7], v35, v155
	s_or_b64 vcc, vcc, s[6:7]
	v_or_b32_e32 v35, 41, v0
	v_cndmask_b32_e32 v92, v38, v204, vcc
	v_cmp_gt_u32_e32 vcc, v35, v154
	v_cmp_lt_i32_e64 s[6:7], v35, v155
	s_or_b64 vcc, vcc, s[6:7]
	v_or_b32_e32 v35, 42, v0
	v_cndmask_b32_e32 v91, v39, v204, vcc
	v_cmp_gt_u32_e32 vcc, v35, v154
	v_cmp_lt_i32_e64 s[6:7], v35, v155
	s_or_b64 vcc, vcc, s[6:7]
	v_or_b32_e32 v35, 43, v0
	v_cndmask_b32_e32 v93, v40, v204, vcc
	v_cmp_gt_u32_e32 vcc, v35, v154
	v_cmp_lt_i32_e64 s[6:7], v35, v155
	s_or_b64 vcc, vcc, s[6:7]
	v_or_b32_e32 v35, 48, v0
	v_cndmask_b32_e32 v94, v41, v204, vcc
	v_cmp_gt_u32_e32 vcc, v35, v154
	v_cmp_lt_i32_e64 s[6:7], v35, v155
	s_or_b64 vcc, vcc, s[6:7]
	v_or_b32_e32 v35, 49, v0
	v_max3_f32 v50, v86, s35, v87
	v_cndmask_b32_e32 v95, v42, v204, vcc
	v_cmp_gt_u32_e32 vcc, v35, v154
	v_cmp_lt_i32_e64 s[6:7], v35, v155
	v_max3_f32 v50, v50, v88, v89
	s_or_b64 vcc, vcc, s[6:7]
	v_or_b32_e32 v35, 50, v0
	v_max3_f32 v50, v50, v90, v192
	v_cndmask_b32_e32 v96, v43, v204, vcc
	v_cmp_gt_u32_e32 vcc, v35, v154
	v_cmp_lt_i32_e64 s[6:7], v35, v155
	v_max3_f32 v50, v50, v191, v193
	s_or_b64 vcc, vcc, s[6:7]
	v_or_b32_e32 v35, 51, v0
	v_max3_f32 v50, v50, v188, v190
	v_cndmask_b32_e32 v161, v44, v204, vcc
	v_cmp_gt_u32_e32 vcc, v35, v154
	v_cmp_lt_i32_e64 s[6:7], v35, v155
	v_max3_f32 v50, v50, v189, v187
	s_or_b64 vcc, vcc, s[6:7]
	v_or_b32_e32 v35, 56, v0
	v_max3_f32 v50, v50, v186, v185
	v_cndmask_b32_e32 v163, v45, v204, vcc
	v_cmp_gt_u32_e32 vcc, v35, v154
	v_cmp_lt_i32_e64 s[6:7], v35, v155
	v_max3_f32 v50, v50, v184, v182
	s_or_b64 vcc, vcc, s[6:7]
	v_or_b32_e32 v35, 57, v0
	v_max3_f32 v34, v50, v164, v162
	v_cndmask_b32_e32 v165, v46, v204, vcc
	v_cmp_gt_u32_e32 vcc, v35, v154
	v_cmp_lt_i32_e64 s[6:7], v35, v155
	v_max3_f32 v34, v34, v159, v97
	s_or_b64 vcc, vcc, s[6:7]
	v_or_b32_e32 v35, 58, v0
	v_max3_f32 v34, v34, v92, v91
	v_cndmask_b32_e32 v180, v47, v204, vcc
	v_cmp_gt_u32_e32 vcc, v35, v154
	v_cmp_lt_i32_e64 s[6:7], v35, v155
	v_max3_f32 v34, v34, v93, v94
	s_or_b64 vcc, vcc, s[6:7]
	v_or_b32_e32 v0, 59, v0
	v_max3_f32 v34, v34, v95, v96
	v_cndmask_b32_e32 v181, v48, v204, vcc
	v_cmp_gt_u32_e32 vcc, v0, v154
	v_cmp_lt_i32_e64 s[6:7], v0, v155
	v_max3_f32 v34, v34, v161, v163
	s_or_b64 vcc, vcc, s[6:7]
	v_max3_f32 v34, v34, v165, v180
	v_cndmask_b32_e32 v183, v49, v204, vcc
	v_and_b32_e32 v35, 64, v202
	v_max3_f32 v0, v34, v181, v183
	v_xor_b32_e32 v34, 32, v202
	v_add_u32_e32 v35, 64, v35
	v_cmp_lt_i32_e32 vcc, v34, v35
	s_nop 1
	v_cndmask_b32_e32 v34, v202, v34, vcc
	v_lshlrev_b32_e32 v34, 2, v34
	ds_bpermute_b32 v34, v34, v0
	s_waitcnt lgkmcnt(0)
	v_max_f32_e32 v34, v34, v34
	v_max_f32_e32 v0, v0, v34
	v_mul_f32_e32 v0, 0x3fb8aa3b, v0
	v_max_f32_e32 v34, v158, v158
	v_sub_f32_e32 v232, v0, v34
	v_cmp_lt_f32_e32 vcc, 0x41000000, v232
	s_nop 1
	v_cndmask_b32_e32 v157, v34, v0, vcc
	v_sub_f32_e32 v0, v158, v157
	v_exp_f32_e32 v0, v0
	v_cmp_neq_f32_e32 vcc, v157, v158
	s_cbranch_vccz .LBB0_701
	v_pk_mul_f32 v[32:33], v[32:33], v[0:1] op_sel_hi:[1,0]
	v_pk_mul_f32 v[30:31], v[30:31], v[0:1] op_sel_hi:[1,0]
	v_pk_mul_f32 v[28:29], v[28:29], v[0:1] op_sel_hi:[1,0]
	v_pk_mul_f32 v[26:27], v[26:27], v[0:1] op_sel_hi:[1,0]
	v_pk_mul_f32 v[24:25], v[24:25], v[0:1] op_sel_hi:[1,0]
	v_pk_mul_f32 v[22:23], v[22:23], v[0:1] op_sel_hi:[1,0]
	v_pk_mul_f32 v[20:21], v[20:21], v[0:1] op_sel_hi:[1,0]
	v_pk_mul_f32 v[18:19], v[18:19], v[0:1] op_sel_hi:[1,0]
	v_pk_mul_f32 v[16:17], v[16:17], v[0:1] op_sel_hi:[1,0]
	v_pk_mul_f32 v[14:15], v[14:15], v[0:1] op_sel_hi:[1,0]
	v_pk_mul_f32 v[12:13], v[12:13], v[0:1] op_sel_hi:[1,0]
	v_pk_mul_f32 v[10:11], v[10:11], v[0:1] op_sel_hi:[1,0]
	v_pk_mul_f32 v[8:9], v[8:9], v[0:1] op_sel_hi:[1,0]
	v_pk_mul_f32 v[6:7], v[6:7], v[0:1] op_sel_hi:[1,0]
	v_pk_mul_f32 v[4:5], v[4:5], v[0:1] op_sel_hi:[1,0]
	v_pk_mul_f32 v[2:3], v[2:3], v[0:1] op_sel_hi:[1,0]

;     ...
;   f32x16 s[2];
; #pragma unroll
;   for (int k2 = 0; k2 < 2; ++k2) {
;     if (!(HM & (1 << k2))) continue;
; #pragma unroll
;     for (int i = 0; i < 16; ++i) s[k2][i] = 0.f;
; #pragma unroll
;     for (int ks = 0; ks < 4; ++ks) {
;       const bf16x8 a = *(const bf16x8*)(Ks + (32 * k2 + r) * LSTR + 16 * ks + 8 * h);
;       s[k2] = mfma32(a, qf[ks], s[k2]);
;     }
;   }
;   if (MODE == 1) {
; #pragma unroll
;     for (int k2 = 0; k2 < 2; ++k2)
; #pragma unroll
;       for (int g = 0; g < 4; ++g) {
;         if (!(HM & (1 << k2))) continue;
;         const f32x4 cv = *(const f32x4*)(cn_lds + key0 + 32 * k2 + 8 * g + 4 * h);
; #pragma unroll
;         for (int e = 0; e < 4; ++e) s[k2][4 * g + e] = fmaf(s[k2][4 * g + e], L2E, cv[e]);
;       }
;   }
;   float mx = NINF;
; #pragma unroll
;   for (int k2 = 0; k2 < 2; ++k2)
; #pragma unroll
;     for (int i = 0; i < 16; ++i) {
;       if (!(HM & (1 << k2))) continue;
;       float v = s[k2][i];
;       if (MASKED) {
;         const int tk = key0 + 32 * k2 + crow(i, h);
;         const bool valid = (MODE == 0) ? ((tk <= tq) && (tq - tk <= maxdist)) : (tk <= tq);
;         v = valid ? v : NINF; s[k2][i] = v;
;       }
;       mx = fmaxf(mx, v);
;     }
;   mx = fmaxf(mx, __shfl_xor(mx, 32));
;   if (MODE != 1) mx *= L2E;
;   if (MODE == 2) mx = lanesel ? mx : NINF;
;   const float mn = fmaxf(m, mx); const float alpha = __builtin_amdgcn_exp2f(m - mn);
;   const float neg = (MODE == 2 && !lanesel) ? NINF : -mn;
;   float ps = 0.f;
; #pragma unroll
;   for (int k2 = 0; k2 < 2; ++k2)
; #pragma unroll
;     for (int i = 0; i < 16; ++i) {
;       if (!(HM & (1 << k2))) continue;
;       const float pv = (MODE == 1) ? __builtin_amdgcn_exp2f(s[k2][i] + neg) : __builtin_amdgcn_exp2f(fmaf(s[k2][i], L2E, neg));
;       s[k2][i] = pv; ps += pv;
;     }
;   l = l * alpha + ps;
; template <int MODE>
; DI void flash_loop(char* smem, const bf16_t* Kbase, size_t ldk, const bf16_t* Vtbase, size_t ldv, ull tiles, ull wtiles,
;                    const bf16x8 (&qf)[4], f32x16 (&o)[2], float& m, float& l, int tq, int tqmin, int tqmax, int maxdist, const float* cn_lds, ull lmask) {
;     ...
;     if (!((wtiles >> kt) & 1ull)) return;
;     const bf16_t* Ks = (const bf16_t*)(smem + stage * (2 * 64 * LSTR * 2)); const bf16_t* Vs = Ks + 64 * LSTR;
;     const bool sel = ((lmask >> kt) & 1ull) != 0;
.LBB0_784:
	s_lshr_b64 s[30:31], s[2:3], s9
	s_and_b32 s58, s30, 1
	s_cmp_eq_u64 s[58:59], 0
	s_cbranch_scc1 .LBB0_794
	ds_read_b128 v[130:133], v196
	ds_read_b128 v[126:129], v196 offset:32
	ds_read_b128 v[122:125], v196 offset:64
	ds_read_b128 v[114:117], v196 offset:96
	ds_read_b128 v[118:121], v196 offset:4608
	s_lshl_b32 s30, s9, 6
	s_or_b32 s8, s30, 63
	s_cmp_gt_i32 s8, s11
	s_mov_b64 s[8:9], -1
	v_lshl_add_u32 v195, s30, 2, v177
	s_cbranch_scc1 .LBB0_789
	s_waitcnt lgkmcnt(4)
	v_mfma_f32_32x32x16_bf16 v[50:65], v[130:133], v[66:69], 0
	ds_read_b128 v[134:137], v196 offset:4704
	ds_read_b128 v[160:163], v195 offset:36864
	ds_read_b128 v[138:141], v196 offset:4640
	ds_read_b128 v[142:145], v196 offset:4672
	ds_read_b128 v[156:159], v195 offset:36896
	ds_read_b128 v[152:155], v195 offset:36928
	ds_read_b128 v[146:149], v195 offset:36992
	s_waitcnt lgkmcnt(10)
	v_mfma_f32_32x32x16_bf16 v[50:65], v[126:129], v[70:73], v[50:65]
	s_waitcnt lgkmcnt(7)
	v_mfma_f32_32x32x16_bf16 v[34:49], v[118:121], v[66:69], 0
	v_mfma_f32_32x32x16_bf16 v[50:65], v[122:125], v[74:77], v[50:65]
	s_waitcnt lgkmcnt(4)
	v_mfma_f32_32x32x16_bf16 v[34:49], v[138:141], v[70:73], v[34:49]
	ds_read_b128 v[138:141], v195 offset:37056
	v_mfma_f32_32x32x16_bf16 v[50:65], v[114:117], v[78:81], v[50:65]
	s_waitcnt lgkmcnt(4)
	v_mfma_f32_32x32x16_bf16 v[34:49], v[142:145], v[74:77], v[34:49]
	s_nop 9
	v_fmamk_f32 v211, v50, 0x3fb8aa3b, v160
	v_fmamk_f32 v210, v51, 0x3fb8aa3b, v161
	v_fmamk_f32 v209, v52, 0x3fb8aa3b, v162
	v_fmac_f32_e32 v163, 0x3fb8aa3b, v53
	s_waitcnt lgkmcnt(3)
	v_fmamk_f32 v161, v56, 0x3fb8aa3b, v158
	s_waitcnt lgkmcnt(2)
	v_fmamk_f32 v160, v58, 0x3fb8aa3b, v152
	v_fmamk_f32 v158, v59, 0x3fb8aa3b, v153
	v_mfma_f32_32x32x16_bf16 v[34:49], v[134:137], v[78:81], v[34:49]
	ds_read_b128 v[150:153], v195 offset:36960
	ds_read_b128 v[142:145], v195 offset:37024
	v_max3_f32 v0, v211, s35, v210
	v_fmamk_f32 v194, v54, 0x3fb8aa3b, v156
	v_fmamk_f32 v162, v55, 0x3fb8aa3b, v157
	v_max3_f32 v0, v0, v209, v163
	v_fmac_f32_e32 v159, 0x3fb8aa3b, v57
	v_max3_f32 v0, v0, v194, v162
	v_max3_f32 v0, v0, v161, v159
	v_fmamk_f32 v157, v60, 0x3fb8aa3b, v154
	v_fmac_f32_e32 v155, 0x3fb8aa3b, v61
	v_max3_f32 v0, v0, v160, v158
	s_waitcnt lgkmcnt(1)
	v_fmamk_f32 v156, v62, 0x3fb8aa3b, v150
	v_fmamk_f32 v154, v63, 0x3fb8aa3b, v151
	v_max3_f32 v0, v0, v157, v155
	v_fmamk_f32 v152, v64, 0x3fb8aa3b, v152
	v_fmac_f32_e32 v153, 0x3fb8aa3b, v65
	v_max3_f32 v0, v0, v156, v154
	v_fmamk_f32 v151, v34, 0x3fb8aa3b, v146
	v_fmamk_f32 v150, v35, 0x3fb8aa3b, v147
	v_max3_f32 v0, v0, v152, v153
	v_fmamk_f32 v148, v36, 0x3fb8aa3b, v148
	v_fmac_f32_e32 v149, 0x3fb8aa3b, v37
	ds_read_b128 v[134:137], v195 offset:37088
	v_max3_f32 v0, v0, v151, v150
	s_waitcnt lgkmcnt(1)
	v_fmamk_f32 v147, v38, 0x3fb8aa3b, v142
	v_fmamk_f32 v146, v39, 0x3fb8aa3b, v143
	v_max3_f32 v0, v0, v148, v149
	v_fmamk_f32 v142, v40, 0x3fb8aa3b, v144
	v_fmac_f32_e32 v145, 0x3fb8aa3b, v41
	v_max3_f32 v0, v0, v147, v146
	v_fmamk_f32 v144, v42, 0x3fb8aa3b, v138
	v_fmamk_f32 v143, v43, 0x3fb8aa3b, v139
	v_max3_f32 v0, v0, v142, v145
	v_fmamk_f32 v139, v44, 0x3fb8aa3b, v140
	v_fmac_f32_e32 v141, 0x3fb8aa3b, v45
	v_max3_f32 v0, v0, v144, v143
	s_waitcnt lgkmcnt(0)
	v_fmamk_f32 v138, v46, 0x3fb8aa3b, v134
	v_fmamk_f32 v135, v47, 0x3fb8aa3b, v135
	v_max3_f32 v0, v0, v139, v141
	v_fmamk_f32 v134, v48, 0x3fb8aa3b, v136
	v_fmac_f32_e32 v137, 0x3fb8aa3b, v49
	v_max3_f32 v0, v0, v138, v135
	v_max3_f32 v0, v0, v134, v137
	ds_bpermute_b32 v34, v190, v0
	s_waitcnt lgkmcnt(0)
	v_max_f32_e32 v232, v0, v34
	v_sub_f32_e32 v233, v232, v191
	v_cmp_lt_f32_e32 vcc, 0x41000000, v233
	s_nop 1
	v_cndmask_b32_e32 v192, v191, v232, vcc
	v_sub_f32_e32 v0, v191, v192
	v_exp_f32_e32 v0, v0
	v_cmp_neq_f32_e32 vcc, v192, v191
	s_cbranch_vccz .LBB0_788
	v_pk_mul_f32 v[32:33], v[32:33], v[0:1] op_sel_hi:[1,0]
	v_pk_mul_f32 v[30:31], v[30:31], v[0:1] op_sel_hi:[1,0]
	v_pk_mul_f32 v[28:29], v[28:29], v[0:1] op_sel_hi:[1,0]
	v_pk_mul_f32 v[26:27], v[26:27], v[0:1] op_sel_hi:[1,0]
	v_pk_mul_f32 v[24:25], v[24:25], v[0:1] op_sel_hi:[1,0]
	v_pk_mul_f32 v[22:23], v[22:23], v[0:1] op_sel_hi:[1,0]
	v_pk_mul_f32 v[20:21], v[20:21], v[0:1] op_sel_hi:[1,0]
	v_pk_mul_f32 v[18:19], v[18:19], v[0:1] op_sel_hi:[1,0]
	v_pk_mul_f32 v[16:17], v[16:17], v[0:1] op_sel_hi:[1,0]
	v_pk_mul_f32 v[14:15], v[14:15], v[0:1] op_sel_hi:[1,0]
	v_pk_mul_f32 v[12:13], v[12:13], v[0:1] op_sel_hi:[1,0]
	v_pk_mul_f32 v[10:11], v[10:11], v[0:1] op_sel_hi:[1,0]
	v_pk_mul_f32 v[8:9], v[8:9], v[0:1] op_sel_hi:[1,0]
	v_pk_mul_f32 v[6:7], v[6:7], v[0:1] op_sel_hi:[1,0]
	v_pk_mul_f32 v[4:5], v[4:5], v[0:1] op_sel_hi:[1,0]
	v_pk_mul_f32 v[2:3], v[2:3], v[0:1] op_sel_hi:[1,0]

; DI f32x16 mfma32(bf16x8 a, bf16x8 b, f32x16 c) { return __builtin_amdgcn_mfma_f32_32x32x16_bf16(a, b, c, 0, 0, 0); }
; DI int crow(int i, int h) { return (i & 3) + 8 * (i >> 2) + 4 * h; }
;     ...
;   f32x16 s[2];
; #pragma unroll
;   for (int k2 = 0; k2 < 2; ++k2) {
;     if (!(HM & (1 << k2))) continue;
; #pragma unroll
;     for (int i = 0; i < 16; ++i) s[k2][i] = 0.f;
; #pragma unroll
;     for (int ks = 0; ks < 4; ++ks) {
;       const bf16x8 a = *(const bf16x8*)(Ks + (32 * k2 + r) * LSTR + 16 * ks + 8 * h);
;       s[k2] = mfma32(a, qf[ks], s[k2]);
;     }
;   }
;   if (MODE == 1) {
; #pragma unroll
;     for (int k2 = 0; k2 < 2; ++k2)
; #pragma unroll
;       for (int g = 0; g < 4; ++g) {
;         if (!(HM & (1 << k2))) continue;
;         const f32x4 cv = *(const f32x4*)(cn_lds + key0 + 32 * k2 + 8 * g + 4 * h);
; #pragma unroll
;         for (int e = 0; e < 4; ++e) s[k2][4 * g + e] = fmaf(s[k2][4 * g + e], L2E, cv[e]);
;       }
;   }
;   float mx = NINF;
; #pragma unroll
;   for (int k2 = 0; k2 < 2; ++k2)
; #pragma unroll
;     for (int i = 0; i < 16; ++i) {
;       if (!(HM & (1 << k2))) continue;
;       float v = s[k2][i];
;       if (MASKED) {
;         const int tk = key0 + 32 * k2 + crow(i, h);
;         const bool valid = (MODE == 0) ? ((tk <= tq) && (tq - tk <= maxdist)) : (tk <= tq);
;         v = valid ? v : NINF; s[k2][i] = v;
;       }
;       mx = fmaxf(mx, v);
;     }
;   mx = fmaxf(mx, __shfl_xor(mx, 32));
;   if (MODE != 1) mx *= L2E;
;   if (MODE == 2) mx = lanesel ? mx : NINF;
;   const float mn = fmaxf(m, mx); const float alpha = __builtin_amdgcn_exp2f(m - mn);
;   const float neg = (MODE == 2 && !lanesel) ? NINF : -mn;
;   float ps = 0.f;
; #pragma unroll
;   for (int k2 = 0; k2 < 2; ++k2)
; #pragma unroll
;     for (int i = 0; i < 16; ++i) {
;       if (!(HM & (1 << k2))) continue;
;       const float pv = (MODE == 1) ? __builtin_amdgcn_exp2f(s[k2][i] + neg) : __builtin_amdgcn_exp2f(fmaf(s[k2][i], L2E, neg));
;       s[k2][i] = pv; ps += pv;
;     }
;   l = l * alpha + ps;
;   if (__builtin_amdgcn_ballot_w64(mn != m) != 0ull) {
; #pragma unroll
;     for (int dt = 0; dt < 2; ++dt)
; #pragma unroll
;       for (int i = 0; i < 16; ++i) o[dt][i] *= alpha;
;   }
.LBB0_789:
	s_and_b64 vcc, exec, s[8:9]
	s_cbranch_vccz .LBB0_793
	s_waitcnt lgkmcnt(4)
	v_mfma_f32_32x32x16_bf16 v[50:65], v[130:133], v[66:69], 0
	s_waitcnt lgkmcnt(3)
	v_mfma_f32_32x32x16_bf16 v[50:65], v[126:129], v[70:73], v[50:65]
	s_waitcnt lgkmcnt(2)
	v_mfma_f32_32x32x16_bf16 v[50:65], v[122:125], v[74:77], v[50:65]
	s_waitcnt lgkmcnt(0)
	v_mfma_f32_32x32x16_bf16 v[34:49], v[118:121], v[66:69], 0
	v_mfma_f32_32x32x16_bf16 v[50:65], v[114:117], v[78:81], v[50:65]
	ds_read_b128 v[114:117], v196 offset:4640
	ds_read_b128 v[118:121], v196 offset:4672
	s_waitcnt lgkmcnt(1)
	v_mfma_f32_32x32x16_bf16 v[34:49], v[114:117], v[70:73], v[34:49]
	ds_read_b128 v[114:117], v196 offset:4704
	s_waitcnt lgkmcnt(1)
	v_mfma_f32_32x32x16_bf16 v[34:49], v[118:121], v[74:77], v[34:49]
	s_waitcnt lgkmcnt(0)
	v_mfma_f32_32x32x16_bf16 v[34:49], v[114:117], v[78:81], v[34:49]
	ds_read_b128 v[114:117], v195 offset:36864
	ds_read_b128 v[118:121], v195 offset:36896
	ds_read_b128 v[122:125], v195 offset:36960
	ds_read_b128 v[126:129], v195 offset:36992
	ds_read_b128 v[130:133], v195 offset:37056
	s_waitcnt lgkmcnt(4)
	v_fmamk_f32 v0, v50, 0x3fb8aa3b, v114
	v_fmamk_f32 v114, v51, 0x3fb8aa3b, v115
	v_fmamk_f32 v115, v52, 0x3fb8aa3b, v116
	v_fmac_f32_e32 v117, 0x3fb8aa3b, v53
	ds_read_b128 v[50:53], v195 offset:36928
	s_waitcnt lgkmcnt(4)
	v_fmamk_f32 v54, v54, 0x3fb8aa3b, v118
	v_fmamk_f32 v56, v56, 0x3fb8aa3b, v120
	s_waitcnt lgkmcnt(3)
	v_fmamk_f32 v116, v62, 0x3fb8aa3b, v122
	v_fmamk_f32 v118, v63, 0x3fb8aa3b, v123
	s_waitcnt lgkmcnt(2)
	v_fmamk_f32 v120, v34, 0x3fb8aa3b, v126
	v_fmamk_f32 v122, v35, 0x3fb8aa3b, v127
	v_fmamk_f32 v123, v36, 0x3fb8aa3b, v128
	v_fmac_f32_e32 v129, 0x3fb8aa3b, v37
	ds_read_b128 v[34:37], v195 offset:37024
	v_fmamk_f32 v55, v55, 0x3fb8aa3b, v119
	v_fmamk_f32 v119, v64, 0x3fb8aa3b, v124
	v_or_b32_e32 v124, s30, v197
	v_cmp_le_i32_e32 vcc, v124, v180
	v_fmac_f32_e32 v125, 0x3fb8aa3b, v65
	s_waitcnt lgkmcnt(0)
	v_fmac_f32_e32 v37, 0x3fb8aa3b, v41
	v_cndmask_b32_e32 v65, v204, v0, vcc
	v_cmp_lt_i32_e32 vcc, v124, v180
	v_or_b32_e32 v41, 2, v124
	v_fmac_f32_e32 v53, 0x3fb8aa3b, v61
	v_cndmask_b32_e32 v64, v204, v114, vcc
	v_cmp_le_i32_e32 vcc, v41, v180
	v_or_b32_e32 v41, 3, v124
	v_fmamk_f32 v52, v60, 0x3fb8aa3b, v52
	v_cndmask_b32_e32 v63, v204, v115, vcc
	v_cmp_le_i32_e32 vcc, v41, v180
	v_or_b32_e32 v41, 8, v124
	v_fmac_f32_e32 v121, 0x3fb8aa3b, v57
	v_cndmask_b32_e32 v62, v204, v117, vcc
	v_cmp_le_i32_e32 vcc, v41, v180
	v_or_b32_e32 v41, 9, v124
	v_fmamk_f32 v51, v59, 0x3fb8aa3b, v51
	v_cndmask_b32_e32 v61, v204, v54, vcc
	v_cmp_le_i32_e32 vcc, v41, v180
	v_or_b32_e32 v41, 10, v124
	v_fmamk_f32 v50, v58, 0x3fb8aa3b, v50
	v_cndmask_b32_e32 v60, v204, v55, vcc
	v_cmp_le_i32_e32 vcc, v41, v180
	v_or_b32_e32 v41, 11, v124
	v_fmamk_f32 v34, v38, 0x3fb8aa3b, v34
	v_cndmask_b32_e32 v59, v204, v56, vcc
	v_cmp_le_i32_e32 vcc, v41, v180
	v_or_b32_e32 v41, 16, v124
	v_fmamk_f32 v35, v39, 0x3fb8aa3b, v35
	v_cndmask_b32_e32 v58, v204, v121, vcc
	v_cmp_le_i32_e32 vcc, v41, v180
	v_or_b32_e32 v41, 17, v124
	v_fmamk_f32 v36, v40, 0x3fb8aa3b, v36
	v_cndmask_b32_e32 v57, v204, v50, vcc
	v_cmp_le_i32_e32 vcc, v41, v180
	v_or_b32_e32 v41, 18, v124
	v_fmamk_f32 v38, v42, 0x3fb8aa3b, v130
	v_cndmask_b32_e32 v56, v204, v51, vcc
	v_cmp_le_i32_e32 vcc, v41, v180
	v_or_b32_e32 v41, 19, v124
	v_fmamk_f32 v39, v43, 0x3fb8aa3b, v131
	v_cndmask_b32_e32 v55, v204, v52, vcc
	v_cmp_le_i32_e32 vcc, v41, v180
	v_or_b32_e32 v41, 24, v124
	v_fmamk_f32 v40, v44, 0x3fb8aa3b, v132
	v_fmac_f32_e32 v133, 0x3fb8aa3b, v45
	ds_read_b128 v[42:45], v195 offset:37088
	v_cndmask_b32_e32 v54, v204, v53, vcc
	v_cmp_le_i32_e32 vcc, v41, v180
	v_or_b32_e32 v41, 25, v124
	v_max3_f32 v0, v65, s35, v64
	v_cndmask_b32_e32 v53, v204, v116, vcc
	v_cmp_le_i32_e32 vcc, v41, v180
	v_or_b32_e32 v41, 26, v124
	s_waitcnt lgkmcnt(0)
	v_fmac_f32_e32 v45, 0x3fb8aa3b, v49
	v_cndmask_b32_e32 v52, v204, v118, vcc
	v_cmp_le_i32_e32 vcc, v41, v180
	v_or_b32_e32 v41, 27, v124
	v_fmamk_f32 v44, v48, 0x3fb8aa3b, v44
	v_cndmask_b32_e32 v51, v204, v119, vcc
	v_cmp_le_i32_e32 vcc, v41, v180
	v_or_b32_e32 v41, 32, v124
	v_fmamk_f32 v43, v47, 0x3fb8aa3b, v43
	v_cndmask_b32_e32 v50, v204, v125, vcc
	v_cmp_le_i32_e32 vcc, v41, v180
	v_or_b32_e32 v41, 33, v124
	v_fmamk_f32 v42, v46, 0x3fb8aa3b, v42
	v_cndmask_b32_e32 v49, v204, v120, vcc
	v_cmp_le_i32_e32 vcc, v41, v180
	v_or_b32_e32 v41, 34, v124
	v_max3_f32 v0, v0, v63, v62
	v_cndmask_b32_e32 v48, v204, v122, vcc
	v_cmp_le_i32_e32 vcc, v41, v180
	v_or_b32_e32 v41, 35, v124
	v_max3_f32 v0, v0, v61, v60
	v_cndmask_b32_e32 v47, v204, v123, vcc
	v_cmp_le_i32_e32 vcc, v41, v180
	v_or_b32_e32 v41, 40, v124
	v_max3_f32 v0, v0, v59, v58
	v_cndmask_b32_e32 v46, v204, v129, vcc
	v_cmp_le_i32_e32 vcc, v41, v180
	v_max3_f32 v0, v0, v57, v56
	v_max3_f32 v0, v0, v55, v54
	v_cndmask_b32_e32 v41, v204, v34, vcc
	v_or_b32_e32 v34, 41, v124
	v_cmp_le_i32_e32 vcc, v34, v180
	v_max3_f32 v0, v0, v53, v52
	v_max3_f32 v0, v0, v51, v50
	v_cndmask_b32_e32 v34, v204, v35, vcc
	v_or_b32_e32 v35, 42, v124
	v_cmp_le_i32_e32 vcc, v35, v180
	v_max3_f32 v0, v0, v49, v48
	v_max3_f32 v0, v0, v47, v46
	v_cndmask_b32_e32 v35, v204, v36, vcc
	v_or_b32_e32 v36, 43, v124
	v_cmp_le_i32_e32 vcc, v36, v180
	v_or_b32_e32 v114, 56, v124
	v_max3_f32 v0, v0, v41, v34
	v_cndmask_b32_e32 v36, v204, v37, vcc
	v_or_b32_e32 v37, 48, v124
	v_cmp_le_i32_e32 vcc, v37, v180
	v_max3_f32 v0, v0, v35, v36
	s_nop 0
	v_cndmask_b32_e32 v37, v204, v38, vcc
	v_or_b32_e32 v38, 49, v124
	v_cmp_le_i32_e32 vcc, v38, v180
	s_nop 1
	v_cndmask_b32_e32 v38, v204, v39, vcc
	v_or_b32_e32 v39, 50, v124
	v_cmp_le_i32_e32 vcc, v39, v180
	v_max3_f32 v0, v0, v37, v38
	s_nop 0
	v_cndmask_b32_e32 v39, v204, v40, vcc
	v_or_b32_e32 v40, 51, v124
	v_cmp_le_i32_e32 vcc, v40, v180
	s_nop 1
	v_cndmask_b32_e32 v40, v204, v133, vcc
	v_cmp_le_i32_e32 vcc, v114, v180
	v_or_b32_e32 v114, 57, v124
	v_max3_f32 v0, v0, v39, v40
	v_cndmask_b32_e32 v42, v204, v42, vcc
	v_cmp_le_i32_e32 vcc, v114, v180
	v_or_b32_e32 v114, 58, v124
	s_nop 0
	v_cndmask_b32_e32 v43, v204, v43, vcc
	v_cmp_le_i32_e32 vcc, v114, v180
	v_or_b32_e32 v114, 59, v124
	v_max3_f32 v0, v0, v42, v43
	v_cndmask_b32_e32 v44, v204, v44, vcc
	v_cmp_le_i32_e32 vcc, v114, v180
	s_nop 1
	v_cndmask_b32_e32 v45, v204, v45, vcc
	v_max3_f32 v0, v0, v44, v45
	ds_bpermute_b32 v114, v190, v0
	s_waitcnt lgkmcnt(0)
	v_max_f32_e32 v232, v0, v114
	v_sub_f32_e32 v233, v232, v191
	v_cmp_lt_f32_e32 vcc, 0x41000000, v233
	s_nop 1
	v_cndmask_b32_e32 v192, v191, v232, vcc
	v_sub_f32_e32 v0, v191, v192
	v_exp_f32_e32 v0, v0
	v_cmp_neq_f32_e32 vcc, v192, v191
	s_cbranch_vccz .LBB0_792
;     ...
;   if (__builtin_amdgcn_ballot_w64(mn != m) != 0ull) {
; #pragma unroll
;     for (int dt = 0; dt < 2; ++dt)
; #pragma unroll
;       for (int i = 0; i < 16; ++i) o[dt][i] *= alpha;
;   }
	v_pk_mul_f32 v[32:33], v[32:33], v[0:1] op_sel_hi:[1,0]
	v_pk_mul_f32 v[30:31], v[30:31], v[0:1] op_sel_hi:[1,0]
	v_pk_mul_f32 v[28:29], v[28:29], v[0:1] op_sel_hi:[1,0]
	v_pk_mul_f32 v[26:27], v[26:27], v[0:1] op_sel_hi:[1,0]
	v_pk_mul_f32 v[24:25], v[24:25], v[0:1] op_sel_hi:[1,0]
	v_pk_mul_f32 v[22:23], v[22:23], v[0:1] op_sel_hi:[1,0]
	v_pk_mul_f32 v[20:21], v[20:21], v[0:1] op_sel_hi:[1,0]
	v_pk_mul_f32 v[18:19], v[18:19], v[0:1] op_sel_hi:[1,0]
	v_pk_mul_f32 v[16:17], v[16:17], v[0:1] op_sel_hi:[1,0]
	v_pk_mul_f32 v[14:15], v[14:15], v[0:1] op_sel_hi:[1,0]
	v_pk_mul_f32 v[12:13], v[12:13], v[0:1] op_sel_hi:[1,0]
	v_pk_mul_f32 v[10:11], v[10:11], v[0:1] op_sel_hi:[1,0]
	v_pk_mul_f32 v[8:9], v[8:9], v[0:1] op_sel_hi:[1,0]
	v_pk_mul_f32 v[6:7], v[6:7], v[0:1] op_sel_hi:[1,0]
	v_pk_mul_f32 v[4:5], v[4:5], v[0:1] op_sel_hi:[1,0]
	v_pk_mul_f32 v[2:3], v[2:3], v[0:1] op_sel_hi:[1,0]

;     ...
;   f32x16 s[2];
; #pragma unroll
;   for (int k2 = 0; k2 < 2; ++k2) {
;     if (!(HM & (1 << k2))) continue;
; #pragma unroll
;     for (int i = 0; i < 16; ++i) s[k2][i] = 0.f;
; #pragma unroll
;     for (int ks = 0; ks < 4; ++ks) {
;       const bf16x8 a = *(const bf16x8*)(Ks + (32 * k2 + r) * LSTR + 16 * ks + 8 * h);
;       s[k2] = mfma32(a, qf[ks], s[k2]);
;     }
;   }
;   if (MODE == 1) {
; #pragma unroll
;     for (int k2 = 0; k2 < 2; ++k2)
; #pragma unroll
;       for (int g = 0; g < 4; ++g) {
;         if (!(HM & (1 << k2))) continue;
;         const f32x4 cv = *(const f32x4*)(cn_lds + key0 + 32 * k2 + 8 * g + 4 * h);
; #pragma unroll
;         for (int e = 0; e < 4; ++e) s[k2][4 * g + e] = fmaf(s[k2][4 * g + e], L2E, cv[e]);
;       }
;   }
;   float mx = NINF;
; #pragma unroll
;   for (int k2 = 0; k2 < 2; ++k2)
; #pragma unroll
;     for (int i = 0; i < 16; ++i) {
;       if (!(HM & (1 << k2))) continue;
;       float v = s[k2][i];
;       if (MASKED) {
;         const int tk = key0 + 32 * k2 + crow(i, h);
;         const bool valid = (MODE == 0) ? ((tk <= tq) && (tq - tk <= maxdist)) : (tk <= tq);
;         v = valid ? v : NINF; s[k2][i] = v;
;       }
;       mx = fmaxf(mx, v);
;     }
;   mx = fmaxf(mx, __shfl_xor(mx, 32));
;   if (MODE != 1) mx *= L2E;
;   if (MODE == 2) mx = lanesel ? mx : NINF;
;   const float mn = fmaxf(m, mx); const float alpha = __builtin_amdgcn_exp2f(m - mn);
;   const float neg = (MODE == 2 && !lanesel) ? NINF : -mn;
;   float ps = 0.f;
; #pragma unroll
;   for (int k2 = 0; k2 < 2; ++k2)
; #pragma unroll
;     for (int i = 0; i < 16; ++i) {
;       if (!(HM & (1 << k2))) continue;
;       const float pv = (MODE == 1) ? __builtin_amdgcn_exp2f(s[k2][i] + neg) : __builtin_amdgcn_exp2f(fmaf(s[k2][i], L2E, neg));
;       s[k2][i] = pv; ps += pv;
;     }
;   l = l * alpha + ps;
; template <int MODE>
; DI void flash_loop(char* smem, const bf16_t* Kbase, size_t ldk, const bf16_t* Vtbase, size_t ldv, ull tiles, ull wtiles,
;                    const bf16x8 (&qf)[4], f32x16 (&o)[2], float& m, float& l, int tq, int tqmin, int tqmax, int maxdist, const float* cn_lds, ull lmask) {
;     ...
;     if (!((wtiles >> kt) & 1ull)) return;
;     const bf16_t* Ks = (const bf16_t*)(smem + stage * (2 * 64 * LSTR * 2)); const bf16_t* Vs = Ks + 64 * LSTR;
;     const bool sel = ((lmask >> kt) & 1ull) != 0;
.LBB0_798:
	s_lshr_b64 s[8:9], s[2:3], s29
	s_and_b32 s58, s8, 1
	s_cmp_eq_u64 s[58:59], 0
	s_cbranch_scc1 .LBB0_808
	ds_read_b128 v[130:133], v196 offset:18432
	ds_read_b128 v[126:129], v196 offset:18464
	ds_read_b128 v[122:125], v196 offset:18496
	ds_read_b128 v[114:117], v196 offset:18528
	ds_read_b128 v[118:121], v196 offset:23040
	s_lshl_b32 s29, s29, 6
	s_or_b32 s8, s29, 63
	s_cmp_gt_i32 s8, s11
	s_mov_b64 s[8:9], -1
	v_lshl_add_u32 v195, s29, 2, v177
	s_cbranch_scc1 .LBB0_803
	s_waitcnt lgkmcnt(4)
	v_mfma_f32_32x32x16_bf16 v[50:65], v[130:133], v[66:69], 0
	ds_read_b128 v[134:137], v196 offset:23136
	ds_read_b128 v[160:163], v195 offset:36864
	ds_read_b128 v[138:141], v196 offset:23072
	ds_read_b128 v[142:145], v196 offset:23104
	ds_read_b128 v[156:159], v195 offset:36896
	ds_read_b128 v[152:155], v195 offset:36928
	ds_read_b128 v[146:149], v195 offset:36992
	s_waitcnt lgkmcnt(10)
	v_mfma_f32_32x32x16_bf16 v[50:65], v[126:129], v[70:73], v[50:65]
	s_waitcnt lgkmcnt(7)
	v_mfma_f32_32x32x16_bf16 v[34:49], v[118:121], v[66:69], 0
	v_mfma_f32_32x32x16_bf16 v[50:65], v[122:125], v[74:77], v[50:65]
	s_waitcnt lgkmcnt(4)
	v_mfma_f32_32x32x16_bf16 v[34:49], v[138:141], v[70:73], v[34:49]
	ds_read_b128 v[138:141], v195 offset:37056
	v_mfma_f32_32x32x16_bf16 v[50:65], v[114:117], v[78:81], v[50:65]
	s_waitcnt lgkmcnt(4)
	v_mfma_f32_32x32x16_bf16 v[34:49], v[142:145], v[74:77], v[34:49]
	s_nop 9
	v_fmamk_f32 v211, v50, 0x3fb8aa3b, v160
	v_fmamk_f32 v210, v51, 0x3fb8aa3b, v161
	v_fmamk_f32 v209, v52, 0x3fb8aa3b, v162
	v_fmac_f32_e32 v163, 0x3fb8aa3b, v53
	s_waitcnt lgkmcnt(3)
	v_fmamk_f32 v161, v56, 0x3fb8aa3b, v158
	s_waitcnt lgkmcnt(2)
	v_fmamk_f32 v160, v58, 0x3fb8aa3b, v152
	v_fmamk_f32 v158, v59, 0x3fb8aa3b, v153
	v_mfma_f32_32x32x16_bf16 v[34:49], v[134:137], v[78:81], v[34:49]
	ds_read_b128 v[150:153], v195 offset:36960
	ds_read_b128 v[142:145], v195 offset:37024
	v_max3_f32 v0, v211, s35, v210
	v_fmamk_f32 v193, v54, 0x3fb8aa3b, v156
	v_fmamk_f32 v162, v55, 0x3fb8aa3b, v157
	v_max3_f32 v0, v0, v209, v163
	v_fmac_f32_e32 v159, 0x3fb8aa3b, v57
	v_max3_f32 v0, v0, v193, v162
	v_max3_f32 v0, v0, v161, v159
	v_fmamk_f32 v157, v60, 0x3fb8aa3b, v154
	v_fmac_f32_e32 v155, 0x3fb8aa3b, v61
	v_max3_f32 v0, v0, v160, v158
	s_waitcnt lgkmcnt(1)
	v_fmamk_f32 v156, v62, 0x3fb8aa3b, v150
	v_fmamk_f32 v154, v63, 0x3fb8aa3b, v151
	v_max3_f32 v0, v0, v157, v155
	v_fmamk_f32 v152, v64, 0x3fb8aa3b, v152
	v_fmac_f32_e32 v153, 0x3fb8aa3b, v65
	v_max3_f32 v0, v0, v156, v154
	v_fmamk_f32 v151, v34, 0x3fb8aa3b, v146
	v_fmamk_f32 v150, v35, 0x3fb8aa3b, v147
	v_max3_f32 v0, v0, v152, v153
	v_fmamk_f32 v148, v36, 0x3fb8aa3b, v148
	v_fmac_f32_e32 v149, 0x3fb8aa3b, v37
	ds_read_b128 v[134:137], v195 offset:37088
	v_max3_f32 v0, v0, v151, v150
	s_waitcnt lgkmcnt(1)
	v_fmamk_f32 v147, v38, 0x3fb8aa3b, v142
	v_fmamk_f32 v146, v39, 0x3fb8aa3b, v143
	v_max3_f32 v0, v0, v148, v149
	v_fmamk_f32 v142, v40, 0x3fb8aa3b, v144
	v_fmac_f32_e32 v145, 0x3fb8aa3b, v41
	v_max3_f32 v0, v0, v147, v146
	v_fmamk_f32 v144, v42, 0x3fb8aa3b, v138
	v_fmamk_f32 v143, v43, 0x3fb8aa3b, v139
	v_max3_f32 v0, v0, v142, v145
	v_fmamk_f32 v139, v44, 0x3fb8aa3b, v140
	v_fmac_f32_e32 v141, 0x3fb8aa3b, v45
	v_max3_f32 v0, v0, v144, v143
	s_waitcnt lgkmcnt(0)
	v_fmamk_f32 v138, v46, 0x3fb8aa3b, v134
	v_fmamk_f32 v135, v47, 0x3fb8aa3b, v135
	v_max3_f32 v0, v0, v139, v141
	v_fmamk_f32 v134, v48, 0x3fb8aa3b, v136
	v_fmac_f32_e32 v137, 0x3fb8aa3b, v49
	v_max3_f32 v0, v0, v138, v135
	v_max3_f32 v0, v0, v134, v137
	ds_bpermute_b32 v34, v190, v0
	s_waitcnt lgkmcnt(0)
	v_max_f32_e32 v232, v0, v34
	v_sub_f32_e32 v233, v232, v192
	v_cmp_lt_f32_e32 vcc, 0x41000000, v233
	s_nop 1
	v_cndmask_b32_e32 v191, v192, v232, vcc
	v_sub_f32_e32 v0, v192, v191
	v_exp_f32_e32 v0, v0
	v_cmp_neq_f32_e32 vcc, v191, v192
	s_cbranch_vccz .LBB0_802
	v_pk_mul_f32 v[32:33], v[32:33], v[0:1] op_sel_hi:[1,0]
	v_pk_mul_f32 v[30:31], v[30:31], v[0:1] op_sel_hi:[1,0]
	v_pk_mul_f32 v[28:29], v[28:29], v[0:1] op_sel_hi:[1,0]
	v_pk_mul_f32 v[26:27], v[26:27], v[0:1] op_sel_hi:[1,0]
	v_pk_mul_f32 v[24:25], v[24:25], v[0:1] op_sel_hi:[1,0]
	v_pk_mul_f32 v[22:23], v[22:23], v[0:1] op_sel_hi:[1,0]
	v_pk_mul_f32 v[20:21], v[20:21], v[0:1] op_sel_hi:[1,0]
	v_pk_mul_f32 v[18:19], v[18:19], v[0:1] op_sel_hi:[1,0]
	v_pk_mul_f32 v[16:17], v[16:17], v[0:1] op_sel_hi:[1,0]
	v_pk_mul_f32 v[14:15], v[14:15], v[0:1] op_sel_hi:[1,0]
	v_pk_mul_f32 v[12:13], v[12:13], v[0:1] op_sel_hi:[1,0]
	v_pk_mul_f32 v[10:11], v[10:11], v[0:1] op_sel_hi:[1,0]
	v_pk_mul_f32 v[8:9], v[8:9], v[0:1] op_sel_hi:[1,0]
	v_pk_mul_f32 v[6:7], v[6:7], v[0:1] op_sel_hi:[1,0]
	v_pk_mul_f32 v[4:5], v[4:5], v[0:1] op_sel_hi:[1,0]
	v_pk_mul_f32 v[2:3], v[2:3], v[0:1] op_sel_hi:[1,0]

; DI f32x16 mfma32(bf16x8 a, bf16x8 b, f32x16 c) { return __builtin_amdgcn_mfma_f32_32x32x16_bf16(a, b, c, 0, 0, 0); }
; DI int crow(int i, int h) { return (i & 3) + 8 * (i >> 2) + 4 * h; }
;     ...
;   f32x16 s[2];
; #pragma unroll
;   for (int k2 = 0; k2 < 2; ++k2) {
;     if (!(HM & (1 << k2))) continue;
; #pragma unroll
;     for (int i = 0; i < 16; ++i) s[k2][i] = 0.f;
; #pragma unroll
;     for (int ks = 0; ks < 4; ++ks) {
;       const bf16x8 a = *(const bf16x8*)(Ks + (32 * k2 + r) * LSTR + 16 * ks + 8 * h);
;       s[k2] = mfma32(a, qf[ks], s[k2]);
;     }
;   }
;   if (MODE == 1) {
; #pragma unroll
;     for (int k2 = 0; k2 < 2; ++k2)
; #pragma unroll
;       for (int g = 0; g < 4; ++g) {
;         if (!(HM & (1 << k2))) continue;
;         const f32x4 cv = *(const f32x4*)(cn_lds + key0 + 32 * k2 + 8 * g + 4 * h);
; #pragma unroll
;         for (int e = 0; e < 4; ++e) s[k2][4 * g + e] = fmaf(s[k2][4 * g + e], L2E, cv[e]);
;       }
;   }
;   float mx = NINF;
; #pragma unroll
;   for (int k2 = 0; k2 < 2; ++k2)
; #pragma unroll
;     for (int i = 0; i < 16; ++i) {
;       if (!(HM & (1 << k2))) continue;
;       float v = s[k2][i];
;       if (MASKED) {
;         const int tk = key0 + 32 * k2 + crow(i, h);
;         const bool valid = (MODE == 0) ? ((tk <= tq) && (tq - tk <= maxdist)) : (tk <= tq);
;         v = valid ? v : NINF; s[k2][i] = v;
;       }
;       mx = fmaxf(mx, v);
;     }
;   mx = fmaxf(mx, __shfl_xor(mx, 32));
;   if (MODE != 1) mx *= L2E;
;   if (MODE == 2) mx = lanesel ? mx : NINF;
;   const float mn = fmaxf(m, mx); const float alpha = __builtin_amdgcn_exp2f(m - mn);
;   const float neg = (MODE == 2 && !lanesel) ? NINF : -mn;
;   float ps = 0.f;
; #pragma unroll
;   for (int k2 = 0; k2 < 2; ++k2)
; #pragma unroll
;     for (int i = 0; i < 16; ++i) {
;       if (!(HM & (1 << k2))) continue;
;       const float pv = (MODE == 1) ? __builtin_amdgcn_exp2f(s[k2][i] + neg) : __builtin_amdgcn_exp2f(fmaf(s[k2][i], L2E, neg));
;       s[k2][i] = pv; ps += pv;
;     }
;   l = l * alpha + ps;
;   if (__builtin_amdgcn_ballot_w64(mn != m) != 0ull) {
; #pragma unroll
;     for (int dt = 0; dt < 2; ++dt)
; #pragma unroll
;       for (int i = 0; i < 16; ++i) o[dt][i] *= alpha;
;   }
.LBB0_803:
	s_and_b64 vcc, exec, s[8:9]
	s_cbranch_vccz .LBB0_807
	s_waitcnt lgkmcnt(4)
	v_mfma_f32_32x32x16_bf16 v[50:65], v[130:133], v[66:69], 0
	s_waitcnt lgkmcnt(3)
	v_mfma_f32_32x32x16_bf16 v[50:65], v[126:129], v[70:73], v[50:65]
	s_waitcnt lgkmcnt(2)
	v_mfma_f32_32x32x16_bf16 v[50:65], v[122:125], v[74:77], v[50:65]
	s_waitcnt lgkmcnt(0)
	v_mfma_f32_32x32x16_bf16 v[34:49], v[118:121], v[66:69], 0
	v_mfma_f32_32x32x16_bf16 v[50:65], v[114:117], v[78:81], v[50:65]
	ds_read_b128 v[114:117], v196 offset:23072
	ds_read_b128 v[118:121], v196 offset:23104
	s_waitcnt lgkmcnt(1)
	v_mfma_f32_32x32x16_bf16 v[34:49], v[114:117], v[70:73], v[34:49]
	ds_read_b128 v[114:117], v196 offset:23136
	s_waitcnt lgkmcnt(1)
	v_mfma_f32_32x32x16_bf16 v[34:49], v[118:121], v[74:77], v[34:49]
	s_waitcnt lgkmcnt(0)
	v_mfma_f32_32x32x16_bf16 v[34:49], v[114:117], v[78:81], v[34:49]
	ds_read_b128 v[114:117], v195 offset:36864
	ds_read_b128 v[118:121], v195 offset:36896
	ds_read_b128 v[122:125], v195 offset:36960
	ds_read_b128 v[126:129], v195 offset:36992
	ds_read_b128 v[130:133], v195 offset:37056
	s_waitcnt lgkmcnt(4)
	v_fmamk_f32 v0, v50, 0x3fb8aa3b, v114
	v_fmamk_f32 v114, v51, 0x3fb8aa3b, v115
	v_fmamk_f32 v115, v52, 0x3fb8aa3b, v116
	v_fmac_f32_e32 v117, 0x3fb8aa3b, v53
	ds_read_b128 v[50:53], v195 offset:36928
	s_waitcnt lgkmcnt(4)
	v_fmamk_f32 v54, v54, 0x3fb8aa3b, v118
	v_fmamk_f32 v56, v56, 0x3fb8aa3b, v120
	s_waitcnt lgkmcnt(3)
	v_fmamk_f32 v116, v62, 0x3fb8aa3b, v122
	v_fmamk_f32 v118, v63, 0x3fb8aa3b, v123
	s_waitcnt lgkmcnt(2)
	v_fmamk_f32 v120, v34, 0x3fb8aa3b, v126
	v_fmamk_f32 v122, v35, 0x3fb8aa3b, v127
	v_fmamk_f32 v123, v36, 0x3fb8aa3b, v128
	v_fmac_f32_e32 v129, 0x3fb8aa3b, v37
	ds_read_b128 v[34:37], v195 offset:37024
	v_fmamk_f32 v55, v55, 0x3fb8aa3b, v119
	v_fmamk_f32 v119, v64, 0x3fb8aa3b, v124
	v_or_b32_e32 v124, s29, v197
	v_cmp_le_i32_e32 vcc, v124, v180
	v_fmac_f32_e32 v125, 0x3fb8aa3b, v65
	s_waitcnt lgkmcnt(0)
	v_fmac_f32_e32 v37, 0x3fb8aa3b, v41
	v_cndmask_b32_e32 v65, v204, v0, vcc
	v_cmp_lt_i32_e32 vcc, v124, v180
	v_or_b32_e32 v41, 2, v124
	v_fmac_f32_e32 v53, 0x3fb8aa3b, v61
	v_cndmask_b32_e32 v64, v204, v114, vcc
	v_cmp_le_i32_e32 vcc, v41, v180
	v_or_b32_e32 v41, 3, v124
	v_fmamk_f32 v52, v60, 0x3fb8aa3b, v52
	v_cndmask_b32_e32 v63, v204, v115, vcc
	v_cmp_le_i32_e32 vcc, v41, v180
	v_or_b32_e32 v41, 8, v124
	v_fmac_f32_e32 v121, 0x3fb8aa3b, v57
	v_cndmask_b32_e32 v62, v204, v117, vcc
	v_cmp_le_i32_e32 vcc, v41, v180
	v_or_b32_e32 v41, 9, v124
	v_fmamk_f32 v51, v59, 0x3fb8aa3b, v51
	v_cndmask_b32_e32 v61, v204, v54, vcc
	v_cmp_le_i32_e32 vcc, v41, v180
	v_or_b32_e32 v41, 10, v124
	v_fmamk_f32 v50, v58, 0x3fb8aa3b, v50
	v_cndmask_b32_e32 v60, v204, v55, vcc
	v_cmp_le_i32_e32 vcc, v41, v180
	v_or_b32_e32 v41, 11, v124
	v_fmamk_f32 v34, v38, 0x3fb8aa3b, v34
	v_cndmask_b32_e32 v59, v204, v56, vcc
	v_cmp_le_i32_e32 vcc, v41, v180
	v_or_b32_e32 v41, 16, v124
	v_fmamk_f32 v35, v39, 0x3fb8aa3b, v35
	v_cndmask_b32_e32 v58, v204, v121, vcc
	v_cmp_le_i32_e32 vcc, v41, v180
	v_or_b32_e32 v41, 17, v124
	v_fmamk_f32 v36, v40, 0x3fb8aa3b, v36
	v_cndmask_b32_e32 v57, v204, v50, vcc
	v_cmp_le_i32_e32 vcc, v41, v180
	v_or_b32_e32 v41, 18, v124
	v_fmamk_f32 v38, v42, 0x3fb8aa3b, v130
	v_cndmask_b32_e32 v56, v204, v51, vcc
	v_cmp_le_i32_e32 vcc, v41, v180
	v_or_b32_e32 v41, 19, v124
	v_fmamk_f32 v39, v43, 0x3fb8aa3b, v131
	v_cndmask_b32_e32 v55, v204, v52, vcc
	v_cmp_le_i32_e32 vcc, v41, v180
	v_or_b32_e32 v41, 24, v124
	v_fmamk_f32 v40, v44, 0x3fb8aa3b, v132
	v_fmac_f32_e32 v133, 0x3fb8aa3b, v45
	ds_read_b128 v[42:45], v195 offset:37088
	v_cndmask_b32_e32 v54, v204, v53, vcc
	v_cmp_le_i32_e32 vcc, v41, v180
	v_or_b32_e32 v41, 25, v124
	v_max3_f32 v0, v65, s35, v64
	v_cndmask_b32_e32 v53, v204, v116, vcc
	v_cmp_le_i32_e32 vcc, v41, v180
	v_or_b32_e32 v41, 26, v124
	s_waitcnt lgkmcnt(0)
	v_fmac_f32_e32 v45, 0x3fb8aa3b, v49
	v_cndmask_b32_e32 v52, v204, v118, vcc
	v_cmp_le_i32_e32 vcc, v41, v180
	v_or_b32_e32 v41, 27, v124
	v_fmamk_f32 v44, v48, 0x3fb8aa3b, v44
	v_cndmask_b32_e32 v51, v204, v119, vcc
	v_cmp_le_i32_e32 vcc, v41, v180
	v_or_b32_e32 v41, 32, v124
	v_fmamk_f32 v43, v47, 0x3fb8aa3b, v43
	v_cndmask_b32_e32 v50, v204, v125, vcc
	v_cmp_le_i32_e32 vcc, v41, v180
	v_or_b32_e32 v41, 33, v124
	v_fmamk_f32 v42, v46, 0x3fb8aa3b, v42
	v_cndmask_b32_e32 v49, v204, v120, vcc
	v_cmp_le_i32_e32 vcc, v41, v180
	v_or_b32_e32 v41, 34, v124
	v_max3_f32 v0, v0, v63, v62
	v_cndmask_b32_e32 v48, v204, v122, vcc
	v_cmp_le_i32_e32 vcc, v41, v180
	v_or_b32_e32 v41, 35, v124
	v_max3_f32 v0, v0, v61, v60
	v_cndmask_b32_e32 v47, v204, v123, vcc
	v_cmp_le_i32_e32 vcc, v41, v180
	v_or_b32_e32 v41, 40, v124
	v_max3_f32 v0, v0, v59, v58
	v_cndmask_b32_e32 v46, v204, v129, vcc
	v_cmp_le_i32_e32 vcc, v41, v180
	v_max3_f32 v0, v0, v57, v56
	v_max3_f32 v0, v0, v55, v54
	v_cndmask_b32_e32 v41, v204, v34, vcc
	v_or_b32_e32 v34, 41, v124
	v_cmp_le_i32_e32 vcc, v34, v180
	v_max3_f32 v0, v0, v53, v52
	v_max3_f32 v0, v0, v51, v50
	v_cndmask_b32_e32 v34, v204, v35, vcc
	v_or_b32_e32 v35, 42, v124
	v_cmp_le_i32_e32 vcc, v35, v180
	v_max3_f32 v0, v0, v49, v48
	v_max3_f32 v0, v0, v47, v46
	v_cndmask_b32_e32 v35, v204, v36, vcc
	v_or_b32_e32 v36, 43, v124
	v_cmp_le_i32_e32 vcc, v36, v180
	v_or_b32_e32 v114, 56, v124
	v_max3_f32 v0, v0, v41, v34
	v_cndmask_b32_e32 v36, v204, v37, vcc
	v_or_b32_e32 v37, 48, v124
	v_cmp_le_i32_e32 vcc, v37, v180
	v_max3_f32 v0, v0, v35, v36
	s_nop 0
	v_cndmask_b32_e32 v37, v204, v38, vcc
	v_or_b32_e32 v38, 49, v124
	v_cmp_le_i32_e32 vcc, v38, v180
	s_nop 1
	v_cndmask_b32_e32 v38, v204, v39, vcc
	v_or_b32_e32 v39, 50, v124
	v_cmp_le_i32_e32 vcc, v39, v180
	v_max3_f32 v0, v0, v37, v38
	s_nop 0
	v_cndmask_b32_e32 v39, v204, v40, vcc
	v_or_b32_e32 v40, 51, v124
	v_cmp_le_i32_e32 vcc, v40, v180
	s_nop 1
	v_cndmask_b32_e32 v40, v204, v133, vcc
	v_cmp_le_i32_e32 vcc, v114, v180
	v_or_b32_e32 v114, 57, v124
	v_max3_f32 v0, v0, v39, v40
	v_cndmask_b32_e32 v42, v204, v42, vcc
	v_cmp_le_i32_e32 vcc, v114, v180
	v_or_b32_e32 v114, 58, v124
	s_nop 0
	v_cndmask_b32_e32 v43, v204, v43, vcc
	v_cmp_le_i32_e32 vcc, v114, v180
	v_or_b32_e32 v114, 59, v124
	v_max3_f32 v0, v0, v42, v43
	v_cndmask_b32_e32 v44, v204, v44, vcc
	v_cmp_le_i32_e32 vcc, v114, v180
	s_nop 1
	v_cndmask_b32_e32 v45, v204, v45, vcc
	v_max3_f32 v0, v0, v44, v45
	ds_bpermute_b32 v114, v190, v0
	s_waitcnt lgkmcnt(0)
	v_max_f32_e32 v232, v0, v114
	v_sub_f32_e32 v233, v232, v192
	v_cmp_lt_f32_e32 vcc, 0x41000000, v233
	s_nop 1
	v_cndmask_b32_e32 v191, v192, v232, vcc
	v_sub_f32_e32 v0, v192, v191
	v_exp_f32_e32 v0, v0
	v_cmp_neq_f32_e32 vcc, v191, v192
	s_cbranch_vccz .LBB0_806
;     ...
;   if (__builtin_amdgcn_ballot_w64(mn != m) != 0ull) {
; #pragma unroll
;     for (int dt = 0; dt < 2; ++dt)
; #pragma unroll
;       for (int i = 0; i < 16; ++i) o[dt][i] *= alpha;
;   }
	v_pk_mul_f32 v[32:33], v[32:33], v[0:1] op_sel_hi:[1,0]
	v_pk_mul_f32 v[30:31], v[30:31], v[0:1] op_sel_hi:[1,0]
	v_pk_mul_f32 v[28:29], v[28:29], v[0:1] op_sel_hi:[1,0]
	v_pk_mul_f32 v[26:27], v[26:27], v[0:1] op_sel_hi:[1,0]
	v_pk_mul_f32 v[24:25], v[24:25], v[0:1] op_sel_hi:[1,0]
	v_pk_mul_f32 v[22:23], v[22:23], v[0:1] op_sel_hi:[1,0]
	v_pk_mul_f32 v[20:21], v[20:21], v[0:1] op_sel_hi:[1,0]
	v_pk_mul_f32 v[18:19], v[18:19], v[0:1] op_sel_hi:[1,0]
	v_pk_mul_f32 v[16:17], v[16:17], v[0:1] op_sel_hi:[1,0]
	v_pk_mul_f32 v[14:15], v[14:15], v[0:1] op_sel_hi:[1,0]
	v_pk_mul_f32 v[12:13], v[12:13], v[0:1] op_sel_hi:[1,0]
	v_pk_mul_f32 v[10:11], v[10:11], v[0:1] op_sel_hi:[1,0]
	v_pk_mul_f32 v[8:9], v[8:9], v[0:1] op_sel_hi:[1,0]
	v_pk_mul_f32 v[6:7], v[6:7], v[0:1] op_sel_hi:[1,0]
	v_pk_mul_f32 v[4:5], v[4:5], v[0:1] op_sel_hi:[1,0]
	v_pk_mul_f32 v[2:3], v[2:3], v[0:1] op_sel_hi:[1,0]

;     ...
;   f32x16 s[2];
; #pragma unroll
;   for (int k2 = 0; k2 < 2; ++k2) {
;     if (!(HM & (1 << k2))) continue;
; #pragma unroll
;     for (int i = 0; i < 16; ++i) s[k2][i] = 0.f;
; #pragma unroll
;     for (int ks = 0; ks < 4; ++ks) {
;       const bf16x8 a = *(const bf16x8*)(Ks + (32 * k2 + r) * LSTR + 16 * ks + 8 * h);
;       s[k2] = mfma32(a, qf[ks], s[k2]);
;     }
;   }
;   if (MODE == 1) {
; #pragma unroll
;     for (int k2 = 0; k2 < 2; ++k2)
; #pragma unroll
;       for (int g = 0; g < 4; ++g) {
;         if (!(HM & (1 << k2))) continue;
;         const f32x4 cv = *(const f32x4*)(cn_lds + key0 + 32 * k2 + 8 * g + 4 * h);
; #pragma unroll
;         for (int e = 0; e < 4; ++e) s[k2][4 * g + e] = fmaf(s[k2][4 * g + e], L2E, cv[e]);
;       }
;   }
;   float mx = NINF;
; #pragma unroll
;   for (int k2 = 0; k2 < 2; ++k2)
; #pragma unroll
;     for (int i = 0; i < 16; ++i) {
;       if (!(HM & (1 << k2))) continue;
;       float v = s[k2][i];
;       if (MASKED) {
;         const int tk = key0 + 32 * k2 + crow(i, h);
;         const bool valid = (MODE == 0) ? ((tk <= tq) && (tq - tk <= maxdist)) : (tk <= tq);
;         v = valid ? v : NINF; s[k2][i] = v;
;       }
;       mx = fmaxf(mx, v);
;     }
;   mx = fmaxf(mx, __shfl_xor(mx, 32));
;   if (MODE != 1) mx *= L2E;
;   if (MODE == 2) mx = lanesel ? mx : NINF;
;   const float mn = fmaxf(m, mx); const float alpha = __builtin_amdgcn_exp2f(m - mn);
;   const float neg = (MODE == 2 && !lanesel) ? NINF : -mn;
;   float ps = 0.f;
; #pragma unroll
;   for (int k2 = 0; k2 < 2; ++k2)
; #pragma unroll
;     for (int i = 0; i < 16; ++i) {
;       if (!(HM & (1 << k2))) continue;
;       const float pv = (MODE == 1) ? __builtin_amdgcn_exp2f(s[k2][i] + neg) : __builtin_amdgcn_exp2f(fmaf(s[k2][i], L2E, neg));
;       s[k2][i] = pv; ps += pv;
;     }
;   l = l * alpha + ps;
; template <int MODE>
; DI void flash_loop(char* smem, const bf16_t* Kbase, size_t ldk, const bf16_t* Vtbase, size_t ldv, ull tiles, ull wtiles,
;                    const bf16x8 (&qf)[4], f32x16 (&o)[2], float& m, float& l, int tq, int tqmin, int tqmax, int maxdist, const float* cn_lds, ull lmask) {
;     ...
;     if (!((wtiles >> kt) & 1ull)) return;
;     const bf16_t* Ks = (const bf16_t*)(smem + stage * (2 * 64 * LSTR * 2)); const bf16_t* Vs = Ks + 64 * LSTR;
;     const bool sel = ((lmask >> kt) & 1ull) != 0;
.LBB0_823:
	s_lshl_b64 s[6:7], 1, s11
	v_and_b32_e32 v34, s6, v185
	v_and_b32_e32 v35, s7, v187
	v_cmp_eq_u64_e32 vcc, 0, v[34:35]
	s_cbranch_vccnz .LBB0_833
	ds_read_b128 v[146:149], v196
	ds_read_b128 v[150:153], v196 offset:32
	ds_read_b128 v[154:157], v196 offset:64
	ds_read_b128 v[158:161], v196 offset:96
	ds_read_b128 v[162:165], v196 offset:4608
	s_lshl_b32 s11, s11, 6
	v_and_b32_e32 v35, s7, v189
	v_and_b32_e32 v34, s6, v188
	s_or_b32 s8, s11, 63
	v_cmp_eq_u64_e64 s[6:7], 0, v[34:35]
	s_cmp_gt_i32 s8, s28
	s_mov_b64 s[8:9], -1
	v_max_f32_e32 v216, v211, v211
	s_cbranch_scc1 .LBB0_828
	s_waitcnt lgkmcnt(4)
	v_mfma_f32_32x32x16_bf16 v[82:97], v[146:149], v[98:101], 0
	ds_read_b128 v[34:37], v196 offset:4640
	ds_read_b128 v[38:41], v196 offset:4672
	s_waitcnt lgkmcnt(5)
	v_mfma_f32_32x32x16_bf16 v[82:97], v[150:153], v[102:105], v[82:97]
	s_waitcnt lgkmcnt(2)
	v_mfma_f32_32x32x16_bf16 v[66:81], v[162:165], v[98:101], 0
	v_mfma_f32_32x32x16_bf16 v[82:97], v[154:157], v[106:109], v[82:97]
	s_waitcnt lgkmcnt(1)
	v_mfma_f32_32x32x16_bf16 v[66:81], v[34:37], v[102:105], v[66:81]
	ds_read_b128 v[34:37], v196 offset:4704
	v_mfma_f32_32x32x16_bf16 v[82:97], v[158:161], v[110:113], v[82:97]
	s_waitcnt lgkmcnt(1)
	v_mfma_f32_32x32x16_bf16 v[66:81], v[38:41], v[106:109], v[66:81]
	s_nop 9
	v_max3_f32 v0, v82, s35, v83
	v_max3_f32 v0, v0, v84, v85
	v_max3_f32 v0, v0, v86, v87
	v_max3_f32 v0, v0, v88, v89
	v_max3_f32 v0, v0, v90, v91
	v_max3_f32 v0, v0, v92, v93
	v_max3_f32 v0, v0, v94, v95
	s_waitcnt lgkmcnt(0)
	v_mfma_f32_32x32x16_bf16 v[66:81], v[34:37], v[110:113], v[66:81]
	v_max3_f32 v0, v0, v96, v97
	v_and_b32_e32 v35, 64, v202
	v_xor_b32_e32 v34, 32, v202
	v_add_u32_e32 v35, 64, v35
	v_cmp_lt_i32_e32 vcc, v34, v35
	s_nop 6
	v_max3_f32 v0, v0, v66, v67
	v_max3_f32 v0, v0, v68, v69
	v_max3_f32 v0, v0, v70, v71
	v_max3_f32 v0, v0, v72, v73
	v_max3_f32 v0, v0, v74, v75
	v_max3_f32 v0, v0, v76, v77
	v_max3_f32 v0, v0, v78, v79
	v_cndmask_b32_e32 v34, v202, v34, vcc
	v_max3_f32 v0, v0, v80, v81
	v_lshlrev_b32_e32 v34, 2, v34
	ds_bpermute_b32 v34, v34, v0
	s_waitcnt lgkmcnt(0)
	v_max_f32_e32 v34, v34, v34
	v_max_f32_e32 v0, v0, v34
	v_mul_f32_e32 v0, 0x3fb8aa3b, v0
	v_cndmask_b32_e64 v0, v0, v204, s[6:7]
	v_sub_f32_e32 v232, v0, v216
	v_cmp_lt_f32_e32 vcc, 0x41000000, v232
	s_nop 1
	v_cndmask_b32_e32 v212, v216, v0, vcc
	v_sub_f32_e32 v0, v211, v212
	v_exp_f32_e32 v0, v0
	v_cmp_neq_f32_e32 vcc, v212, v211
	s_cbranch_vccz .LBB0_827
	v_pk_mul_f32 v[32:33], v[32:33], v[0:1] op_sel_hi:[1,0]
	v_pk_mul_f32 v[30:31], v[30:31], v[0:1] op_sel_hi:[1,0]
	v_pk_mul_f32 v[28:29], v[28:29], v[0:1] op_sel_hi:[1,0]
	v_pk_mul_f32 v[26:27], v[26:27], v[0:1] op_sel_hi:[1,0]
	v_pk_mul_f32 v[24:25], v[24:25], v[0:1] op_sel_hi:[1,0]
	v_pk_mul_f32 v[22:23], v[22:23], v[0:1] op_sel_hi:[1,0]
	v_pk_mul_f32 v[20:21], v[20:21], v[0:1] op_sel_hi:[1,0]
	v_pk_mul_f32 v[18:19], v[18:19], v[0:1] op_sel_hi:[1,0]
	v_pk_mul_f32 v[16:17], v[16:17], v[0:1] op_sel_hi:[1,0]
	v_pk_mul_f32 v[14:15], v[14:15], v[0:1] op_sel_hi:[1,0]
	v_pk_mul_f32 v[12:13], v[12:13], v[0:1] op_sel_hi:[1,0]
	v_pk_mul_f32 v[10:11], v[10:11], v[0:1] op_sel_hi:[1,0]
	v_pk_mul_f32 v[8:9], v[8:9], v[0:1] op_sel_hi:[1,0]
	v_pk_mul_f32 v[6:7], v[6:7], v[0:1] op_sel_hi:[1,0]
	v_pk_mul_f32 v[4:5], v[4:5], v[0:1] op_sel_hi:[1,0]
	v_pk_mul_f32 v[2:3], v[2:3], v[0:1] op_sel_hi:[1,0]

; DI f32x16 mfma32(bf16x8 a, bf16x8 b, f32x16 c) { return __builtin_amdgcn_mfma_f32_32x32x16_bf16(a, b, c, 0, 0, 0); }
; DI int crow(int i, int h) { return (i & 3) + 8 * (i >> 2) + 4 * h; }
;     ...
;   f32x16 s[2];
; #pragma unroll
;   for (int k2 = 0; k2 < 2; ++k2) {
;     if (!(HM & (1 << k2))) continue;
; #pragma unroll
;     for (int i = 0; i < 16; ++i) s[k2][i] = 0.f;
; #pragma unroll
;     for (int ks = 0; ks < 4; ++ks) {
;       const bf16x8 a = *(const bf16x8*)(Ks + (32 * k2 + r) * LSTR + 16 * ks + 8 * h);
;       s[k2] = mfma32(a, qf[ks], s[k2]);
;     }
;   }
;   if (MODE == 1) {
; #pragma unroll
;     for (int k2 = 0; k2 < 2; ++k2)
; #pragma unroll
;       for (int g = 0; g < 4; ++g) {
;         if (!(HM & (1 << k2))) continue;
;         const f32x4 cv = *(const f32x4*)(cn_lds + key0 + 32 * k2 + 8 * g + 4 * h);
; #pragma unroll
;         for (int e = 0; e < 4; ++e) s[k2][4 * g + e] = fmaf(s[k2][4 * g + e], L2E, cv[e]);
;       }
;   }
;   float mx = NINF;
; #pragma unroll
;   for (int k2 = 0; k2 < 2; ++k2)
; #pragma unroll
;     for (int i = 0; i < 16; ++i) {
;       if (!(HM & (1 << k2))) continue;
;       float v = s[k2][i];
;       if (MASKED) {
;         const int tk = key0 + 32 * k2 + crow(i, h);
;         const bool valid = (MODE == 0) ? ((tk <= tq) && (tq - tk <= maxdist)) : (tk <= tq);
;         v = valid ? v : NINF; s[k2][i] = v;
;       }
;       mx = fmaxf(mx, v);
;     }
;   mx = fmaxf(mx, __shfl_xor(mx, 32));
;   if (MODE != 1) mx *= L2E;
;   if (MODE == 2) mx = lanesel ? mx : NINF;
;   const float mn = fmaxf(m, mx); const float alpha = __builtin_amdgcn_exp2f(m - mn);
;   const float neg = (MODE == 2 && !lanesel) ? NINF : -mn;
;   float ps = 0.f;
; #pragma unroll
;   for (int k2 = 0; k2 < 2; ++k2)
; #pragma unroll
;     for (int i = 0; i < 16; ++i) {
;       if (!(HM & (1 << k2))) continue;
;       const float pv = (MODE == 1) ? __builtin_amdgcn_exp2f(s[k2][i] + neg) : __builtin_amdgcn_exp2f(fmaf(s[k2][i], L2E, neg));
;       s[k2][i] = pv; ps += pv;
;     }
;   l = l * alpha + ps;
;   if (__builtin_amdgcn_ballot_w64(mn != m) != 0ull) {
; #pragma unroll
;     for (int dt = 0; dt < 2; ++dt)
; #pragma unroll
;       for (int i = 0; i < 16; ++i) o[dt][i] *= alpha;
;   }
.LBB0_828:
	s_and_b64 vcc, exec, s[8:9]
	s_cbranch_vccz .LBB0_832
	s_waitcnt lgkmcnt(4)
	v_mfma_f32_32x32x16_bf16 v[50:65], v[146:149], v[98:101], 0
	ds_read_b128 v[66:69], v196 offset:4640
	ds_read_b128 v[70:73], v196 offset:4672
	v_or_b32_e32 v0, s11, v197
	v_cmp_le_i32_e32 vcc, v0, v186
	s_waitcnt lgkmcnt(5)
	v_mfma_f32_32x32x16_bf16 v[50:65], v[150:153], v[102:105], v[50:65]
	s_waitcnt lgkmcnt(2)
	v_mfma_f32_32x32x16_bf16 v[34:49], v[162:165], v[98:101], 0
	v_mfma_f32_32x32x16_bf16 v[50:65], v[154:157], v[106:109], v[50:65]
	s_waitcnt lgkmcnt(1)
	v_mfma_f32_32x32x16_bf16 v[34:49], v[66:69], v[102:105], v[34:49]
	ds_read_b128 v[66:69], v196 offset:4704
	v_mfma_f32_32x32x16_bf16 v[50:65], v[158:161], v[110:113], v[50:65]
	s_waitcnt lgkmcnt(1)
	v_mfma_f32_32x32x16_bf16 v[34:49], v[70:73], v[106:109], v[34:49]
	s_waitcnt lgkmcnt(0)
	v_mfma_f32_32x32x16_bf16 v[34:49], v[66:69], v[110:113], v[34:49]
	s_nop 7
	v_cndmask_b32_e32 v66, v204, v50, vcc
	v_cmp_lt_i32_e32 vcc, v0, v186
	s_nop 1
	v_cndmask_b32_e32 v50, v204, v51, vcc
	v_or_b32_e32 v51, 2, v0
	v_cmp_le_i32_e32 vcc, v51, v186
	v_max3_f32 v67, v66, s35, v50
	s_nop 0
	v_cndmask_b32_e32 v51, v204, v52, vcc
	v_or_b32_e32 v52, 3, v0
	v_cmp_le_i32_e32 vcc, v52, v186
	s_nop 1
	v_cndmask_b32_e32 v52, v204, v53, vcc
	v_or_b32_e32 v53, 8, v0
	v_cmp_le_i32_e32 vcc, v53, v186
	v_max3_f32 v67, v67, v51, v52
	s_nop 0
	v_cndmask_b32_e32 v53, v204, v54, vcc
	v_or_b32_e32 v54, 9, v0
	v_cmp_le_i32_e32 vcc, v54, v186
	s_nop 1
	v_cndmask_b32_e32 v54, v204, v55, vcc
	v_or_b32_e32 v55, 10, v0
	v_cmp_le_i32_e32 vcc, v55, v186
	v_max3_f32 v67, v67, v53, v54
	s_nop 0
	v_cndmask_b32_e32 v55, v204, v56, vcc
	v_or_b32_e32 v56, 11, v0
	v_cmp_le_i32_e32 vcc, v56, v186
	s_nop 1
	v_cndmask_b32_e32 v56, v204, v57, vcc
	v_max3_f32 v57, v67, v55, v56
	v_or_b32_e32 v67, 16, v0
	v_cmp_le_i32_e32 vcc, v67, v186
	s_nop 1
	v_cndmask_b32_e32 v67, v204, v58, vcc
	v_or_b32_e32 v58, 17, v0
	v_cmp_le_i32_e32 vcc, v58, v186
	v_or_b32_e32 v58, 18, v0
	s_nop 0
	v_cndmask_b32_e32 v72, v204, v59, vcc
	v_cmp_le_i32_e32 vcc, v58, v186
	v_or_b32_e32 v58, 19, v0
	v_max3_f32 v57, v57, v67, v72
	v_cndmask_b32_e32 v70, v204, v60, vcc
	v_cmp_le_i32_e32 vcc, v58, v186
	v_or_b32_e32 v58, 24, v0
	s_nop 0
	v_cndmask_b32_e32 v71, v204, v61, vcc
	v_cmp_le_i32_e32 vcc, v58, v186
	v_or_b32_e32 v58, 25, v0
	v_max3_f32 v57, v57, v70, v71
	v_cndmask_b32_e32 v68, v204, v62, vcc
	v_cmp_le_i32_e32 vcc, v58, v186
	v_or_b32_e32 v58, 26, v0
	s_nop 0
	v_cndmask_b32_e32 v69, v204, v63, vcc
	v_cmp_le_i32_e32 vcc, v58, v186
	v_or_b32_e32 v58, 27, v0
	v_max3_f32 v57, v57, v68, v69
	v_cndmask_b32_e32 v62, v204, v64, vcc
	v_cmp_le_i32_e32 vcc, v58, v186
	v_or_b32_e32 v58, 32, v0
	s_nop 0
	v_cndmask_b32_e32 v63, v204, v65, vcc
	v_cmp_le_i32_e32 vcc, v58, v186
	v_max3_f32 v57, v57, v62, v63
	s_nop 0
	v_cndmask_b32_e32 v61, v204, v34, vcc
	v_or_b32_e32 v34, 33, v0
	v_cmp_le_i32_e32 vcc, v34, v186
	s_nop 1
	v_cndmask_b32_e32 v60, v204, v35, vcc
	v_or_b32_e32 v35, 34, v0
	v_cmp_le_i32_e32 vcc, v35, v186
	v_or_b32_e32 v35, 35, v0
	v_max3_f32 v34, v57, v61, v60
	v_cndmask_b32_e32 v59, v204, v36, vcc
	v_cmp_le_i32_e32 vcc, v35, v186
	v_or_b32_e32 v36, 43, v0
	s_nop 0
	v_cndmask_b32_e32 v58, v204, v37, vcc
	v_max3_f32 v35, v34, v59, v58
	v_or_b32_e32 v34, 40, v0
	v_cmp_le_i32_e32 vcc, v34, v186
	v_or_b32_e32 v34, 41, v0
	s_nop 0
	v_cndmask_b32_e32 v57, v204, v38, vcc
	v_cmp_le_i32_e32 vcc, v34, v186
	v_or_b32_e32 v38, 49, v0
	s_nop 0
	v_cndmask_b32_e32 v34, v204, v39, vcc
	v_max3_f32 v37, v35, v57, v34
	v_or_b32_e32 v35, 42, v0
	v_cmp_le_i32_e32 vcc, v35, v186
	s_nop 1
	v_cndmask_b32_e32 v35, v204, v40, vcc
	v_cmp_le_i32_e32 vcc, v36, v186
	v_or_b32_e32 v40, 51, v0
	s_nop 0
	v_cndmask_b32_e32 v36, v204, v41, vcc
	v_max3_f32 v39, v37, v35, v36
	v_or_b32_e32 v37, 48, v0
	v_cmp_le_i32_e32 vcc, v37, v186
	s_nop 1
	v_cndmask_b32_e32 v37, v204, v42, vcc
	v_cmp_le_i32_e32 vcc, v38, v186
	v_or_b32_e32 v42, 57, v0
	s_nop 0
	v_cndmask_b32_e32 v38, v204, v43, vcc
	v_max3_f32 v41, v39, v37, v38
	v_or_b32_e32 v39, 50, v0
	v_cmp_le_i32_e32 vcc, v39, v186
	s_nop 1
	v_cndmask_b32_e32 v39, v204, v44, vcc
	v_cmp_le_i32_e32 vcc, v40, v186
	s_nop 1
	v_cndmask_b32_e32 v40, v204, v45, vcc
	v_max3_f32 v43, v41, v39, v40
	v_or_b32_e32 v41, 56, v0
	v_cmp_le_i32_e32 vcc, v41, v186
	s_nop 1
	v_cndmask_b32_e32 v41, v204, v46, vcc
	v_cmp_le_i32_e32 vcc, v42, v186
	v_and_b32_e32 v46, 64, v202
	v_add_u32_e32 v46, 64, v46
	v_cndmask_b32_e32 v42, v204, v47, vcc
	v_max3_f32 v45, v43, v41, v42
	v_or_b32_e32 v43, 58, v0
	v_cmp_le_i32_e32 vcc, v43, v186
	v_or_b32_e32 v0, 59, v0
	s_nop 0
	v_cndmask_b32_e32 v43, v204, v48, vcc
	v_cmp_le_i32_e32 vcc, v0, v186
	s_nop 1
	v_cndmask_b32_e32 v44, v204, v49, vcc
	v_max3_f32 v0, v45, v43, v44
	v_xor_b32_e32 v45, 32, v202
	v_cmp_lt_i32_e32 vcc, v45, v46
	s_nop 1
	v_cndmask_b32_e32 v45, v202, v45, vcc
	v_lshlrev_b32_e32 v45, 2, v45
	ds_bpermute_b32 v45, v45, v0
	s_waitcnt lgkmcnt(0)
	v_max_f32_e32 v45, v45, v45
	v_max_f32_e32 v0, v0, v45
	v_mul_f32_e32 v0, 0x3fb8aa3b, v0
	v_cndmask_b32_e64 v0, v0, v204, s[6:7]
	v_sub_f32_e32 v232, v0, v216
	v_cmp_lt_f32_e32 vcc, 0x41000000, v232
	s_nop 1
	v_cndmask_b32_e32 v212, v216, v0, vcc
	v_sub_f32_e32 v0, v211, v212
	v_exp_f32_e32 v0, v0
	v_cmp_neq_f32_e32 vcc, v212, v211
	s_cbranch_vccz .LBB0_831
	v_pk_mul_f32 v[32:33], v[32:33], v[0:1] op_sel_hi:[1,0]
	v_pk_mul_f32 v[30:31], v[30:31], v[0:1] op_sel_hi:[1,0]
	v_pk_mul_f32 v[28:29], v[28:29], v[0:1] op_sel_hi:[1,0]
	v_pk_mul_f32 v[26:27], v[26:27], v[0:1] op_sel_hi:[1,0]
	v_pk_mul_f32 v[24:25], v[24:25], v[0:1] op_sel_hi:[1,0]
	v_pk_mul_f32 v[22:23], v[22:23], v[0:1] op_sel_hi:[1,0]
	v_pk_mul_f32 v[20:21], v[20:21], v[0:1] op_sel_hi:[1,0]
	v_pk_mul_f32 v[18:19], v[18:19], v[0:1] op_sel_hi:[1,0]
	v_pk_mul_f32 v[16:17], v[16:17], v[0:1] op_sel_hi:[1,0]
	v_pk_mul_f32 v[14:15], v[14:15], v[0:1] op_sel_hi:[1,0]
	v_pk_mul_f32 v[12:13], v[12:13], v[0:1] op_sel_hi:[1,0]
	v_pk_mul_f32 v[10:11], v[10:11], v[0:1] op_sel_hi:[1,0]
	v_pk_mul_f32 v[8:9], v[8:9], v[0:1] op_sel_hi:[1,0]
	v_pk_mul_f32 v[6:7], v[6:7], v[0:1] op_sel_hi:[1,0]
	v_pk_mul_f32 v[4:5], v[4:5], v[0:1] op_sel_hi:[1,0]
	v_pk_mul_f32 v[2:3], v[2:3], v[0:1] op_sel_hi:[1,0]

;     ...
;   f32x16 s[2];
; #pragma unroll
;   for (int k2 = 0; k2 < 2; ++k2) {
;     if (!(HM & (1 << k2))) continue;
; #pragma unroll
;     for (int i = 0; i < 16; ++i) s[k2][i] = 0.f;
; #pragma unroll
;     for (int ks = 0; ks < 4; ++ks) {
;       const bf16x8 a = *(const bf16x8*)(Ks + (32 * k2 + r) * LSTR + 16 * ks + 8 * h);
;       s[k2] = mfma32(a, qf[ks], s[k2]);
;     }
;   }
;   if (MODE == 1) {
; #pragma unroll
;     for (int k2 = 0; k2 < 2; ++k2)
; #pragma unroll
;       for (int g = 0; g < 4; ++g) {
;         if (!(HM & (1 << k2))) continue;
;         const f32x4 cv = *(const f32x4*)(cn_lds + key0 + 32 * k2 + 8 * g + 4 * h);
; #pragma unroll
;         for (int e = 0; e < 4; ++e) s[k2][4 * g + e] = fmaf(s[k2][4 * g + e], L2E, cv[e]);
;       }
;   }
;   float mx = NINF;
; #pragma unroll
;   for (int k2 = 0; k2 < 2; ++k2)
; #pragma unroll
;     for (int i = 0; i < 16; ++i) {
;       if (!(HM & (1 << k2))) continue;
;       float v = s[k2][i];
;       if (MASKED) {
;         const int tk = key0 + 32 * k2 + crow(i, h);
;         const bool valid = (MODE == 0) ? ((tk <= tq) && (tq - tk <= maxdist)) : (tk <= tq);
;         v = valid ? v : NINF; s[k2][i] = v;
;       }
;       mx = fmaxf(mx, v);
;     }
;   mx = fmaxf(mx, __shfl_xor(mx, 32));
;   if (MODE != 1) mx *= L2E;
;   if (MODE == 2) mx = lanesel ? mx : NINF;
;   const float mn = fmaxf(m, mx); const float alpha = __builtin_amdgcn_exp2f(m - mn);
;   const float neg = (MODE == 2 && !lanesel) ? NINF : -mn;
;   float ps = 0.f;
; #pragma unroll
;   for (int k2 = 0; k2 < 2; ++k2)
; #pragma unroll
;     for (int i = 0; i < 16; ++i) {
;       if (!(HM & (1 << k2))) continue;
;       const float pv = (MODE == 1) ? __builtin_amdgcn_exp2f(s[k2][i] + neg) : __builtin_amdgcn_exp2f(fmaf(s[k2][i], L2E, neg));
;       s[k2][i] = pv; ps += pv;
;     }
;   l = l * alpha + ps;
; template <int MODE>
; DI void flash_loop(char* smem, const bf16_t* Kbase, size_t ldk, const bf16_t* Vtbase, size_t ldv, ull tiles, ull wtiles,
;                    const bf16x8 (&qf)[4], f32x16 (&o)[2], float& m, float& l, int tq, int tqmin, int tqmax, int maxdist, const float* cn_lds, ull lmask) {
;     ...
;     if (!((wtiles >> kt) & 1ull)) return;
;     const bf16_t* Ks = (const bf16_t*)(smem + stage * (2 * 64 * LSTR * 2)); const bf16_t* Vs = Ks + 64 * LSTR;
;     const bool sel = ((lmask >> kt) & 1ull) != 0;
.LBB0_836:
	v_lshlrev_b64 v[34:35], v215, 1
	v_and_b32_e32 v36, v34, v185
	v_and_b32_e32 v37, v35, v187
	v_cmp_eq_u64_e32 vcc, 0, v[36:37]
	s_cbranch_vccnz .LBB0_846
	ds_read_b128 v[146:149], v196 offset:18432
	ds_read_b128 v[150:153], v196 offset:18464
	ds_read_b128 v[154:157], v196 offset:18496
	ds_read_b128 v[158:161], v196 offset:18528
	ds_read_b128 v[162:165], v196 offset:23040
	v_lshlrev_b32_e32 v216, 6, v215
	v_or_b32_e32 v0, 63, v216
	v_and_b32_e32 v35, v35, v189
	v_and_b32_e32 v34, v34, v188
	v_cmp_lt_i32_e32 vcc, s28, v0
	v_cmp_eq_u64_e64 s[6:7], 0, v[34:35]
	s_mov_b64 s[8:9], -1
	s_and_b64 vcc, exec, vcc
	v_max_f32_e32 v215, v212, v212
	s_cbranch_vccnz .LBB0_841
	s_waitcnt lgkmcnt(4)
	v_mfma_f32_32x32x16_bf16 v[82:97], v[146:149], v[98:101], 0
	ds_read_b128 v[34:37], v196 offset:23072
	ds_read_b128 v[38:41], v196 offset:23104
	s_waitcnt lgkmcnt(5)
	v_mfma_f32_32x32x16_bf16 v[82:97], v[150:153], v[102:105], v[82:97]
	s_waitcnt lgkmcnt(2)
	v_mfma_f32_32x32x16_bf16 v[66:81], v[162:165], v[98:101], 0
	v_mfma_f32_32x32x16_bf16 v[82:97], v[154:157], v[106:109], v[82:97]
	s_waitcnt lgkmcnt(1)
	v_mfma_f32_32x32x16_bf16 v[66:81], v[34:37], v[102:105], v[66:81]
	ds_read_b128 v[34:37], v196 offset:23136
	v_mfma_f32_32x32x16_bf16 v[82:97], v[158:161], v[110:113], v[82:97]
	s_waitcnt lgkmcnt(1)
	v_mfma_f32_32x32x16_bf16 v[66:81], v[38:41], v[106:109], v[66:81]
	s_nop 9
	v_max3_f32 v0, v82, s35, v83
	v_max3_f32 v0, v0, v84, v85
	v_max3_f32 v0, v0, v86, v87
	v_max3_f32 v0, v0, v88, v89
	v_max3_f32 v0, v0, v90, v91
	v_max3_f32 v0, v0, v92, v93
	v_max3_f32 v0, v0, v94, v95
	s_waitcnt lgkmcnt(0)
	v_mfma_f32_32x32x16_bf16 v[66:81], v[34:37], v[110:113], v[66:81]
	v_max3_f32 v0, v0, v96, v97
	v_and_b32_e32 v35, 64, v202
	v_xor_b32_e32 v34, 32, v202
	v_add_u32_e32 v35, 64, v35
	v_cmp_lt_i32_e32 vcc, v34, v35
	s_nop 6
	v_max3_f32 v0, v0, v66, v67
	v_max3_f32 v0, v0, v68, v69
	v_max3_f32 v0, v0, v70, v71
	v_max3_f32 v0, v0, v72, v73
	v_max3_f32 v0, v0, v74, v75
	v_max3_f32 v0, v0, v76, v77
	v_max3_f32 v0, v0, v78, v79
	v_cndmask_b32_e32 v34, v202, v34, vcc
	v_max3_f32 v0, v0, v80, v81
	v_lshlrev_b32_e32 v34, 2, v34
	ds_bpermute_b32 v34, v34, v0
	s_waitcnt lgkmcnt(0)
	v_max_f32_e32 v34, v34, v34
	v_max_f32_e32 v0, v0, v34
	v_mul_f32_e32 v0, 0x3fb8aa3b, v0
	v_cndmask_b32_e64 v0, v0, v204, s[6:7]
	v_sub_f32_e32 v232, v0, v215
	v_cmp_lt_f32_e32 vcc, 0x41000000, v232
	s_nop 1
	v_cndmask_b32_e32 v211, v215, v0, vcc
	v_sub_f32_e32 v0, v212, v211
	v_exp_f32_e32 v0, v0
	v_cmp_neq_f32_e32 vcc, v211, v212
	s_cbranch_vccz .LBB0_840
	v_pk_mul_f32 v[32:33], v[32:33], v[0:1] op_sel_hi:[1,0]
	v_pk_mul_f32 v[30:31], v[30:31], v[0:1] op_sel_hi:[1,0]
	v_pk_mul_f32 v[28:29], v[28:29], v[0:1] op_sel_hi:[1,0]
	v_pk_mul_f32 v[26:27], v[26:27], v[0:1] op_sel_hi:[1,0]
	v_pk_mul_f32 v[24:25], v[24:25], v[0:1] op_sel_hi:[1,0]
	v_pk_mul_f32 v[22:23], v[22:23], v[0:1] op_sel_hi:[1,0]
	v_pk_mul_f32 v[20:21], v[20:21], v[0:1] op_sel_hi:[1,0]
	v_pk_mul_f32 v[18:19], v[18:19], v[0:1] op_sel_hi:[1,0]
	v_pk_mul_f32 v[16:17], v[16:17], v[0:1] op_sel_hi:[1,0]
	v_pk_mul_f32 v[14:15], v[14:15], v[0:1] op_sel_hi:[1,0]
	v_pk_mul_f32 v[12:13], v[12:13], v[0:1] op_sel_hi:[1,0]
	v_pk_mul_f32 v[10:11], v[10:11], v[0:1] op_sel_hi:[1,0]
	v_pk_mul_f32 v[8:9], v[8:9], v[0:1] op_sel_hi:[1,0]
	v_pk_mul_f32 v[6:7], v[6:7], v[0:1] op_sel_hi:[1,0]
	v_pk_mul_f32 v[4:5], v[4:5], v[0:1] op_sel_hi:[1,0]
	v_pk_mul_f32 v[2:3], v[2:3], v[0:1] op_sel_hi:[1,0]

; DI f32x16 mfma32(bf16x8 a, bf16x8 b, f32x16 c) { return __builtin_amdgcn_mfma_f32_32x32x16_bf16(a, b, c, 0, 0, 0); }
; DI int crow(int i, int h) { return (i & 3) + 8 * (i >> 2) + 4 * h; }
;     ...
;   f32x16 s[2];
; #pragma unroll
;   for (int k2 = 0; k2 < 2; ++k2) {
;     if (!(HM & (1 << k2))) continue;
; #pragma unroll
;     for (int i = 0; i < 16; ++i) s[k2][i] = 0.f;
; #pragma unroll
;     for (int ks = 0; ks < 4; ++ks) {
;       const bf16x8 a = *(const bf16x8*)(Ks + (32 * k2 + r) * LSTR + 16 * ks + 8 * h);
;       s[k2] = mfma32(a, qf[ks], s[k2]);
;     }
;   }
;   if (MODE == 1) {
; #pragma unroll
;     for (int k2 = 0; k2 < 2; ++k2)
; #pragma unroll
;       for (int g = 0; g < 4; ++g) {
;         if (!(HM & (1 << k2))) continue;
;         const f32x4 cv = *(const f32x4*)(cn_lds + key0 + 32 * k2 + 8 * g + 4 * h);
; #pragma unroll
;         for (int e = 0; e < 4; ++e) s[k2][4 * g + e] = fmaf(s[k2][4 * g + e], L2E, cv[e]);
;       }
;   }
;   float mx = NINF;
; #pragma unroll
;   for (int k2 = 0; k2 < 2; ++k2)
; #pragma unroll
;     for (int i = 0; i < 16; ++i) {
;       if (!(HM & (1 << k2))) continue;
;       float v = s[k2][i];
;       if (MASKED) {
;         const int tk = key0 + 32 * k2 + crow(i, h);
;         const bool valid = (MODE == 0) ? ((tk <= tq) && (tq - tk <= maxdist)) : (tk <= tq);
;         v = valid ? v : NINF; s[k2][i] = v;
;       }
;       mx = fmaxf(mx, v);
;     }
;   mx = fmaxf(mx, __shfl_xor(mx, 32));
;   if (MODE != 1) mx *= L2E;
;   if (MODE == 2) mx = lanesel ? mx : NINF;
;   const float mn = fmaxf(m, mx); const float alpha = __builtin_amdgcn_exp2f(m - mn);
;   const float neg = (MODE == 2 && !lanesel) ? NINF : -mn;
;   float ps = 0.f;
; #pragma unroll
;   for (int k2 = 0; k2 < 2; ++k2)
; #pragma unroll
;     for (int i = 0; i < 16; ++i) {
;       if (!(HM & (1 << k2))) continue;
;       const float pv = (MODE == 1) ? __builtin_amdgcn_exp2f(s[k2][i] + neg) : __builtin_amdgcn_exp2f(fmaf(s[k2][i], L2E, neg));
;       s[k2][i] = pv; ps += pv;
;     }
;   l = l * alpha + ps;
;   if (__builtin_amdgcn_ballot_w64(mn != m) != 0ull) {
; #pragma unroll
;     for (int dt = 0; dt < 2; ++dt)
; #pragma unroll
;       for (int i = 0; i < 16; ++i) o[dt][i] *= alpha;
;   }
.LBB0_841:
	s_and_b64 vcc, exec, s[8:9]
	s_cbranch_vccz .LBB0_845
	s_waitcnt lgkmcnt(4)
	v_mfma_f32_32x32x16_bf16 v[50:65], v[146:149], v[98:101], 0
	ds_read_b128 v[66:69], v196 offset:23072
	ds_read_b128 v[70:73], v196 offset:23104
	v_or_b32_e32 v0, v216, v197
	v_cmp_le_i32_e32 vcc, v0, v186
	s_waitcnt lgkmcnt(5)
	v_mfma_f32_32x32x16_bf16 v[50:65], v[150:153], v[102:105], v[50:65]
	s_waitcnt lgkmcnt(2)
	v_mfma_f32_32x32x16_bf16 v[34:49], v[162:165], v[98:101], 0
	v_mfma_f32_32x32x16_bf16 v[50:65], v[154:157], v[106:109], v[50:65]
	s_waitcnt lgkmcnt(1)
	v_mfma_f32_32x32x16_bf16 v[34:49], v[66:69], v[102:105], v[34:49]
	ds_read_b128 v[66:69], v196 offset:23136
	v_mfma_f32_32x32x16_bf16 v[50:65], v[158:161], v[110:113], v[50:65]
	s_waitcnt lgkmcnt(1)
	v_mfma_f32_32x32x16_bf16 v[34:49], v[70:73], v[106:109], v[34:49]
	s_waitcnt lgkmcnt(0)
	v_mfma_f32_32x32x16_bf16 v[34:49], v[66:69], v[110:113], v[34:49]
	s_nop 7
	v_cndmask_b32_e32 v66, v204, v50, vcc
	v_cmp_lt_i32_e32 vcc, v0, v186
	s_nop 1
	v_cndmask_b32_e32 v50, v204, v51, vcc
	v_or_b32_e32 v51, 2, v0
	v_cmp_le_i32_e32 vcc, v51, v186
	v_max3_f32 v67, v66, s35, v50
	s_nop 0
	v_cndmask_b32_e32 v51, v204, v52, vcc
	v_or_b32_e32 v52, 3, v0
	v_cmp_le_i32_e32 vcc, v52, v186
	s_nop 1
	v_cndmask_b32_e32 v52, v204, v53, vcc
	v_or_b32_e32 v53, 8, v0
	v_cmp_le_i32_e32 vcc, v53, v186
	v_max3_f32 v67, v67, v51, v52
	s_nop 0
	v_cndmask_b32_e32 v53, v204, v54, vcc
	v_or_b32_e32 v54, 9, v0
	v_cmp_le_i32_e32 vcc, v54, v186
	s_nop 1
	v_cndmask_b32_e32 v54, v204, v55, vcc
	v_or_b32_e32 v55, 10, v0
	v_cmp_le_i32_e32 vcc, v55, v186
	v_max3_f32 v67, v67, v53, v54
	s_nop 0
	v_cndmask_b32_e32 v55, v204, v56, vcc
	v_or_b32_e32 v56, 11, v0
	v_cmp_le_i32_e32 vcc, v56, v186
	s_nop 1
	v_cndmask_b32_e32 v56, v204, v57, vcc
	v_max3_f32 v57, v67, v55, v56
	v_or_b32_e32 v67, 16, v0
	v_cmp_le_i32_e32 vcc, v67, v186
	s_nop 1
	v_cndmask_b32_e32 v67, v204, v58, vcc
	v_or_b32_e32 v58, 17, v0
	v_cmp_le_i32_e32 vcc, v58, v186
	v_or_b32_e32 v58, 18, v0
	s_nop 0
	v_cndmask_b32_e32 v72, v204, v59, vcc
	v_cmp_le_i32_e32 vcc, v58, v186
	v_or_b32_e32 v58, 19, v0
	v_max3_f32 v57, v57, v67, v72
	v_cndmask_b32_e32 v70, v204, v60, vcc
	v_cmp_le_i32_e32 vcc, v58, v186
	v_or_b32_e32 v58, 24, v0
	s_nop 0
	v_cndmask_b32_e32 v71, v204, v61, vcc
	v_cmp_le_i32_e32 vcc, v58, v186
	v_or_b32_e32 v58, 25, v0
	v_max3_f32 v57, v57, v70, v71
	v_cndmask_b32_e32 v68, v204, v62, vcc
	v_cmp_le_i32_e32 vcc, v58, v186
	v_or_b32_e32 v58, 26, v0
	s_nop 0
	v_cndmask_b32_e32 v69, v204, v63, vcc
	v_cmp_le_i32_e32 vcc, v58, v186
	v_or_b32_e32 v58, 27, v0
	v_max3_f32 v57, v57, v68, v69
	v_cndmask_b32_e32 v62, v204, v64, vcc
	v_cmp_le_i32_e32 vcc, v58, v186
	v_or_b32_e32 v58, 32, v0
	s_nop 0
	v_cndmask_b32_e32 v63, v204, v65, vcc
	v_cmp_le_i32_e32 vcc, v58, v186
	v_max3_f32 v57, v57, v62, v63
	s_nop 0
	v_cndmask_b32_e32 v61, v204, v34, vcc
	v_or_b32_e32 v34, 33, v0
	v_cmp_le_i32_e32 vcc, v34, v186
	s_nop 1
	v_cndmask_b32_e32 v60, v204, v35, vcc
	v_or_b32_e32 v35, 34, v0
	v_cmp_le_i32_e32 vcc, v35, v186
	v_or_b32_e32 v35, 35, v0
	v_max3_f32 v34, v57, v61, v60
	v_cndmask_b32_e32 v59, v204, v36, vcc
	v_cmp_le_i32_e32 vcc, v35, v186
	v_or_b32_e32 v36, 43, v0
	s_nop 0
	v_cndmask_b32_e32 v58, v204, v37, vcc
	v_max3_f32 v35, v34, v59, v58
	v_or_b32_e32 v34, 40, v0
	v_cmp_le_i32_e32 vcc, v34, v186
	v_or_b32_e32 v34, 41, v0
	s_nop 0
	v_cndmask_b32_e32 v57, v204, v38, vcc
	v_cmp_le_i32_e32 vcc, v34, v186
	v_or_b32_e32 v38, 49, v0
	s_nop 0
	v_cndmask_b32_e32 v34, v204, v39, vcc
	v_max3_f32 v37, v35, v57, v34
	v_or_b32_e32 v35, 42, v0
	v_cmp_le_i32_e32 vcc, v35, v186
	s_nop 1
	v_cndmask_b32_e32 v35, v204, v40, vcc
	v_cmp_le_i32_e32 vcc, v36, v186
	v_or_b32_e32 v40, 51, v0
	s_nop 0
	v_cndmask_b32_e32 v36, v204, v41, vcc
	v_max3_f32 v39, v37, v35, v36
	v_or_b32_e32 v37, 48, v0
	v_cmp_le_i32_e32 vcc, v37, v186
	s_nop 1
	v_cndmask_b32_e32 v37, v204, v42, vcc
	v_cmp_le_i32_e32 vcc, v38, v186
	v_or_b32_e32 v42, 57, v0
	s_nop 0
	v_cndmask_b32_e32 v38, v204, v43, vcc
	v_max3_f32 v41, v39, v37, v38
	v_or_b32_e32 v39, 50, v0
	v_cmp_le_i32_e32 vcc, v39, v186
	s_nop 1
	v_cndmask_b32_e32 v39, v204, v44, vcc
	v_cmp_le_i32_e32 vcc, v40, v186
	s_nop 1
	v_cndmask_b32_e32 v40, v204, v45, vcc
	v_max3_f32 v43, v41, v39, v40
	v_or_b32_e32 v41, 56, v0
	v_cmp_le_i32_e32 vcc, v41, v186
	s_nop 1
	v_cndmask_b32_e32 v41, v204, v46, vcc
	v_cmp_le_i32_e32 vcc, v42, v186
	v_and_b32_e32 v46, 64, v202
	v_add_u32_e32 v46, 64, v46
	v_cndmask_b32_e32 v42, v204, v47, vcc
	v_max3_f32 v45, v43, v41, v42
	v_or_b32_e32 v43, 58, v0
	v_cmp_le_i32_e32 vcc, v43, v186
	v_or_b32_e32 v0, 59, v0
	s_nop 0
	v_cndmask_b32_e32 v43, v204, v48, vcc
	v_cmp_le_i32_e32 vcc, v0, v186
	s_nop 1
	v_cndmask_b32_e32 v44, v204, v49, vcc
	v_max3_f32 v0, v45, v43, v44
	v_xor_b32_e32 v45, 32, v202
	v_cmp_lt_i32_e32 vcc, v45, v46
	s_nop 1
	v_cndmask_b32_e32 v45, v202, v45, vcc
	v_lshlrev_b32_e32 v45, 2, v45
	ds_bpermute_b32 v45, v45, v0
	s_waitcnt lgkmcnt(0)
	v_max_f32_e32 v45, v45, v45
	v_max_f32_e32 v0, v0, v45
	v_mul_f32_e32 v0, 0x3fb8aa3b, v0
	v_cndmask_b32_e64 v0, v0, v204, s[6:7]
	v_sub_f32_e32 v232, v0, v215
	v_cmp_lt_f32_e32 vcc, 0x41000000, v232
	s_nop 1
	v_cndmask_b32_e32 v211, v215, v0, vcc
	v_sub_f32_e32 v0, v212, v211
	v_exp_f32_e32 v0, v0
	v_cmp_neq_f32_e32 vcc, v211, v212
	s_cbranch_vccz .LBB0_844
	v_pk_mul_f32 v[32:33], v[32:33], v[0:1] op_sel_hi:[1,0]
	v_pk_mul_f32 v[30:31], v[30:31], v[0:1] op_sel_hi:[1,0]
	v_pk_mul_f32 v[28:29], v[28:29], v[0:1] op_sel_hi:[1,0]
	v_pk_mul_f32 v[26:27], v[26:27], v[0:1] op_sel_hi:[1,0]
	v_pk_mul_f32 v[24:25], v[24:25], v[0:1] op_sel_hi:[1,0]
	v_pk_mul_f32 v[22:23], v[22:23], v[0:1] op_sel_hi:[1,0]
	v_pk_mul_f32 v[20:21], v[20:21], v[0:1] op_sel_hi:[1,0]
	v_pk_mul_f32 v[18:19], v[18:19], v[0:1] op_sel_hi:[1,0]
	v_pk_mul_f32 v[16:17], v[16:17], v[0:1] op_sel_hi:[1,0]
	v_pk_mul_f32 v[14:15], v[14:15], v[0:1] op_sel_hi:[1,0]
	v_pk_mul_f32 v[12:13], v[12:13], v[0:1] op_sel_hi:[1,0]
	v_pk_mul_f32 v[10:11], v[10:11], v[0:1] op_sel_hi:[1,0]
	v_pk_mul_f32 v[8:9], v[8:9], v[0:1] op_sel_hi:[1,0]
	v_pk_mul_f32 v[6:7], v[6:7], v[0:1] op_sel_hi:[1,0]
	v_pk_mul_f32 v[4:5], v[4:5], v[0:1] op_sel_hi:[1,0]
	v_pk_mul_f32 v[2:3], v[2:3], v[0:1] op_sel_hi:[1,0]

;     ...
;   f32x16 s[2];
; #pragma unroll
;   for (int k2 = 0; k2 < 2; ++k2) {
;     if (!(HM & (1 << k2))) continue;
; #pragma unroll
;     for (int i = 0; i < 16; ++i) s[k2][i] = 0.f;
; #pragma unroll
;     for (int ks = 0; ks < 4; ++ks) {
;       const bf16x8 a = *(const bf16x8*)(Ks + (32 * k2 + r) * LSTR + 16 * ks + 8 * h);
;       s[k2] = mfma32(a, qf[ks], s[k2]);
;     }
;   }
;   if (MODE == 1) {
; #pragma unroll
;     for (int k2 = 0; k2 < 2; ++k2)
; #pragma unroll
;       for (int g = 0; g < 4; ++g) {
;         if (!(HM & (1 << k2))) continue;
;         const f32x4 cv = *(const f32x4*)(cn_lds + key0 + 32 * k2 + 8 * g + 4 * h);
; #pragma unroll
;         for (int e = 0; e < 4; ++e) s[k2][4 * g + e] = fmaf(s[k2][4 * g + e], L2E, cv[e]);
;       }
;   }
;   float mx = NINF;
; #pragma unroll
;   for (int k2 = 0; k2 < 2; ++k2)
; #pragma unroll
;     for (int i = 0; i < 16; ++i) {
;       if (!(HM & (1 << k2))) continue;
;       float v = s[k2][i];
;       if (MASKED) {
;         const int tk = key0 + 32 * k2 + crow(i, h);
;         const bool valid = (MODE == 0) ? ((tk <= tq) && (tq - tk <= maxdist)) : (tk <= tq);
;         v = valid ? v : NINF; s[k2][i] = v;
;       }
;       mx = fmaxf(mx, v);
;     }
;   mx = fmaxf(mx, __shfl_xor(mx, 32));
;   if (MODE != 1) mx *= L2E;
;   if (MODE == 2) mx = lanesel ? mx : NINF;
;   const float mn = fmaxf(m, mx); const float alpha = __builtin_amdgcn_exp2f(m - mn);
;   const float neg = (MODE == 2 && !lanesel) ? NINF : -mn;
;   float ps = 0.f;
; #pragma unroll
;   for (int k2 = 0; k2 < 2; ++k2)
; #pragma unroll
; template <int MODE>
; DI void flash_loop(char* smem, const bf16_t* Kbase, size_t ldk, const bf16_t* Vtbase, size_t ldv, ull tiles, ull wtiles,
;                    const bf16x8 (&qf)[4], f32x16 (&o)[2], float& m, float& l, int tq, int tqmin, int tqmax, int maxdist, const float* cn_lds, ull lmask) {
;     ...
;     if (!((wtiles >> kt) & 1ull)) return;
;     const bf16_t* Ks = (const bf16_t*)(smem + stage * (2 * 64 * LSTR * 2)); const bf16_t* Vs = Ks + 64 * LSTR;
;     const bool sel = ((lmask >> kt) & 1ull) != 0;
;     const bool interior = (64 * kt + 63 <= tqmin) && (MODE != 0 || (tqmax - 64 * kt <= maxdist));
;     int hm = 3;
;     if (MODE == 0) {
;       hm = 0;
;       if (64 * kt <= tqmax && 64 * kt + 31 >= tqmin - maxdist) hm |= 1;
;       if (64 * kt + 32 <= tqmax && 64 * kt + 63 >= tqmin - maxdist) hm |= 2;
;     }
.LBB0_923:
	s_lshr_b64 s[6:7], s[8:9], s33
	s_and_b32 s58, s6, 1
	s_cmp_eq_u64 s[58:59], 0
	s_cbranch_scc1 .LBB0_947
	s_lshl_b32 s58, s33, 6
	s_or_b32 s33, s58, 63
	s_cmp_le_u32 s58, s29
	s_cselect_b64 s[6:7], -1, 0
	s_or_b32 s36, s58, 31
	s_cmp_ge_i32 s36, s28
	s_cselect_b64 s[36:37], -1, 0
	s_and_b64 s[6:7], s[6:7], s[36:37]
	v_cndmask_b32_e64 v0, 0, 1, s[6:7]
	s_or_b32 s6, s58, 32
	s_cmp_gt_u32 s6, s29
	s_cselect_b64 s[6:7], -1, 0
	s_cmp_lt_i32 s33, s28
	s_cselect_b64 s[36:37], -1, 0
	v_readfirstlane_b32 s38, v0
	s_or_b32 s39, s38, 2
	s_or_b64 s[6:7], s[6:7], s[36:37]
	s_and_b64 s[6:7], s[6:7], exec
	s_cselect_b32 s68, s38, s39
	s_mov_b64 s[62:63], -1
	s_mov_b64 s[54:55], 0
	s_cmp_lt_i32 s68, 2
	s_mov_b64 s[6:7], 0
	s_cbranch_scc1 .LBB0_940
	s_cmp_eq_u32 s68, 2
	s_mov_b64 s[6:7], -1
	s_cbranch_scc0 .LBB0_929
	ds_read_b128 v[34:37], v199 offset:4608
	ds_read_b128 v[50:53], v199 offset:4640
	v_or_b32_e32 v0, s58, v197
	s_waitcnt lgkmcnt(1)
	v_mfma_f32_32x32x16_bf16 v[34:49], v[34:37], v[98:101], 0
	s_waitcnt lgkmcnt(0)
	v_mfma_f32_32x32x16_bf16 v[34:49], v[50:53], v[102:105], v[34:49]
	ds_read_b128 v[50:53], v199 offset:4672
	s_waitcnt lgkmcnt(0)
	v_mfma_f32_32x32x16_bf16 v[34:49], v[50:53], v[106:109], v[34:49]
	ds_read_b128 v[50:53], v199 offset:4704
	s_waitcnt lgkmcnt(0)
	v_mfma_f32_32x32x16_bf16 v[34:49], v[50:53], v[110:113], v[34:49]
	v_or_b32_e32 v50, 32, v0
	v_cmp_gt_u32_e32 vcc, v50, v157
	v_cmp_lt_i32_e64 s[6:7], v50, v147
	s_or_b64 vcc, vcc, s[6:7]
	s_nop 7
	v_cndmask_b32_e32 v66, v34, v204, vcc
	v_bitop3_b32 v34, s58, v205, v197 bitop3:0x36
	v_cmp_ge_u32_e32 vcc, v50, v157
	v_cmp_gt_i32_e64 s[6:7], v34, v158
	s_or_b64 vcc, vcc, s[6:7]
	v_cndmask_b32_e32 v67, v35, v204, vcc
	v_or_b32_e32 v35, 34, v0
	v_cmp_gt_u32_e32 vcc, v35, v157
	v_cmp_lt_i32_e64 s[6:7], v35, v147
	s_or_b64 vcc, vcc, s[6:7]
	v_or_b32_e32 v35, 35, v0
	v_cndmask_b32_e32 v68, v36, v204, vcc
	v_cmp_gt_u32_e32 vcc, v35, v157
	v_cmp_lt_i32_e64 s[6:7], v35, v147
	s_or_b64 vcc, vcc, s[6:7]
	v_or_b32_e32 v35, 40, v0
	v_cndmask_b32_e32 v69, v37, v204, vcc
	v_cmp_gt_u32_e32 vcc, v35, v157
	v_cmp_lt_i32_e64 s[6:7], v35, v147
	s_or_b64 vcc, vcc, s[6:7]
	v_or_b32_e32 v35, 41, v0
	v_cndmask_b32_e32 v70, v38, v204, vcc
	v_cmp_gt_u32_e32 vcc, v35, v157
	v_cmp_lt_i32_e64 s[6:7], v35, v147
	s_or_b64 vcc, vcc, s[6:7]
	v_or_b32_e32 v35, 42, v0
	v_cndmask_b32_e32 v71, v39, v204, vcc
	v_cmp_gt_u32_e32 vcc, v35, v157
	v_cmp_lt_i32_e64 s[6:7], v35, v147
	s_or_b64 vcc, vcc, s[6:7]
	v_or_b32_e32 v35, 43, v0
	v_cndmask_b32_e32 v77, v40, v204, vcc
	v_cmp_gt_u32_e32 vcc, v35, v157
	v_cmp_lt_i32_e64 s[6:7], v35, v147
	s_or_b64 vcc, vcc, s[6:7]
	v_or_b32_e32 v35, 48, v0
	v_cndmask_b32_e32 v78, v41, v204, vcc
	v_cmp_gt_u32_e32 vcc, v35, v157
	v_cmp_lt_i32_e64 s[6:7], v35, v147
	s_or_b64 vcc, vcc, s[6:7]
	v_or_b32_e32 v35, 49, v0
	v_cndmask_b32_e32 v79, v42, v204, vcc
	v_cmp_gt_u32_e32 vcc, v35, v157
	v_cmp_lt_i32_e64 s[6:7], v35, v147
	s_or_b64 vcc, vcc, s[6:7]
	v_or_b32_e32 v35, 50, v0
	v_cndmask_b32_e32 v80, v43, v204, vcc
	v_cmp_gt_u32_e32 vcc, v35, v157
	v_cmp_lt_i32_e64 s[6:7], v35, v147
	s_or_b64 vcc, vcc, s[6:7]
	v_or_b32_e32 v35, 51, v0
	v_cndmask_b32_e32 v81, v44, v204, vcc
	v_cmp_gt_u32_e32 vcc, v35, v157
	v_cmp_lt_i32_e64 s[6:7], v35, v147
	s_or_b64 vcc, vcc, s[6:7]
	v_or_b32_e32 v35, 56, v0
	v_cndmask_b32_e32 v76, v45, v204, vcc
	v_cmp_gt_u32_e32 vcc, v35, v157
	v_cmp_lt_i32_e64 s[6:7], v35, v147
	s_or_b64 vcc, vcc, s[6:7]
	v_or_b32_e32 v35, 57, v0
	v_max3_f32 v34, v66, s35, v67
	v_cndmask_b32_e32 v73, v46, v204, vcc
	v_cmp_gt_u32_e32 vcc, v35, v157
	v_cmp_lt_i32_e64 s[6:7], v35, v147
	v_max3_f32 v34, v34, v68, v69
	s_or_b64 vcc, vcc, s[6:7]
	v_or_b32_e32 v35, 58, v0
	v_max3_f32 v34, v34, v70, v71
	v_cndmask_b32_e32 v74, v47, v204, vcc
	v_cmp_gt_u32_e32 vcc, v35, v157
	v_cmp_lt_i32_e64 s[6:7], v35, v147
	v_max3_f32 v34, v34, v77, v78
	s_or_b64 vcc, vcc, s[6:7]
	v_or_b32_e32 v0, 59, v0
	v_max3_f32 v34, v34, v79, v80
	v_cndmask_b32_e32 v75, v48, v204, vcc
	v_cmp_gt_u32_e32 vcc, v0, v157
	v_cmp_lt_i32_e64 s[6:7], v0, v147
	v_max3_f32 v34, v34, v81, v76
	s_or_b64 vcc, vcc, s[6:7]
	v_max3_f32 v34, v34, v73, v74
	v_cndmask_b32_e32 v72, v49, v204, vcc
	v_and_b32_e32 v35, 64, v202
	v_max3_f32 v0, v34, v75, v72
	v_xor_b32_e32 v34, 32, v202
	v_add_u32_e32 v35, 64, v35
	v_cmp_lt_i32_e32 vcc, v34, v35
	s_nop 1
	v_cndmask_b32_e32 v34, v202, v34, vcc
	v_lshlrev_b32_e32 v34, 2, v34
	ds_bpermute_b32 v34, v34, v0
	s_waitcnt lgkmcnt(0)
	v_max_f32_e32 v34, v34, v34
	v_max_f32_e32 v0, v0, v34
	v_mul_f32_e32 v0, 0x3fb8aa3b, v0
	v_max_f32_e32 v34, v159, v159
	v_sub_f32_e32 v232, v0, v34
	v_cmp_lt_f32_e32 vcc, 0x41000000, v232
	s_nop 1
	v_cndmask_b32_e32 v160, v34, v0, vcc
	v_sub_f32_e32 v0, v159, v160
	v_exp_f32_e32 v0, v0
	v_cmp_neq_f32_e32 vcc, v160, v159
	s_cbranch_vccz .LBB0_928
	v_pk_mul_f32 v[32:33], v[32:33], v[0:1] op_sel_hi:[1,0]
	v_pk_mul_f32 v[30:31], v[30:31], v[0:1] op_sel_hi:[1,0]
	v_pk_mul_f32 v[28:29], v[28:29], v[0:1] op_sel_hi:[1,0]
	v_pk_mul_f32 v[26:27], v[26:27], v[0:1] op_sel_hi:[1,0]
	v_pk_mul_f32 v[24:25], v[24:25], v[0:1] op_sel_hi:[1,0]
	v_pk_mul_f32 v[22:23], v[22:23], v[0:1] op_sel_hi:[1,0]
	v_pk_mul_f32 v[20:21], v[20:21], v[0:1] op_sel_hi:[1,0]
	v_pk_mul_f32 v[18:19], v[18:19], v[0:1] op_sel_hi:[1,0]
	v_pk_mul_f32 v[16:17], v[16:17], v[0:1] op_sel_hi:[1,0]
	v_pk_mul_f32 v[14:15], v[14:15], v[0:1] op_sel_hi:[1,0]
	v_pk_mul_f32 v[12:13], v[12:13], v[0:1] op_sel_hi:[1,0]
	v_pk_mul_f32 v[10:11], v[10:11], v[0:1] op_sel_hi:[1,0]
	v_pk_mul_f32 v[8:9], v[8:9], v[0:1] op_sel_hi:[1,0]
	v_pk_mul_f32 v[6:7], v[6:7], v[0:1] op_sel_hi:[1,0]
	v_pk_mul_f32 v[4:5], v[4:5], v[0:1] op_sel_hi:[1,0]
	v_pk_mul_f32 v[2:3], v[2:3], v[0:1] op_sel_hi:[1,0]

; DI f32x16 mfma32(bf16x8 a, bf16x8 b, f32x16 c) { return __builtin_amdgcn_mfma_f32_32x32x16_bf16(a, b, c, 0, 0, 0); }
; DI int crow(int i, int h) { return (i & 3) + 8 * (i >> 2) + 4 * h; }
;     ...
;   f32x16 s[2];
; #pragma unroll
;   for (int k2 = 0; k2 < 2; ++k2) {
;     if (!(HM & (1 << k2))) continue;
; #pragma unroll
;     for (int i = 0; i < 16; ++i) s[k2][i] = 0.f;
; #pragma unroll
;     for (int ks = 0; ks < 4; ++ks) {
;       const bf16x8 a = *(const bf16x8*)(Ks + (32 * k2 + r) * LSTR + 16 * ks + 8 * h);
;       s[k2] = mfma32(a, qf[ks], s[k2]);
;     }
;   }
;   if (MODE == 1) {
; #pragma unroll
;     for (int k2 = 0; k2 < 2; ++k2)
; #pragma unroll
;       for (int g = 0; g < 4; ++g) {
;         if (!(HM & (1 << k2))) continue;
;         const f32x4 cv = *(const f32x4*)(cn_lds + key0 + 32 * k2 + 8 * g + 4 * h);
; #pragma unroll
;         for (int e = 0; e < 4; ++e) s[k2][4 * g + e] = fmaf(s[k2][4 * g + e], L2E, cv[e]);
;       }
;   }
;   float mx = NINF;
; #pragma unroll
;   for (int k2 = 0; k2 < 2; ++k2)
; #pragma unroll
;     for (int i = 0; i < 16; ++i) {
;       if (!(HM & (1 << k2))) continue;
;       float v = s[k2][i];
;       if (MASKED) {
;         const int tk = key0 + 32 * k2 + crow(i, h);
;         const bool valid = (MODE == 0) ? ((tk <= tq) && (tq - tk <= maxdist)) : (tk <= tq);
;         v = valid ? v : NINF; s[k2][i] = v;
;       }
;       mx = fmaxf(mx, v);
;     }
.LBB0_931:
	ds_read_b128 v[82:85], v196
	ds_read_b128 v[78:81], v196 offset:32
	ds_read_b128 v[74:77], v196 offset:64
	ds_read_b128 v[66:69], v196 offset:96
	ds_read_b128 v[70:73], v196 offset:4608
	s_cmp_le_u32 s33, s5
	s_cselect_b64 s[6:7], -1, 0
	s_cmp_ge_i32 s58, s30
	s_cselect_b64 s[36:37], -1, 0
	s_and_b64 s[6:7], s[6:7], s[36:37]
	s_andn2_b64 vcc, exec, s[6:7]
	s_mov_b64 s[6:7], -1
	s_cbranch_vccz .LBB0_935
	s_waitcnt lgkmcnt(4)
	v_mfma_f32_32x32x16_bf16 v[50:65], v[82:85], v[98:101], 0
	ds_read_b128 v[86:89], v196 offset:4640
	ds_read_b128 v[90:93], v196 offset:4672
	v_or_b32_e32 v0, s58, v197
	v_cmp_gt_u32_e32 vcc, v0, v157
	v_cmp_lt_i32_e64 s[6:7], v0, v147
	s_or_b64 vcc, vcc, s[6:7]
	s_waitcnt lgkmcnt(5)
	v_mfma_f32_32x32x16_bf16 v[50:65], v[78:81], v[102:105], v[50:65]
	s_waitcnt lgkmcnt(2)
	v_mfma_f32_32x32x16_bf16 v[34:49], v[70:73], v[98:101], 0
	v_mfma_f32_32x32x16_bf16 v[50:65], v[74:77], v[106:109], v[50:65]
	s_waitcnt lgkmcnt(1)
	v_mfma_f32_32x32x16_bf16 v[34:49], v[86:89], v[102:105], v[34:49]
	ds_read_b128 v[86:89], v196 offset:4704
	v_mfma_f32_32x32x16_bf16 v[50:65], v[66:69], v[110:113], v[50:65]
	s_waitcnt lgkmcnt(1)
	v_mfma_f32_32x32x16_bf16 v[34:49], v[90:93], v[106:109], v[34:49]
	s_waitcnt lgkmcnt(0)
	v_mfma_f32_32x32x16_bf16 v[34:49], v[86:89], v[110:113], v[34:49]
	s_nop 7
	v_cndmask_b32_e32 v86, v50, v204, vcc
	v_bitop3_b32 v50, s58, v197, s58 bitop3:3
	v_cmp_ge_u32_e32 vcc, v0, v157
	v_cmp_lt_i32_e64 s[6:7], v158, v50
	s_or_b64 vcc, vcc, s[6:7]
	v_cndmask_b32_e32 v87, v51, v204, vcc
	v_or_b32_e32 v51, 2, v0
	v_cmp_gt_u32_e32 vcc, v51, v157
	v_cmp_lt_i32_e64 s[6:7], v51, v147
	s_or_b64 vcc, vcc, s[6:7]
	v_or_b32_e32 v51, 3, v0
	v_cndmask_b32_e32 v88, v52, v204, vcc
	v_cmp_gt_u32_e32 vcc, v51, v157
	v_cmp_lt_i32_e64 s[6:7], v51, v147
	s_or_b64 vcc, vcc, s[6:7]
	v_or_b32_e32 v51, 8, v0
	v_cndmask_b32_e32 v89, v53, v204, vcc
	v_cmp_gt_u32_e32 vcc, v51, v157
	v_cmp_lt_i32_e64 s[6:7], v51, v147
	s_or_b64 vcc, vcc, s[6:7]
	v_or_b32_e32 v51, 9, v0
	v_cndmask_b32_e32 v90, v54, v204, vcc
	v_cmp_gt_u32_e32 vcc, v51, v157
	v_cmp_lt_i32_e64 s[6:7], v51, v147
	s_or_b64 vcc, vcc, s[6:7]
	v_or_b32_e32 v51, 10, v0
	v_cndmask_b32_e32 v194, v55, v204, vcc
	v_cmp_gt_u32_e32 vcc, v51, v157
	v_cmp_lt_i32_e64 s[6:7], v51, v147
	s_or_b64 vcc, vcc, s[6:7]
	v_or_b32_e32 v51, 11, v0
	v_cndmask_b32_e32 v193, v56, v204, vcc
	v_cmp_gt_u32_e32 vcc, v51, v157
	v_cmp_lt_i32_e64 s[6:7], v51, v147
	s_or_b64 vcc, vcc, s[6:7]
	v_or_b32_e32 v51, 16, v0
	v_cndmask_b32_e32 v195, v57, v204, vcc
	v_cmp_gt_u32_e32 vcc, v51, v157
	v_cmp_lt_i32_e64 s[6:7], v51, v147
	s_or_b64 vcc, vcc, s[6:7]
	v_or_b32_e32 v51, 17, v0
	v_cndmask_b32_e32 v190, v58, v204, vcc
	v_cmp_gt_u32_e32 vcc, v51, v157
	v_cmp_lt_i32_e64 s[6:7], v51, v147
	s_or_b64 vcc, vcc, s[6:7]
	v_or_b32_e32 v51, 18, v0
	v_cndmask_b32_e32 v192, v59, v204, vcc
	v_cmp_gt_u32_e32 vcc, v51, v157
	v_cmp_lt_i32_e64 s[6:7], v51, v147
	s_or_b64 vcc, vcc, s[6:7]
	v_or_b32_e32 v51, 19, v0
	v_cndmask_b32_e32 v191, v60, v204, vcc
	v_cmp_gt_u32_e32 vcc, v51, v157
	v_cmp_lt_i32_e64 s[6:7], v51, v147
	s_or_b64 vcc, vcc, s[6:7]
	v_or_b32_e32 v51, 24, v0
	v_cndmask_b32_e32 v189, v61, v204, vcc
	v_cmp_gt_u32_e32 vcc, v51, v157
	v_cmp_lt_i32_e64 s[6:7], v51, v147
	s_or_b64 vcc, vcc, s[6:7]
	v_or_b32_e32 v51, 25, v0
	v_cndmask_b32_e32 v188, v62, v204, vcc
	v_cmp_gt_u32_e32 vcc, v51, v157
	v_cmp_lt_i32_e64 s[6:7], v51, v147
	s_or_b64 vcc, vcc, s[6:7]
	v_or_b32_e32 v51, 26, v0
	v_cndmask_b32_e32 v187, v63, v204, vcc
	v_cmp_gt_u32_e32 vcc, v51, v157
	v_cmp_lt_i32_e64 s[6:7], v51, v147
	s_or_b64 vcc, vcc, s[6:7]
	v_or_b32_e32 v51, 27, v0
	v_cndmask_b32_e32 v186, v64, v204, vcc
	v_cmp_gt_u32_e32 vcc, v51, v157
	v_cmp_lt_i32_e64 s[6:7], v51, v147
	s_or_b64 vcc, vcc, s[6:7]
	v_or_b32_e32 v51, 32, v0
	v_cndmask_b32_e32 v184, v65, v204, vcc
	v_cmp_gt_u32_e32 vcc, v51, v157
	v_cmp_lt_i32_e64 s[6:7], v51, v147
	s_or_b64 vcc, vcc, s[6:7]
	v_cndmask_b32_e32 v180, v34, v204, vcc
	v_or_b32_e32 v34, 33, v0
	v_cmp_gt_u32_e32 vcc, v34, v157
	v_cmp_lt_i32_e64 s[6:7], v34, v147
	s_or_b64 vcc, vcc, s[6:7]
	v_cndmask_b32_e32 v164, v35, v204, vcc
	v_or_b32_e32 v35, 34, v0
	v_cmp_gt_u32_e32 vcc, v35, v157
; DI int crow(int i, int h) { return (i & 3) + 8 * (i >> 2) + 4 * h; }
;     ...
;     for (int i = 0; i < 16; ++i) {
;       if (!(HM & (1 << k2))) continue;
;       float v = s[k2][i];
;       if (MASKED) {
;         const int tk = key0 + 32 * k2 + crow(i, h);
;         const bool valid = (MODE == 0) ? ((tk <= tq) && (tq - tk <= maxdist)) : (tk <= tq);
;         v = valid ? v : NINF; s[k2][i] = v;
;       }
;       mx = fmaxf(mx, v);
;     }
;   mx = fmaxf(mx, __shfl_xor(mx, 32));
;   if (MODE != 1) mx *= L2E;
;   if (MODE == 2) mx = lanesel ? mx : NINF;
;   const float mn = fmaxf(m, mx); const float alpha = __builtin_amdgcn_exp2f(m - mn);
;   const float neg = (MODE == 2 && !lanesel) ? NINF : -mn;
;   float ps = 0.f;
; #pragma unroll
;   for (int k2 = 0; k2 < 2; ++k2)
; #pragma unroll
;     for (int i = 0; i < 16; ++i) {
;       if (!(HM & (1 << k2))) continue;
;       const float pv = (MODE == 1) ? __builtin_amdgcn_exp2f(s[k2][i] + neg) : __builtin_amdgcn_exp2f(fmaf(s[k2][i], L2E, neg));
;       s[k2][i] = pv; ps += pv;
;     }
;   l = l * alpha + ps;
;   if (__builtin_amdgcn_ballot_w64(mn != m) != 0ull) {
; #pragma unroll
;     for (int dt = 0; dt < 2; ++dt)
; #pragma unroll
;       for (int i = 0; i < 16; ++i) o[dt][i] *= alpha;
;   }
	v_cmp_lt_i32_e64 s[6:7], v35, v147
	s_or_b64 vcc, vcc, s[6:7]
	v_or_b32_e32 v35, 35, v0
	v_cndmask_b32_e32 v162, v36, v204, vcc
	v_cmp_gt_u32_e32 vcc, v35, v157
	v_cmp_lt_i32_e64 s[6:7], v35, v147
	s_or_b64 vcc, vcc, s[6:7]
	v_or_b32_e32 v35, 40, v0
	v_cndmask_b32_e32 v97, v37, v204, vcc
	v_cmp_gt_u32_e32 vcc, v35, v157
	v_cmp_lt_i32_e64 s[6:7], v35, v147
	s_or_b64 vcc, vcc, s[6:7]
	v_or_b32_e32 v35, 41, v0
	v_cndmask_b32_e32 v92, v38, v204, vcc
	v_cmp_gt_u32_e32 vcc, v35, v157
	v_cmp_lt_i32_e64 s[6:7], v35, v147
	s_or_b64 vcc, vcc, s[6:7]
	v_or_b32_e32 v35, 42, v0
	v_cndmask_b32_e32 v91, v39, v204, vcc
	v_cmp_gt_u32_e32 vcc, v35, v157
	v_cmp_lt_i32_e64 s[6:7], v35, v147
	s_or_b64 vcc, vcc, s[6:7]
	v_or_b32_e32 v35, 43, v0
	v_cndmask_b32_e32 v93, v40, v204, vcc
	v_cmp_gt_u32_e32 vcc, v35, v157
	v_cmp_lt_i32_e64 s[6:7], v35, v147
	s_or_b64 vcc, vcc, s[6:7]
	v_or_b32_e32 v35, 48, v0
	v_cndmask_b32_e32 v94, v41, v204, vcc
	v_cmp_gt_u32_e32 vcc, v35, v157
	v_cmp_lt_i32_e64 s[6:7], v35, v147
	s_or_b64 vcc, vcc, s[6:7]
	v_or_b32_e32 v35, 49, v0
	v_max3_f32 v50, v86, s35, v87
	v_cndmask_b32_e32 v95, v42, v204, vcc
	v_cmp_gt_u32_e32 vcc, v35, v157
	v_cmp_lt_i32_e64 s[6:7], v35, v147
	v_max3_f32 v50, v50, v88, v89
	s_or_b64 vcc, vcc, s[6:7]
	v_or_b32_e32 v35, 50, v0
	v_max3_f32 v50, v50, v90, v194
	v_cndmask_b32_e32 v96, v43, v204, vcc
	v_cmp_gt_u32_e32 vcc, v35, v157
	v_cmp_lt_i32_e64 s[6:7], v35, v147
	v_max3_f32 v50, v50, v193, v195
	s_or_b64 vcc, vcc, s[6:7]
	v_or_b32_e32 v35, 51, v0
	v_max3_f32 v50, v50, v190, v192
	v_cndmask_b32_e32 v163, v44, v204, vcc
	v_cmp_gt_u32_e32 vcc, v35, v157
	v_cmp_lt_i32_e64 s[6:7], v35, v147
	v_max3_f32 v50, v50, v191, v189
	s_or_b64 vcc, vcc, s[6:7]
	v_or_b32_e32 v35, 56, v0
	v_max3_f32 v50, v50, v188, v187
	v_cndmask_b32_e32 v165, v45, v204, vcc
	v_cmp_gt_u32_e32 vcc, v35, v157
	v_cmp_lt_i32_e64 s[6:7], v35, v147
	v_max3_f32 v50, v50, v186, v184
	s_or_b64 vcc, vcc, s[6:7]
	v_or_b32_e32 v35, 57, v0
	v_max3_f32 v34, v50, v180, v164
	v_cndmask_b32_e32 v181, v46, v204, vcc
	v_cmp_gt_u32_e32 vcc, v35, v157
	v_cmp_lt_i32_e64 s[6:7], v35, v147
	v_max3_f32 v34, v34, v162, v97
	s_or_b64 vcc, vcc, s[6:7]
	v_or_b32_e32 v35, 58, v0
	v_max3_f32 v34, v34, v92, v91
	v_cndmask_b32_e32 v182, v47, v204, vcc
	v_cmp_gt_u32_e32 vcc, v35, v157
	v_cmp_lt_i32_e64 s[6:7], v35, v147
	v_max3_f32 v34, v34, v93, v94
	s_or_b64 vcc, vcc, s[6:7]
	v_or_b32_e32 v0, 59, v0
	v_max3_f32 v34, v34, v95, v96
	v_cndmask_b32_e32 v183, v48, v204, vcc
	v_cmp_gt_u32_e32 vcc, v0, v157
	v_cmp_lt_i32_e64 s[6:7], v0, v147
	v_max3_f32 v34, v34, v163, v165
	s_or_b64 vcc, vcc, s[6:7]
	v_max3_f32 v34, v34, v181, v182
	v_cndmask_b32_e32 v185, v49, v204, vcc
	v_and_b32_e32 v35, 64, v202
	v_max3_f32 v0, v34, v183, v185
	v_xor_b32_e32 v34, 32, v202
	v_add_u32_e32 v35, 64, v35
	v_cmp_lt_i32_e32 vcc, v34, v35
	s_nop 1
	v_cndmask_b32_e32 v34, v202, v34, vcc
	v_lshlrev_b32_e32 v34, 2, v34
	ds_bpermute_b32 v34, v34, v0
	s_waitcnt lgkmcnt(0)
	v_max_f32_e32 v34, v34, v34
	v_max_f32_e32 v0, v0, v34
	v_mul_f32_e32 v0, 0x3fb8aa3b, v0
	v_max_f32_e32 v34, v159, v159
	v_sub_f32_e32 v232, v0, v34
	v_cmp_lt_f32_e32 vcc, 0x41000000, v232
	s_nop 1
	v_cndmask_b32_e32 v160, v34, v0, vcc
	v_sub_f32_e32 v0, v159, v160
	v_exp_f32_e32 v0, v0
	v_cmp_neq_f32_e32 vcc, v160, v159
	s_cbranch_vccz .LBB0_934
	v_pk_mul_f32 v[32:33], v[32:33], v[0:1] op_sel_hi:[1,0]
	v_pk_mul_f32 v[30:31], v[30:31], v[0:1] op_sel_hi:[1,0]
	v_pk_mul_f32 v[28:29], v[28:29], v[0:1] op_sel_hi:[1,0]
	v_pk_mul_f32 v[26:27], v[26:27], v[0:1] op_sel_hi:[1,0]
	v_pk_mul_f32 v[24:25], v[24:25], v[0:1] op_sel_hi:[1,0]
	v_pk_mul_f32 v[22:23], v[22:23], v[0:1] op_sel_hi:[1,0]
	v_pk_mul_f32 v[20:21], v[20:21], v[0:1] op_sel_hi:[1,0]
	v_pk_mul_f32 v[18:19], v[18:19], v[0:1] op_sel_hi:[1,0]
	v_pk_mul_f32 v[16:17], v[16:17], v[0:1] op_sel_hi:[1,0]
	v_pk_mul_f32 v[14:15], v[14:15], v[0:1] op_sel_hi:[1,0]
	v_pk_mul_f32 v[12:13], v[12:13], v[0:1] op_sel_hi:[1,0]
	v_pk_mul_f32 v[10:11], v[10:11], v[0:1] op_sel_hi:[1,0]
	v_pk_mul_f32 v[8:9], v[8:9], v[0:1] op_sel_hi:[1,0]
	v_pk_mul_f32 v[6:7], v[6:7], v[0:1] op_sel_hi:[1,0]
	v_pk_mul_f32 v[4:5], v[4:5], v[0:1] op_sel_hi:[1,0]
	v_pk_mul_f32 v[2:3], v[2:3], v[0:1] op_sel_hi:[1,0]

; DI f32x16 mfma32(bf16x8 a, bf16x8 b, f32x16 c) { return __builtin_amdgcn_mfma_f32_32x32x16_bf16(a, b, c, 0, 0, 0); }
; DI int crow(int i, int h) { return (i & 3) + 8 * (i >> 2) + 4 * h; }
;     ...
;   f32x16 s[2];
; #pragma unroll
;   for (int k2 = 0; k2 < 2; ++k2) {
;     if (!(HM & (1 << k2))) continue;
; #pragma unroll
;     for (int i = 0; i < 16; ++i) s[k2][i] = 0.f;
; #pragma unroll
;     for (int ks = 0; ks < 4; ++ks) {
;       const bf16x8 a = *(const bf16x8*)(Ks + (32 * k2 + r) * LSTR + 16 * ks + 8 * h);
;       s[k2] = mfma32(a, qf[ks], s[k2]);
;     }
;   }
;   if (MODE == 1) {
; #pragma unroll
;     for (int k2 = 0; k2 < 2; ++k2)
; #pragma unroll
;       for (int g = 0; g < 4; ++g) {
;         if (!(HM & (1 << k2))) continue;
;         const f32x4 cv = *(const f32x4*)(cn_lds + key0 + 32 * k2 + 8 * g + 4 * h);
; #pragma unroll
;         for (int e = 0; e < 4; ++e) s[k2][4 * g + e] = fmaf(s[k2][4 * g + e], L2E, cv[e]);
;       }
;   }
;   float mx = NINF;
; #pragma unroll
;   for (int k2 = 0; k2 < 2; ++k2)
; #pragma unroll
;     for (int i = 0; i < 16; ++i) {
;       if (!(HM & (1 << k2))) continue;
;       float v = s[k2][i];
;       if (MASKED) {
;         const int tk = key0 + 32 * k2 + crow(i, h);
;         const bool valid = (MODE == 0) ? ((tk <= tq) && (tq - tk <= maxdist)) : (tk <= tq);
;         v = valid ? v : NINF; s[k2][i] = v;
;       }
;       mx = fmaxf(mx, v);
;     }
;   mx = fmaxf(mx, __shfl_xor(mx, 32));
;   if (MODE != 1) mx *= L2E;
;   if (MODE == 2) mx = lanesel ? mx : NINF;
;   const float mn = fmaxf(m, mx); const float alpha = __builtin_amdgcn_exp2f(m - mn);
;   const float neg = (MODE == 2 && !lanesel) ? NINF : -mn;
;   float ps = 0.f;
; #pragma unroll
;   for (int k2 = 0; k2 < 2; ++k2)
; #pragma unroll
;     for (int i = 0; i < 16; ++i) {
;       if (!(HM & (1 << k2))) continue;
;       const float pv = (MODE == 1) ? __builtin_amdgcn_exp2f(s[k2][i] + neg) : __builtin_amdgcn_exp2f(fmaf(s[k2][i], L2E, neg));
;       s[k2][i] = pv; ps += pv;
;     }
;   l = l * alpha + ps;
;   if (__builtin_amdgcn_ballot_w64(mn != m) != 0ull) {
; #pragma unroll
;     for (int dt = 0; dt < 2; ++dt)
; #pragma unroll
;       for (int i = 0; i < 16; ++i) o[dt][i] *= alpha;
;   }
.LBB0_935:
	s_and_b64 vcc, exec, s[6:7]
	s_cbranch_vccz .LBB0_939
	s_waitcnt lgkmcnt(4)
	v_mfma_f32_32x32x16_bf16 v[82:97], v[82:85], v[98:101], 0
	s_nop 4
	ds_read_b128 v[34:37], v196 offset:4640
	ds_read_b128 v[38:41], v196 offset:4672
	s_waitcnt lgkmcnt(5)
	v_mfma_f32_32x32x16_bf16 v[82:97], v[78:81], v[102:105], v[82:97]
	s_waitcnt lgkmcnt(4)
	v_mfma_f32_32x32x16_bf16 v[82:97], v[74:77], v[106:109], v[82:97]
	s_waitcnt lgkmcnt(3)
	v_mfma_f32_32x32x16_bf16 v[82:97], v[66:69], v[110:113], v[82:97]
	s_waitcnt lgkmcnt(2)
	v_mfma_f32_32x32x16_bf16 v[66:81], v[70:73], v[98:101], 0
	s_nop 9
	v_max3_f32 v0, v82, s35, v83
	v_max3_f32 v0, v0, v84, v85
	v_max3_f32 v0, v0, v86, v87
	v_max3_f32 v0, v0, v88, v89
	v_max3_f32 v0, v0, v90, v91
	v_max3_f32 v0, v0, v92, v93
	v_max3_f32 v0, v0, v94, v95
	s_waitcnt lgkmcnt(1)
	v_mfma_f32_32x32x16_bf16 v[66:81], v[34:37], v[102:105], v[66:81]
	ds_read_b128 v[34:37], v196 offset:4704
	v_max3_f32 v0, v0, v96, v97
	s_waitcnt lgkmcnt(1)
	v_mfma_f32_32x32x16_bf16 v[66:81], v[38:41], v[106:109], v[66:81]
	s_waitcnt lgkmcnt(0)
	v_mfma_f32_32x32x16_bf16 v[66:81], v[34:37], v[110:113], v[66:81]
	v_and_b32_e32 v35, 64, v202
	v_xor_b32_e32 v34, 32, v202
	v_add_u32_e32 v35, 64, v35
	v_cmp_lt_i32_e32 vcc, v34, v35
	s_nop 1
	v_cndmask_b32_e32 v34, v202, v34, vcc
	s_nop 4
	v_max3_f32 v0, v0, v66, v67
	v_max3_f32 v0, v0, v68, v69
	v_max3_f32 v0, v0, v70, v71
	v_max3_f32 v0, v0, v72, v73
	v_max3_f32 v0, v0, v74, v75
	v_max3_f32 v0, v0, v76, v77
	v_max3_f32 v0, v0, v78, v79
	v_max3_f32 v0, v0, v80, v81
	v_lshlrev_b32_e32 v34, 2, v34
	ds_bpermute_b32 v34, v34, v0
	s_waitcnt lgkmcnt(0)
	v_max_f32_e32 v34, v34, v34
	v_max_f32_e32 v0, v0, v34
	v_mul_f32_e32 v0, 0x3fb8aa3b, v0
	v_max_f32_e32 v34, v159, v159
	v_sub_f32_e32 v232, v0, v34
	v_cmp_lt_f32_e32 vcc, 0x41000000, v232
	s_nop 1
	v_cndmask_b32_e32 v160, v34, v0, vcc
	v_sub_f32_e32 v0, v159, v160
	v_exp_f32_e32 v0, v0
	v_cmp_neq_f32_e32 vcc, v160, v159
	s_cbranch_vccz .LBB0_938
	v_pk_mul_f32 v[32:33], v[32:33], v[0:1] op_sel_hi:[1,0]
	v_pk_mul_f32 v[30:31], v[30:31], v[0:1] op_sel_hi:[1,0]
	v_pk_mul_f32 v[28:29], v[28:29], v[0:1] op_sel_hi:[1,0]
	v_pk_mul_f32 v[26:27], v[26:27], v[0:1] op_sel_hi:[1,0]
	v_pk_mul_f32 v[24:25], v[24:25], v[0:1] op_sel_hi:[1,0]
	v_pk_mul_f32 v[22:23], v[22:23], v[0:1] op_sel_hi:[1,0]
	v_pk_mul_f32 v[20:21], v[20:21], v[0:1] op_sel_hi:[1,0]
	v_pk_mul_f32 v[18:19], v[18:19], v[0:1] op_sel_hi:[1,0]
	v_pk_mul_f32 v[16:17], v[16:17], v[0:1] op_sel_hi:[1,0]
	v_pk_mul_f32 v[14:15], v[14:15], v[0:1] op_sel_hi:[1,0]
	v_pk_mul_f32 v[12:13], v[12:13], v[0:1] op_sel_hi:[1,0]
	v_pk_mul_f32 v[10:11], v[10:11], v[0:1] op_sel_hi:[1,0]
	v_pk_mul_f32 v[8:9], v[8:9], v[0:1] op_sel_hi:[1,0]
	v_pk_mul_f32 v[6:7], v[6:7], v[0:1] op_sel_hi:[1,0]
	v_pk_mul_f32 v[4:5], v[4:5], v[0:1] op_sel_hi:[1,0]
	v_pk_mul_f32 v[2:3], v[2:3], v[0:1] op_sel_hi:[1,0]

; DI f32x16 mfma32(bf16x8 a, bf16x8 b, f32x16 c) { return __builtin_amdgcn_mfma_f32_32x32x16_bf16(a, b, c, 0, 0, 0); }
; DI int crow(int i, int h) { return (i & 3) + 8 * (i >> 2) + 4 * h; }
;     ...
;   f32x16 s[2];
; #pragma unroll
;   for (int k2 = 0; k2 < 2; ++k2) {
;     if (!(HM & (1 << k2))) continue;
; #pragma unroll
;     for (int i = 0; i < 16; ++i) s[k2][i] = 0.f;
; #pragma unroll
;     for (int ks = 0; ks < 4; ++ks) {
;       const bf16x8 a = *(const bf16x8*)(Ks + (32 * k2 + r) * LSTR + 16 * ks + 8 * h);
;       s[k2] = mfma32(a, qf[ks], s[k2]);
;     }
;   }
;   if (MODE == 1) {
; #pragma unroll
;     for (int k2 = 0; k2 < 2; ++k2)
; #pragma unroll
;       for (int g = 0; g < 4; ++g) {
;         if (!(HM & (1 << k2))) continue;
;         const f32x4 cv = *(const f32x4*)(cn_lds + key0 + 32 * k2 + 8 * g + 4 * h);
; #pragma unroll
;         for (int e = 0; e < 4; ++e) s[k2][4 * g + e] = fmaf(s[k2][4 * g + e], L2E, cv[e]);
;       }
;   }
;   float mx = NINF;
; #pragma unroll
;   for (int k2 = 0; k2 < 2; ++k2)
; #pragma unroll
;     for (int i = 0; i < 16; ++i) {
;       if (!(HM & (1 << k2))) continue;
;       float v = s[k2][i];
;       if (MASKED) {
;         const int tk = key0 + 32 * k2 + crow(i, h);
;         const bool valid = (MODE == 0) ? ((tk <= tq) && (tq - tk <= maxdist)) : (tk <= tq);
;         v = valid ? v : NINF; s[k2][i] = v;
;       }
;       mx = fmaxf(mx, v);
;     }
;   mx = fmaxf(mx, __shfl_xor(mx, 32));
;   if (MODE != 1) mx *= L2E;
;   if (MODE == 2) mx = lanesel ? mx : NINF;
;   const float mn = fmaxf(m, mx); const float alpha = __builtin_amdgcn_exp2f(m - mn);
;   const float neg = (MODE == 2 && !lanesel) ? NINF : -mn;
;   float ps = 0.f;
; #pragma unroll
;   for (int k2 = 0; k2 < 2; ++k2)
; #pragma unroll
;     for (int i = 0; i < 16; ++i) {
;       if (!(HM & (1 << k2))) continue;
;       const float pv = (MODE == 1) ? __builtin_amdgcn_exp2f(s[k2][i] + neg) : __builtin_amdgcn_exp2f(fmaf(s[k2][i], L2E, neg));
;       s[k2][i] = pv; ps += pv;
;     }
;   l = l * alpha + ps;
;   if (__builtin_amdgcn_ballot_w64(mn != m) != 0ull) {
; #pragma unroll
;     for (int dt = 0; dt < 2; ++dt)
; #pragma unroll
;       for (int i = 0; i < 16; ++i) o[dt][i] *= alpha;
;   }
.LBB0_943:
	s_nop 6
	ds_read_b128 v[34:37], v196
	s_nop 1
	ds_read_b128 v[50:53], v196 offset:32
	v_or_b32_e32 v0, s58, v197
	v_cmp_gt_u32_e32 vcc, v0, v157
	v_cmp_lt_i32_e64 s[6:7], v0, v147
	s_waitcnt lgkmcnt(1)
	v_mfma_f32_32x32x16_bf16 v[34:49], v[34:37], v[98:101], 0
	s_or_b64 vcc, vcc, s[6:7]
	s_waitcnt lgkmcnt(0)
	v_mfma_f32_32x32x16_bf16 v[34:49], v[50:53], v[102:105], v[34:49]
	ds_read_b128 v[50:53], v196 offset:64
	s_waitcnt lgkmcnt(0)
	v_mfma_f32_32x32x16_bf16 v[34:49], v[50:53], v[106:109], v[34:49]
	ds_read_b128 v[50:53], v196 offset:96
	s_waitcnt lgkmcnt(0)
	v_mfma_f32_32x32x16_bf16 v[34:49], v[50:53], v[110:113], v[34:49]
	v_bitop3_b32 v50, s58, v197, s58 bitop3:3
	v_cmp_lt_i32_e64 s[6:7], v158, v50
	v_or_b32_e32 v51, 2, v0
	s_nop 8
	v_cndmask_b32_e32 v34, v34, v204, vcc
	v_cmp_ge_u32_e32 vcc, v0, v157
	s_or_b64 vcc, vcc, s[6:7]
	v_cmp_lt_i32_e64 s[6:7], v51, v147
	v_cndmask_b32_e32 v35, v35, v204, vcc
	v_cmp_gt_u32_e32 vcc, v51, v157
	s_or_b64 vcc, vcc, s[6:7]
	v_or_b32_e32 v51, 3, v0
	v_cndmask_b32_e32 v36, v36, v204, vcc
	v_cmp_gt_u32_e32 vcc, v51, v157
	v_cmp_lt_i32_e64 s[6:7], v51, v147
	s_or_b64 vcc, vcc, s[6:7]
	v_or_b32_e32 v51, 8, v0
	v_cndmask_b32_e32 v37, v37, v204, vcc
	v_cmp_gt_u32_e32 vcc, v51, v157
	v_cmp_lt_i32_e64 s[6:7], v51, v147
	s_or_b64 vcc, vcc, s[6:7]
	v_or_b32_e32 v51, 9, v0
	v_cndmask_b32_e32 v38, v38, v204, vcc
	v_cmp_gt_u32_e32 vcc, v51, v157
	v_cmp_lt_i32_e64 s[6:7], v51, v147
	v_max3_f32 v50, v34, s35, v35
	s_or_b64 vcc, vcc, s[6:7]
	v_max3_f32 v50, v50, v36, v37
	v_cndmask_b32_e32 v39, v39, v204, vcc
	v_max3_f32 v52, v50, v38, v39
	v_or_b32_e32 v50, 10, v0
	v_cmp_gt_u32_e32 vcc, v50, v157
	v_cmp_lt_i32_e64 s[6:7], v50, v147
	s_or_b64 vcc, vcc, s[6:7]
	v_cndmask_b32_e32 v50, v40, v204, vcc
	v_or_b32_e32 v40, 11, v0
	v_cmp_gt_u32_e32 vcc, v40, v157
	v_cmp_lt_i32_e64 s[6:7], v40, v147
	s_or_b64 vcc, vcc, s[6:7]
	v_cndmask_b32_e32 v51, v41, v204, vcc
	v_or_b32_e32 v41, 16, v0
	v_cmp_gt_u32_e32 vcc, v41, v157
	v_cmp_lt_i32_e64 s[6:7], v41, v147
	s_or_b64 vcc, vcc, s[6:7]
	v_or_b32_e32 v41, 17, v0
	v_max3_f32 v40, v52, v50, v51
	v_cndmask_b32_e32 v52, v42, v204, vcc
	v_cmp_gt_u32_e32 vcc, v41, v157
	v_cmp_lt_i32_e64 s[6:7], v41, v147
	s_or_b64 vcc, vcc, s[6:7]
	v_or_b32_e32 v41, 18, v0
	v_cndmask_b32_e32 v53, v43, v204, vcc
	v_cmp_gt_u32_e32 vcc, v41, v157
	v_cmp_lt_i32_e64 s[6:7], v41, v147
	s_or_b64 vcc, vcc, s[6:7]
	v_or_b32_e32 v41, 19, v0
	v_cndmask_b32_e32 v54, v44, v204, vcc
	v_cmp_gt_u32_e32 vcc, v41, v157
	v_cmp_lt_i32_e64 s[6:7], v41, v147
	s_or_b64 vcc, vcc, s[6:7]
	v_or_b32_e32 v41, 24, v0
	v_cndmask_b32_e32 v44, v45, v204, vcc
	v_cmp_gt_u32_e32 vcc, v41, v157
	v_cmp_lt_i32_e64 s[6:7], v41, v147
	s_or_b64 vcc, vcc, s[6:7]
	v_or_b32_e32 v42, 25, v0
	v_cndmask_b32_e32 v41, v46, v204, vcc
	v_cmp_gt_u32_e32 vcc, v42, v157
	v_cmp_lt_i32_e64 s[6:7], v42, v147
	v_max3_f32 v40, v40, v52, v53
	s_or_b64 vcc, vcc, s[6:7]
	v_max3_f32 v40, v40, v54, v44
	v_cndmask_b32_e32 v42, v47, v204, vcc
	v_max3_f32 v45, v40, v41, v42
	v_or_b32_e32 v40, 26, v0
	v_cmp_gt_u32_e32 vcc, v40, v157
	v_cmp_lt_i32_e64 s[6:7], v40, v147
	s_or_b64 vcc, vcc, s[6:7]
	v_or_b32_e32 v0, 27, v0
	v_cndmask_b32_e32 v43, v48, v204, vcc
	v_cmp_gt_u32_e32 vcc, v0, v157
	v_cmp_lt_i32_e64 s[6:7], v0, v147
	s_or_b64 vcc, vcc, s[6:7]
	v_cndmask_b32_e32 v40, v49, v204, vcc
	v_and_b32_e32 v46, 64, v202
	v_max3_f32 v0, v45, v43, v40
	v_xor_b32_e32 v45, 32, v202
	v_add_u32_e32 v46, 64, v46
	v_cmp_lt_i32_e32 vcc, v45, v46
	s_nop 1
	v_cndmask_b32_e32 v45, v202, v45, vcc
	v_lshlrev_b32_e32 v45, 2, v45
	ds_bpermute_b32 v45, v45, v0
	s_waitcnt lgkmcnt(0)
	v_max_f32_e32 v45, v45, v45
	v_max_f32_e32 v0, v0, v45
	v_mul_f32_e32 v0, 0x3fb8aa3b, v0
	v_max_f32_e32 v45, v159, v159
	v_sub_f32_e32 v232, v0, v45
	v_cmp_lt_f32_e32 vcc, 0x41000000, v232
	s_nop 1
	v_cndmask_b32_e32 v160, v45, v0, vcc
	v_sub_f32_e32 v0, v159, v160
	v_exp_f32_e32 v0, v0
	v_cmp_neq_f32_e32 vcc, v160, v159
	s_cbranch_vccz .LBB0_945
	v_pk_mul_f32 v[32:33], v[32:33], v[0:1] op_sel_hi:[1,0]
	v_pk_mul_f32 v[30:31], v[30:31], v[0:1] op_sel_hi:[1,0]
	v_pk_mul_f32 v[28:29], v[28:29], v[0:1] op_sel_hi:[1,0]
	v_pk_mul_f32 v[26:27], v[26:27], v[0:1] op_sel_hi:[1,0]
	v_pk_mul_f32 v[24:25], v[24:25], v[0:1] op_sel_hi:[1,0]
	v_pk_mul_f32 v[22:23], v[22:23], v[0:1] op_sel_hi:[1,0]
	v_pk_mul_f32 v[20:21], v[20:21], v[0:1] op_sel_hi:[1,0]
	v_pk_mul_f32 v[18:19], v[18:19], v[0:1] op_sel_hi:[1,0]
	v_pk_mul_f32 v[16:17], v[16:17], v[0:1] op_sel_hi:[1,0]
	v_pk_mul_f32 v[14:15], v[14:15], v[0:1] op_sel_hi:[1,0]
	v_pk_mul_f32 v[12:13], v[12:13], v[0:1] op_sel_hi:[1,0]
	v_pk_mul_f32 v[10:11], v[10:11], v[0:1] op_sel_hi:[1,0]
	v_pk_mul_f32 v[8:9], v[8:9], v[0:1] op_sel_hi:[1,0]
	v_pk_mul_f32 v[6:7], v[6:7], v[0:1] op_sel_hi:[1,0]
	v_pk_mul_f32 v[4:5], v[4:5], v[0:1] op_sel_hi:[1,0]
	v_pk_mul_f32 v[2:3], v[2:3], v[0:1] op_sel_hi:[1,0]

;     ...
;   f32x16 s[2];
; #pragma unroll
;   for (int k2 = 0; k2 < 2; ++k2) {
;     if (!(HM & (1 << k2))) continue;
; #pragma unroll
;     for (int i = 0; i < 16; ++i) s[k2][i] = 0.f;
; #pragma unroll
;     for (int ks = 0; ks < 4; ++ks) {
;       const bf16x8 a = *(const bf16x8*)(Ks + (32 * k2 + r) * LSTR + 16 * ks + 8 * h);
;       s[k2] = mfma32(a, qf[ks], s[k2]);
;     }
;   }
;   if (MODE == 1) {
; #pragma unroll
;     for (int k2 = 0; k2 < 2; ++k2)
; #pragma unroll
;       for (int g = 0; g < 4; ++g) {
;         if (!(HM & (1 << k2))) continue;
;         const f32x4 cv = *(const f32x4*)(cn_lds + key0 + 32 * k2 + 8 * g + 4 * h);
; #pragma unroll
;         for (int e = 0; e < 4; ++e) s[k2][4 * g + e] = fmaf(s[k2][4 * g + e], L2E, cv[e]);
;       }
;   }
;   float mx = NINF;
; #pragma unroll
;   for (int k2 = 0; k2 < 2; ++k2)
; #pragma unroll
;     for (int i = 0; i < 16; ++i) {
;       if (!(HM & (1 << k2))) continue;
;       float v = s[k2][i];
;       if (MASKED) {
;         const int tk = key0 + 32 * k2 + crow(i, h);
;         const bool valid = (MODE == 0) ? ((tk <= tq) && (tq - tk <= maxdist)) : (tk <= tq);
;         v = valid ? v : NINF; s[k2][i] = v;
;       }
;       mx = fmaxf(mx, v);
;     }
;   mx = fmaxf(mx, __shfl_xor(mx, 32));
;   if (MODE != 1) mx *= L2E;
;   if (MODE == 2) mx = lanesel ? mx : NINF;
; template <int MODE>
; DI void flash_loop(char* smem, const bf16_t* Kbase, size_t ldk, const bf16_t* Vtbase, size_t ldv, ull tiles, ull wtiles,
;                    const bf16x8 (&qf)[4], f32x16 (&o)[2], float& m, float& l, int tq, int tqmin, int tqmax, int maxdist, const float* cn_lds, ull lmask) {
;     ...
;     if (!((wtiles >> kt) & 1ull)) return;
;     const bf16_t* Ks = (const bf16_t*)(smem + stage * (2 * 64 * LSTR * 2)); const bf16_t* Vs = Ks + 64 * LSTR;
;     const bool sel = ((lmask >> kt) & 1ull) != 0;
;     const bool interior = (64 * kt + 63 <= tqmin) && (MODE != 0 || (tqmax - 64 * kt <= maxdist));
;     int hm = 3;
;     if (MODE == 0) {
;       hm = 0;
;       if (64 * kt <= tqmax && 64 * kt + 31 >= tqmin - maxdist) hm |= 1;
;       if (64 * kt + 32 <= tqmax && 64 * kt + 63 >= tqmin - maxdist) hm |= 2;
;     }
;     if (MODE == 0 && hm == 1) attn_tile<MODE, true, 1>(Ks, Vs, qf, o, m, l, 64 * kt, tq, maxdist, cn_lds, sel);
;     else if (MODE == 0 && hm == 2) attn_tile<MODE, true, 2>(Ks, Vs, qf, o, m, l, 64 * kt, tq, maxdist, cn_lds, sel);
.LBB0_951:
	s_lshr_b64 s[6:7], s[8:9], s67
	s_and_b32 s58, s6, 1
	s_cmp_eq_u64 s[58:59], 0
	s_cbranch_scc1 .LBB0_975
	s_lshl_b32 s58, s67, 6
	s_or_b32 s33, s58, 63
	s_cmp_le_u32 s58, s29
	s_cselect_b64 s[6:7], -1, 0
	s_or_b32 s36, s58, 31
	s_cmp_ge_i32 s36, s28
	s_cselect_b64 s[36:37], -1, 0
	s_and_b64 s[6:7], s[6:7], s[36:37]
	v_cndmask_b32_e64 v0, 0, 1, s[6:7]
	s_or_b32 s6, s58, 32
	s_cmp_gt_u32 s6, s29
	s_cselect_b64 s[6:7], -1, 0
	s_cmp_lt_i32 s33, s28
	s_cselect_b64 s[36:37], -1, 0
	v_readfirstlane_b32 s38, v0
	s_or_b32 s39, s38, 2
	s_or_b64 s[6:7], s[6:7], s[36:37]
	s_and_b64 s[6:7], s[6:7], exec
	s_cselect_b32 s67, s38, s39
	s_mov_b64 s[62:63], -1
	s_mov_b64 s[54:55], 0
	s_cmp_lt_i32 s67, 2
	s_mov_b64 s[6:7], 0
	s_cbranch_scc1 .LBB0_968
	s_cmp_eq_u32 s67, 2
	s_mov_b64 s[6:7], -1
	s_cbranch_scc0 .LBB0_957
	ds_read_b128 v[34:37], v199 offset:23040
	ds_read_b128 v[50:53], v199 offset:23072
	v_or_b32_e32 v0, s58, v197
	s_waitcnt lgkmcnt(1)
	v_mfma_f32_32x32x16_bf16 v[34:49], v[34:37], v[98:101], 0
	s_waitcnt lgkmcnt(0)
	v_mfma_f32_32x32x16_bf16 v[34:49], v[50:53], v[102:105], v[34:49]
	ds_read_b128 v[50:53], v199 offset:23104
	s_waitcnt lgkmcnt(0)
	v_mfma_f32_32x32x16_bf16 v[34:49], v[50:53], v[106:109], v[34:49]
	ds_read_b128 v[50:53], v199 offset:23136
	s_waitcnt lgkmcnt(0)
	v_mfma_f32_32x32x16_bf16 v[34:49], v[50:53], v[110:113], v[34:49]
	v_or_b32_e32 v50, 32, v0
	v_cmp_gt_u32_e32 vcc, v50, v157
	v_cmp_lt_i32_e64 s[6:7], v50, v147
	s_or_b64 vcc, vcc, s[6:7]
	s_nop 7
	v_cndmask_b32_e32 v66, v34, v204, vcc
	v_bitop3_b32 v34, s58, v205, v197 bitop3:0x36
	v_cmp_ge_u32_e32 vcc, v50, v157
	v_cmp_gt_i32_e64 s[6:7], v34, v158
	s_or_b64 vcc, vcc, s[6:7]
	v_cndmask_b32_e32 v67, v35, v204, vcc
	v_or_b32_e32 v35, 34, v0
	v_cmp_gt_u32_e32 vcc, v35, v157
	v_cmp_lt_i32_e64 s[6:7], v35, v147
	s_or_b64 vcc, vcc, s[6:7]
	v_or_b32_e32 v35, 35, v0
	v_cndmask_b32_e32 v68, v36, v204, vcc
	v_cmp_gt_u32_e32 vcc, v35, v157
	v_cmp_lt_i32_e64 s[6:7], v35, v147
	s_or_b64 vcc, vcc, s[6:7]
	v_or_b32_e32 v35, 40, v0
	v_cndmask_b32_e32 v69, v37, v204, vcc
	v_cmp_gt_u32_e32 vcc, v35, v157
	v_cmp_lt_i32_e64 s[6:7], v35, v147
	s_or_b64 vcc, vcc, s[6:7]
	v_or_b32_e32 v35, 41, v0
	v_cndmask_b32_e32 v70, v38, v204, vcc
	v_cmp_gt_u32_e32 vcc, v35, v157
	v_cmp_lt_i32_e64 s[6:7], v35, v147
	s_or_b64 vcc, vcc, s[6:7]
	v_or_b32_e32 v35, 42, v0
	v_cndmask_b32_e32 v71, v39, v204, vcc
	v_cmp_gt_u32_e32 vcc, v35, v157
	v_cmp_lt_i32_e64 s[6:7], v35, v147
	s_or_b64 vcc, vcc, s[6:7]
	v_or_b32_e32 v35, 43, v0
	v_cndmask_b32_e32 v76, v40, v204, vcc
	v_cmp_gt_u32_e32 vcc, v35, v157
	v_cmp_lt_i32_e64 s[6:7], v35, v147
	s_or_b64 vcc, vcc, s[6:7]
	v_or_b32_e32 v35, 48, v0
	v_cndmask_b32_e32 v77, v41, v204, vcc
	v_cmp_gt_u32_e32 vcc, v35, v157
	v_cmp_lt_i32_e64 s[6:7], v35, v147
	s_or_b64 vcc, vcc, s[6:7]
	v_or_b32_e32 v35, 49, v0
	v_cndmask_b32_e32 v78, v42, v204, vcc
	v_cmp_gt_u32_e32 vcc, v35, v157
	v_cmp_lt_i32_e64 s[6:7], v35, v147
	s_or_b64 vcc, vcc, s[6:7]
	v_or_b32_e32 v35, 50, v0
	v_cndmask_b32_e32 v79, v43, v204, vcc
	v_cmp_gt_u32_e32 vcc, v35, v157
	v_cmp_lt_i32_e64 s[6:7], v35, v147
	s_or_b64 vcc, vcc, s[6:7]
	v_or_b32_e32 v35, 51, v0
	v_cndmask_b32_e32 v80, v44, v204, vcc
	v_cmp_gt_u32_e32 vcc, v35, v157
	v_cmp_lt_i32_e64 s[6:7], v35, v147
	s_or_b64 vcc, vcc, s[6:7]
	v_or_b32_e32 v35, 56, v0
	v_cndmask_b32_e32 v81, v45, v204, vcc
	v_cmp_gt_u32_e32 vcc, v35, v157
	v_cmp_lt_i32_e64 s[6:7], v35, v147
	s_or_b64 vcc, vcc, s[6:7]
	v_or_b32_e32 v35, 57, v0
	v_max3_f32 v34, v66, s35, v67
	v_cndmask_b32_e32 v73, v46, v204, vcc
	v_cmp_gt_u32_e32 vcc, v35, v157
	v_cmp_lt_i32_e64 s[6:7], v35, v147
	v_max3_f32 v34, v34, v68, v69
	s_or_b64 vcc, vcc, s[6:7]
	v_or_b32_e32 v35, 58, v0
	v_max3_f32 v34, v34, v70, v71
	v_cndmask_b32_e32 v74, v47, v204, vcc
	v_cmp_gt_u32_e32 vcc, v35, v157
	v_cmp_lt_i32_e64 s[6:7], v35, v147
	v_max3_f32 v34, v34, v76, v77
	s_or_b64 vcc, vcc, s[6:7]
	v_or_b32_e32 v0, 59, v0
	v_max3_f32 v34, v34, v78, v79
	v_cndmask_b32_e32 v75, v48, v204, vcc
	v_cmp_gt_u32_e32 vcc, v0, v157
	v_cmp_lt_i32_e64 s[6:7], v0, v147
	v_max3_f32 v34, v34, v80, v81
	s_or_b64 vcc, vcc, s[6:7]
	v_max3_f32 v34, v34, v73, v74
	v_cndmask_b32_e32 v72, v49, v204, vcc
	v_and_b32_e32 v35, 64, v202
	v_max3_f32 v0, v34, v75, v72
	v_xor_b32_e32 v34, 32, v202
	v_add_u32_e32 v35, 64, v35
	v_cmp_lt_i32_e32 vcc, v34, v35
	s_nop 1
	v_cndmask_b32_e32 v34, v202, v34, vcc
	v_lshlrev_b32_e32 v34, 2, v34
	ds_bpermute_b32 v34, v34, v0
	s_waitcnt lgkmcnt(0)
	v_max_f32_e32 v34, v34, v34
	v_max_f32_e32 v0, v0, v34
	v_mul_f32_e32 v0, 0x3fb8aa3b, v0
	v_max_f32_e32 v34, v160, v160
	v_sub_f32_e32 v232, v0, v34
	v_cmp_lt_f32_e32 vcc, 0x41000000, v232
	s_nop 1
	v_cndmask_b32_e32 v159, v34, v0, vcc
	v_sub_f32_e32 v0, v160, v159
	v_exp_f32_e32 v0, v0
	v_cmp_neq_f32_e32 vcc, v159, v160
	s_cbranch_vccz .LBB0_956
	v_pk_mul_f32 v[32:33], v[32:33], v[0:1] op_sel_hi:[1,0]
	v_pk_mul_f32 v[30:31], v[30:31], v[0:1] op_sel_hi:[1,0]
	v_pk_mul_f32 v[28:29], v[28:29], v[0:1] op_sel_hi:[1,0]
	v_pk_mul_f32 v[26:27], v[26:27], v[0:1] op_sel_hi:[1,0]
	v_pk_mul_f32 v[24:25], v[24:25], v[0:1] op_sel_hi:[1,0]
	v_pk_mul_f32 v[22:23], v[22:23], v[0:1] op_sel_hi:[1,0]
	v_pk_mul_f32 v[20:21], v[20:21], v[0:1] op_sel_hi:[1,0]
	v_pk_mul_f32 v[18:19], v[18:19], v[0:1] op_sel_hi:[1,0]
	v_pk_mul_f32 v[16:17], v[16:17], v[0:1] op_sel_hi:[1,0]
	v_pk_mul_f32 v[14:15], v[14:15], v[0:1] op_sel_hi:[1,0]
	v_pk_mul_f32 v[12:13], v[12:13], v[0:1] op_sel_hi:[1,0]
	v_pk_mul_f32 v[10:11], v[10:11], v[0:1] op_sel_hi:[1,0]
	v_pk_mul_f32 v[8:9], v[8:9], v[0:1] op_sel_hi:[1,0]
	v_pk_mul_f32 v[6:7], v[6:7], v[0:1] op_sel_hi:[1,0]
	v_pk_mul_f32 v[4:5], v[4:5], v[0:1] op_sel_hi:[1,0]
	v_pk_mul_f32 v[2:3], v[2:3], v[0:1] op_sel_hi:[1,0]

; DI f32x16 mfma32(bf16x8 a, bf16x8 b, f32x16 c) { return __builtin_amdgcn_mfma_f32_32x32x16_bf16(a, b, c, 0, 0, 0); }
; DI int crow(int i, int h) { return (i & 3) + 8 * (i >> 2) + 4 * h; }
;     ...
;   f32x16 s[2];
; #pragma unroll
;   for (int k2 = 0; k2 < 2; ++k2) {
;     if (!(HM & (1 << k2))) continue;
; #pragma unroll
;     for (int i = 0; i < 16; ++i) s[k2][i] = 0.f;
; #pragma unroll
;     for (int ks = 0; ks < 4; ++ks) {
;       const bf16x8 a = *(const bf16x8*)(Ks + (32 * k2 + r) * LSTR + 16 * ks + 8 * h);
;       s[k2] = mfma32(a, qf[ks], s[k2]);
;     }
;   }
;   if (MODE == 1) {
; #pragma unroll
;     for (int k2 = 0; k2 < 2; ++k2)
; #pragma unroll
;       for (int g = 0; g < 4; ++g) {
;         if (!(HM & (1 << k2))) continue;
;         const f32x4 cv = *(const f32x4*)(cn_lds + key0 + 32 * k2 + 8 * g + 4 * h);
; #pragma unroll
;         for (int e = 0; e < 4; ++e) s[k2][4 * g + e] = fmaf(s[k2][4 * g + e], L2E, cv[e]);
;       }
;   }
;   float mx = NINF;
; #pragma unroll
;   for (int k2 = 0; k2 < 2; ++k2)
; #pragma unroll
;     for (int i = 0; i < 16; ++i) {
;       if (!(HM & (1 << k2))) continue;
;       float v = s[k2][i];
;       if (MASKED) {
;         const int tk = key0 + 32 * k2 + crow(i, h);
;         const bool valid = (MODE == 0) ? ((tk <= tq) && (tq - tk <= maxdist)) : (tk <= tq);
;         v = valid ? v : NINF; s[k2][i] = v;
;       }
;       mx = fmaxf(mx, v);
;     }
.LBB0_959:
	ds_read_b128 v[82:85], v196 offset:18432
	ds_read_b128 v[78:81], v196 offset:18464
	ds_read_b128 v[74:77], v196 offset:18496
	ds_read_b128 v[66:69], v196 offset:18528
	ds_read_b128 v[70:73], v196 offset:23040
	s_cmp_le_u32 s33, s5
	s_cselect_b64 s[6:7], -1, 0
	s_cmp_ge_i32 s58, s30
	s_cselect_b64 s[36:37], -1, 0
	s_and_b64 s[6:7], s[6:7], s[36:37]
	s_andn2_b64 vcc, exec, s[6:7]
	s_mov_b64 s[6:7], -1
	s_cbranch_vccz .LBB0_963
	s_waitcnt lgkmcnt(4)
	v_mfma_f32_32x32x16_bf16 v[50:65], v[82:85], v[98:101], 0
	ds_read_b128 v[86:89], v196 offset:23072
	ds_read_b128 v[90:93], v196 offset:23104
	v_or_b32_e32 v0, s58, v197
	v_cmp_gt_u32_e32 vcc, v0, v157
	v_cmp_lt_i32_e64 s[6:7], v0, v147
	s_or_b64 vcc, vcc, s[6:7]
	s_waitcnt lgkmcnt(5)
	v_mfma_f32_32x32x16_bf16 v[50:65], v[78:81], v[102:105], v[50:65]
	s_waitcnt lgkmcnt(2)
	v_mfma_f32_32x32x16_bf16 v[34:49], v[70:73], v[98:101], 0
	v_mfma_f32_32x32x16_bf16 v[50:65], v[74:77], v[106:109], v[50:65]
	s_waitcnt lgkmcnt(1)
	v_mfma_f32_32x32x16_bf16 v[34:49], v[86:89], v[102:105], v[34:49]
	ds_read_b128 v[86:89], v196 offset:23136
	v_mfma_f32_32x32x16_bf16 v[50:65], v[66:69], v[110:113], v[50:65]
	s_waitcnt lgkmcnt(1)
	v_mfma_f32_32x32x16_bf16 v[34:49], v[90:93], v[106:109], v[34:49]
	s_waitcnt lgkmcnt(0)
	v_mfma_f32_32x32x16_bf16 v[34:49], v[86:89], v[110:113], v[34:49]
	s_nop 7
	v_cndmask_b32_e32 v86, v50, v204, vcc
	v_bitop3_b32 v50, s58, v197, s58 bitop3:3
	v_cmp_ge_u32_e32 vcc, v0, v157
	v_cmp_lt_i32_e64 s[6:7], v158, v50
	s_or_b64 vcc, vcc, s[6:7]
	v_cndmask_b32_e32 v87, v51, v204, vcc
	v_or_b32_e32 v51, 2, v0
	v_cmp_gt_u32_e32 vcc, v51, v157
	v_cmp_lt_i32_e64 s[6:7], v51, v147
	s_or_b64 vcc, vcc, s[6:7]
	v_or_b32_e32 v51, 3, v0
	v_cndmask_b32_e32 v88, v52, v204, vcc
	v_cmp_gt_u32_e32 vcc, v51, v157
	v_cmp_lt_i32_e64 s[6:7], v51, v147
	s_or_b64 vcc, vcc, s[6:7]
	v_or_b32_e32 v51, 8, v0
	v_cndmask_b32_e32 v89, v53, v204, vcc
	v_cmp_gt_u32_e32 vcc, v51, v157
	v_cmp_lt_i32_e64 s[6:7], v51, v147
	s_or_b64 vcc, vcc, s[6:7]
	v_or_b32_e32 v51, 9, v0
	v_cndmask_b32_e32 v90, v54, v204, vcc
	v_cmp_gt_u32_e32 vcc, v51, v157
	v_cmp_lt_i32_e64 s[6:7], v51, v147
	s_or_b64 vcc, vcc, s[6:7]
	v_or_b32_e32 v51, 10, v0
	v_cndmask_b32_e32 v194, v55, v204, vcc
	v_cmp_gt_u32_e32 vcc, v51, v157
	v_cmp_lt_i32_e64 s[6:7], v51, v147
	s_or_b64 vcc, vcc, s[6:7]
	v_or_b32_e32 v51, 11, v0
	v_cndmask_b32_e32 v193, v56, v204, vcc
	v_cmp_gt_u32_e32 vcc, v51, v157
	v_cmp_lt_i32_e64 s[6:7], v51, v147
	s_or_b64 vcc, vcc, s[6:7]
	v_or_b32_e32 v51, 16, v0
	v_cndmask_b32_e32 v195, v57, v204, vcc
	v_cmp_gt_u32_e32 vcc, v51, v157
	v_cmp_lt_i32_e64 s[6:7], v51, v147
	s_or_b64 vcc, vcc, s[6:7]
	v_or_b32_e32 v51, 17, v0
	v_cndmask_b32_e32 v190, v58, v204, vcc
	v_cmp_gt_u32_e32 vcc, v51, v157
	v_cmp_lt_i32_e64 s[6:7], v51, v147
	s_or_b64 vcc, vcc, s[6:7]
	v_or_b32_e32 v51, 18, v0
	v_cndmask_b32_e32 v192, v59, v204, vcc
	v_cmp_gt_u32_e32 vcc, v51, v157
	v_cmp_lt_i32_e64 s[6:7], v51, v147
	s_or_b64 vcc, vcc, s[6:7]
	v_or_b32_e32 v51, 19, v0
	v_cndmask_b32_e32 v191, v60, v204, vcc
	v_cmp_gt_u32_e32 vcc, v51, v157
	v_cmp_lt_i32_e64 s[6:7], v51, v147
	s_or_b64 vcc, vcc, s[6:7]
	v_or_b32_e32 v51, 24, v0
	v_cndmask_b32_e32 v189, v61, v204, vcc
	v_cmp_gt_u32_e32 vcc, v51, v157
	v_cmp_lt_i32_e64 s[6:7], v51, v147
	s_or_b64 vcc, vcc, s[6:7]
	v_or_b32_e32 v51, 25, v0
	v_cndmask_b32_e32 v188, v62, v204, vcc
	v_cmp_gt_u32_e32 vcc, v51, v157
	v_cmp_lt_i32_e64 s[6:7], v51, v147
	s_or_b64 vcc, vcc, s[6:7]
	v_or_b32_e32 v51, 26, v0
	v_cndmask_b32_e32 v187, v63, v204, vcc
	v_cmp_gt_u32_e32 vcc, v51, v157
	v_cmp_lt_i32_e64 s[6:7], v51, v147
	s_or_b64 vcc, vcc, s[6:7]
	v_or_b32_e32 v51, 27, v0
	v_cndmask_b32_e32 v186, v64, v204, vcc
	v_cmp_gt_u32_e32 vcc, v51, v157
	v_cmp_lt_i32_e64 s[6:7], v51, v147
	s_or_b64 vcc, vcc, s[6:7]
	v_or_b32_e32 v51, 32, v0
	v_cndmask_b32_e32 v184, v65, v204, vcc
	v_cmp_gt_u32_e32 vcc, v51, v157
	v_cmp_lt_i32_e64 s[6:7], v51, v147
	s_or_b64 vcc, vcc, s[6:7]
	v_cndmask_b32_e32 v180, v34, v204, vcc
	v_or_b32_e32 v34, 33, v0
	v_cmp_gt_u32_e32 vcc, v34, v157
	v_cmp_lt_i32_e64 s[6:7], v34, v147
	s_or_b64 vcc, vcc, s[6:7]
	v_cndmask_b32_e32 v164, v35, v204, vcc
	v_or_b32_e32 v35, 34, v0
	v_cmp_gt_u32_e32 vcc, v35, v157
; DI int crow(int i, int h) { return (i & 3) + 8 * (i >> 2) + 4 * h; }
;     ...
;     for (int i = 0; i < 16; ++i) {
;       if (!(HM & (1 << k2))) continue;
;       float v = s[k2][i];
;       if (MASKED) {
;         const int tk = key0 + 32 * k2 + crow(i, h);
;         const bool valid = (MODE == 0) ? ((tk <= tq) && (tq - tk <= maxdist)) : (tk <= tq);
;         v = valid ? v : NINF; s[k2][i] = v;
;       }
;       mx = fmaxf(mx, v);
;     }
;   mx = fmaxf(mx, __shfl_xor(mx, 32));
;   if (MODE != 1) mx *= L2E;
;   if (MODE == 2) mx = lanesel ? mx : NINF;
;   const float mn = fmaxf(m, mx); const float alpha = __builtin_amdgcn_exp2f(m - mn);
;   const float neg = (MODE == 2 && !lanesel) ? NINF : -mn;
;   float ps = 0.f;
; #pragma unroll
;   for (int k2 = 0; k2 < 2; ++k2)
; #pragma unroll
;     for (int i = 0; i < 16; ++i) {
;       if (!(HM & (1 << k2))) continue;
;       const float pv = (MODE == 1) ? __builtin_amdgcn_exp2f(s[k2][i] + neg) : __builtin_amdgcn_exp2f(fmaf(s[k2][i], L2E, neg));
;       s[k2][i] = pv; ps += pv;
;     }
;   l = l * alpha + ps;
;   if (__builtin_amdgcn_ballot_w64(mn != m) != 0ull) {
; #pragma unroll
;     for (int dt = 0; dt < 2; ++dt)
; #pragma unroll
;       for (int i = 0; i < 16; ++i) o[dt][i] *= alpha;
;   }
	v_cmp_lt_i32_e64 s[6:7], v35, v147
	s_or_b64 vcc, vcc, s[6:7]
	v_or_b32_e32 v35, 35, v0
	v_cndmask_b32_e32 v161, v36, v204, vcc
	v_cmp_gt_u32_e32 vcc, v35, v157
	v_cmp_lt_i32_e64 s[6:7], v35, v147
	s_or_b64 vcc, vcc, s[6:7]
	v_or_b32_e32 v35, 40, v0
	v_cndmask_b32_e32 v97, v37, v204, vcc
	v_cmp_gt_u32_e32 vcc, v35, v157
	v_cmp_lt_i32_e64 s[6:7], v35, v147
	s_or_b64 vcc, vcc, s[6:7]
	v_or_b32_e32 v35, 41, v0
	v_cndmask_b32_e32 v92, v38, v204, vcc
	v_cmp_gt_u32_e32 vcc, v35, v157
	v_cmp_lt_i32_e64 s[6:7], v35, v147
	s_or_b64 vcc, vcc, s[6:7]
	v_or_b32_e32 v35, 42, v0
	v_cndmask_b32_e32 v91, v39, v204, vcc
	v_cmp_gt_u32_e32 vcc, v35, v157
	v_cmp_lt_i32_e64 s[6:7], v35, v147
	s_or_b64 vcc, vcc, s[6:7]
	v_or_b32_e32 v35, 43, v0
	v_cndmask_b32_e32 v93, v40, v204, vcc
	v_cmp_gt_u32_e32 vcc, v35, v157
	v_cmp_lt_i32_e64 s[6:7], v35, v147
	s_or_b64 vcc, vcc, s[6:7]
	v_or_b32_e32 v35, 48, v0
	v_cndmask_b32_e32 v94, v41, v204, vcc
	v_cmp_gt_u32_e32 vcc, v35, v157
	v_cmp_lt_i32_e64 s[6:7], v35, v147
	s_or_b64 vcc, vcc, s[6:7]
	v_or_b32_e32 v35, 49, v0
	v_max3_f32 v50, v86, s35, v87
	v_cndmask_b32_e32 v95, v42, v204, vcc
	v_cmp_gt_u32_e32 vcc, v35, v157
	v_cmp_lt_i32_e64 s[6:7], v35, v147
	v_max3_f32 v50, v50, v88, v89
	s_or_b64 vcc, vcc, s[6:7]
	v_or_b32_e32 v35, 50, v0
	v_max3_f32 v50, v50, v90, v194
	v_cndmask_b32_e32 v96, v43, v204, vcc
	v_cmp_gt_u32_e32 vcc, v35, v157
	v_cmp_lt_i32_e64 s[6:7], v35, v147
	v_max3_f32 v50, v50, v193, v195
	s_or_b64 vcc, vcc, s[6:7]
	v_or_b32_e32 v35, 51, v0
	v_max3_f32 v50, v50, v190, v192
	v_cndmask_b32_e32 v163, v44, v204, vcc
	v_cmp_gt_u32_e32 vcc, v35, v157
	v_cmp_lt_i32_e64 s[6:7], v35, v147
	v_max3_f32 v50, v50, v191, v189
	s_or_b64 vcc, vcc, s[6:7]
	v_or_b32_e32 v35, 56, v0
	v_max3_f32 v50, v50, v188, v187
	v_cndmask_b32_e32 v165, v45, v204, vcc
	v_cmp_gt_u32_e32 vcc, v35, v157
	v_cmp_lt_i32_e64 s[6:7], v35, v147
	v_max3_f32 v50, v50, v186, v184
	s_or_b64 vcc, vcc, s[6:7]
	v_or_b32_e32 v35, 57, v0
	v_max3_f32 v34, v50, v180, v164
	v_cndmask_b32_e32 v181, v46, v204, vcc
	v_cmp_gt_u32_e32 vcc, v35, v157
	v_cmp_lt_i32_e64 s[6:7], v35, v147
	v_max3_f32 v34, v34, v161, v97
	s_or_b64 vcc, vcc, s[6:7]
	v_or_b32_e32 v35, 58, v0
	v_max3_f32 v34, v34, v92, v91
	v_cndmask_b32_e32 v182, v47, v204, vcc
	v_cmp_gt_u32_e32 vcc, v35, v157
	v_cmp_lt_i32_e64 s[6:7], v35, v147
	v_max3_f32 v34, v34, v93, v94
	s_or_b64 vcc, vcc, s[6:7]
	v_or_b32_e32 v0, 59, v0
	v_max3_f32 v34, v34, v95, v96
	v_cndmask_b32_e32 v183, v48, v204, vcc
	v_cmp_gt_u32_e32 vcc, v0, v157
	v_cmp_lt_i32_e64 s[6:7], v0, v147
	v_max3_f32 v34, v34, v163, v165
	s_or_b64 vcc, vcc, s[6:7]
	v_max3_f32 v34, v34, v181, v182
	v_cndmask_b32_e32 v185, v49, v204, vcc
	v_and_b32_e32 v35, 64, v202
	v_max3_f32 v0, v34, v183, v185
	v_xor_b32_e32 v34, 32, v202
	v_add_u32_e32 v35, 64, v35
	v_cmp_lt_i32_e32 vcc, v34, v35
	s_nop 1
	v_cndmask_b32_e32 v34, v202, v34, vcc
	v_lshlrev_b32_e32 v34, 2, v34
	ds_bpermute_b32 v34, v34, v0
	s_waitcnt lgkmcnt(0)
	v_max_f32_e32 v34, v34, v34
	v_max_f32_e32 v0, v0, v34
	v_mul_f32_e32 v0, 0x3fb8aa3b, v0
	v_max_f32_e32 v34, v160, v160
	v_sub_f32_e32 v232, v0, v34
	v_cmp_lt_f32_e32 vcc, 0x41000000, v232
	s_nop 1
	v_cndmask_b32_e32 v159, v34, v0, vcc
	v_sub_f32_e32 v0, v160, v159
	v_exp_f32_e32 v0, v0
	v_cmp_neq_f32_e32 vcc, v159, v160
	s_cbranch_vccz .LBB0_962
	v_pk_mul_f32 v[32:33], v[32:33], v[0:1] op_sel_hi:[1,0]
	v_pk_mul_f32 v[30:31], v[30:31], v[0:1] op_sel_hi:[1,0]
	v_pk_mul_f32 v[28:29], v[28:29], v[0:1] op_sel_hi:[1,0]
	v_pk_mul_f32 v[26:27], v[26:27], v[0:1] op_sel_hi:[1,0]
	v_pk_mul_f32 v[24:25], v[24:25], v[0:1] op_sel_hi:[1,0]
	v_pk_mul_f32 v[22:23], v[22:23], v[0:1] op_sel_hi:[1,0]
	v_pk_mul_f32 v[20:21], v[20:21], v[0:1] op_sel_hi:[1,0]
	v_pk_mul_f32 v[18:19], v[18:19], v[0:1] op_sel_hi:[1,0]
	v_pk_mul_f32 v[16:17], v[16:17], v[0:1] op_sel_hi:[1,0]
	v_pk_mul_f32 v[14:15], v[14:15], v[0:1] op_sel_hi:[1,0]
	v_pk_mul_f32 v[12:13], v[12:13], v[0:1] op_sel_hi:[1,0]
	v_pk_mul_f32 v[10:11], v[10:11], v[0:1] op_sel_hi:[1,0]
	v_pk_mul_f32 v[8:9], v[8:9], v[0:1] op_sel_hi:[1,0]
	v_pk_mul_f32 v[6:7], v[6:7], v[0:1] op_sel_hi:[1,0]
	v_pk_mul_f32 v[4:5], v[4:5], v[0:1] op_sel_hi:[1,0]
	v_pk_mul_f32 v[2:3], v[2:3], v[0:1] op_sel_hi:[1,0]

; DI f32x16 mfma32(bf16x8 a, bf16x8 b, f32x16 c) { return __builtin_amdgcn_mfma_f32_32x32x16_bf16(a, b, c, 0, 0, 0); }
; DI int crow(int i, int h) { return (i & 3) + 8 * (i >> 2) + 4 * h; }
;     ...
;   f32x16 s[2];
; #pragma unroll
;   for (int k2 = 0; k2 < 2; ++k2) {
;     if (!(HM & (1 << k2))) continue;
; #pragma unroll
;     for (int i = 0; i < 16; ++i) s[k2][i] = 0.f;
; #pragma unroll
;     for (int ks = 0; ks < 4; ++ks) {
;       const bf16x8 a = *(const bf16x8*)(Ks + (32 * k2 + r) * LSTR + 16 * ks + 8 * h);
;       s[k2] = mfma32(a, qf[ks], s[k2]);
;     }
;   }
;   if (MODE == 1) {
; #pragma unroll
;     for (int k2 = 0; k2 < 2; ++k2)
; #pragma unroll
;       for (int g = 0; g < 4; ++g) {
;         if (!(HM & (1 << k2))) continue;
;         const f32x4 cv = *(const f32x4*)(cn_lds + key0 + 32 * k2 + 8 * g + 4 * h);
; #pragma unroll
;         for (int e = 0; e < 4; ++e) s[k2][4 * g + e] = fmaf(s[k2][4 * g + e], L2E, cv[e]);
;       }
;   }
;   float mx = NINF;
; #pragma unroll
;   for (int k2 = 0; k2 < 2; ++k2)
; #pragma unroll
;     for (int i = 0; i < 16; ++i) {
;       if (!(HM & (1 << k2))) continue;
;       float v = s[k2][i];
;       if (MASKED) {
;         const int tk = key0 + 32 * k2 + crow(i, h);
;         const bool valid = (MODE == 0) ? ((tk <= tq) && (tq - tk <= maxdist)) : (tk <= tq);
;         v = valid ? v : NINF; s[k2][i] = v;
;       }
;       mx = fmaxf(mx, v);
;     }
;   mx = fmaxf(mx, __shfl_xor(mx, 32));
;   if (MODE != 1) mx *= L2E;
;   if (MODE == 2) mx = lanesel ? mx : NINF;
;   const float mn = fmaxf(m, mx); const float alpha = __builtin_amdgcn_exp2f(m - mn);
;   const float neg = (MODE == 2 && !lanesel) ? NINF : -mn;
;   float ps = 0.f;
; #pragma unroll
;   for (int k2 = 0; k2 < 2; ++k2)
; #pragma unroll
;     for (int i = 0; i < 16; ++i) {
;       if (!(HM & (1 << k2))) continue;
;       const float pv = (MODE == 1) ? __builtin_amdgcn_exp2f(s[k2][i] + neg) : __builtin_amdgcn_exp2f(fmaf(s[k2][i], L2E, neg));
;       s[k2][i] = pv; ps += pv;
;     }
;   l = l * alpha + ps;
;   if (__builtin_amdgcn_ballot_w64(mn != m) != 0ull) {
; #pragma unroll
;     for (int dt = 0; dt < 2; ++dt)
; #pragma unroll
;       for (int i = 0; i < 16; ++i) o[dt][i] *= alpha;
;   }
.LBB0_963:
	s_and_b64 vcc, exec, s[6:7]
	s_cbranch_vccz .LBB0_967
	s_waitcnt lgkmcnt(4)
	v_mfma_f32_32x32x16_bf16 v[82:97], v[82:85], v[98:101], 0
	s_nop 4
	ds_read_b128 v[34:37], v196 offset:23072
	ds_read_b128 v[38:41], v196 offset:23104
	s_waitcnt lgkmcnt(5)
	v_mfma_f32_32x32x16_bf16 v[82:97], v[78:81], v[102:105], v[82:97]
	s_waitcnt lgkmcnt(4)
	v_mfma_f32_32x32x16_bf16 v[82:97], v[74:77], v[106:109], v[82:97]
	s_waitcnt lgkmcnt(3)
	v_mfma_f32_32x32x16_bf16 v[82:97], v[66:69], v[110:113], v[82:97]
	s_waitcnt lgkmcnt(2)
	v_mfma_f32_32x32x16_bf16 v[66:81], v[70:73], v[98:101], 0
	s_nop 9
	v_max3_f32 v0, v82, s35, v83
	v_max3_f32 v0, v0, v84, v85
	v_max3_f32 v0, v0, v86, v87
	v_max3_f32 v0, v0, v88, v89
	v_max3_f32 v0, v0, v90, v91
	v_max3_f32 v0, v0, v92, v93
	v_max3_f32 v0, v0, v94, v95
	s_waitcnt lgkmcnt(1)
	v_mfma_f32_32x32x16_bf16 v[66:81], v[34:37], v[102:105], v[66:81]
	ds_read_b128 v[34:37], v196 offset:23136
	v_max3_f32 v0, v0, v96, v97
	s_waitcnt lgkmcnt(1)
	v_mfma_f32_32x32x16_bf16 v[66:81], v[38:41], v[106:109], v[66:81]
	s_waitcnt lgkmcnt(0)
	v_mfma_f32_32x32x16_bf16 v[66:81], v[34:37], v[110:113], v[66:81]
	v_and_b32_e32 v35, 64, v202
	v_xor_b32_e32 v34, 32, v202
	v_add_u32_e32 v35, 64, v35
	v_cmp_lt_i32_e32 vcc, v34, v35
	s_nop 1
	v_cndmask_b32_e32 v34, v202, v34, vcc
	s_nop 4
	v_max3_f32 v0, v0, v66, v67
	v_max3_f32 v0, v0, v68, v69
	v_max3_f32 v0, v0, v70, v71
	v_max3_f32 v0, v0, v72, v73
	v_max3_f32 v0, v0, v74, v75
	v_max3_f32 v0, v0, v76, v77
	v_max3_f32 v0, v0, v78, v79
	v_max3_f32 v0, v0, v80, v81
	v_lshlrev_b32_e32 v34, 2, v34
	ds_bpermute_b32 v34, v34, v0
	s_waitcnt lgkmcnt(0)
	v_max_f32_e32 v34, v34, v34
	v_max_f32_e32 v0, v0, v34
	v_mul_f32_e32 v0, 0x3fb8aa3b, v0
	v_max_f32_e32 v34, v160, v160
	v_sub_f32_e32 v232, v0, v34
	v_cmp_lt_f32_e32 vcc, 0x41000000, v232
	s_nop 1
	v_cndmask_b32_e32 v159, v34, v0, vcc
	v_sub_f32_e32 v0, v160, v159
	v_exp_f32_e32 v0, v0
	v_cmp_neq_f32_e32 vcc, v159, v160
	s_cbranch_vccz .LBB0_966
	v_pk_mul_f32 v[32:33], v[32:33], v[0:1] op_sel_hi:[1,0]
	v_pk_mul_f32 v[30:31], v[30:31], v[0:1] op_sel_hi:[1,0]
	v_pk_mul_f32 v[28:29], v[28:29], v[0:1] op_sel_hi:[1,0]
	v_pk_mul_f32 v[26:27], v[26:27], v[0:1] op_sel_hi:[1,0]
	v_pk_mul_f32 v[24:25], v[24:25], v[0:1] op_sel_hi:[1,0]
	v_pk_mul_f32 v[22:23], v[22:23], v[0:1] op_sel_hi:[1,0]
	v_pk_mul_f32 v[20:21], v[20:21], v[0:1] op_sel_hi:[1,0]
	v_pk_mul_f32 v[18:19], v[18:19], v[0:1] op_sel_hi:[1,0]
	v_pk_mul_f32 v[16:17], v[16:17], v[0:1] op_sel_hi:[1,0]
	v_pk_mul_f32 v[14:15], v[14:15], v[0:1] op_sel_hi:[1,0]
	v_pk_mul_f32 v[12:13], v[12:13], v[0:1] op_sel_hi:[1,0]
	v_pk_mul_f32 v[10:11], v[10:11], v[0:1] op_sel_hi:[1,0]
	v_pk_mul_f32 v[8:9], v[8:9], v[0:1] op_sel_hi:[1,0]
	v_pk_mul_f32 v[6:7], v[6:7], v[0:1] op_sel_hi:[1,0]
	v_pk_mul_f32 v[4:5], v[4:5], v[0:1] op_sel_hi:[1,0]
	v_pk_mul_f32 v[2:3], v[2:3], v[0:1] op_sel_hi:[1,0]

; DI f32x16 mfma32(bf16x8 a, bf16x8 b, f32x16 c) { return __builtin_amdgcn_mfma_f32_32x32x16_bf16(a, b, c, 0, 0, 0); }
; DI int crow(int i, int h) { return (i & 3) + 8 * (i >> 2) + 4 * h; }
;     ...
;   f32x16 s[2];
; #pragma unroll
;   for (int k2 = 0; k2 < 2; ++k2) {
;     if (!(HM & (1 << k2))) continue;
; #pragma unroll
;     for (int i = 0; i < 16; ++i) s[k2][i] = 0.f;
; #pragma unroll
;     for (int ks = 0; ks < 4; ++ks) {
;       const bf16x8 a = *(const bf16x8*)(Ks + (32 * k2 + r) * LSTR + 16 * ks + 8 * h);
;       s[k2] = mfma32(a, qf[ks], s[k2]);
;     }
;   }
;   if (MODE == 1) {
; #pragma unroll
;     for (int k2 = 0; k2 < 2; ++k2)
; #pragma unroll
;       for (int g = 0; g < 4; ++g) {
;         if (!(HM & (1 << k2))) continue;
;         const f32x4 cv = *(const f32x4*)(cn_lds + key0 + 32 * k2 + 8 * g + 4 * h);
; #pragma unroll
;         for (int e = 0; e < 4; ++e) s[k2][4 * g + e] = fmaf(s[k2][4 * g + e], L2E, cv[e]);
;       }
;   }
;   float mx = NINF;
; #pragma unroll
;   for (int k2 = 0; k2 < 2; ++k2)
; #pragma unroll
;     for (int i = 0; i < 16; ++i) {
;       if (!(HM & (1 << k2))) continue;
;       float v = s[k2][i];
;       if (MASKED) {
;         const int tk = key0 + 32 * k2 + crow(i, h);
;         const bool valid = (MODE == 0) ? ((tk <= tq) && (tq - tk <= maxdist)) : (tk <= tq);
;         v = valid ? v : NINF; s[k2][i] = v;
;       }
;       mx = fmaxf(mx, v);
;     }
;   mx = fmaxf(mx, __shfl_xor(mx, 32));
;   if (MODE != 1) mx *= L2E;
;   if (MODE == 2) mx = lanesel ? mx : NINF;
;   const float mn = fmaxf(m, mx); const float alpha = __builtin_amdgcn_exp2f(m - mn);
;   const float neg = (MODE == 2 && !lanesel) ? NINF : -mn;
;   float ps = 0.f;
; #pragma unroll
;   for (int k2 = 0; k2 < 2; ++k2)
; #pragma unroll
;     for (int i = 0; i < 16; ++i) {
;       if (!(HM & (1 << k2))) continue;
;       const float pv = (MODE == 1) ? __builtin_amdgcn_exp2f(s[k2][i] + neg) : __builtin_amdgcn_exp2f(fmaf(s[k2][i], L2E, neg));
;       s[k2][i] = pv; ps += pv;
;     }
;   l = l * alpha + ps;
;   if (__builtin_amdgcn_ballot_w64(mn != m) != 0ull) {
; #pragma unroll
;     for (int dt = 0; dt < 2; ++dt)
; #pragma unroll
;       for (int i = 0; i < 16; ++i) o[dt][i] *= alpha;
;   }
.LBB0_971:
	s_nop 6
	ds_read_b128 v[34:37], v196 offset:18432
	s_nop 1
	ds_read_b128 v[50:53], v196 offset:18464
	v_or_b32_e32 v0, s58, v197
	v_cmp_gt_u32_e32 vcc, v0, v157
	v_cmp_lt_i32_e64 s[6:7], v0, v147
	s_waitcnt lgkmcnt(1)
	v_mfma_f32_32x32x16_bf16 v[34:49], v[34:37], v[98:101], 0
	s_or_b64 vcc, vcc, s[6:7]
	s_waitcnt lgkmcnt(0)
	v_mfma_f32_32x32x16_bf16 v[34:49], v[50:53], v[102:105], v[34:49]
	ds_read_b128 v[50:53], v196 offset:18496
	s_waitcnt lgkmcnt(0)
	v_mfma_f32_32x32x16_bf16 v[34:49], v[50:53], v[106:109], v[34:49]
	ds_read_b128 v[50:53], v196 offset:18528
	s_waitcnt lgkmcnt(0)
	v_mfma_f32_32x32x16_bf16 v[34:49], v[50:53], v[110:113], v[34:49]
	v_bitop3_b32 v50, s58, v197, s58 bitop3:3
	v_cmp_lt_i32_e64 s[6:7], v158, v50
	v_or_b32_e32 v51, 2, v0
	s_nop 8
	v_cndmask_b32_e32 v34, v34, v204, vcc
	v_cmp_ge_u32_e32 vcc, v0, v157
	s_or_b64 vcc, vcc, s[6:7]
	v_cmp_lt_i32_e64 s[6:7], v51, v147
	v_cndmask_b32_e32 v35, v35, v204, vcc
	v_cmp_gt_u32_e32 vcc, v51, v157
	s_or_b64 vcc, vcc, s[6:7]
	v_or_b32_e32 v51, 3, v0
	v_cndmask_b32_e32 v36, v36, v204, vcc
	v_cmp_gt_u32_e32 vcc, v51, v157
	v_cmp_lt_i32_e64 s[6:7], v51, v147
	s_or_b64 vcc, vcc, s[6:7]
	v_or_b32_e32 v51, 8, v0
	v_cndmask_b32_e32 v37, v37, v204, vcc
	v_cmp_gt_u32_e32 vcc, v51, v157
	v_cmp_lt_i32_e64 s[6:7], v51, v147
	s_or_b64 vcc, vcc, s[6:7]
	v_or_b32_e32 v51, 9, v0
	v_cndmask_b32_e32 v38, v38, v204, vcc
	v_cmp_gt_u32_e32 vcc, v51, v157
	v_cmp_lt_i32_e64 s[6:7], v51, v147
	v_max3_f32 v50, v34, s35, v35
	s_or_b64 vcc, vcc, s[6:7]
	v_max3_f32 v50, v50, v36, v37
	v_cndmask_b32_e32 v39, v39, v204, vcc
	v_max3_f32 v52, v50, v38, v39
	v_or_b32_e32 v50, 10, v0
	v_cmp_gt_u32_e32 vcc, v50, v157
	v_cmp_lt_i32_e64 s[6:7], v50, v147
	s_or_b64 vcc, vcc, s[6:7]
	v_cndmask_b32_e32 v50, v40, v204, vcc
	v_or_b32_e32 v40, 11, v0
	v_cmp_gt_u32_e32 vcc, v40, v157
	v_cmp_lt_i32_e64 s[6:7], v40, v147
	s_or_b64 vcc, vcc, s[6:7]
	v_cndmask_b32_e32 v51, v41, v204, vcc
	v_or_b32_e32 v41, 16, v0
	v_cmp_gt_u32_e32 vcc, v41, v157
	v_cmp_lt_i32_e64 s[6:7], v41, v147
	s_or_b64 vcc, vcc, s[6:7]
	v_or_b32_e32 v41, 17, v0
	v_max3_f32 v40, v52, v50, v51
	v_cndmask_b32_e32 v52, v42, v204, vcc
	v_cmp_gt_u32_e32 vcc, v41, v157
	v_cmp_lt_i32_e64 s[6:7], v41, v147
	s_or_b64 vcc, vcc, s[6:7]
	v_or_b32_e32 v41, 18, v0
	v_cndmask_b32_e32 v53, v43, v204, vcc
	v_cmp_gt_u32_e32 vcc, v41, v157
	v_cmp_lt_i32_e64 s[6:7], v41, v147
	s_or_b64 vcc, vcc, s[6:7]
	v_or_b32_e32 v41, 19, v0
	v_cndmask_b32_e32 v44, v44, v204, vcc
	v_cmp_gt_u32_e32 vcc, v41, v157
	v_cmp_lt_i32_e64 s[6:7], v41, v147
	s_or_b64 vcc, vcc, s[6:7]
	v_or_b32_e32 v41, 24, v0
	v_cndmask_b32_e32 v45, v45, v204, vcc
	v_cmp_gt_u32_e32 vcc, v41, v157
	v_cmp_lt_i32_e64 s[6:7], v41, v147
	s_or_b64 vcc, vcc, s[6:7]
	v_or_b32_e32 v42, 25, v0
	v_cndmask_b32_e32 v41, v46, v204, vcc
	v_cmp_gt_u32_e32 vcc, v42, v157
	v_cmp_lt_i32_e64 s[6:7], v42, v147
	v_max3_f32 v40, v40, v52, v53
	s_or_b64 vcc, vcc, s[6:7]
	v_max3_f32 v40, v40, v44, v45
	v_cndmask_b32_e32 v42, v47, v204, vcc
	v_max3_f32 v46, v40, v41, v42
	v_or_b32_e32 v40, 26, v0
	v_cmp_gt_u32_e32 vcc, v40, v157
	v_cmp_lt_i32_e64 s[6:7], v40, v147
	s_or_b64 vcc, vcc, s[6:7]
	v_or_b32_e32 v0, 27, v0
	v_cndmask_b32_e32 v43, v48, v204, vcc
	v_cmp_gt_u32_e32 vcc, v0, v157
	v_cmp_lt_i32_e64 s[6:7], v0, v147
	s_or_b64 vcc, vcc, s[6:7]
	v_cndmask_b32_e32 v40, v49, v204, vcc
	v_and_b32_e32 v47, 64, v202
	v_max3_f32 v0, v46, v43, v40
	v_xor_b32_e32 v46, 32, v202
	v_add_u32_e32 v47, 64, v47
	v_cmp_lt_i32_e32 vcc, v46, v47
	s_nop 1
	v_cndmask_b32_e32 v46, v202, v46, vcc
	v_lshlrev_b32_e32 v46, 2, v46
	ds_bpermute_b32 v46, v46, v0
	s_waitcnt lgkmcnt(0)
	v_max_f32_e32 v46, v46, v46
	v_max_f32_e32 v0, v0, v46
	v_mul_f32_e32 v0, 0x3fb8aa3b, v0
	v_max_f32_e32 v46, v160, v160
	v_sub_f32_e32 v232, v0, v46
	v_cmp_lt_f32_e32 vcc, 0x41000000, v232
	s_nop 1
	v_cndmask_b32_e32 v159, v46, v0, vcc
	v_sub_f32_e32 v0, v160, v159
	v_exp_f32_e32 v0, v0
	v_cmp_neq_f32_e32 vcc, v159, v160
	s_cbranch_vccz .LBB0_973
	v_pk_mul_f32 v[32:33], v[32:33], v[0:1] op_sel_hi:[1,0]
	v_pk_mul_f32 v[30:31], v[30:31], v[0:1] op_sel_hi:[1,0]
	v_pk_mul_f32 v[28:29], v[28:29], v[0:1] op_sel_hi:[1,0]
	v_pk_mul_f32 v[26:27], v[26:27], v[0:1] op_sel_hi:[1,0]
	v_pk_mul_f32 v[24:25], v[24:25], v[0:1] op_sel_hi:[1,0]
	v_pk_mul_f32 v[22:23], v[22:23], v[0:1] op_sel_hi:[1,0]
	v_pk_mul_f32 v[20:21], v[20:21], v[0:1] op_sel_hi:[1,0]
	v_pk_mul_f32 v[18:19], v[18:19], v[0:1] op_sel_hi:[1,0]
	v_pk_mul_f32 v[16:17], v[16:17], v[0:1] op_sel_hi:[1,0]
	v_pk_mul_f32 v[14:15], v[14:15], v[0:1] op_sel_hi:[1,0]
	v_pk_mul_f32 v[12:13], v[12:13], v[0:1] op_sel_hi:[1,0]
	v_pk_mul_f32 v[10:11], v[10:11], v[0:1] op_sel_hi:[1,0]
	v_pk_mul_f32 v[8:9], v[8:9], v[0:1] op_sel_hi:[1,0]
	v_pk_mul_f32 v[6:7], v[6:7], v[0:1] op_sel_hi:[1,0]
	v_pk_mul_f32 v[4:5], v[4:5], v[0:1] op_sel_hi:[1,0]
	v_pk_mul_f32 v[2:3], v[2:3], v[0:1] op_sel_hi:[1,0]

;     ...
;   f32x16 s[2];
; #pragma unroll
;   for (int k2 = 0; k2 < 2; ++k2) {
;     if (!(HM & (1 << k2))) continue;
; #pragma unroll
;     for (int i = 0; i < 16; ++i) s[k2][i] = 0.f;
; #pragma unroll
;     for (int ks = 0; ks < 4; ++ks) {
;       const bf16x8 a = *(const bf16x8*)(Ks + (32 * k2 + r) * LSTR + 16 * ks + 8 * h);
;       s[k2] = mfma32(a, qf[ks], s[k2]);
;     }
;   }
;   if (MODE == 1) {
; #pragma unroll
;     for (int k2 = 0; k2 < 2; ++k2)
; #pragma unroll
;       for (int g = 0; g < 4; ++g) {
;         if (!(HM & (1 << k2))) continue;
;         const f32x4 cv = *(const f32x4*)(cn_lds + key0 + 32 * k2 + 8 * g + 4 * h);
; #pragma unroll
;         for (int e = 0; e < 4; ++e) s[k2][4 * g + e] = fmaf(s[k2][4 * g + e], L2E, cv[e]);
;       }
;   }
;   float mx = NINF;
; #pragma unroll
;   for (int k2 = 0; k2 < 2; ++k2)
; #pragma unroll
;     for (int i = 0; i < 16; ++i) {
;       if (!(HM & (1 << k2))) continue;
;       float v = s[k2][i];
;       if (MASKED) {
;         const int tk = key0 + 32 * k2 + crow(i, h);
;         const bool valid = (MODE == 0) ? ((tk <= tq) && (tq - tk <= maxdist)) : (tk <= tq);
;         v = valid ? v : NINF; s[k2][i] = v;
;       }
;       mx = fmaxf(mx, v);
;     }
;   mx = fmaxf(mx, __shfl_xor(mx, 32));
;   if (MODE != 1) mx *= L2E;
;   if (MODE == 2) mx = lanesel ? mx : NINF;
; template <int MODE>
; DI void flash_loop(char* smem, const bf16_t* Kbase, size_t ldk, const bf16_t* Vtbase, size_t ldv, ull tiles, ull wtiles,
;                    const bf16x8 (&qf)[4], f32x16 (&o)[2], float& m, float& l, int tq, int tqmin, int tqmax, int maxdist, const float* cn_lds, ull lmask) {
;     ...
;     if (!((wtiles >> kt) & 1ull)) return;
;     const bf16_t* Ks = (const bf16_t*)(smem + stage * (2 * 64 * LSTR * 2)); const bf16_t* Vs = Ks + 64 * LSTR;
;     const bool sel = ((lmask >> kt) & 1ull) != 0;
;     const bool interior = (64 * kt + 63 <= tqmin) && (MODE != 0 || (tqmax - 64 * kt <= maxdist));
;     int hm = 3;
;     if (MODE == 0) {
;       hm = 0;
;       if (64 * kt <= tqmax && 64 * kt + 31 >= tqmin - maxdist) hm |= 1;
;       if (64 * kt + 32 <= tqmax && 64 * kt + 63 >= tqmin - maxdist) hm |= 2;
;     }
;     if (MODE == 0 && hm == 1) attn_tile<MODE, true, 1>(Ks, Vs, qf, o, m, l, 64 * kt, tq, maxdist, cn_lds, sel);
;     else if (MODE == 0 && hm == 2) attn_tile<MODE, true, 2>(Ks, Vs, qf, o, m, l, 64 * kt, tq, maxdist, cn_lds, sel);
.LBB0_990:
	s_lshr_b64 s[6:7], s[4:5], s33
	s_and_b32 s58, s6, 1
	s_cmp_eq_u64 s[58:59], 0
	s_cbranch_scc1 .LBB0_1014
	s_lshl_b32 s58, s33, 6
	s_or_b32 s33, s58, 63
	s_cmp_le_u32 s58, s3
	s_cselect_b64 s[6:7], -1, 0
	s_or_b32 s36, s58, 31
	s_cmp_ge_i32 s36, s29
	s_cselect_b64 s[36:37], -1, 0
	s_and_b64 s[6:7], s[6:7], s[36:37]
	v_cndmask_b32_e64 v0, 0, 1, s[6:7]
	s_or_b32 s6, s58, 32
	s_cmp_gt_u32 s6, s3
	s_cselect_b64 s[6:7], -1, 0
	s_cmp_lt_i32 s33, s29
	s_cselect_b64 s[36:37], -1, 0
	v_readfirstlane_b32 s38, v0
	s_or_b32 s39, s38, 2
	s_or_b64 s[6:7], s[6:7], s[36:37]
	s_and_b64 s[6:7], s[6:7], exec
	s_cselect_b32 s65, s38, s39
	s_mov_b64 s[62:63], -1
	s_mov_b64 s[54:55], 0
	s_cmp_lt_i32 s65, 2
	s_mov_b64 s[6:7], 0
	s_cbranch_scc1 .LBB0_1007
	s_cmp_eq_u32 s65, 2
	s_mov_b64 s[6:7], -1
	s_cbranch_scc0 .LBB0_996
	ds_read_b128 v[34:37], v199 offset:4608
	ds_read_b128 v[50:53], v199 offset:4640
	v_or_b32_e32 v0, s58, v197
	s_waitcnt lgkmcnt(1)
	v_mfma_f32_32x32x16_bf16 v[34:49], v[34:37], v[98:101], 0
	s_waitcnt lgkmcnt(0)
	v_mfma_f32_32x32x16_bf16 v[34:49], v[50:53], v[102:105], v[34:49]
	ds_read_b128 v[50:53], v199 offset:4672
	s_waitcnt lgkmcnt(0)
	v_mfma_f32_32x32x16_bf16 v[34:49], v[50:53], v[106:109], v[34:49]
	ds_read_b128 v[50:53], v199 offset:4704
	s_waitcnt lgkmcnt(0)
	v_mfma_f32_32x32x16_bf16 v[34:49], v[50:53], v[110:113], v[34:49]
	v_or_b32_e32 v50, 32, v0
	v_cmp_gt_u32_e32 vcc, v50, v154
	v_cmp_lt_i32_e64 s[6:7], v50, v155
	s_or_b64 vcc, vcc, s[6:7]
	s_nop 7
	v_cndmask_b32_e32 v66, v34, v204, vcc
	v_bitop3_b32 v34, s58, v205, v197 bitop3:0x36
	v_cmp_ge_u32_e32 vcc, v50, v154
	v_cmp_gt_i32_e64 s[6:7], v34, v156
	s_or_b64 vcc, vcc, s[6:7]
	v_cndmask_b32_e32 v67, v35, v204, vcc
	v_or_b32_e32 v35, 34, v0
	v_cmp_gt_u32_e32 vcc, v35, v154
	v_cmp_lt_i32_e64 s[6:7], v35, v155
	s_or_b64 vcc, vcc, s[6:7]
	v_or_b32_e32 v35, 35, v0
	v_cndmask_b32_e32 v68, v36, v204, vcc
	v_cmp_gt_u32_e32 vcc, v35, v154
	v_cmp_lt_i32_e64 s[6:7], v35, v155
	s_or_b64 vcc, vcc, s[6:7]
	v_or_b32_e32 v35, 40, v0
	v_cndmask_b32_e32 v69, v37, v204, vcc
	v_cmp_gt_u32_e32 vcc, v35, v154
	v_cmp_lt_i32_e64 s[6:7], v35, v155
	s_or_b64 vcc, vcc, s[6:7]
	v_or_b32_e32 v35, 41, v0
	v_cndmask_b32_e32 v70, v38, v204, vcc
	v_cmp_gt_u32_e32 vcc, v35, v154
	v_cmp_lt_i32_e64 s[6:7], v35, v155
	s_or_b64 vcc, vcc, s[6:7]
	v_or_b32_e32 v35, 42, v0
	v_cndmask_b32_e32 v71, v39, v204, vcc
	v_cmp_gt_u32_e32 vcc, v35, v154
	v_cmp_lt_i32_e64 s[6:7], v35, v155
	s_or_b64 vcc, vcc, s[6:7]
	v_or_b32_e32 v35, 43, v0
	v_cndmask_b32_e32 v77, v40, v204, vcc
	v_cmp_gt_u32_e32 vcc, v35, v154
	v_cmp_lt_i32_e64 s[6:7], v35, v155
	s_or_b64 vcc, vcc, s[6:7]
	v_or_b32_e32 v35, 48, v0
	v_cndmask_b32_e32 v78, v41, v204, vcc
	v_cmp_gt_u32_e32 vcc, v35, v154
	v_cmp_lt_i32_e64 s[6:7], v35, v155
	s_or_b64 vcc, vcc, s[6:7]
	v_or_b32_e32 v35, 49, v0
	v_cndmask_b32_e32 v79, v42, v204, vcc
	v_cmp_gt_u32_e32 vcc, v35, v154
	v_cmp_lt_i32_e64 s[6:7], v35, v155
	s_or_b64 vcc, vcc, s[6:7]
	v_or_b32_e32 v35, 50, v0
	v_cndmask_b32_e32 v80, v43, v204, vcc
	v_cmp_gt_u32_e32 vcc, v35, v154
	v_cmp_lt_i32_e64 s[6:7], v35, v155
	s_or_b64 vcc, vcc, s[6:7]
	v_or_b32_e32 v35, 51, v0
	v_cndmask_b32_e32 v81, v44, v204, vcc
	v_cmp_gt_u32_e32 vcc, v35, v154
	v_cmp_lt_i32_e64 s[6:7], v35, v155
	s_or_b64 vcc, vcc, s[6:7]
	v_or_b32_e32 v35, 56, v0
	v_cndmask_b32_e32 v76, v45, v204, vcc
	v_cmp_gt_u32_e32 vcc, v35, v154
	v_cmp_lt_i32_e64 s[6:7], v35, v155
	s_or_b64 vcc, vcc, s[6:7]
	v_or_b32_e32 v35, 57, v0
	v_max3_f32 v34, v66, s35, v67
	v_cndmask_b32_e32 v73, v46, v204, vcc
	v_cmp_gt_u32_e32 vcc, v35, v154
	v_cmp_lt_i32_e64 s[6:7], v35, v155
	v_max3_f32 v34, v34, v68, v69
	s_or_b64 vcc, vcc, s[6:7]
	v_or_b32_e32 v35, 58, v0
	v_max3_f32 v34, v34, v70, v71
	v_cndmask_b32_e32 v74, v47, v204, vcc
	v_cmp_gt_u32_e32 vcc, v35, v154
	v_cmp_lt_i32_e64 s[6:7], v35, v155
	v_max3_f32 v34, v34, v77, v78
	s_or_b64 vcc, vcc, s[6:7]
	v_or_b32_e32 v0, 59, v0
	v_max3_f32 v34, v34, v79, v80
	v_cndmask_b32_e32 v75, v48, v204, vcc
	v_cmp_gt_u32_e32 vcc, v0, v154
	v_cmp_lt_i32_e64 s[6:7], v0, v155
	v_max3_f32 v34, v34, v81, v76
	s_or_b64 vcc, vcc, s[6:7]
	v_max3_f32 v34, v34, v73, v74
	v_cndmask_b32_e32 v72, v49, v204, vcc
	v_and_b32_e32 v35, 64, v202
	v_max3_f32 v0, v34, v75, v72
	v_xor_b32_e32 v34, 32, v202
	v_add_u32_e32 v35, 64, v35
	v_cmp_lt_i32_e32 vcc, v34, v35
	s_nop 1
	v_cndmask_b32_e32 v34, v202, v34, vcc
	v_lshlrev_b32_e32 v34, 2, v34
	ds_bpermute_b32 v34, v34, v0
	s_waitcnt lgkmcnt(0)
	v_max_f32_e32 v34, v34, v34
	v_max_f32_e32 v0, v0, v34
	v_mul_f32_e32 v0, 0x3fb8aa3b, v0
	v_max_f32_e32 v34, v157, v157
	v_sub_f32_e32 v232, v0, v34
	v_cmp_lt_f32_e32 vcc, 0x41000000, v232
	s_nop 1
	v_cndmask_b32_e32 v158, v34, v0, vcc
	v_sub_f32_e32 v0, v157, v158
	v_exp_f32_e32 v0, v0
	v_cmp_neq_f32_e32 vcc, v158, v157
	s_cbranch_vccz .LBB0_995
	v_pk_mul_f32 v[32:33], v[32:33], v[0:1] op_sel_hi:[1,0]
	v_pk_mul_f32 v[30:31], v[30:31], v[0:1] op_sel_hi:[1,0]
	v_pk_mul_f32 v[28:29], v[28:29], v[0:1] op_sel_hi:[1,0]
	v_pk_mul_f32 v[26:27], v[26:27], v[0:1] op_sel_hi:[1,0]
	v_pk_mul_f32 v[24:25], v[24:25], v[0:1] op_sel_hi:[1,0]
	v_pk_mul_f32 v[22:23], v[22:23], v[0:1] op_sel_hi:[1,0]
	v_pk_mul_f32 v[20:21], v[20:21], v[0:1] op_sel_hi:[1,0]
	v_pk_mul_f32 v[18:19], v[18:19], v[0:1] op_sel_hi:[1,0]
	v_pk_mul_f32 v[16:17], v[16:17], v[0:1] op_sel_hi:[1,0]
	v_pk_mul_f32 v[14:15], v[14:15], v[0:1] op_sel_hi:[1,0]
	v_pk_mul_f32 v[12:13], v[12:13], v[0:1] op_sel_hi:[1,0]
	v_pk_mul_f32 v[10:11], v[10:11], v[0:1] op_sel_hi:[1,0]
	v_pk_mul_f32 v[8:9], v[8:9], v[0:1] op_sel_hi:[1,0]
	v_pk_mul_f32 v[6:7], v[6:7], v[0:1] op_sel_hi:[1,0]
	v_pk_mul_f32 v[4:5], v[4:5], v[0:1] op_sel_hi:[1,0]
	v_pk_mul_f32 v[2:3], v[2:3], v[0:1] op_sel_hi:[1,0]

; DI f32x16 mfma32(bf16x8 a, bf16x8 b, f32x16 c) { return __builtin_amdgcn_mfma_f32_32x32x16_bf16(a, b, c, 0, 0, 0); }
; DI int crow(int i, int h) { return (i & 3) + 8 * (i >> 2) + 4 * h; }
;     ...
;   f32x16 s[2];
; #pragma unroll
;   for (int k2 = 0; k2 < 2; ++k2) {
;     if (!(HM & (1 << k2))) continue;
; #pragma unroll
;     for (int i = 0; i < 16; ++i) s[k2][i] = 0.f;
; #pragma unroll
;     for (int ks = 0; ks < 4; ++ks) {
;       const bf16x8 a = *(const bf16x8*)(Ks + (32 * k2 + r) * LSTR + 16 * ks + 8 * h);
;       s[k2] = mfma32(a, qf[ks], s[k2]);
;     }
;   }
;   if (MODE == 1) {
; #pragma unroll
;     for (int k2 = 0; k2 < 2; ++k2)
; #pragma unroll
;       for (int g = 0; g < 4; ++g) {
;         if (!(HM & (1 << k2))) continue;
;         const f32x4 cv = *(const f32x4*)(cn_lds + key0 + 32 * k2 + 8 * g + 4 * h);
; #pragma unroll
;         for (int e = 0; e < 4; ++e) s[k2][4 * g + e] = fmaf(s[k2][4 * g + e], L2E, cv[e]);
;       }
;   }
;   float mx = NINF;
; #pragma unroll
;   for (int k2 = 0; k2 < 2; ++k2)
; #pragma unroll
;     for (int i = 0; i < 16; ++i) {
;       if (!(HM & (1 << k2))) continue;
;       float v = s[k2][i];
;       if (MASKED) {
;         const int tk = key0 + 32 * k2 + crow(i, h);
;         const bool valid = (MODE == 0) ? ((tk <= tq) && (tq - tk <= maxdist)) : (tk <= tq);
;         v = valid ? v : NINF; s[k2][i] = v;
;       }
;       mx = fmaxf(mx, v);
;     }
.LBB0_998:
	ds_read_b128 v[82:85], v196
	ds_read_b128 v[78:81], v196 offset:32
	ds_read_b128 v[74:77], v196 offset:64
	ds_read_b128 v[66:69], v196 offset:96
	ds_read_b128 v[70:73], v196 offset:4608
	s_cmp_le_u32 s33, s28
	s_cselect_b64 s[6:7], -1, 0
	s_cmp_ge_i32 s58, s30
	s_cselect_b64 s[36:37], -1, 0
	s_and_b64 s[6:7], s[6:7], s[36:37]
	s_andn2_b64 vcc, exec, s[6:7]
	s_mov_b64 s[6:7], -1
	s_cbranch_vccz .LBB0_1002
	s_waitcnt lgkmcnt(4)
	v_mfma_f32_32x32x16_bf16 v[50:65], v[82:85], v[98:101], 0
	ds_read_b128 v[86:89], v196 offset:4640
	ds_read_b128 v[90:93], v196 offset:4672
	v_or_b32_e32 v0, s58, v197
	v_cmp_gt_u32_e32 vcc, v0, v154
	v_cmp_lt_i32_e64 s[6:7], v0, v155
	s_or_b64 vcc, vcc, s[6:7]
	s_waitcnt lgkmcnt(5)
	v_mfma_f32_32x32x16_bf16 v[50:65], v[78:81], v[102:105], v[50:65]
	s_waitcnt lgkmcnt(2)
	v_mfma_f32_32x32x16_bf16 v[34:49], v[70:73], v[98:101], 0
	v_mfma_f32_32x32x16_bf16 v[50:65], v[74:77], v[106:109], v[50:65]
	s_waitcnt lgkmcnt(1)
	v_mfma_f32_32x32x16_bf16 v[34:49], v[86:89], v[102:105], v[34:49]
	ds_read_b128 v[86:89], v196 offset:4704
	v_mfma_f32_32x32x16_bf16 v[50:65], v[66:69], v[110:113], v[50:65]
	s_waitcnt lgkmcnt(1)
	v_mfma_f32_32x32x16_bf16 v[34:49], v[90:93], v[106:109], v[34:49]
	s_waitcnt lgkmcnt(0)
	v_mfma_f32_32x32x16_bf16 v[34:49], v[86:89], v[110:113], v[34:49]
	s_nop 7
	v_cndmask_b32_e32 v86, v50, v204, vcc
	v_bitop3_b32 v50, s58, v197, s58 bitop3:3
	v_cmp_ge_u32_e32 vcc, v0, v154
	v_cmp_lt_i32_e64 s[6:7], v156, v50
	s_or_b64 vcc, vcc, s[6:7]
	v_cndmask_b32_e32 v87, v51, v204, vcc
	v_or_b32_e32 v51, 2, v0
	v_cmp_gt_u32_e32 vcc, v51, v154
	v_cmp_lt_i32_e64 s[6:7], v51, v155
	s_or_b64 vcc, vcc, s[6:7]
	v_or_b32_e32 v51, 3, v0
	v_cndmask_b32_e32 v88, v52, v204, vcc
	v_cmp_gt_u32_e32 vcc, v51, v154
	v_cmp_lt_i32_e64 s[6:7], v51, v155
	s_or_b64 vcc, vcc, s[6:7]
	v_or_b32_e32 v51, 8, v0
	v_cndmask_b32_e32 v89, v53, v204, vcc
	v_cmp_gt_u32_e32 vcc, v51, v154
	v_cmp_lt_i32_e64 s[6:7], v51, v155
	s_or_b64 vcc, vcc, s[6:7]
	v_or_b32_e32 v51, 9, v0
	v_cndmask_b32_e32 v90, v54, v204, vcc
	v_cmp_gt_u32_e32 vcc, v51, v154
	v_cmp_lt_i32_e64 s[6:7], v51, v155
	s_or_b64 vcc, vcc, s[6:7]
	v_or_b32_e32 v51, 10, v0
	v_cndmask_b32_e32 v192, v55, v204, vcc
	v_cmp_gt_u32_e32 vcc, v51, v154
	v_cmp_lt_i32_e64 s[6:7], v51, v155
	s_or_b64 vcc, vcc, s[6:7]
	v_or_b32_e32 v51, 11, v0
	v_cndmask_b32_e32 v191, v56, v204, vcc
	v_cmp_gt_u32_e32 vcc, v51, v154
	v_cmp_lt_i32_e64 s[6:7], v51, v155
	s_or_b64 vcc, vcc, s[6:7]
	v_or_b32_e32 v51, 16, v0
	v_cndmask_b32_e32 v193, v57, v204, vcc
	v_cmp_gt_u32_e32 vcc, v51, v154
	v_cmp_lt_i32_e64 s[6:7], v51, v155
	s_or_b64 vcc, vcc, s[6:7]
	v_or_b32_e32 v51, 17, v0
	v_cndmask_b32_e32 v188, v58, v204, vcc
	v_cmp_gt_u32_e32 vcc, v51, v154
	v_cmp_lt_i32_e64 s[6:7], v51, v155
	s_or_b64 vcc, vcc, s[6:7]
	v_or_b32_e32 v51, 18, v0
	v_cndmask_b32_e32 v190, v59, v204, vcc
	v_cmp_gt_u32_e32 vcc, v51, v154
	v_cmp_lt_i32_e64 s[6:7], v51, v155
	s_or_b64 vcc, vcc, s[6:7]
	v_or_b32_e32 v51, 19, v0
	v_cndmask_b32_e32 v189, v60, v204, vcc
	v_cmp_gt_u32_e32 vcc, v51, v154
	v_cmp_lt_i32_e64 s[6:7], v51, v155
	s_or_b64 vcc, vcc, s[6:7]
	v_or_b32_e32 v51, 24, v0
	v_cndmask_b32_e32 v187, v61, v204, vcc
	v_cmp_gt_u32_e32 vcc, v51, v154
	v_cmp_lt_i32_e64 s[6:7], v51, v155
	s_or_b64 vcc, vcc, s[6:7]
	v_or_b32_e32 v51, 25, v0
	v_cndmask_b32_e32 v186, v62, v204, vcc
	v_cmp_gt_u32_e32 vcc, v51, v154
	v_cmp_lt_i32_e64 s[6:7], v51, v155
	s_or_b64 vcc, vcc, s[6:7]
	v_or_b32_e32 v51, 26, v0
	v_cndmask_b32_e32 v185, v63, v204, vcc
	v_cmp_gt_u32_e32 vcc, v51, v154
	v_cmp_lt_i32_e64 s[6:7], v51, v155
	s_or_b64 vcc, vcc, s[6:7]
	v_or_b32_e32 v51, 27, v0
	v_cndmask_b32_e32 v184, v64, v204, vcc
	v_cmp_gt_u32_e32 vcc, v51, v154
	v_cmp_lt_i32_e64 s[6:7], v51, v155
	s_or_b64 vcc, vcc, s[6:7]
	v_or_b32_e32 v51, 32, v0
	v_cndmask_b32_e32 v182, v65, v204, vcc
	v_cmp_gt_u32_e32 vcc, v51, v154
	v_cmp_lt_i32_e64 s[6:7], v51, v155
	s_or_b64 vcc, vcc, s[6:7]
	v_cndmask_b32_e32 v164, v34, v204, vcc
	v_or_b32_e32 v34, 33, v0
	v_cmp_gt_u32_e32 vcc, v34, v154
	v_cmp_lt_i32_e64 s[6:7], v34, v155
	s_or_b64 vcc, vcc, s[6:7]
	v_cndmask_b32_e32 v162, v35, v204, vcc
	v_or_b32_e32 v35, 34, v0
	v_cmp_gt_u32_e32 vcc, v35, v154
; DI int crow(int i, int h) { return (i & 3) + 8 * (i >> 2) + 4 * h; }
;     ...
;     for (int i = 0; i < 16; ++i) {
;       if (!(HM & (1 << k2))) continue;
;       float v = s[k2][i];
;       if (MASKED) {
;         const int tk = key0 + 32 * k2 + crow(i, h);
;         const bool valid = (MODE == 0) ? ((tk <= tq) && (tq - tk <= maxdist)) : (tk <= tq);
;         v = valid ? v : NINF; s[k2][i] = v;
;       }
;       mx = fmaxf(mx, v);
;     }
;   mx = fmaxf(mx, __shfl_xor(mx, 32));
;   if (MODE != 1) mx *= L2E;
;   if (MODE == 2) mx = lanesel ? mx : NINF;
;   const float mn = fmaxf(m, mx); const float alpha = __builtin_amdgcn_exp2f(m - mn);
;   const float neg = (MODE == 2 && !lanesel) ? NINF : -mn;
;   float ps = 0.f;
; #pragma unroll
;   for (int k2 = 0; k2 < 2; ++k2)
; #pragma unroll
;     for (int i = 0; i < 16; ++i) {
;       if (!(HM & (1 << k2))) continue;
;       const float pv = (MODE == 1) ? __builtin_amdgcn_exp2f(s[k2][i] + neg) : __builtin_amdgcn_exp2f(fmaf(s[k2][i], L2E, neg));
;       s[k2][i] = pv; ps += pv;
;     }
;   l = l * alpha + ps;
;   if (__builtin_amdgcn_ballot_w64(mn != m) != 0ull) {
; #pragma unroll
;     for (int dt = 0; dt < 2; ++dt)
; #pragma unroll
;       for (int i = 0; i < 16; ++i) o[dt][i] *= alpha;
;   }
	v_cmp_lt_i32_e64 s[6:7], v35, v155
	s_or_b64 vcc, vcc, s[6:7]
	v_or_b32_e32 v35, 35, v0
	v_cndmask_b32_e32 v160, v36, v204, vcc
	v_cmp_gt_u32_e32 vcc, v35, v154
	v_cmp_lt_i32_e64 s[6:7], v35, v155
	s_or_b64 vcc, vcc, s[6:7]
	v_or_b32_e32 v35, 40, v0
	v_cndmask_b32_e32 v97, v37, v204, vcc
	v_cmp_gt_u32_e32 vcc, v35, v154
	v_cmp_lt_i32_e64 s[6:7], v35, v155
	s_or_b64 vcc, vcc, s[6:7]
	v_or_b32_e32 v35, 41, v0
	v_cndmask_b32_e32 v92, v38, v204, vcc
	v_cmp_gt_u32_e32 vcc, v35, v154
	v_cmp_lt_i32_e64 s[6:7], v35, v155
	s_or_b64 vcc, vcc, s[6:7]
	v_or_b32_e32 v35, 42, v0
	v_cndmask_b32_e32 v91, v39, v204, vcc
	v_cmp_gt_u32_e32 vcc, v35, v154
	v_cmp_lt_i32_e64 s[6:7], v35, v155
	s_or_b64 vcc, vcc, s[6:7]
	v_or_b32_e32 v35, 43, v0
	v_cndmask_b32_e32 v93, v40, v204, vcc
	v_cmp_gt_u32_e32 vcc, v35, v154
	v_cmp_lt_i32_e64 s[6:7], v35, v155
	s_or_b64 vcc, vcc, s[6:7]
	v_or_b32_e32 v35, 48, v0
	v_cndmask_b32_e32 v94, v41, v204, vcc
	v_cmp_gt_u32_e32 vcc, v35, v154
	v_cmp_lt_i32_e64 s[6:7], v35, v155
	s_or_b64 vcc, vcc, s[6:7]
	v_or_b32_e32 v35, 49, v0
	v_max3_f32 v50, v86, s35, v87
	v_cndmask_b32_e32 v95, v42, v204, vcc
	v_cmp_gt_u32_e32 vcc, v35, v154
	v_cmp_lt_i32_e64 s[6:7], v35, v155
	v_max3_f32 v50, v50, v88, v89
	s_or_b64 vcc, vcc, s[6:7]
	v_or_b32_e32 v35, 50, v0
	v_max3_f32 v50, v50, v90, v192
	v_cndmask_b32_e32 v96, v43, v204, vcc
	v_cmp_gt_u32_e32 vcc, v35, v154
	v_cmp_lt_i32_e64 s[6:7], v35, v155
	v_max3_f32 v50, v50, v191, v193
	s_or_b64 vcc, vcc, s[6:7]
	v_or_b32_e32 v35, 51, v0
	v_max3_f32 v50, v50, v188, v190
	v_cndmask_b32_e32 v161, v44, v204, vcc
	v_cmp_gt_u32_e32 vcc, v35, v154
	v_cmp_lt_i32_e64 s[6:7], v35, v155
	v_max3_f32 v50, v50, v189, v187
	s_or_b64 vcc, vcc, s[6:7]
	v_or_b32_e32 v35, 56, v0
	v_max3_f32 v50, v50, v186, v185
	v_cndmask_b32_e32 v163, v45, v204, vcc
	v_cmp_gt_u32_e32 vcc, v35, v154
	v_cmp_lt_i32_e64 s[6:7], v35, v155
	v_max3_f32 v50, v50, v184, v182
	s_or_b64 vcc, vcc, s[6:7]
	v_or_b32_e32 v35, 57, v0
	v_max3_f32 v34, v50, v164, v162
	v_cndmask_b32_e32 v165, v46, v204, vcc
	v_cmp_gt_u32_e32 vcc, v35, v154
	v_cmp_lt_i32_e64 s[6:7], v35, v155
	v_max3_f32 v34, v34, v160, v97
	s_or_b64 vcc, vcc, s[6:7]
	v_or_b32_e32 v35, 58, v0
	v_max3_f32 v34, v34, v92, v91
	v_cndmask_b32_e32 v180, v47, v204, vcc
	v_cmp_gt_u32_e32 vcc, v35, v154
	v_cmp_lt_i32_e64 s[6:7], v35, v155
	v_max3_f32 v34, v34, v93, v94
	s_or_b64 vcc, vcc, s[6:7]
	v_or_b32_e32 v0, 59, v0
	v_max3_f32 v34, v34, v95, v96
	v_cndmask_b32_e32 v181, v48, v204, vcc
	v_cmp_gt_u32_e32 vcc, v0, v154
	v_cmp_lt_i32_e64 s[6:7], v0, v155
	v_max3_f32 v34, v34, v161, v163
	s_or_b64 vcc, vcc, s[6:7]
	v_max3_f32 v34, v34, v165, v180
	v_cndmask_b32_e32 v183, v49, v204, vcc
	v_and_b32_e32 v35, 64, v202
	v_max3_f32 v0, v34, v181, v183
	v_xor_b32_e32 v34, 32, v202
	v_add_u32_e32 v35, 64, v35
	v_cmp_lt_i32_e32 vcc, v34, v35
	s_nop 1
	v_cndmask_b32_e32 v34, v202, v34, vcc
	v_lshlrev_b32_e32 v34, 2, v34
	ds_bpermute_b32 v34, v34, v0
	s_waitcnt lgkmcnt(0)
	v_max_f32_e32 v34, v34, v34
	v_max_f32_e32 v0, v0, v34
	v_mul_f32_e32 v0, 0x3fb8aa3b, v0
	v_max_f32_e32 v34, v157, v157
	v_sub_f32_e32 v232, v0, v34
	v_cmp_lt_f32_e32 vcc, 0x41000000, v232
	s_nop 1
	v_cndmask_b32_e32 v158, v34, v0, vcc
	v_sub_f32_e32 v0, v157, v158
	v_exp_f32_e32 v0, v0
	v_cmp_neq_f32_e32 vcc, v158, v157
	s_cbranch_vccz .LBB0_1001
	v_pk_mul_f32 v[32:33], v[32:33], v[0:1] op_sel_hi:[1,0]
	v_pk_mul_f32 v[30:31], v[30:31], v[0:1] op_sel_hi:[1,0]
	v_pk_mul_f32 v[28:29], v[28:29], v[0:1] op_sel_hi:[1,0]
	v_pk_mul_f32 v[26:27], v[26:27], v[0:1] op_sel_hi:[1,0]
	v_pk_mul_f32 v[24:25], v[24:25], v[0:1] op_sel_hi:[1,0]
	v_pk_mul_f32 v[22:23], v[22:23], v[0:1] op_sel_hi:[1,0]
	v_pk_mul_f32 v[20:21], v[20:21], v[0:1] op_sel_hi:[1,0]
	v_pk_mul_f32 v[18:19], v[18:19], v[0:1] op_sel_hi:[1,0]
	v_pk_mul_f32 v[16:17], v[16:17], v[0:1] op_sel_hi:[1,0]
	v_pk_mul_f32 v[14:15], v[14:15], v[0:1] op_sel_hi:[1,0]
	v_pk_mul_f32 v[12:13], v[12:13], v[0:1] op_sel_hi:[1,0]
	v_pk_mul_f32 v[10:11], v[10:11], v[0:1] op_sel_hi:[1,0]
	v_pk_mul_f32 v[8:9], v[8:9], v[0:1] op_sel_hi:[1,0]
	v_pk_mul_f32 v[6:7], v[6:7], v[0:1] op_sel_hi:[1,0]
	v_pk_mul_f32 v[4:5], v[4:5], v[0:1] op_sel_hi:[1,0]
	v_pk_mul_f32 v[2:3], v[2:3], v[0:1] op_sel_hi:[1,0]

;     ...
;   f32x16 s[2];
; #pragma unroll
;   for (int k2 = 0; k2 < 2; ++k2) {
;     if (!(HM & (1 << k2))) continue;
; #pragma unroll
;     for (int i = 0; i < 16; ++i) s[k2][i] = 0.f;
; #pragma unroll
;     for (int ks = 0; ks < 4; ++ks) {
;       const bf16x8 a = *(const bf16x8*)(Ks + (32 * k2 + r) * LSTR + 16 * ks + 8 * h);
;       s[k2] = mfma32(a, qf[ks], s[k2]);
;     }
;   }
;   if (MODE == 1) {
; #pragma unroll
;     for (int k2 = 0; k2 < 2; ++k2)
; #pragma unroll
;       for (int g = 0; g < 4; ++g) {
;         if (!(HM & (1 << k2))) continue;
;         const f32x4 cv = *(const f32x4*)(cn_lds + key0 + 32 * k2 + 8 * g + 4 * h);
; #pragma unroll
;         for (int e = 0; e < 4; ++e) s[k2][4 * g + e] = fmaf(s[k2][4 * g + e], L2E, cv[e]);
;       }
;   }
;   float mx = NINF;
; #pragma unroll
;   for (int k2 = 0; k2 < 2; ++k2)
; #pragma unroll
;     for (int i = 0; i < 16; ++i) {
;       if (!(HM & (1 << k2))) continue;
;       float v = s[k2][i];
;       if (MASKED) {
;         const int tk = key0 + 32 * k2 + crow(i, h);
;         const bool valid = (MODE == 0) ? ((tk <= tq) && (tq - tk <= maxdist)) : (tk <= tq);
;         v = valid ? v : NINF; s[k2][i] = v;
;       }
;       mx = fmaxf(mx, v);
;     }
;   mx = fmaxf(mx, __shfl_xor(mx, 32));
;   if (MODE != 1) mx *= L2E;
;   if (MODE == 2) mx = lanesel ? mx : NINF;
; template <int MODE>
; DI void flash_loop(char* smem, const bf16_t* Kbase, size_t ldk, const bf16_t* Vtbase, size_t ldv, ull tiles, ull wtiles,
;                    const bf16x8 (&qf)[4], f32x16 (&o)[2], float& m, float& l, int tq, int tqmin, int tqmax, int maxdist, const float* cn_lds, ull lmask) {
;     ...
;     if (!((wtiles >> kt) & 1ull)) return;
;     const bf16_t* Ks = (const bf16_t*)(smem + stage * (2 * 64 * LSTR * 2)); const bf16_t* Vs = Ks + 64 * LSTR;
;     const bool sel = ((lmask >> kt) & 1ull) != 0;
;     const bool interior = (64 * kt + 63 <= tqmin) && (MODE != 0 || (tqmax - 64 * kt <= maxdist));
;     int hm = 3;
;     if (MODE == 0) {
;       hm = 0;
;       if (64 * kt <= tqmax && 64 * kt + 31 >= tqmin - maxdist) hm |= 1;
;       if (64 * kt + 32 <= tqmax && 64 * kt + 63 >= tqmin - maxdist) hm |= 2;
;     }
;     if (MODE == 0 && hm == 1) attn_tile<MODE, true, 1>(Ks, Vs, qf, o, m, l, 64 * kt, tq, maxdist, cn_lds, sel);
;     else if (MODE == 0 && hm == 2) attn_tile<MODE, true, 2>(Ks, Vs, qf, o, m, l, 64 * kt, tq, maxdist, cn_lds, sel);
.LBB0_1018:
	s_lshr_b64 s[6:7], s[4:5], s64
	s_and_b32 s58, s6, 1
	s_cmp_eq_u64 s[58:59], 0
	s_cbranch_scc1 .LBB0_1042
	s_lshl_b32 s58, s64, 6
	s_or_b32 s33, s58, 63
	s_cmp_le_u32 s58, s3
	s_cselect_b64 s[6:7], -1, 0
	s_or_b32 s36, s58, 31
	s_cmp_ge_i32 s36, s29
	s_cselect_b64 s[36:37], -1, 0
	s_and_b64 s[6:7], s[6:7], s[36:37]
	v_cndmask_b32_e64 v0, 0, 1, s[6:7]
	s_or_b32 s6, s58, 32
	s_cmp_gt_u32 s6, s3
	s_cselect_b64 s[6:7], -1, 0
	s_cmp_lt_i32 s33, s29
	s_cselect_b64 s[36:37], -1, 0
	v_readfirstlane_b32 s38, v0
	s_or_b32 s39, s38, 2
	s_or_b64 s[6:7], s[6:7], s[36:37]
	s_and_b64 s[6:7], s[6:7], exec
	s_cselect_b32 s64, s38, s39
	s_mov_b64 s[62:63], -1
	s_mov_b64 s[54:55], 0
	s_cmp_lt_i32 s64, 2
	s_mov_b64 s[6:7], 0
	s_cbranch_scc1 .LBB0_1035
	s_cmp_eq_u32 s64, 2
	s_mov_b64 s[6:7], -1
	s_cbranch_scc0 .LBB0_1024
	ds_read_b128 v[34:37], v199 offset:23040
	ds_read_b128 v[50:53], v199 offset:23072
	v_or_b32_e32 v0, s58, v197
	s_waitcnt lgkmcnt(1)
	v_mfma_f32_32x32x16_bf16 v[34:49], v[34:37], v[98:101], 0
	s_waitcnt lgkmcnt(0)
	v_mfma_f32_32x32x16_bf16 v[34:49], v[50:53], v[102:105], v[34:49]
	ds_read_b128 v[50:53], v199 offset:23104
	s_waitcnt lgkmcnt(0)
	v_mfma_f32_32x32x16_bf16 v[34:49], v[50:53], v[106:109], v[34:49]
	ds_read_b128 v[50:53], v199 offset:23136
	s_waitcnt lgkmcnt(0)
	v_mfma_f32_32x32x16_bf16 v[34:49], v[50:53], v[110:113], v[34:49]
	v_or_b32_e32 v50, 32, v0
	v_cmp_gt_u32_e32 vcc, v50, v154
	v_cmp_lt_i32_e64 s[6:7], v50, v155
	s_or_b64 vcc, vcc, s[6:7]
	s_nop 7
	v_cndmask_b32_e32 v66, v34, v204, vcc
	v_bitop3_b32 v34, s58, v205, v197 bitop3:0x36
	v_cmp_ge_u32_e32 vcc, v50, v154
	v_cmp_gt_i32_e64 s[6:7], v34, v156
	s_or_b64 vcc, vcc, s[6:7]
	v_cndmask_b32_e32 v67, v35, v204, vcc
	v_or_b32_e32 v35, 34, v0
	v_cmp_gt_u32_e32 vcc, v35, v154
	v_cmp_lt_i32_e64 s[6:7], v35, v155
	s_or_b64 vcc, vcc, s[6:7]
	v_or_b32_e32 v35, 35, v0
	v_cndmask_b32_e32 v68, v36, v204, vcc
	v_cmp_gt_u32_e32 vcc, v35, v154
	v_cmp_lt_i32_e64 s[6:7], v35, v155
	s_or_b64 vcc, vcc, s[6:7]
	v_or_b32_e32 v35, 40, v0
	v_cndmask_b32_e32 v69, v37, v204, vcc
	v_cmp_gt_u32_e32 vcc, v35, v154
	v_cmp_lt_i32_e64 s[6:7], v35, v155
	s_or_b64 vcc, vcc, s[6:7]
	v_or_b32_e32 v35, 41, v0
	v_cndmask_b32_e32 v70, v38, v204, vcc
	v_cmp_gt_u32_e32 vcc, v35, v154
	v_cmp_lt_i32_e64 s[6:7], v35, v155
	s_or_b64 vcc, vcc, s[6:7]
	v_or_b32_e32 v35, 42, v0
	v_cndmask_b32_e32 v71, v39, v204, vcc
	v_cmp_gt_u32_e32 vcc, v35, v154
	v_cmp_lt_i32_e64 s[6:7], v35, v155
	s_or_b64 vcc, vcc, s[6:7]
	v_or_b32_e32 v35, 43, v0
	v_cndmask_b32_e32 v76, v40, v204, vcc
	v_cmp_gt_u32_e32 vcc, v35, v154
	v_cmp_lt_i32_e64 s[6:7], v35, v155
	s_or_b64 vcc, vcc, s[6:7]
	v_or_b32_e32 v35, 48, v0
	v_cndmask_b32_e32 v77, v41, v204, vcc
	v_cmp_gt_u32_e32 vcc, v35, v154
	v_cmp_lt_i32_e64 s[6:7], v35, v155
	s_or_b64 vcc, vcc, s[6:7]
	v_or_b32_e32 v35, 49, v0
	v_cndmask_b32_e32 v78, v42, v204, vcc
	v_cmp_gt_u32_e32 vcc, v35, v154
	v_cmp_lt_i32_e64 s[6:7], v35, v155
	s_or_b64 vcc, vcc, s[6:7]
	v_or_b32_e32 v35, 50, v0
	v_cndmask_b32_e32 v79, v43, v204, vcc
	v_cmp_gt_u32_e32 vcc, v35, v154
	v_cmp_lt_i32_e64 s[6:7], v35, v155
	s_or_b64 vcc, vcc, s[6:7]
	v_or_b32_e32 v35, 51, v0
	v_cndmask_b32_e32 v80, v44, v204, vcc
	v_cmp_gt_u32_e32 vcc, v35, v154
	v_cmp_lt_i32_e64 s[6:7], v35, v155
	s_or_b64 vcc, vcc, s[6:7]
	v_or_b32_e32 v35, 56, v0
	v_cndmask_b32_e32 v81, v45, v204, vcc
	v_cmp_gt_u32_e32 vcc, v35, v154
	v_cmp_lt_i32_e64 s[6:7], v35, v155
	s_or_b64 vcc, vcc, s[6:7]
	v_or_b32_e32 v35, 57, v0
	v_max3_f32 v34, v66, s35, v67
	v_cndmask_b32_e32 v73, v46, v204, vcc
	v_cmp_gt_u32_e32 vcc, v35, v154
	v_cmp_lt_i32_e64 s[6:7], v35, v155
	v_max3_f32 v34, v34, v68, v69
	s_or_b64 vcc, vcc, s[6:7]
	v_or_b32_e32 v35, 58, v0
	v_max3_f32 v34, v34, v70, v71
	v_cndmask_b32_e32 v74, v47, v204, vcc
	v_cmp_gt_u32_e32 vcc, v35, v154
	v_cmp_lt_i32_e64 s[6:7], v35, v155
	v_max3_f32 v34, v34, v76, v77
	s_or_b64 vcc, vcc, s[6:7]
	v_or_b32_e32 v0, 59, v0
	v_max3_f32 v34, v34, v78, v79
	v_cndmask_b32_e32 v75, v48, v204, vcc
	v_cmp_gt_u32_e32 vcc, v0, v154
	v_cmp_lt_i32_e64 s[6:7], v0, v155
	v_max3_f32 v34, v34, v80, v81
	s_or_b64 vcc, vcc, s[6:7]
	v_max3_f32 v34, v34, v73, v74
	v_cndmask_b32_e32 v72, v49, v204, vcc
	v_and_b32_e32 v35, 64, v202
	v_max3_f32 v0, v34, v75, v72
	v_xor_b32_e32 v34, 32, v202
	v_add_u32_e32 v35, 64, v35
	v_cmp_lt_i32_e32 vcc, v34, v35
	s_nop 1
	v_cndmask_b32_e32 v34, v202, v34, vcc
	v_lshlrev_b32_e32 v34, 2, v34
	ds_bpermute_b32 v34, v34, v0
	s_waitcnt lgkmcnt(0)
	v_max_f32_e32 v34, v34, v34
	v_max_f32_e32 v0, v0, v34
	v_mul_f32_e32 v0, 0x3fb8aa3b, v0
	v_max_f32_e32 v34, v158, v158
	v_sub_f32_e32 v232, v0, v34
	v_cmp_lt_f32_e32 vcc, 0x41000000, v232
	s_nop 1
	v_cndmask_b32_e32 v157, v34, v0, vcc
	v_sub_f32_e32 v0, v158, v157
	v_exp_f32_e32 v0, v0
	v_cmp_neq_f32_e32 vcc, v157, v158
	s_cbranch_vccz .LBB0_1023
	v_pk_mul_f32 v[32:33], v[32:33], v[0:1] op_sel_hi:[1,0]
	v_pk_mul_f32 v[30:31], v[30:31], v[0:1] op_sel_hi:[1,0]
	v_pk_mul_f32 v[28:29], v[28:29], v[0:1] op_sel_hi:[1,0]
	v_pk_mul_f32 v[26:27], v[26:27], v[0:1] op_sel_hi:[1,0]
	v_pk_mul_f32 v[24:25], v[24:25], v[0:1] op_sel_hi:[1,0]
	v_pk_mul_f32 v[22:23], v[22:23], v[0:1] op_sel_hi:[1,0]
	v_pk_mul_f32 v[20:21], v[20:21], v[0:1] op_sel_hi:[1,0]
	v_pk_mul_f32 v[18:19], v[18:19], v[0:1] op_sel_hi:[1,0]
	v_pk_mul_f32 v[16:17], v[16:17], v[0:1] op_sel_hi:[1,0]
	v_pk_mul_f32 v[14:15], v[14:15], v[0:1] op_sel_hi:[1,0]
	v_pk_mul_f32 v[12:13], v[12:13], v[0:1] op_sel_hi:[1,0]
	v_pk_mul_f32 v[10:11], v[10:11], v[0:1] op_sel_hi:[1,0]
	v_pk_mul_f32 v[8:9], v[8:9], v[0:1] op_sel_hi:[1,0]
	v_pk_mul_f32 v[6:7], v[6:7], v[0:1] op_sel_hi:[1,0]
	v_pk_mul_f32 v[4:5], v[4:5], v[0:1] op_sel_hi:[1,0]
	v_pk_mul_f32 v[2:3], v[2:3], v[0:1] op_sel_hi:[1,0]

; DI f32x16 mfma32(bf16x8 a, bf16x8 b, f32x16 c) { return __builtin_amdgcn_mfma_f32_32x32x16_bf16(a, b, c, 0, 0, 0); }
; DI int crow(int i, int h) { return (i & 3) + 8 * (i >> 2) + 4 * h; }
;     ...
;   f32x16 s[2];
; #pragma unroll
;   for (int k2 = 0; k2 < 2; ++k2) {
;     if (!(HM & (1 << k2))) continue;
; #pragma unroll
;     for (int i = 0; i < 16; ++i) s[k2][i] = 0.f;
; #pragma unroll
;     for (int ks = 0; ks < 4; ++ks) {
;       const bf16x8 a = *(const bf16x8*)(Ks + (32 * k2 + r) * LSTR + 16 * ks + 8 * h);
;       s[k2] = mfma32(a, qf[ks], s[k2]);
;     }
;   }
;   if (MODE == 1) {
; #pragma unroll
;     for (int k2 = 0; k2 < 2; ++k2)
; #pragma unroll
;       for (int g = 0; g < 4; ++g) {
;         if (!(HM & (1 << k2))) continue;
;         const f32x4 cv = *(const f32x4*)(cn_lds + key0 + 32 * k2 + 8 * g + 4 * h);
; #pragma unroll
;         for (int e = 0; e < 4; ++e) s[k2][4 * g + e] = fmaf(s[k2][4 * g + e], L2E, cv[e]);
;       }
;   }
;   float mx = NINF;
; #pragma unroll
;   for (int k2 = 0; k2 < 2; ++k2)
; #pragma unroll
;     for (int i = 0; i < 16; ++i) {
;       if (!(HM & (1 << k2))) continue;
;       float v = s[k2][i];
;       if (MASKED) {
;         const int tk = key0 + 32 * k2 + crow(i, h);
;         const bool valid = (MODE == 0) ? ((tk <= tq) && (tq - tk <= maxdist)) : (tk <= tq);
;         v = valid ? v : NINF; s[k2][i] = v;
;       }
;       mx = fmaxf(mx, v);
;     }
.LBB0_1026:
	ds_read_b128 v[82:85], v196 offset:18432
	ds_read_b128 v[78:81], v196 offset:18464
	ds_read_b128 v[74:77], v196 offset:18496
	ds_read_b128 v[66:69], v196 offset:18528
	ds_read_b128 v[70:73], v196 offset:23040
	s_cmp_le_u32 s33, s28
	s_cselect_b64 s[6:7], -1, 0
	s_cmp_ge_i32 s58, s30
	s_cselect_b64 s[36:37], -1, 0
	s_and_b64 s[6:7], s[6:7], s[36:37]
	s_andn2_b64 vcc, exec, s[6:7]
	s_mov_b64 s[6:7], -1
	s_cbranch_vccz .LBB0_1030
	s_waitcnt lgkmcnt(4)
	v_mfma_f32_32x32x16_bf16 v[50:65], v[82:85], v[98:101], 0
	ds_read_b128 v[86:89], v196 offset:23072
	ds_read_b128 v[90:93], v196 offset:23104
	v_or_b32_e32 v0, s58, v197
	v_cmp_gt_u32_e32 vcc, v0, v154
	v_cmp_lt_i32_e64 s[6:7], v0, v155
	s_or_b64 vcc, vcc, s[6:7]
	s_waitcnt lgkmcnt(5)
	v_mfma_f32_32x32x16_bf16 v[50:65], v[78:81], v[102:105], v[50:65]
	s_waitcnt lgkmcnt(2)
	v_mfma_f32_32x32x16_bf16 v[34:49], v[70:73], v[98:101], 0
	v_mfma_f32_32x32x16_bf16 v[50:65], v[74:77], v[106:109], v[50:65]
	s_waitcnt lgkmcnt(1)
	v_mfma_f32_32x32x16_bf16 v[34:49], v[86:89], v[102:105], v[34:49]
	ds_read_b128 v[86:89], v196 offset:23136
	v_mfma_f32_32x32x16_bf16 v[50:65], v[66:69], v[110:113], v[50:65]
	s_waitcnt lgkmcnt(1)
	v_mfma_f32_32x32x16_bf16 v[34:49], v[90:93], v[106:109], v[34:49]
	s_waitcnt lgkmcnt(0)
	v_mfma_f32_32x32x16_bf16 v[34:49], v[86:89], v[110:113], v[34:49]
	s_nop 7
	v_cndmask_b32_e32 v86, v50, v204, vcc
	v_bitop3_b32 v50, s58, v197, s58 bitop3:3
	v_cmp_ge_u32_e32 vcc, v0, v154
	v_cmp_lt_i32_e64 s[6:7], v156, v50
	s_or_b64 vcc, vcc, s[6:7]
	v_cndmask_b32_e32 v87, v51, v204, vcc
	v_or_b32_e32 v51, 2, v0
	v_cmp_gt_u32_e32 vcc, v51, v154
	v_cmp_lt_i32_e64 s[6:7], v51, v155
	s_or_b64 vcc, vcc, s[6:7]
	v_or_b32_e32 v51, 3, v0
	v_cndmask_b32_e32 v88, v52, v204, vcc
	v_cmp_gt_u32_e32 vcc, v51, v154
	v_cmp_lt_i32_e64 s[6:7], v51, v155
	s_or_b64 vcc, vcc, s[6:7]
	v_or_b32_e32 v51, 8, v0
	v_cndmask_b32_e32 v89, v53, v204, vcc
	v_cmp_gt_u32_e32 vcc, v51, v154
	v_cmp_lt_i32_e64 s[6:7], v51, v155
	s_or_b64 vcc, vcc, s[6:7]
	v_or_b32_e32 v51, 9, v0
	v_cndmask_b32_e32 v90, v54, v204, vcc
	v_cmp_gt_u32_e32 vcc, v51, v154
	v_cmp_lt_i32_e64 s[6:7], v51, v155
	s_or_b64 vcc, vcc, s[6:7]
	v_or_b32_e32 v51, 10, v0
	v_cndmask_b32_e32 v192, v55, v204, vcc
	v_cmp_gt_u32_e32 vcc, v51, v154
	v_cmp_lt_i32_e64 s[6:7], v51, v155
	s_or_b64 vcc, vcc, s[6:7]
	v_or_b32_e32 v51, 11, v0
	v_cndmask_b32_e32 v191, v56, v204, vcc
	v_cmp_gt_u32_e32 vcc, v51, v154
	v_cmp_lt_i32_e64 s[6:7], v51, v155
	s_or_b64 vcc, vcc, s[6:7]
	v_or_b32_e32 v51, 16, v0
	v_cndmask_b32_e32 v193, v57, v204, vcc
	v_cmp_gt_u32_e32 vcc, v51, v154
	v_cmp_lt_i32_e64 s[6:7], v51, v155
	s_or_b64 vcc, vcc, s[6:7]
	v_or_b32_e32 v51, 17, v0
	v_cndmask_b32_e32 v188, v58, v204, vcc
	v_cmp_gt_u32_e32 vcc, v51, v154
	v_cmp_lt_i32_e64 s[6:7], v51, v155
	s_or_b64 vcc, vcc, s[6:7]
	v_or_b32_e32 v51, 18, v0
	v_cndmask_b32_e32 v190, v59, v204, vcc
	v_cmp_gt_u32_e32 vcc, v51, v154
	v_cmp_lt_i32_e64 s[6:7], v51, v155
	s_or_b64 vcc, vcc, s[6:7]
	v_or_b32_e32 v51, 19, v0
	v_cndmask_b32_e32 v189, v60, v204, vcc
	v_cmp_gt_u32_e32 vcc, v51, v154
	v_cmp_lt_i32_e64 s[6:7], v51, v155
	s_or_b64 vcc, vcc, s[6:7]
	v_or_b32_e32 v51, 24, v0
	v_cndmask_b32_e32 v187, v61, v204, vcc
	v_cmp_gt_u32_e32 vcc, v51, v154
	v_cmp_lt_i32_e64 s[6:7], v51, v155
	s_or_b64 vcc, vcc, s[6:7]
	v_or_b32_e32 v51, 25, v0
	v_cndmask_b32_e32 v186, v62, v204, vcc
	v_cmp_gt_u32_e32 vcc, v51, v154
	v_cmp_lt_i32_e64 s[6:7], v51, v155
	s_or_b64 vcc, vcc, s[6:7]
	v_or_b32_e32 v51, 26, v0
	v_cndmask_b32_e32 v185, v63, v204, vcc
	v_cmp_gt_u32_e32 vcc, v51, v154
	v_cmp_lt_i32_e64 s[6:7], v51, v155
	s_or_b64 vcc, vcc, s[6:7]
	v_or_b32_e32 v51, 27, v0
	v_cndmask_b32_e32 v184, v64, v204, vcc
	v_cmp_gt_u32_e32 vcc, v51, v154
	v_cmp_lt_i32_e64 s[6:7], v51, v155
	s_or_b64 vcc, vcc, s[6:7]
	v_or_b32_e32 v51, 32, v0
	v_cndmask_b32_e32 v182, v65, v204, vcc
	v_cmp_gt_u32_e32 vcc, v51, v154
	v_cmp_lt_i32_e64 s[6:7], v51, v155
	s_or_b64 vcc, vcc, s[6:7]
	v_cndmask_b32_e32 v164, v34, v204, vcc
	v_or_b32_e32 v34, 33, v0
	v_cmp_gt_u32_e32 vcc, v34, v154
	v_cmp_lt_i32_e64 s[6:7], v34, v155
	s_or_b64 vcc, vcc, s[6:7]
	v_cndmask_b32_e32 v162, v35, v204, vcc
	v_or_b32_e32 v35, 34, v0
	v_cmp_gt_u32_e32 vcc, v35, v154
; DI int crow(int i, int h) { return (i & 3) + 8 * (i >> 2) + 4 * h; }
;     ...
;     for (int i = 0; i < 16; ++i) {
;       if (!(HM & (1 << k2))) continue;
;       float v = s[k2][i];
;       if (MASKED) {
;         const int tk = key0 + 32 * k2 + crow(i, h);
;         const bool valid = (MODE == 0) ? ((tk <= tq) && (tq - tk <= maxdist)) : (tk <= tq);
;         v = valid ? v : NINF; s[k2][i] = v;
;       }
;       mx = fmaxf(mx, v);
;     }
;   mx = fmaxf(mx, __shfl_xor(mx, 32));
;   if (MODE != 1) mx *= L2E;
;   if (MODE == 2) mx = lanesel ? mx : NINF;
;   const float mn = fmaxf(m, mx); const float alpha = __builtin_amdgcn_exp2f(m - mn);
;   const float neg = (MODE == 2 && !lanesel) ? NINF : -mn;
;   float ps = 0.f;
; #pragma unroll
;   for (int k2 = 0; k2 < 2; ++k2)
; #pragma unroll
;     for (int i = 0; i < 16; ++i) {
;       if (!(HM & (1 << k2))) continue;
;       const float pv = (MODE == 1) ? __builtin_amdgcn_exp2f(s[k2][i] + neg) : __builtin_amdgcn_exp2f(fmaf(s[k2][i], L2E, neg));
;       s[k2][i] = pv; ps += pv;
;     }
;   l = l * alpha + ps;
;   if (__builtin_amdgcn_ballot_w64(mn != m) != 0ull) {
; #pragma unroll
;     for (int dt = 0; dt < 2; ++dt)
; #pragma unroll
;       for (int i = 0; i < 16; ++i) o[dt][i] *= alpha;
;   }
	v_cmp_lt_i32_e64 s[6:7], v35, v155
	s_or_b64 vcc, vcc, s[6:7]
	v_or_b32_e32 v35, 35, v0
	v_cndmask_b32_e32 v159, v36, v204, vcc
	v_cmp_gt_u32_e32 vcc, v35, v154
	v_cmp_lt_i32_e64 s[6:7], v35, v155
	s_or_b64 vcc, vcc, s[6:7]
	v_or_b32_e32 v35, 40, v0
	v_cndmask_b32_e32 v97, v37, v204, vcc
	v_cmp_gt_u32_e32 vcc, v35, v154
	v_cmp_lt_i32_e64 s[6:7], v35, v155
	s_or_b64 vcc, vcc, s[6:7]
	v_or_b32_e32 v35, 41, v0
	v_cndmask_b32_e32 v92, v38, v204, vcc
	v_cmp_gt_u32_e32 vcc, v35, v154
	v_cmp_lt_i32_e64 s[6:7], v35, v155
	s_or_b64 vcc, vcc, s[6:7]
	v_or_b32_e32 v35, 42, v0
	v_cndmask_b32_e32 v91, v39, v204, vcc
	v_cmp_gt_u32_e32 vcc, v35, v154
	v_cmp_lt_i32_e64 s[6:7], v35, v155
	s_or_b64 vcc, vcc, s[6:7]
	v_or_b32_e32 v35, 43, v0
	v_cndmask_b32_e32 v93, v40, v204, vcc
	v_cmp_gt_u32_e32 vcc, v35, v154
	v_cmp_lt_i32_e64 s[6:7], v35, v155
	s_or_b64 vcc, vcc, s[6:7]
	v_or_b32_e32 v35, 48, v0
	v_cndmask_b32_e32 v94, v41, v204, vcc
	v_cmp_gt_u32_e32 vcc, v35, v154
	v_cmp_lt_i32_e64 s[6:7], v35, v155
	s_or_b64 vcc, vcc, s[6:7]
	v_or_b32_e32 v35, 49, v0
	v_max3_f32 v50, v86, s35, v87
	v_cndmask_b32_e32 v95, v42, v204, vcc
	v_cmp_gt_u32_e32 vcc, v35, v154
	v_cmp_lt_i32_e64 s[6:7], v35, v155
	v_max3_f32 v50, v50, v88, v89
	s_or_b64 vcc, vcc, s[6:7]
	v_or_b32_e32 v35, 50, v0
	v_max3_f32 v50, v50, v90, v192
	v_cndmask_b32_e32 v96, v43, v204, vcc
	v_cmp_gt_u32_e32 vcc, v35, v154
	v_cmp_lt_i32_e64 s[6:7], v35, v155
	v_max3_f32 v50, v50, v191, v193
	s_or_b64 vcc, vcc, s[6:7]
	v_or_b32_e32 v35, 51, v0
	v_max3_f32 v50, v50, v188, v190
	v_cndmask_b32_e32 v161, v44, v204, vcc
	v_cmp_gt_u32_e32 vcc, v35, v154
	v_cmp_lt_i32_e64 s[6:7], v35, v155
	v_max3_f32 v50, v50, v189, v187
	s_or_b64 vcc, vcc, s[6:7]
	v_or_b32_e32 v35, 56, v0
	v_max3_f32 v50, v50, v186, v185
	v_cndmask_b32_e32 v163, v45, v204, vcc
	v_cmp_gt_u32_e32 vcc, v35, v154
	v_cmp_lt_i32_e64 s[6:7], v35, v155
	v_max3_f32 v50, v50, v184, v182
	s_or_b64 vcc, vcc, s[6:7]
	v_or_b32_e32 v35, 57, v0
	v_max3_f32 v34, v50, v164, v162
	v_cndmask_b32_e32 v165, v46, v204, vcc
	v_cmp_gt_u32_e32 vcc, v35, v154
	v_cmp_lt_i32_e64 s[6:7], v35, v155
	v_max3_f32 v34, v34, v159, v97
	s_or_b64 vcc, vcc, s[6:7]
	v_or_b32_e32 v35, 58, v0
	v_max3_f32 v34, v34, v92, v91
	v_cndmask_b32_e32 v180, v47, v204, vcc
	v_cmp_gt_u32_e32 vcc, v35, v154
	v_cmp_lt_i32_e64 s[6:7], v35, v155
	v_max3_f32 v34, v34, v93, v94
	s_or_b64 vcc, vcc, s[6:7]
	v_or_b32_e32 v0, 59, v0
	v_max3_f32 v34, v34, v95, v96
	v_cndmask_b32_e32 v181, v48, v204, vcc
	v_cmp_gt_u32_e32 vcc, v0, v154
	v_cmp_lt_i32_e64 s[6:7], v0, v155
	v_max3_f32 v34, v34, v161, v163
	s_or_b64 vcc, vcc, s[6:7]
	v_max3_f32 v34, v34, v165, v180
	v_cndmask_b32_e32 v183, v49, v204, vcc
	v_and_b32_e32 v35, 64, v202
	v_max3_f32 v0, v34, v181, v183
	v_xor_b32_e32 v34, 32, v202
	v_add_u32_e32 v35, 64, v35
	v_cmp_lt_i32_e32 vcc, v34, v35
	s_nop 1
	v_cndmask_b32_e32 v34, v202, v34, vcc
	v_lshlrev_b32_e32 v34, 2, v34
	ds_bpermute_b32 v34, v34, v0
	s_waitcnt lgkmcnt(0)
	v_max_f32_e32 v34, v34, v34
	v_max_f32_e32 v0, v0, v34
	v_mul_f32_e32 v0, 0x3fb8aa3b, v0
	v_max_f32_e32 v34, v158, v158
	v_sub_f32_e32 v232, v0, v34
	v_cmp_lt_f32_e32 vcc, 0x41000000, v232
	s_nop 1
	v_cndmask_b32_e32 v157, v34, v0, vcc
	v_sub_f32_e32 v0, v158, v157
	v_exp_f32_e32 v0, v0
	v_cmp_neq_f32_e32 vcc, v157, v158
	s_cbranch_vccz .LBB0_1029
	v_pk_mul_f32 v[32:33], v[32:33], v[0:1] op_sel_hi:[1,0]
	v_pk_mul_f32 v[30:31], v[30:31], v[0:1] op_sel_hi:[1,0]
	v_pk_mul_f32 v[28:29], v[28:29], v[0:1] op_sel_hi:[1,0]
	v_pk_mul_f32 v[26:27], v[26:27], v[0:1] op_sel_hi:[1,0]
	v_pk_mul_f32 v[24:25], v[24:25], v[0:1] op_sel_hi:[1,0]
	v_pk_mul_f32 v[22:23], v[22:23], v[0:1] op_sel_hi:[1,0]
	v_pk_mul_f32 v[20:21], v[20:21], v[0:1] op_sel_hi:[1,0]
	v_pk_mul_f32 v[18:19], v[18:19], v[0:1] op_sel_hi:[1,0]
	v_pk_mul_f32 v[16:17], v[16:17], v[0:1] op_sel_hi:[1,0]
	v_pk_mul_f32 v[14:15], v[14:15], v[0:1] op_sel_hi:[1,0]
	v_pk_mul_f32 v[12:13], v[12:13], v[0:1] op_sel_hi:[1,0]
	v_pk_mul_f32 v[10:11], v[10:11], v[0:1] op_sel_hi:[1,0]
	v_pk_mul_f32 v[8:9], v[8:9], v[0:1] op_sel_hi:[1,0]
	v_pk_mul_f32 v[6:7], v[6:7], v[0:1] op_sel_hi:[1,0]
	v_pk_mul_f32 v[4:5], v[4:5], v[0:1] op_sel_hi:[1,0]
	v_pk_mul_f32 v[2:3], v[2:3], v[0:1] op_sel_hi:[1,0]
